# GEMM loops: LDS-DMA loads use scalar base + 32-bit lane offset (saddr form), 8 of 16 per iteration: removes the 64-bit VALU address adds from the load segments
# speedup vs baseline: 1.0149x; 1.0149x over previous
; #define PG8_STAGE(bufoff, gbase, voff) do { _Pragma("unroll") for (int _i = 0; _i < 2; ++_i) \
;         __builtin_amdgcn_global_load_lds((const unsigned*)((const char*)(gbase) + (voff)[_i]), (LAS unsigned*)(lds + (bufoff) + ldsw + _i * 8192), 16, 0, 0); } while (0)
; #define PG8_LDA(dst, b, h) do { _Pragma("unroll") for (int m = 0; m < 4; ++m) _Pragma("unroll") for (int k = 0; k < 2; ++k) dst[m][k] = *(const LAS bf16x8*)(lds + PG8_SA(b, h) + aoff + m * 2048 + k * 1024); } while (0)
; #define PG8_LDB(dst, b, h) do { _Pragma("unroll") for (int n = 0; n < 2; ++n) _Pragma("unroll") for (int k = 0; k < 2; ++k) dst[n][k] = *(const LAS bf16x8*)(lds + PG8_SB(b, h) + boff + n * 2048 + k * 1024); } while (0)
; #define PG8_MMA(ai, bj, At, Bt) do { __builtin_amdgcn_s_setprio(1); _Pragma("unroll") for (int m = 0; m < 4; ++m) _Pragma("unroll") for (int n = 0; n < 2; ++n) _Pragma("unroll") for (int k = 0; k < 2; ++k) \
;         acc[ai][bj][m][n] = __builtin_amdgcn_mfma_f32_16x16x32_bf16(Bt[n][k], At[m][k], acc[ai][bj][m][n], 0, 0, 0); __builtin_amdgcn_s_setprio(0); } while (0)
; #define PG8_WAIT_L(n) asm volatile("s_waitcnt lgkmcnt(" #n ")" ::: "memory")
; #define PG8_BAR __builtin_amdgcn_s_barrier()
; #define PG8_SCHED __builtin_amdgcn_sched_barrier(0)
; template <class Sched, class Epi>
; __device__ __forceinline__ void gemm_phase(LAS unsigned char* lds, const Sched& S, const Epi& E, const int K, const int lda, const int ldb) {
;     ...
;             PG8_LDB(B0, 0, 0); PG8_SCHED; PG8_LDA(At, 0, 0); PG8_STAGE(PG8_SA(1, 1), a1 + hstepA, voffA);
;             PG8_WAIT_L(8); PG8_BAR; PG8_WAIT_L(0); PG8_MMA(0, 0, At, B0); PG8_BAR; PG8_SCHED;
;             PG8_LDB(B1, 0, 1); PG8_STAGE(PG8_SB(0, 0), b2, voffB);
;             PG8_BAR; PG8_WAIT_L(0); PG8_MMA(0, 1, At, B1); PG8_BAR;
;             PG8_LDA(At, 0, 1); PG8_STAGE(PG8_SA(0, 0), a2, voffA);
;             PG8_BAR; PG8_WAIT_L(0); if (!chalf) PG8_MMA(1, 0, At, B0); PG8_BAR; PG8_SCHED;
.LBB0_393:
	ds_read_b128 v[146:149], v228
	ds_read_b128 v[150:153], v228 offset:1024
	ds_read_b128 v[154:157], v228 offset:2048
	ds_read_b128 v[158:161], v228 offset:3072
	s_add_u32 s4, s38, 0xfff80080
	s_addc_u32 s5, s39, -1
	s_cmp_eq_u32 s27, 28
	s_cselect_b32 s43, s29, s5
	s_cselect_b32 s42, s28, s4
	s_cselect_b32 s41, s35, s21
	s_cselect_b32 s40, s34, s19
	s_add_i32 m0, s10, 0xc000
	s_waitcnt lgkmcnt(0)
	ds_read_b128 v[162:165], v229
	ds_read_b128 v[166:169], v229 offset:1024
	ds_read_b128 v[170:173], v229 offset:2048
	ds_read_b128 v[174:177], v229 offset:3072
	ds_read_b128 v[178:181], v229 offset:4096
	ds_read_b128 v[182:185], v229 offset:5120
	ds_read_b128 v[186:189], v229 offset:6144
	ds_read_b128 v[190:193], v229 offset:7168
	global_load_lds_dwordx4 v206, s[38:39]
	s_add_i32 m0, s10, 0xe000
	s_nop 0
	global_load_lds_dwordx4 v204, s[38:39]
	s_waitcnt lgkmcnt(8)
	s_barrier
	s_waitcnt lgkmcnt(0)
	s_setprio 1
	s_waitcnt lgkmcnt(0)
	v_mfma_f32_16x16x32_bf16 v[126:129], v[146:149], v[162:165], v[126:129]
	v_mfma_f32_16x16x32_bf16 v[122:125], v[154:157], v[162:165], v[122:125]
	v_mfma_f32_16x16x32_bf16 v[114:117], v[146:149], v[170:173], v[114:117]
	v_mfma_f32_16x16x32_bf16 v[106:109], v[154:157], v[170:173], v[106:109]
	v_mfma_f32_16x16x32_bf16 v[98:101], v[146:149], v[178:181], v[98:101]
	v_mfma_f32_16x16x32_bf16 v[90:93], v[154:157], v[178:181], v[90:93]
	v_mfma_f32_16x16x32_bf16 v[82:85], v[146:149], v[186:189], v[82:85]
	v_mfma_f32_16x16x32_bf16 v[74:77], v[154:157], v[186:189], v[74:77]
	v_mfma_f32_16x16x32_bf16 v[126:129], v[150:153], v[166:169], v[126:129]
	v_mfma_f32_16x16x32_bf16 v[122:125], v[158:161], v[166:169], v[122:125]
	v_mfma_f32_16x16x32_bf16 v[114:117], v[150:153], v[174:177], v[114:117]
	v_mfma_f32_16x16x32_bf16 v[106:109], v[158:161], v[174:177], v[106:109]
	v_mfma_f32_16x16x32_bf16 v[98:101], v[150:153], v[182:185], v[98:101]
	v_mfma_f32_16x16x32_bf16 v[90:93], v[158:161], v[182:185], v[90:93]
	v_mfma_f32_16x16x32_bf16 v[82:85], v[150:153], v[190:193], v[82:85]
	v_mfma_f32_16x16x32_bf16 v[74:77], v[158:161], v[190:193], v[74:77]
	s_setprio 0
	s_barrier
	s_add_i32 s4, s54, s9
	v_lshl_add_u64 v[212:213], s[40:41], 0, v[196:197]
	s_mov_b32 m0, s4
	ds_read_b128 v[130:133], v231
	ds_read_b128 v[134:137], v231 offset:1024
	ds_read_b128 v[138:141], v231 offset:2048
	ds_read_b128 v[142:145], v231 offset:3072
	global_load_lds_dwordx4 v[212:213], off
	v_lshl_add_u64 v[214:215], s[40:41], 0, v[200:201]
	s_add_i32 m0, s4, 0x2000
	s_nop 0
	global_load_lds_dwordx4 v[214:215], off
	s_barrier
	s_waitcnt lgkmcnt(0)
	s_setprio 1
	s_waitcnt lgkmcnt(0)
	v_mfma_f32_16x16x32_bf16 v[118:121], v[130:133], v[162:165], v[118:121]
	v_mfma_f32_16x16x32_bf16 v[110:113], v[138:141], v[162:165], v[110:113]
	v_mfma_f32_16x16x32_bf16 v[102:105], v[130:133], v[170:173], v[102:105]
	v_mfma_f32_16x16x32_bf16 v[94:97], v[138:141], v[170:173], v[94:97]
	v_mfma_f32_16x16x32_bf16 v[86:89], v[130:133], v[178:181], v[86:89]
	v_mfma_f32_16x16x32_bf16 v[78:81], v[138:141], v[178:181], v[78:81]
	v_mfma_f32_16x16x32_bf16 v[70:73], v[130:133], v[186:189], v[70:73]
	v_mfma_f32_16x16x32_bf16 v[66:69], v[138:141], v[186:189], v[66:69]
	v_mfma_f32_16x16x32_bf16 v[118:121], v[134:137], v[166:169], v[118:121]
	v_mfma_f32_16x16x32_bf16 v[110:113], v[142:145], v[166:169], v[110:113]
	v_mfma_f32_16x16x32_bf16 v[102:105], v[134:137], v[174:177], v[102:105]
	v_mfma_f32_16x16x32_bf16 v[94:97], v[142:145], v[174:177], v[94:97]
	v_mfma_f32_16x16x32_bf16 v[86:89], v[134:137], v[182:185], v[86:89]
	v_mfma_f32_16x16x32_bf16 v[78:81], v[142:145], v[182:185], v[78:81]
	v_mfma_f32_16x16x32_bf16 v[70:73], v[134:137], v[190:193], v[70:73]
	v_mfma_f32_16x16x32_bf16 v[66:69], v[142:145], v[190:193], v[66:69]
	s_setprio 0
	s_mov_b32 m0, s10
	v_lshl_add_u64 v[216:217], s[42:43], 0, v[194:195]
	s_barrier
	ds_read_b128 v[186:189], v229 offset:16384
	ds_read_b128 v[190:193], v229 offset:17408
	ds_read_b128 v[178:181], v229 offset:18432
	ds_read_b128 v[182:185], v229 offset:19456
	ds_read_b128 v[170:173], v229 offset:20480
	ds_read_b128 v[174:177], v229 offset:21504
	ds_read_b128 v[162:165], v229 offset:22528
	ds_read_b128 v[166:169], v229 offset:23552
	global_load_lds_dwordx4 v[216:217], off
	v_lshl_add_u64 v[218:219], s[42:43], 0, v[198:199]
	s_mov_b32 m0, s11
	v_cmp_ne_u32_e64 s[4:5], 1, v232
	global_load_lds_dwordx4 v[218:219], off
	s_barrier
	s_waitcnt lgkmcnt(0)
	s_andn2_b64 vcc, exec, s[36:37]
	s_cbranch_vccnz .LBB0_395
	s_setprio 1
	s_waitcnt lgkmcnt(0)
	v_mfma_f32_16x16x32_bf16 v[62:65], v[146:149], v[186:189], v[62:65]
	v_mfma_f32_16x16x32_bf16 v[58:61], v[154:157], v[186:189], v[58:61]
	v_mfma_f32_16x16x32_bf16 v[46:49], v[146:149], v[178:181], v[46:49]
	v_mfma_f32_16x16x32_bf16 v[42:45], v[154:157], v[178:181], v[42:45]
	v_mfma_f32_16x16x32_bf16 v[30:33], v[146:149], v[170:173], v[30:33]
	v_mfma_f32_16x16x32_bf16 v[26:29], v[154:157], v[170:173], v[26:29]
	v_mfma_f32_16x16x32_bf16 v[14:17], v[146:149], v[162:165], v[14:17]
	v_mfma_f32_16x16x32_bf16 v[10:13], v[154:157], v[162:165], v[10:13]
	v_mfma_f32_16x16x32_bf16 v[62:65], v[150:153], v[190:193], v[62:65]
	v_mfma_f32_16x16x32_bf16 v[58:61], v[158:161], v[190:193], v[58:61]
	v_mfma_f32_16x16x32_bf16 v[46:49], v[150:153], v[182:185], v[46:49]
	v_mfma_f32_16x16x32_bf16 v[42:45], v[158:161], v[182:185], v[42:45]
	v_mfma_f32_16x16x32_bf16 v[30:33], v[150:153], v[174:177], v[30:33]
	v_mfma_f32_16x16x32_bf16 v[26:29], v[158:161], v[174:177], v[26:29]
	v_mfma_f32_16x16x32_bf16 v[14:17], v[150:153], v[166:169], v[14:17]
	v_mfma_f32_16x16x32_bf16 v[10:13], v[158:161], v[166:169], v[10:13]
	s_setprio 0
; #define PG8_STAGE(bufoff, gbase, voff) do { _Pragma("unroll") for (int _i = 0; _i < 2; ++_i) \
;         __builtin_amdgcn_global_load_lds((const unsigned*)((const char*)(gbase) + (voff)[_i]), (LAS unsigned*)(lds + (bufoff) + ldsw + _i * 8192), 16, 0, 0); } while (0)
; #define PG8_LDA(dst, b, h) do { _Pragma("unroll") for (int m = 0; m < 4; ++m) _Pragma("unroll") for (int k = 0; k < 2; ++k) dst[m][k] = *(const LAS bf16x8*)(lds + PG8_SA(b, h) + aoff + m * 2048 + k * 1024); } while (0)
; #define PG8_LDB(dst, b, h) do { _Pragma("unroll") for (int n = 0; n < 2; ++n) _Pragma("unroll") for (int k = 0; k < 2; ++k) dst[n][k] = *(const LAS bf16x8*)(lds + PG8_SB(b, h) + boff + n * 2048 + k * 1024); } while (0)
; #define PG8_MMA(ai, bj, At, Bt) do { __builtin_amdgcn_s_setprio(1); _Pragma("unroll") for (int m = 0; m < 4; ++m) _Pragma("unroll") for (int n = 0; n < 2; ++n) _Pragma("unroll") for (int k = 0; k < 2; ++k) \
;         acc[ai][bj][m][n] = __builtin_amdgcn_mfma_f32_16x16x32_bf16(Bt[n][k], At[m][k], acc[ai][bj][m][n], 0, 0, 0); __builtin_amdgcn_s_setprio(0); } while (0)
; #define PG8_WAIT_V(n) asm volatile("s_waitcnt vmcnt(" #n ")" ::: "memory")
; #define PG8_WAIT_L(n) asm volatile("s_waitcnt lgkmcnt(" #n ")" ::: "memory")
; #define PG8_BAR __builtin_amdgcn_s_barrier()
; #define PG8_SCHED __builtin_amdgcn_sched_barrier(0)
; template <class Sched, class Epi>
; __device__ __forceinline__ void gemm_phase(LAS unsigned char* lds, const Sched& S, const Epi& E, const int K, const int lda, const int ldb) {
;     ...
;             PG8_BAR; PG8_WAIT_L(0); if (!chalf) PG8_MMA(1, 0, At, B0); PG8_BAR; PG8_SCHED;
;             PG8_STAGE(PG8_SB(0, 1), b2 + hstepB, voffB);
;             PG8_WAIT_V(6); PG8_BAR; if (!chalf) PG8_MMA(1, 1, At, B1); PG8_BAR;
;             PG8_LDB(B0, 1, 0); PG8_SCHED; PG8_LDA(At, 1, 0); PG8_STAGE(PG8_SA(0, 1), a2 + hstepA, voffA);
;             PG8_WAIT_L(8); PG8_BAR; PG8_WAIT_L(0); PG8_MMA(0, 0, At, B0); PG8_BAR; PG8_SCHED;
;             PG8_LDB(B1, 1, 1); PG8_STAGE(PG8_SB(1, 0), b3, voffB);
;             PG8_BAR; PG8_WAIT_L(0); PG8_MMA(0, 1, At, B1); PG8_BAR;
;             PG8_LDA(At, 1, 1); PG8_STAGE(PG8_SA(1, 0), a3, voffA);
;             PG8_BAR; PG8_WAIT_L(0); if (!chalf) PG8_MMA(1, 0, At, B0); PG8_BAR; PG8_SCHED;
.LBB0_395:
	s_barrier
	s_add_u32 s58, s40, 0x80000
	s_addc_u32 s59, s41, 0
	s_mov_b32 m0, s13
	s_nop 0
	global_load_lds_dwordx4 v196, s[58:59]
	s_mov_b32 m0, s30
	s_and_b64 vcc, exec, s[4:5]
	global_load_lds_dwordx4 v200, s[58:59]
	s_waitcnt vmcnt(6)
	s_barrier
	s_cbranch_vccnz .LBB0_397
	s_setprio 1
	s_waitcnt lgkmcnt(0)
	v_mfma_f32_16x16x32_bf16 v[54:57], v[130:133], v[186:189], v[54:57]
	v_mfma_f32_16x16x32_bf16 v[50:53], v[138:141], v[186:189], v[50:53]
	v_mfma_f32_16x16x32_bf16 v[38:41], v[130:133], v[178:181], v[38:41]
	v_mfma_f32_16x16x32_bf16 v[34:37], v[138:141], v[178:181], v[34:37]
	v_mfma_f32_16x16x32_bf16 v[22:25], v[130:133], v[170:173], v[22:25]
	v_mfma_f32_16x16x32_bf16 v[18:21], v[138:141], v[170:173], v[18:21]
	v_mfma_f32_16x16x32_bf16 v[6:9], v[130:133], v[162:165], v[6:9]
	v_mfma_f32_16x16x32_bf16 v[2:5], v[138:141], v[162:165], v[2:5]
	v_mfma_f32_16x16x32_bf16 v[54:57], v[134:137], v[190:193], v[54:57]
	v_mfma_f32_16x16x32_bf16 v[50:53], v[142:145], v[190:193], v[50:53]
	v_mfma_f32_16x16x32_bf16 v[38:41], v[134:137], v[182:185], v[38:41]
	v_mfma_f32_16x16x32_bf16 v[34:37], v[142:145], v[182:185], v[34:37]
	v_mfma_f32_16x16x32_bf16 v[22:25], v[134:137], v[174:177], v[22:25]
	v_mfma_f32_16x16x32_bf16 v[18:21], v[142:145], v[174:177], v[18:21]
	v_mfma_f32_16x16x32_bf16 v[6:9], v[134:137], v[166:169], v[6:9]
	v_mfma_f32_16x16x32_bf16 v[2:5], v[142:145], v[166:169], v[2:5]
	s_setprio 0
.LBB0_397:
	s_add_i32 s57, 16, 0x18000
	v_add_u32_e32 v130, s57, v220
	s_barrier
	ds_read_b128 v[146:149], v130
	ds_read_b128 v[150:153], v130 offset:1024
	ds_read_b128 v[154:157], v130 offset:2048
	ds_read_b128 v[158:161], v130 offset:3072
	s_add_u32 s42, s42, 0x80000
	s_addc_u32 s43, s43, 0
	s_mov_b32 m0, s31
	s_waitcnt lgkmcnt(0)
	ds_read_b128 v[162:165], v229 offset:32768
	ds_read_b128 v[166:169], v229 offset:33792
	ds_read_b128 v[170:173], v229 offset:34816
	ds_read_b128 v[174:177], v229 offset:35840
	ds_read_b128 v[178:181], v229 offset:36864
	ds_read_b128 v[182:185], v229 offset:37888
	ds_read_b128 v[186:189], v229 offset:38912
	ds_read_b128 v[190:193], v229 offset:39936
	global_load_lds_dwordx4 v194, s[42:43]
	s_mov_b32 m0, s33
	s_nop 0
	global_load_lds_dwordx4 v198, s[42:43]
	s_waitcnt lgkmcnt(8)
	s_barrier
	s_waitcnt lgkmcnt(0)
	s_setprio 1
	s_waitcnt lgkmcnt(0)
	v_mfma_f32_16x16x32_bf16 v[126:129], v[146:149], v[162:165], v[126:129]
	v_mfma_f32_16x16x32_bf16 v[122:125], v[154:157], v[162:165], v[122:125]
	v_mfma_f32_16x16x32_bf16 v[114:117], v[146:149], v[170:173], v[114:117]
	v_mfma_f32_16x16x32_bf16 v[106:109], v[154:157], v[170:173], v[106:109]
	v_mfma_f32_16x16x32_bf16 v[98:101], v[146:149], v[178:181], v[98:101]
	v_mfma_f32_16x16x32_bf16 v[90:93], v[154:157], v[178:181], v[90:93]
	v_mfma_f32_16x16x32_bf16 v[82:85], v[146:149], v[186:189], v[82:85]
	v_mfma_f32_16x16x32_bf16 v[74:77], v[154:157], v[186:189], v[74:77]
	v_mfma_f32_16x16x32_bf16 v[126:129], v[150:153], v[166:169], v[126:129]
	v_mfma_f32_16x16x32_bf16 v[122:125], v[158:161], v[166:169], v[122:125]
	v_mfma_f32_16x16x32_bf16 v[114:117], v[150:153], v[174:177], v[114:117]
	v_mfma_f32_16x16x32_bf16 v[106:109], v[158:161], v[174:177], v[106:109]
	v_mfma_f32_16x16x32_bf16 v[98:101], v[150:153], v[182:185], v[98:101]
	v_mfma_f32_16x16x32_bf16 v[90:93], v[158:161], v[182:185], v[90:93]
	v_mfma_f32_16x16x32_bf16 v[82:85], v[150:153], v[190:193], v[82:85]
	v_mfma_f32_16x16x32_bf16 v[74:77], v[158:161], v[190:193], v[74:77]
	s_setprio 0
	s_barrier
	s_add_i32 s42, s57, s9
	v_add_u32_e32 v142, 0x1c000, v230
	v_lshl_add_u64 v[212:213], v[212:213], 0, s[14:15]
	s_mov_b32 m0, s42
	ds_read_b128 v[130:133], v142
	ds_read_b128 v[134:137], v142 offset:1024
	ds_read_b128 v[138:141], v142 offset:2048
	ds_read_b128 v[142:145], v142 offset:3072
	global_load_lds_dwordx4 v[212:213], off
	v_lshl_add_u64 v[212:213], v[214:215], 0, s[14:15]
	s_add_i32 m0, s42, 0x2000
	s_nop 0
	global_load_lds_dwordx4 v[212:213], off
	s_barrier
	s_waitcnt lgkmcnt(0)
	s_setprio 1
	s_waitcnt lgkmcnt(0)
	v_mfma_f32_16x16x32_bf16 v[118:121], v[130:133], v[162:165], v[118:121]
	v_mfma_f32_16x16x32_bf16 v[110:113], v[138:141], v[162:165], v[110:113]
	v_mfma_f32_16x16x32_bf16 v[102:105], v[130:133], v[170:173], v[102:105]
	v_mfma_f32_16x16x32_bf16 v[94:97], v[138:141], v[170:173], v[94:97]
	v_mfma_f32_16x16x32_bf16 v[86:89], v[130:133], v[178:181], v[86:89]
	v_mfma_f32_16x16x32_bf16 v[78:81], v[138:141], v[178:181], v[78:81]
	v_mfma_f32_16x16x32_bf16 v[70:73], v[130:133], v[186:189], v[70:73]
	v_mfma_f32_16x16x32_bf16 v[66:69], v[138:141], v[186:189], v[66:69]
	v_mfma_f32_16x16x32_bf16 v[118:121], v[134:137], v[166:169], v[118:121]
	v_mfma_f32_16x16x32_bf16 v[110:113], v[142:145], v[166:169], v[110:113]
	v_mfma_f32_16x16x32_bf16 v[102:105], v[134:137], v[174:177], v[102:105]
	v_mfma_f32_16x16x32_bf16 v[94:97], v[142:145], v[174:177], v[94:97]
	v_mfma_f32_16x16x32_bf16 v[86:89], v[134:137], v[182:185], v[86:89]
	v_mfma_f32_16x16x32_bf16 v[78:81], v[142:145], v[182:185], v[78:81]
	v_mfma_f32_16x16x32_bf16 v[70:73], v[134:137], v[190:193], v[70:73]
	v_mfma_f32_16x16x32_bf16 v[66:69], v[142:145], v[190:193], v[66:69]
	s_setprio 0
	s_mov_b32 m0, s46
	v_lshl_add_u64 v[212:213], v[216:217], 0, s[14:15]
	s_barrier
	ds_read_b128 v[186:189], v229 offset:49152
	ds_read_b128 v[190:193], v229 offset:50176
	ds_read_b128 v[178:181], v229 offset:51200
	ds_read_b128 v[182:185], v229 offset:52224
	ds_read_b128 v[170:173], v229 offset:53248
	ds_read_b128 v[174:177], v229 offset:54272
	ds_read_b128 v[162:165], v229 offset:55296
	ds_read_b128 v[166:169], v229 offset:56320
	global_load_lds_dwordx4 v[212:213], off
	v_lshl_add_u64 v[212:213], v[218:219], 0, s[14:15]
	s_mov_b32 m0, s47
	s_and_b64 vcc, exec, s[4:5]
	global_load_lds_dwordx4 v[212:213], off
	s_barrier
	s_waitcnt lgkmcnt(0)
	s_cbranch_vccnz .LBB0_399
	s_setprio 1
	s_waitcnt lgkmcnt(0)
	v_mfma_f32_16x16x32_bf16 v[62:65], v[146:149], v[186:189], v[62:65]
	v_mfma_f32_16x16x32_bf16 v[58:61], v[154:157], v[186:189], v[58:61]
	v_mfma_f32_16x16x32_bf16 v[46:49], v[146:149], v[178:181], v[46:49]
	v_mfma_f32_16x16x32_bf16 v[42:45], v[154:157], v[178:181], v[42:45]
	v_mfma_f32_16x16x32_bf16 v[30:33], v[146:149], v[170:173], v[30:33]
	v_mfma_f32_16x16x32_bf16 v[26:29], v[154:157], v[170:173], v[26:29]
	v_mfma_f32_16x16x32_bf16 v[14:17], v[146:149], v[162:165], v[14:17]
	v_mfma_f32_16x16x32_bf16 v[10:13], v[154:157], v[162:165], v[10:13]
	v_mfma_f32_16x16x32_bf16 v[62:65], v[150:153], v[190:193], v[62:65]
	v_mfma_f32_16x16x32_bf16 v[58:61], v[158:161], v[190:193], v[58:61]
	v_mfma_f32_16x16x32_bf16 v[46:49], v[150:153], v[182:185], v[46:49]
	v_mfma_f32_16x16x32_bf16 v[42:45], v[158:161], v[182:185], v[42:45]
	v_mfma_f32_16x16x32_bf16 v[30:33], v[150:153], v[174:177], v[30:33]
	v_mfma_f32_16x16x32_bf16 v[26:29], v[158:161], v[174:177], v[26:29]
	v_mfma_f32_16x16x32_bf16 v[14:17], v[150:153], v[166:169], v[14:17]
	v_mfma_f32_16x16x32_bf16 v[10:13], v[158:161], v[166:169], v[10:13]
	s_setprio 0
; #define PG8_STAGE(bufoff, gbase, voff) do { _Pragma("unroll") for (int _i = 0; _i < 2; ++_i) \
;         __builtin_amdgcn_global_load_lds((const unsigned*)((const char*)(gbase) + (voff)[_i]), (LAS unsigned*)(lds + (bufoff) + ldsw + _i * 8192), 16, 0, 0); } while (0)
; #define PG8_MMA(ai, bj, At, Bt) do { __builtin_amdgcn_s_setprio(1); _Pragma("unroll") for (int m = 0; m < 4; ++m) _Pragma("unroll") for (int n = 0; n < 2; ++n) _Pragma("unroll") for (int k = 0; k < 2; ++k) \
;         acc[ai][bj][m][n] = __builtin_amdgcn_mfma_f32_16x16x32_bf16(Bt[n][k], At[m][k], acc[ai][bj][m][n], 0, 0, 0); __builtin_amdgcn_s_setprio(0); } while (0)
; #define PG8_WAIT_V(n) asm volatile("s_waitcnt vmcnt(" #n ")" ::: "memory")
; #define PG8_BAR __builtin_amdgcn_s_barrier()
; template <class Sched, class Epi>
; __device__ __forceinline__ void gemm_phase(LAS unsigned char* lds, const Sched& S, const Epi& E, const int K, const int lda, const int ldb) {
;     ...
;             PG8_STAGE(PG8_SB(1, 1), b3 + hstepB, voffB);
;             PG8_WAIT_V(6); PG8_BAR; if (!chalf) PG8_MMA(1, 1, At, B1); PG8_BAR;
.LBB0_399:
	s_barrier
	s_add_u32 s40, s40, 0x80080
	s_addc_u32 s41, s41, 0
	s_mov_b32 m0, s48
	s_nop 0
	global_load_lds_dwordx4 v196, s[40:41]
	s_mov_b32 m0, s49
	s_and_b64 vcc, exec, s[4:5]
	global_load_lds_dwordx4 v200, s[40:41]
	s_waitcnt vmcnt(6)
	s_barrier
	s_cbranch_vccnz .LBB0_392
	s_setprio 1
	s_waitcnt lgkmcnt(0)
	v_mfma_f32_16x16x32_bf16 v[54:57], v[130:133], v[186:189], v[54:57]
	v_mfma_f32_16x16x32_bf16 v[50:53], v[138:141], v[186:189], v[50:53]
	v_mfma_f32_16x16x32_bf16 v[38:41], v[130:133], v[178:181], v[38:41]
	v_mfma_f32_16x16x32_bf16 v[34:37], v[138:141], v[178:181], v[34:37]
	v_mfma_f32_16x16x32_bf16 v[22:25], v[130:133], v[170:173], v[22:25]
	v_mfma_f32_16x16x32_bf16 v[18:21], v[138:141], v[170:173], v[18:21]
	v_mfma_f32_16x16x32_bf16 v[6:9], v[130:133], v[162:165], v[6:9]
	v_mfma_f32_16x16x32_bf16 v[2:5], v[138:141], v[162:165], v[2:5]
	v_mfma_f32_16x16x32_bf16 v[54:57], v[134:137], v[190:193], v[54:57]
	v_mfma_f32_16x16x32_bf16 v[50:53], v[142:145], v[190:193], v[50:53]
	v_mfma_f32_16x16x32_bf16 v[38:41], v[134:137], v[182:185], v[38:41]
	v_mfma_f32_16x16x32_bf16 v[34:37], v[142:145], v[182:185], v[34:37]
	v_mfma_f32_16x16x32_bf16 v[22:25], v[134:137], v[174:177], v[22:25]
	v_mfma_f32_16x16x32_bf16 v[18:21], v[142:145], v[174:177], v[18:21]
	v_mfma_f32_16x16x32_bf16 v[6:9], v[134:137], v[166:169], v[6:9]
	v_mfma_f32_16x16x32_bf16 v[2:5], v[142:145], v[166:169], v[2:5]
	s_setprio 0
	s_branch .LBB0_392

; #define PG8_STAGE(bufoff, gbase, voff) do { _Pragma("unroll") for (int _i = 0; _i < 2; ++_i) \
;         __builtin_amdgcn_global_load_lds((const unsigned*)((const char*)(gbase) + (voff)[_i]), (LAS unsigned*)(lds + (bufoff) + ldsw + _i * 8192), 16, 0, 0); } while (0)
; #define PG8_LDA(dst, b, h) do { _Pragma("unroll") for (int m = 0; m < 4; ++m) _Pragma("unroll") for (int k = 0; k < 2; ++k) dst[m][k] = *(const LAS bf16x8*)(lds + PG8_SA(b, h) + aoff + m * 2048 + k * 1024); } while (0)
; #define PG8_LDB(dst, b, h) do { _Pragma("unroll") for (int n = 0; n < 2; ++n) _Pragma("unroll") for (int k = 0; k < 2; ++k) dst[n][k] = *(const LAS bf16x8*)(lds + PG8_SB(b, h) + boff + n * 2048 + k * 1024); } while (0)
; #define PG8_MMA(ai, bj, At, Bt) do { __builtin_amdgcn_s_setprio(1); _Pragma("unroll") for (int m = 0; m < 4; ++m) _Pragma("unroll") for (int n = 0; n < 2; ++n) _Pragma("unroll") for (int k = 0; k < 2; ++k) \
;         acc[ai][bj][m][n] = __builtin_amdgcn_mfma_f32_16x16x32_bf16(Bt[n][k], At[m][k], acc[ai][bj][m][n], 0, 0, 0); __builtin_amdgcn_s_setprio(0); } while (0)
; #define PG8_WAIT_V(n) asm volatile("s_waitcnt vmcnt(" #n ")" ::: "memory")
; #define PG8_WAIT_L(n) asm volatile("s_waitcnt lgkmcnt(" #n ")" ::: "memory")
; #define PG8_BAR __builtin_amdgcn_s_barrier()
; #define PG8_SCHED __builtin_amdgcn_sched_barrier(0)
; template <class Sched, class Epi>
; __device__ __forceinline__ void gemm_phase(LAS unsigned char* lds, const Sched& S, const Epi& E, const int K, const int lda, const int ldb) {
;     ...
;             PG8_LDB(B0, 0, 0); PG8_SCHED; PG8_LDA(At, 0, 0); PG8_STAGE(PG8_SA(1, 1), a1 + hstepA, voffA);
;             PG8_WAIT_L(8); PG8_BAR; PG8_WAIT_L(0); PG8_MMA(0, 0, At, B0); PG8_BAR; PG8_SCHED;
;             PG8_LDB(B1, 0, 1); PG8_STAGE(PG8_SB(0, 0), b2, voffB);
;             PG8_BAR; PG8_WAIT_L(0); PG8_MMA(0, 1, At, B1); PG8_BAR;
;             PG8_LDA(At, 0, 1); PG8_STAGE(PG8_SA(0, 0), a2, voffA);
;             PG8_BAR; PG8_WAIT_L(0); if (!chalf) PG8_MMA(1, 0, At, B0); PG8_BAR; PG8_SCHED;
;             PG8_STAGE(PG8_SB(0, 1), b2 + hstepB, voffB);
;             PG8_WAIT_V(6); PG8_BAR; if (!chalf) PG8_MMA(1, 1, At, B1); PG8_BAR;
;             PG8_LDB(B0, 1, 0); PG8_SCHED; PG8_LDA(At, 1, 0); PG8_STAGE(PG8_SA(0, 1), a2 + hstepA, voffA);
;             PG8_WAIT_L(8); PG8_BAR; PG8_WAIT_L(0); PG8_MMA(0, 0, At, B0); PG8_BAR; PG8_SCHED;
.LBB0_430:
	ds_read_b128 v[2:5], v92
	ds_read_b128 v[6:9], v92 offset:1024
	ds_read_b128 v[10:13], v92 offset:2048
	ds_read_b128 v[14:17], v92 offset:3072
	s_add_u32 s52, s24, 0x40080
	s_addc_u32 s53, s25, 0
	s_mov_b32 m0, s46
	ds_read_b128 v[18:21], v93
	ds_read_b128 v[22:25], v93 offset:1024
	ds_read_b128 v[26:29], v93 offset:2048
	ds_read_b128 v[30:33], v93 offset:3072
	ds_read_b128 v[34:37], v93 offset:4096
	ds_read_b128 v[38:41], v93 offset:5120
	ds_read_b128 v[42:45], v93 offset:6144
	ds_read_b128 v[46:49], v93 offset:7168
	global_load_lds_dwordx4 v80, s[52:53]
	s_mov_b32 m0, s47
	s_nop 0
	global_load_lds_dwordx4 v76, s[52:53]
	s_waitcnt lgkmcnt(8)
	s_barrier
	s_waitcnt lgkmcnt(0)
	s_setprio 1
	s_waitcnt lgkmcnt(0)
	v_mfma_f32_16x16x32_bf16 v[50:53], v[2:5], v[18:21], 0
	v_mfma_f32_16x16x32_bf16 v[54:57], v[10:13], v[18:21], 0
	v_mfma_f32_16x16x32_bf16 v[58:61], v[2:5], v[26:29], 0
	v_mfma_f32_16x16x32_bf16 v[62:65], v[10:13], v[26:29], 0
	v_mfma_f32_16x16x32_bf16 v[66:69], v[2:5], v[34:37], 0
	v_mfma_f32_16x16x32_bf16 v[70:73], v[10:13], v[34:37], 0
	v_mfma_f32_16x16x32_bf16 v[96:99], v[2:5], v[42:45], 0
	v_mfma_f32_16x16x32_bf16 v[100:103], v[10:13], v[42:45], 0
	v_mfma_f32_16x16x32_bf16 v[50:53], v[6:9], v[22:25], v[50:53]
	v_mfma_f32_16x16x32_bf16 v[54:57], v[14:17], v[22:25], v[54:57]
	v_mfma_f32_16x16x32_bf16 v[58:61], v[6:9], v[30:33], v[58:61]
	v_mfma_f32_16x16x32_bf16 v[62:65], v[14:17], v[30:33], v[62:65]
	v_mfma_f32_16x16x32_bf16 v[66:69], v[6:9], v[38:41], v[66:69]
	v_mfma_f32_16x16x32_bf16 v[70:73], v[14:17], v[38:41], v[70:73]
	v_mfma_f32_16x16x32_bf16 v[96:99], v[6:9], v[46:49], v[96:99]
	v_mfma_f32_16x16x32_bf16 v[100:103], v[14:17], v[46:49], v[100:103]
	s_setprio 0
	s_barrier
	v_lshl_add_u64 v[216:217], s[26:27], 0, v[78:79]
	s_mov_b32 m0, s48
	v_lshl_add_u64 v[120:121], v[216:217], 0, s[8:9]
	v_lshl_add_u64 v[218:219], s[26:27], 0, v[74:75]
	s_add_i32 s52, s48, 0x2000
	ds_read_b128 v[104:107], v94
	ds_read_b128 v[108:111], v94 offset:1024
	ds_read_b128 v[112:115], v94 offset:2048
	ds_read_b128 v[116:119], v94 offset:3072
	global_load_lds_dwordx4 v[120:121], off
	v_lshl_add_u64 v[120:121], v[218:219], 0, s[8:9]
	s_mov_b32 m0, s52
	s_nop 0
	global_load_lds_dwordx4 v[120:121], off
	s_barrier
	s_waitcnt lgkmcnt(0)
	s_setprio 1
	s_waitcnt lgkmcnt(0)
	v_mfma_f32_16x16x32_bf16 v[120:123], v[104:107], v[18:21], 0
	v_mfma_f32_16x16x32_bf16 v[18:21], v[112:115], v[18:21], 0
	v_mfma_f32_16x16x32_bf16 v[120:123], v[108:111], v[22:25], v[120:123]
	v_mfma_f32_16x16x32_bf16 v[18:21], v[116:119], v[22:25], v[18:21]
	v_mfma_f32_16x16x32_bf16 v[22:25], v[104:107], v[26:29], 0
	v_mfma_f32_16x16x32_bf16 v[26:29], v[112:115], v[26:29], 0
	v_mfma_f32_16x16x32_bf16 v[22:25], v[108:111], v[30:33], v[22:25]
	v_mfma_f32_16x16x32_bf16 v[26:29], v[116:119], v[30:33], v[26:29]
	v_mfma_f32_16x16x32_bf16 v[30:33], v[104:107], v[34:37], 0
	v_mfma_f32_16x16x32_bf16 v[34:37], v[112:115], v[34:37], 0
	v_mfma_f32_16x16x32_bf16 v[30:33], v[108:111], v[38:41], v[30:33]
	v_mfma_f32_16x16x32_bf16 v[34:37], v[116:119], v[38:41], v[34:37]
	v_mfma_f32_16x16x32_bf16 v[38:41], v[104:107], v[42:45], 0
	v_mfma_f32_16x16x32_bf16 v[42:45], v[112:115], v[42:45], 0
	v_mfma_f32_16x16x32_bf16 v[38:41], v[108:111], v[46:49], v[38:41]
	v_mfma_f32_16x16x32_bf16 v[42:45], v[116:119], v[46:49], v[42:45]
	s_setprio 0
	v_lshl_add_u64 v[220:221], s[24:25], 0, v[80:81]
	s_mov_b32 m0, s11
	v_lshl_add_u64 v[152:153], v[220:221], 0, s[8:9]
	v_lshl_add_u64 v[222:223], s[24:25], 0, v[76:77]
	s_barrier
	ds_read_b128 v[46:49], v93 offset:16384
	ds_read_b128 v[124:127], v93 offset:17408
	ds_read_b128 v[128:131], v93 offset:18432
	ds_read_b128 v[132:135], v93 offset:19456
	ds_read_b128 v[136:139], v93 offset:20480
	ds_read_b128 v[140:143], v93 offset:21504
	ds_read_b128 v[144:147], v93 offset:22528
	ds_read_b128 v[148:151], v93 offset:23552
	global_load_lds_dwordx4 v[152:153], off
	v_lshl_add_u64 v[152:153], v[222:223], 0, s[8:9]
	s_mov_b32 m0, s28
	s_nop 0
	global_load_lds_dwordx4 v[152:153], off
	s_barrier
	s_waitcnt lgkmcnt(0)
	s_setprio 1
	s_waitcnt lgkmcnt(0)
	v_mfma_f32_16x16x32_bf16 v[152:155], v[2:5], v[46:49], 0
	v_mfma_f32_16x16x32_bf16 v[160:163], v[2:5], v[128:131], 0
	v_mfma_f32_16x16x32_bf16 v[168:171], v[2:5], v[136:139], 0
	v_mfma_f32_16x16x32_bf16 v[2:5], v[2:5], v[144:147], 0
	v_mfma_f32_16x16x32_bf16 v[152:155], v[6:9], v[124:127], v[152:155]
	v_mfma_f32_16x16x32_bf16 v[156:159], v[10:13], v[46:49], 0
	v_mfma_f32_16x16x32_bf16 v[160:163], v[6:9], v[132:135], v[160:163]
	v_mfma_f32_16x16x32_bf16 v[164:167], v[10:13], v[128:131], 0
	v_mfma_f32_16x16x32_bf16 v[168:171], v[6:9], v[140:143], v[168:171]
	v_mfma_f32_16x16x32_bf16 v[172:175], v[10:13], v[136:139], 0
	v_mfma_f32_16x16x32_bf16 v[2:5], v[6:9], v[148:151], v[2:5]
	v_mfma_f32_16x16x32_bf16 v[6:9], v[10:13], v[144:147], 0
	v_mfma_f32_16x16x32_bf16 v[156:159], v[14:17], v[124:127], v[156:159]
	v_mfma_f32_16x16x32_bf16 v[164:167], v[14:17], v[132:135], v[164:167]
	v_mfma_f32_16x16x32_bf16 v[172:175], v[14:17], v[140:143], v[172:175]
	v_mfma_f32_16x16x32_bf16 v[6:9], v[14:17], v[148:151], v[6:9]
	s_setprio 0
	s_barrier
	s_add_u32 s56, s26, 0x10100
	s_addc_u32 s57, s27, 0
	s_add_i32 s54, s45, s2
	s_mov_b32 m0, s54
	s_add_i32 s53, s54, 0x2000
	global_load_lds_dwordx4 v78, s[56:57]
	s_mov_b32 m0, s53
	s_nop 0
	global_load_lds_dwordx4 v74, s[56:57]
	s_waitcnt vmcnt(6)
	s_barrier
; #define PG8_STAGE(bufoff, gbase, voff) do { _Pragma("unroll") for (int _i = 0; _i < 2; ++_i) \
;         __builtin_amdgcn_global_load_lds((const unsigned*)((const char*)(gbase) + (voff)[_i]), (LAS unsigned*)(lds + (bufoff) + ldsw + _i * 8192), 16, 0, 0); } while (0)
; #define PG8_LDA(dst, b, h) do { _Pragma("unroll") for (int m = 0; m < 4; ++m) _Pragma("unroll") for (int k = 0; k < 2; ++k) dst[m][k] = *(const LAS bf16x8*)(lds + PG8_SA(b, h) + aoff + m * 2048 + k * 1024); } while (0)
; #define PG8_LDB(dst, b, h) do { _Pragma("unroll") for (int n = 0; n < 2; ++n) _Pragma("unroll") for (int k = 0; k < 2; ++k) dst[n][k] = *(const LAS bf16x8*)(lds + PG8_SB(b, h) + boff + n * 2048 + k * 1024); } while (0)
; #define PG8_MMA(ai, bj, At, Bt) do { __builtin_amdgcn_s_setprio(1); _Pragma("unroll") for (int m = 0; m < 4; ++m) _Pragma("unroll") for (int n = 0; n < 2; ++n) _Pragma("unroll") for (int k = 0; k < 2; ++k) \
;         acc[ai][bj][m][n] = __builtin_amdgcn_mfma_f32_16x16x32_bf16(Bt[n][k], At[m][k], acc[ai][bj][m][n], 0, 0, 0); __builtin_amdgcn_s_setprio(0); } while (0)
; #define PG8_WAIT_V(n) asm volatile("s_waitcnt vmcnt(" #n ")" ::: "memory")
; #define PG8_WAIT_L(n) asm volatile("s_waitcnt lgkmcnt(" #n ")" ::: "memory")
; #define PG8_BAR __builtin_amdgcn_s_barrier()
; #define PG8_SCHED __builtin_amdgcn_sched_barrier(0)
; template <class Sched, class Epi>
; __device__ __forceinline__ void gemm_phase(LAS unsigned char* lds, const Sched& S, const Epi& E, const int K, const int lda, const int ldb) {
;     ...
;             PG8_BAR; PG8_WAIT_L(0); if (!chalf) PG8_MMA(1, 0, At, B0); PG8_BAR; PG8_SCHED;
;             PG8_STAGE(PG8_SB(0, 1), b2 + hstepB, voffB);
;             PG8_WAIT_V(6); PG8_BAR; if (!chalf) PG8_MMA(1, 1, At, B1); PG8_BAR;
;             PG8_LDB(B0, 1, 0); PG8_SCHED; PG8_LDA(At, 1, 0); PG8_STAGE(PG8_SA(0, 1), a2 + hstepA, voffA);
;             PG8_WAIT_L(8); PG8_BAR; PG8_WAIT_L(0); PG8_MMA(0, 0, At, B0); PG8_BAR; PG8_SCHED;
;             PG8_LDB(B1, 1, 1); PG8_STAGE(PG8_SB(1, 0), b3, voffB);
;             PG8_BAR; PG8_WAIT_L(0); PG8_MMA(0, 1, At, B1); PG8_BAR;
;             PG8_LDA(At, 1, 1); PG8_STAGE(PG8_SA(1, 0), a3, voffA);
;             PG8_BAR; PG8_WAIT_L(0); if (!chalf) PG8_MMA(1, 0, At, B0); PG8_BAR; PG8_SCHED;
	s_setprio 1
	v_mfma_f32_16x16x32_bf16 v[10:13], v[104:107], v[46:49], 0
	v_mfma_f32_16x16x32_bf16 v[14:17], v[112:115], v[46:49], 0
	v_mfma_f32_16x16x32_bf16 v[10:13], v[108:111], v[124:127], v[10:13]
	v_mfma_f32_16x16x32_bf16 v[14:17], v[116:119], v[124:127], v[14:17]
	v_mfma_f32_16x16x32_bf16 v[46:49], v[104:107], v[128:131], 0
	v_mfma_f32_16x16x32_bf16 v[124:127], v[112:115], v[128:131], 0
	v_mfma_f32_16x16x32_bf16 v[128:131], v[104:107], v[136:139], 0
	v_mfma_f32_16x16x32_bf16 v[104:107], v[104:107], v[144:147], 0
	v_mfma_f32_16x16x32_bf16 v[46:49], v[108:111], v[132:135], v[46:49]
	v_mfma_f32_16x16x32_bf16 v[124:127], v[116:119], v[132:135], v[124:127]
	v_mfma_f32_16x16x32_bf16 v[128:131], v[108:111], v[140:143], v[128:131]
	v_mfma_f32_16x16x32_bf16 v[132:135], v[112:115], v[136:139], 0
	v_mfma_f32_16x16x32_bf16 v[104:107], v[108:111], v[148:151], v[104:107]
	v_mfma_f32_16x16x32_bf16 v[108:111], v[112:115], v[144:147], 0
	v_mfma_f32_16x16x32_bf16 v[132:135], v[116:119], v[140:143], v[132:135]
	v_mfma_f32_16x16x32_bf16 v[108:111], v[116:119], v[148:151], v[108:111]
	s_setprio 0
	s_add_i32 s55, 16, 0x18000
	v_add_u32_e32 v95, s55, v84
	s_barrier
	ds_read_b128 v[112:115], v95
	ds_read_b128 v[116:119], v95 offset:1024
	ds_read_b128 v[136:139], v95 offset:2048
	ds_read_b128 v[140:143], v95 offset:3072
	s_add_u32 s56, s24, 0x40100
	s_addc_u32 s57, s25, 0
	s_mov_b32 m0, s29
	ds_read_b128 v[144:147], v93 offset:32768
	ds_read_b128 v[148:151], v93 offset:33792
	ds_read_b128 v[176:179], v93 offset:34816
	ds_read_b128 v[180:183], v93 offset:35840
	ds_read_b128 v[184:187], v93 offset:36864
	ds_read_b128 v[188:191], v93 offset:37888
	ds_read_b128 v[192:195], v93 offset:38912
	ds_read_b128 v[196:199], v93 offset:39936
	global_load_lds_dwordx4 v80, s[56:57]
	s_mov_b32 m0, s30
	s_nop 0
	global_load_lds_dwordx4 v76, s[56:57]
	s_waitcnt lgkmcnt(8)
	s_barrier
	s_waitcnt lgkmcnt(0)
	s_setprio 1
	s_waitcnt lgkmcnt(0)
	v_mfma_f32_16x16x32_bf16 v[50:53], v[112:115], v[144:147], v[50:53]
	v_mfma_f32_16x16x32_bf16 v[54:57], v[136:139], v[144:147], v[54:57]
	v_mfma_f32_16x16x32_bf16 v[58:61], v[112:115], v[176:179], v[58:61]
	v_mfma_f32_16x16x32_bf16 v[62:65], v[136:139], v[176:179], v[62:65]
	v_mfma_f32_16x16x32_bf16 v[66:69], v[112:115], v[184:187], v[66:69]
	v_mfma_f32_16x16x32_bf16 v[70:73], v[136:139], v[184:187], v[70:73]
	v_mfma_f32_16x16x32_bf16 v[96:99], v[112:115], v[192:195], v[96:99]
	v_mfma_f32_16x16x32_bf16 v[100:103], v[136:139], v[192:195], v[100:103]
	v_mfma_f32_16x16x32_bf16 v[50:53], v[116:119], v[148:151], v[50:53]
	v_mfma_f32_16x16x32_bf16 v[54:57], v[140:143], v[148:151], v[54:57]
	v_mfma_f32_16x16x32_bf16 v[58:61], v[116:119], v[180:183], v[58:61]
	v_mfma_f32_16x16x32_bf16 v[62:65], v[140:143], v[180:183], v[62:65]
	v_mfma_f32_16x16x32_bf16 v[66:69], v[116:119], v[188:191], v[66:69]
	v_mfma_f32_16x16x32_bf16 v[70:73], v[140:143], v[188:191], v[70:73]
	v_mfma_f32_16x16x32_bf16 v[96:99], v[116:119], v[196:199], v[96:99]
	v_mfma_f32_16x16x32_bf16 v[100:103], v[140:143], v[196:199], v[100:103]
	s_setprio 0
	s_barrier
	s_add_i32 s57, 16, 0x1c000
	s_add_i32 s56, s55, s2
	v_add_u32_e32 v228, s57, v84
	v_lshl_add_u64 v[216:217], v[216:217], 0, s[16:17]
	s_mov_b32 m0, s56
	s_add_i32 s55, s56, 0x2000
	ds_read_b128 v[200:203], v228
	ds_read_b128 v[204:207], v228 offset:1024
	ds_read_b128 v[208:211], v228 offset:2048
	ds_read_b128 v[212:215], v228 offset:3072
	global_load_lds_dwordx4 v[216:217], off
	v_lshl_add_u64 v[216:217], v[218:219], 0, s[16:17]
	s_mov_b32 m0, s55
	s_nop 0
	global_load_lds_dwordx4 v[216:217], off
	s_barrier
	s_waitcnt lgkmcnt(0)
	s_setprio 1
	s_waitcnt lgkmcnt(0)
	v_mfma_f32_16x16x32_bf16 v[120:123], v[200:203], v[144:147], v[120:123]
	v_mfma_f32_16x16x32_bf16 v[18:21], v[208:211], v[144:147], v[18:21]
	v_mfma_f32_16x16x32_bf16 v[22:25], v[200:203], v[176:179], v[22:25]
	v_mfma_f32_16x16x32_bf16 v[26:29], v[208:211], v[176:179], v[26:29]
	v_mfma_f32_16x16x32_bf16 v[30:33], v[200:203], v[184:187], v[30:33]
	v_mfma_f32_16x16x32_bf16 v[34:37], v[208:211], v[184:187], v[34:37]
	v_mfma_f32_16x16x32_bf16 v[38:41], v[200:203], v[192:195], v[38:41]
	v_mfma_f32_16x16x32_bf16 v[42:45], v[208:211], v[192:195], v[42:45]
	v_mfma_f32_16x16x32_bf16 v[120:123], v[204:207], v[148:151], v[120:123]
	v_mfma_f32_16x16x32_bf16 v[18:21], v[212:215], v[148:151], v[18:21]
	v_mfma_f32_16x16x32_bf16 v[22:25], v[204:207], v[180:183], v[22:25]
	v_mfma_f32_16x16x32_bf16 v[26:29], v[212:215], v[180:183], v[26:29]
	v_mfma_f32_16x16x32_bf16 v[30:33], v[204:207], v[188:191], v[30:33]
	v_mfma_f32_16x16x32_bf16 v[34:37], v[212:215], v[188:191], v[34:37]
	v_mfma_f32_16x16x32_bf16 v[38:41], v[204:207], v[196:199], v[38:41]
	v_mfma_f32_16x16x32_bf16 v[42:45], v[212:215], v[196:199], v[42:45]
	s_setprio 0
	s_mov_b32 m0, s33
	v_lshl_add_u64 v[216:217], v[220:221], 0, s[16:17]
	s_barrier
	ds_read_b128 v[144:147], v93 offset:49152
	ds_read_b128 v[148:151], v93 offset:50176
	ds_read_b128 v[176:179], v93 offset:51200
	ds_read_b128 v[180:183], v93 offset:52224
	ds_read_b128 v[184:187], v93 offset:53248
	ds_read_b128 v[188:191], v93 offset:54272
	ds_read_b128 v[192:195], v93 offset:55296
	ds_read_b128 v[196:199], v93 offset:56320
	global_load_lds_dwordx4 v[216:217], off
	v_lshl_add_u64 v[216:217], v[222:223], 0, s[16:17]
	s_mov_b32 m0, s34
	s_nop 0
	global_load_lds_dwordx4 v[216:217], off
	s_barrier
; #define PG8_STAGE(bufoff, gbase, voff) do { _Pragma("unroll") for (int _i = 0; _i < 2; ++_i) \
;         __builtin_amdgcn_global_load_lds((const unsigned*)((const char*)(gbase) + (voff)[_i]), (LAS unsigned*)(lds + (bufoff) + ldsw + _i * 8192), 16, 0, 0); } while (0)
; #define PG8_LDA(dst, b, h) do { _Pragma("unroll") for (int m = 0; m < 4; ++m) _Pragma("unroll") for (int k = 0; k < 2; ++k) dst[m][k] = *(const LAS bf16x8*)(lds + PG8_SA(b, h) + aoff + m * 2048 + k * 1024); } while (0)
; #define PG8_LDB(dst, b, h) do { _Pragma("unroll") for (int n = 0; n < 2; ++n) _Pragma("unroll") for (int k = 0; k < 2; ++k) dst[n][k] = *(const LAS bf16x8*)(lds + PG8_SB(b, h) + boff + n * 2048 + k * 1024); } while (0)
; #define PG8_MMA(ai, bj, At, Bt) do { __builtin_amdgcn_s_setprio(1); _Pragma("unroll") for (int m = 0; m < 4; ++m) _Pragma("unroll") for (int n = 0; n < 2; ++n) _Pragma("unroll") for (int k = 0; k < 2; ++k) \
;         acc[ai][bj][m][n] = __builtin_amdgcn_mfma_f32_16x16x32_bf16(Bt[n][k], At[m][k], acc[ai][bj][m][n], 0, 0, 0); __builtin_amdgcn_s_setprio(0); } while (0)
; #define PG8_WAIT_V(n) asm volatile("s_waitcnt vmcnt(" #n ")" ::: "memory")
; #define PG8_WAIT_L(n) asm volatile("s_waitcnt lgkmcnt(" #n ")" ::: "memory")
; #define PG8_BAR __builtin_amdgcn_s_barrier()
; #define PG8_SCHED __builtin_amdgcn_sched_barrier(0)
; template <class Sched, class Epi>
; __device__ __forceinline__ void gemm_phase(LAS unsigned char* lds, const Sched& S, const Epi& E, const int K, const int lda, const int ldb) {
;     ...
;             PG8_WAIT_V(6); PG8_BAR; if (!chalf) PG8_MMA(1, 1, At, B1); PG8_BAR;
;             PG8_LDB(B0, 1, 0); PG8_SCHED; PG8_LDA(At, 1, 0); PG8_STAGE(PG8_SA(0, 1), a2 + hstepA, voffA);
;             PG8_WAIT_L(8); PG8_BAR; PG8_WAIT_L(0); PG8_MMA(0, 0, At, B0); PG8_BAR; PG8_SCHED;
;             PG8_LDB(B1, 1, 1); PG8_STAGE(PG8_SB(1, 0), b3, voffB);
;             PG8_BAR; PG8_WAIT_L(0); PG8_MMA(0, 1, At, B1); PG8_BAR;
;             PG8_LDA(At, 1, 1); PG8_STAGE(PG8_SA(1, 0), a3, voffA);
;             PG8_BAR; PG8_WAIT_L(0); if (!chalf) PG8_MMA(1, 0, At, B0); PG8_BAR; PG8_SCHED;
	s_waitcnt lgkmcnt(0)
	s_setprio 1
	s_waitcnt lgkmcnt(0)
	v_mfma_f32_16x16x32_bf16 v[152:155], v[112:115], v[144:147], v[152:155]
	v_mfma_f32_16x16x32_bf16 v[156:159], v[136:139], v[144:147], v[156:159]
	v_mfma_f32_16x16x32_bf16 v[160:163], v[112:115], v[176:179], v[160:163]
	v_mfma_f32_16x16x32_bf16 v[164:167], v[136:139], v[176:179], v[164:167]
	v_mfma_f32_16x16x32_bf16 v[168:171], v[112:115], v[184:187], v[168:171]
	v_mfma_f32_16x16x32_bf16 v[172:175], v[136:139], v[184:187], v[172:175]
	v_mfma_f32_16x16x32_bf16 v[2:5], v[112:115], v[192:195], v[2:5]
	v_mfma_f32_16x16x32_bf16 v[6:9], v[136:139], v[192:195], v[6:9]
	v_mfma_f32_16x16x32_bf16 v[152:155], v[116:119], v[148:151], v[152:155]
	v_mfma_f32_16x16x32_bf16 v[156:159], v[140:143], v[148:151], v[156:159]
	v_mfma_f32_16x16x32_bf16 v[160:163], v[116:119], v[180:183], v[160:163]
	v_mfma_f32_16x16x32_bf16 v[164:167], v[140:143], v[180:183], v[164:167]
	v_mfma_f32_16x16x32_bf16 v[168:171], v[116:119], v[188:191], v[168:171]
	v_mfma_f32_16x16x32_bf16 v[172:175], v[140:143], v[188:191], v[172:175]
	v_mfma_f32_16x16x32_bf16 v[2:5], v[116:119], v[196:199], v[2:5]
	v_mfma_f32_16x16x32_bf16 v[6:9], v[140:143], v[196:199], v[6:9]
	s_setprio 0
	s_barrier
	s_add_u32 s58, s26, 0x10180
	s_addc_u32 s59, s27, 0
	s_add_i32 s27, s57, s2
	s_mov_b32 m0, s27
	s_add_i32 s26, s27, 0x2000
	global_load_lds_dwordx4 v78, s[58:59]
	s_mov_b32 m0, s26
	s_nop 0
	global_load_lds_dwordx4 v74, s[58:59]
	s_waitcnt vmcnt(6)
	s_barrier
	s_setprio 1
	v_mfma_f32_16x16x32_bf16 v[10:13], v[200:203], v[144:147], v[10:13]
	v_mfma_f32_16x16x32_bf16 v[14:17], v[208:211], v[144:147], v[14:17]
	v_mfma_f32_16x16x32_bf16 v[46:49], v[200:203], v[176:179], v[46:49]
	v_mfma_f32_16x16x32_bf16 v[112:115], v[208:211], v[176:179], v[124:127]
	v_mfma_f32_16x16x32_bf16 v[116:119], v[200:203], v[184:187], v[128:131]
	v_mfma_f32_16x16x32_bf16 v[124:127], v[208:211], v[184:187], v[132:135]
	v_mfma_f32_16x16x32_bf16 v[104:107], v[200:203], v[192:195], v[104:107]
	v_mfma_f32_16x16x32_bf16 v[108:111], v[208:211], v[192:195], v[108:111]
	v_mfma_f32_16x16x32_bf16 v[10:13], v[204:207], v[148:151], v[10:13]
	v_mfma_f32_16x16x32_bf16 v[14:17], v[212:215], v[148:151], v[14:17]
	v_mfma_f32_16x16x32_bf16 v[46:49], v[204:207], v[180:183], v[46:49]
	v_mfma_f32_16x16x32_bf16 v[112:115], v[212:215], v[180:183], v[112:115]
	v_mfma_f32_16x16x32_bf16 v[116:119], v[204:207], v[188:191], v[116:119]
	v_mfma_f32_16x16x32_bf16 v[124:127], v[212:215], v[188:191], v[124:127]
	v_mfma_f32_16x16x32_bf16 v[104:107], v[204:207], v[196:199], v[104:107]
	v_mfma_f32_16x16x32_bf16 v[108:111], v[212:215], v[196:199], v[108:111]
	s_setprio 0
	s_barrier
	ds_read_b128 v[128:131], v92
	ds_read_b128 v[132:135], v92 offset:1024
	ds_read_b128 v[136:139], v92 offset:2048
	ds_read_b128 v[140:143], v92 offset:3072
	s_add_u32 s24, s24, 0x40180
	s_addc_u32 s25, s25, 0
	s_mov_b32 m0, s46
	ds_read_b128 v[144:147], v93
	ds_read_b128 v[148:151], v93 offset:1024
	ds_read_b128 v[176:179], v93 offset:2048
	ds_read_b128 v[180:183], v93 offset:3072
	ds_read_b128 v[184:187], v93 offset:4096
	ds_read_b128 v[188:191], v93 offset:5120
	ds_read_b128 v[192:195], v93 offset:6144
	ds_read_b128 v[196:199], v93 offset:7168
	global_load_lds_dwordx4 v80, s[24:25]
	s_mov_b32 m0, s47
	s_nop 0
	global_load_lds_dwordx4 v76, s[24:25]
	s_waitcnt lgkmcnt(8)
	s_barrier
	s_waitcnt lgkmcnt(0)
	s_setprio 1
	s_waitcnt lgkmcnt(0)
	v_mfma_f32_16x16x32_bf16 v[50:53], v[128:131], v[144:147], v[50:53]
	v_mfma_f32_16x16x32_bf16 v[54:57], v[136:139], v[144:147], v[54:57]
	v_mfma_f32_16x16x32_bf16 v[58:61], v[128:131], v[176:179], v[58:61]
	v_mfma_f32_16x16x32_bf16 v[62:65], v[136:139], v[176:179], v[62:65]
	v_mfma_f32_16x16x32_bf16 v[66:69], v[128:131], v[184:187], v[66:69]
	v_mfma_f32_16x16x32_bf16 v[70:73], v[136:139], v[184:187], v[70:73]
	v_mfma_f32_16x16x32_bf16 v[96:99], v[128:131], v[192:195], v[96:99]
	v_mfma_f32_16x16x32_bf16 v[100:103], v[136:139], v[192:195], v[100:103]
	v_mfma_f32_16x16x32_bf16 v[50:53], v[132:135], v[148:151], v[50:53]
	v_mfma_f32_16x16x32_bf16 v[54:57], v[140:143], v[148:151], v[54:57]
	v_mfma_f32_16x16x32_bf16 v[58:61], v[132:135], v[180:183], v[58:61]
	v_mfma_f32_16x16x32_bf16 v[62:65], v[140:143], v[180:183], v[62:65]
	v_mfma_f32_16x16x32_bf16 v[66:69], v[132:135], v[188:191], v[66:69]
	v_mfma_f32_16x16x32_bf16 v[70:73], v[140:143], v[188:191], v[70:73]
	v_mfma_f32_16x16x32_bf16 v[96:99], v[132:135], v[196:199], v[96:99]
	v_mfma_f32_16x16x32_bf16 v[100:103], v[140:143], v[196:199], v[100:103]
	s_setprio 0
	s_barrier
	s_mov_b32 m0, s48
	v_lshl_add_u64 v[232:233], s[22:23], 0, v[78:79]
	ds_read_b128 v[200:203], v94
	ds_read_b128 v[204:207], v94 offset:1024
	ds_read_b128 v[208:211], v94 offset:2048
	ds_read_b128 v[212:215], v94 offset:3072
	global_load_lds_dwordx4 v[232:233], off
	v_lshl_add_u64 v[234:235], s[22:23], 0, v[74:75]
	s_mov_b32 m0, s52
	s_nop 0
	global_load_lds_dwordx4 v[234:235], off
	s_barrier
	s_waitcnt lgkmcnt(0)
	s_setprio 1
	s_waitcnt lgkmcnt(0)
	v_mfma_f32_16x16x32_bf16 v[120:123], v[200:203], v[144:147], v[120:123]
	v_mfma_f32_16x16x32_bf16 v[18:21], v[208:211], v[144:147], v[18:21]
	v_mfma_f32_16x16x32_bf16 v[22:25], v[200:203], v[176:179], v[22:25]
	v_mfma_f32_16x16x32_bf16 v[26:29], v[208:211], v[176:179], v[26:29]
	v_mfma_f32_16x16x32_bf16 v[30:33], v[200:203], v[184:187], v[30:33]
	v_mfma_f32_16x16x32_bf16 v[34:37], v[208:211], v[184:187], v[34:37]
	v_mfma_f32_16x16x32_bf16 v[38:41], v[200:203], v[192:195], v[38:41]
	v_mfma_f32_16x16x32_bf16 v[42:45], v[208:211], v[192:195], v[42:45]
	v_mfma_f32_16x16x32_bf16 v[120:123], v[204:207], v[148:151], v[120:123]
	v_mfma_f32_16x16x32_bf16 v[18:21], v[212:215], v[148:151], v[18:21]
	v_mfma_f32_16x16x32_bf16 v[22:25], v[204:207], v[180:183], v[22:25]
	v_mfma_f32_16x16x32_bf16 v[26:29], v[212:215], v[180:183], v[26:29]
	v_mfma_f32_16x16x32_bf16 v[30:33], v[204:207], v[188:191], v[30:33]
	v_mfma_f32_16x16x32_bf16 v[34:37], v[212:215], v[188:191], v[34:37]
	v_mfma_f32_16x16x32_bf16 v[38:41], v[204:207], v[196:199], v[38:41]
	v_mfma_f32_16x16x32_bf16 v[42:45], v[212:215], v[196:199], v[42:45]
	s_setprio 0
	s_mov_b32 m0, s11
	v_lshl_add_u64 v[240:241], s[20:21], 0, v[80:81]
	s_barrier
; #define PG8_STAGE(bufoff, gbase, voff) do { _Pragma("unroll") for (int _i = 0; _i < 2; ++_i) \
;         __builtin_amdgcn_global_load_lds((const unsigned*)((const char*)(gbase) + (voff)[_i]), (LAS unsigned*)(lds + (bufoff) + ldsw + _i * 8192), 16, 0, 0); } while (0)
; #define PG8_LDA(dst, b, h) do { _Pragma("unroll") for (int m = 0; m < 4; ++m) _Pragma("unroll") for (int k = 0; k < 2; ++k) dst[m][k] = *(const LAS bf16x8*)(lds + PG8_SA(b, h) + aoff + m * 2048 + k * 1024); } while (0)
; #define PG8_LDB(dst, b, h) do { _Pragma("unroll") for (int n = 0; n < 2; ++n) _Pragma("unroll") for (int k = 0; k < 2; ++k) dst[n][k] = *(const LAS bf16x8*)(lds + PG8_SB(b, h) + boff + n * 2048 + k * 1024); } while (0)
; #define PG8_MMA(ai, bj, At, Bt) do { __builtin_amdgcn_s_setprio(1); _Pragma("unroll") for (int m = 0; m < 4; ++m) _Pragma("unroll") for (int n = 0; n < 2; ++n) _Pragma("unroll") for (int k = 0; k < 2; ++k) \
;         acc[ai][bj][m][n] = __builtin_amdgcn_mfma_f32_16x16x32_bf16(Bt[n][k], At[m][k], acc[ai][bj][m][n], 0, 0, 0); __builtin_amdgcn_s_setprio(0); } while (0)
; #define PG8_WAIT_V(n) asm volatile("s_waitcnt vmcnt(" #n ")" ::: "memory")
; #define PG8_WAIT_L(n) asm volatile("s_waitcnt lgkmcnt(" #n ")" ::: "memory")
; #define PG8_BAR __builtin_amdgcn_s_barrier()
; #define PG8_SCHED __builtin_amdgcn_sched_barrier(0)
; template <class Sched, class Epi>
; __device__ __forceinline__ void gemm_phase(LAS unsigned char* lds, const Sched& S, const Epi& E, const int K, const int lda, const int ldb) {
;     ...
;             PG8_WAIT_L(8); PG8_BAR; PG8_WAIT_L(0); PG8_MMA(0, 0, At, B0); PG8_BAR; PG8_SCHED;
;             PG8_LDB(B1, 1, 1); PG8_STAGE(PG8_SB(1, 0), b3, voffB);
;             PG8_BAR; PG8_WAIT_L(0); PG8_MMA(0, 1, At, B1); PG8_BAR;
;             PG8_LDA(At, 1, 1); PG8_STAGE(PG8_SA(1, 0), a3, voffA);
;             PG8_BAR; PG8_WAIT_L(0); if (!chalf) PG8_MMA(1, 0, At, B0); PG8_BAR; PG8_SCHED;
;             PG8_STAGE(PG8_SB(1, 1), b3 + hstepB, voffB);
;             PG8_WAIT_V(6); PG8_BAR; if (!chalf) PG8_MMA(1, 1, At, B1); PG8_BAR;
	ds_read_b128 v[144:147], v93 offset:16384
	ds_read_b128 v[148:151], v93 offset:17408
	ds_read_b128 v[176:179], v93 offset:18432
	ds_read_b128 v[180:183], v93 offset:19456
	ds_read_b128 v[184:187], v93 offset:20480
	ds_read_b128 v[188:191], v93 offset:21504
	ds_read_b128 v[192:195], v93 offset:22528
	ds_read_b128 v[196:199], v93 offset:23552
	global_load_lds_dwordx4 v[240:241], off
	v_lshl_add_u64 v[242:243], s[20:21], 0, v[76:77]
	s_mov_b32 m0, s28
	s_nop 0
	global_load_lds_dwordx4 v[242:243], off
	s_barrier
	s_waitcnt lgkmcnt(0)
	s_setprio 1
	s_waitcnt lgkmcnt(0)
	v_mfma_f32_16x16x32_bf16 v[152:155], v[128:131], v[144:147], v[152:155]
	v_mfma_f32_16x16x32_bf16 v[156:159], v[136:139], v[144:147], v[156:159]
	v_mfma_f32_16x16x32_bf16 v[160:163], v[128:131], v[176:179], v[160:163]
	v_mfma_f32_16x16x32_bf16 v[164:167], v[136:139], v[176:179], v[164:167]
	v_mfma_f32_16x16x32_bf16 v[168:171], v[128:131], v[184:187], v[168:171]
	v_mfma_f32_16x16x32_bf16 v[172:175], v[136:139], v[184:187], v[172:175]
	v_mfma_f32_16x16x32_bf16 v[2:5], v[128:131], v[192:195], v[2:5]
	v_mfma_f32_16x16x32_bf16 v[6:9], v[136:139], v[192:195], v[6:9]
	v_mfma_f32_16x16x32_bf16 v[152:155], v[132:135], v[148:151], v[152:155]
	v_mfma_f32_16x16x32_bf16 v[156:159], v[140:143], v[148:151], v[156:159]
	v_mfma_f32_16x16x32_bf16 v[160:163], v[132:135], v[180:183], v[160:163]
	v_mfma_f32_16x16x32_bf16 v[164:167], v[140:143], v[180:183], v[164:167]
	v_mfma_f32_16x16x32_bf16 v[168:171], v[132:135], v[188:191], v[168:171]
	v_mfma_f32_16x16x32_bf16 v[172:175], v[140:143], v[188:191], v[172:175]
	v_mfma_f32_16x16x32_bf16 v[2:5], v[132:135], v[196:199], v[2:5]
	v_mfma_f32_16x16x32_bf16 v[128:131], v[140:143], v[196:199], v[6:9]
	s_setprio 0
	s_barrier
	s_add_u32 s24, s22, 0x10000
	s_addc_u32 s25, s23, 0
	s_mov_b32 m0, s54
	s_nop 0
	global_load_lds_dwordx4 v78, s[24:25]
	s_mov_b32 m0, s53
	s_nop 0
	global_load_lds_dwordx4 v74, s[24:25]
	s_waitcnt vmcnt(6)
	s_barrier
	s_setprio 1
	v_mfma_f32_16x16x32_bf16 v[6:9], v[200:203], v[144:147], v[10:13]
	v_mfma_f32_16x16x32_bf16 v[10:13], v[204:207], v[148:151], v[6:9]
	v_mfma_f32_16x16x32_bf16 v[6:9], v[208:211], v[144:147], v[14:17]
	v_mfma_f32_16x16x32_bf16 v[14:17], v[212:215], v[148:151], v[6:9]
	v_mfma_f32_16x16x32_bf16 v[6:9], v[200:203], v[176:179], v[46:49]
	v_mfma_f32_16x16x32_bf16 v[46:49], v[204:207], v[180:183], v[6:9]
	v_mfma_f32_16x16x32_bf16 v[6:9], v[208:211], v[176:179], v[112:115]
	v_mfma_f32_16x16x32_bf16 v[112:115], v[212:215], v[180:183], v[6:9]
	v_mfma_f32_16x16x32_bf16 v[6:9], v[200:203], v[184:187], v[116:119]
	v_mfma_f32_16x16x32_bf16 v[116:119], v[204:207], v[188:191], v[6:9]
	v_mfma_f32_16x16x32_bf16 v[6:9], v[208:211], v[184:187], v[124:127]
	v_mfma_f32_16x16x32_bf16 v[124:127], v[212:215], v[188:191], v[6:9]
	v_mfma_f32_16x16x32_bf16 v[6:9], v[200:203], v[192:195], v[104:107]
	v_mfma_f32_16x16x32_bf16 v[104:107], v[204:207], v[196:199], v[6:9]
	v_mfma_f32_16x16x32_bf16 v[6:9], v[208:211], v[192:195], v[108:111]
	v_mfma_f32_16x16x32_bf16 v[108:111], v[212:215], v[196:199], v[6:9]
	s_setprio 0
	s_barrier
	s_nop 4
	ds_read_b128 v[6:9], v95
	ds_read_b128 v[132:135], v95 offset:1024
	ds_read_b128 v[136:139], v95 offset:2048
	ds_read_b128 v[140:143], v95 offset:3072
	s_add_u32 s24, s20, 0x40000
	s_addc_u32 s25, s21, 0
	s_mov_b32 m0, s29
	ds_read_b128 v[144:147], v93 offset:32768
	ds_read_b128 v[148:151], v93 offset:33792
	ds_read_b128 v[176:179], v93 offset:34816
	ds_read_b128 v[180:183], v93 offset:35840
	ds_read_b128 v[184:187], v93 offset:36864
	ds_read_b128 v[188:191], v93 offset:37888
	ds_read_b128 v[192:195], v93 offset:38912
	ds_read_b128 v[196:199], v93 offset:39936
	global_load_lds_dwordx4 v80, s[24:25]
	s_mov_b32 m0, s30
	s_nop 0
	global_load_lds_dwordx4 v76, s[24:25]
	s_waitcnt lgkmcnt(8)
	s_barrier
	s_waitcnt lgkmcnt(0)
	s_setprio 1
	s_waitcnt lgkmcnt(0)
	v_mfma_f32_16x16x32_bf16 v[50:53], v[6:9], v[144:147], v[50:53]
	v_mfma_f32_16x16x32_bf16 v[200:203], v[132:135], v[148:151], v[50:53]
	v_mfma_f32_16x16x32_bf16 v[50:53], v[136:139], v[144:147], v[54:57]
	v_mfma_f32_16x16x32_bf16 v[204:207], v[140:143], v[148:151], v[50:53]
	v_mfma_f32_16x16x32_bf16 v[50:53], v[6:9], v[176:179], v[58:61]
	v_mfma_f32_16x16x32_bf16 v[208:211], v[132:135], v[180:183], v[50:53]
	v_mfma_f32_16x16x32_bf16 v[50:53], v[136:139], v[176:179], v[62:65]
	v_mfma_f32_16x16x32_bf16 v[212:215], v[140:143], v[180:183], v[50:53]
	v_mfma_f32_16x16x32_bf16 v[50:53], v[6:9], v[184:187], v[66:69]
	v_mfma_f32_16x16x32_bf16 v[216:219], v[132:135], v[188:191], v[50:53]
	v_mfma_f32_16x16x32_bf16 v[50:53], v[136:139], v[184:187], v[70:73]
	v_mfma_f32_16x16x32_bf16 v[220:223], v[140:143], v[188:191], v[50:53]
	v_mfma_f32_16x16x32_bf16 v[50:53], v[6:9], v[192:195], v[96:99]
	v_mfma_f32_16x16x32_bf16 v[54:57], v[132:135], v[196:199], v[50:53]
	v_mfma_f32_16x16x32_bf16 v[50:53], v[136:139], v[192:195], v[100:103]
	v_mfma_f32_16x16x32_bf16 v[50:53], v[140:143], v[196:199], v[50:53]
	s_setprio 0
	s_barrier
	s_mov_b32 m0, s56
	v_lshl_add_u64 v[58:59], v[232:233], 0, s[12:13]
	ds_read_b128 v[96:99], v228
	ds_read_b128 v[100:103], v228 offset:1024
	ds_read_b128 v[224:227], v228 offset:2048
	ds_read_b128 v[228:231], v228 offset:3072
	global_load_lds_dwordx4 v[58:59], off
	v_lshl_add_u64 v[58:59], v[234:235], 0, s[12:13]
	s_mov_b32 m0, s55
	s_nop 0
	global_load_lds_dwordx4 v[58:59], off
	s_barrier
; #define PG8_STAGE(bufoff, gbase, voff) do { _Pragma("unroll") for (int _i = 0; _i < 2; ++_i) \
;         __builtin_amdgcn_global_load_lds((const unsigned*)((const char*)(gbase) + (voff)[_i]), (LAS unsigned*)(lds + (bufoff) + ldsw + _i * 8192), 16, 0, 0); } while (0)
; #define PG8_MMA(ai, bj, At, Bt) do { __builtin_amdgcn_s_setprio(1); _Pragma("unroll") for (int m = 0; m < 4; ++m) _Pragma("unroll") for (int n = 0; n < 2; ++n) _Pragma("unroll") for (int k = 0; k < 2; ++k) \
;         acc[ai][bj][m][n] = __builtin_amdgcn_mfma_f32_16x16x32_bf16(Bt[n][k], At[m][k], acc[ai][bj][m][n], 0, 0, 0); __builtin_amdgcn_s_setprio(0); } while (0)
; #define PG8_WAIT_V(n) asm volatile("s_waitcnt vmcnt(" #n ")" ::: "memory")
; #define PG8_WAIT_L(n) asm volatile("s_waitcnt lgkmcnt(" #n ")" ::: "memory")
; #define PG8_BAR __builtin_amdgcn_s_barrier()
; #define PG8_SCHED __builtin_amdgcn_sched_barrier(0)
; #define EPI_FOR_ROWS _Pragma("unroll") for (int ai = 0; ai < 2; ++ai) if (ai == 0 || !u.half) _Pragma("unroll") for (int m = 0; m < 4; ++m)
; template <class Sched, class Epi>
; __device__ __forceinline__ void gemm_phase(LAS unsigned char* lds, const Sched& S, const Epi& E, const int K, const int lda, const int ldb) {
;     ...
;             PG8_BAR; PG8_WAIT_L(0); if (!chalf) PG8_MMA(1, 0, At, B0); PG8_BAR; PG8_SCHED;
;             PG8_STAGE(PG8_SB(1, 1), b3 + hstepB, voffB);
;             PG8_WAIT_V(6); PG8_BAR; if (!chalf) PG8_MMA(1, 1, At, B1); PG8_BAR;
;     __device__ __forceinline__ void operator()(EPI_ARGS) const {
;         const int l = u.z >> 2, grp = u.z & 3; bf16_t* O = (bf16_t*)(ws + l * SZ_LAYER + LO_WP);
;         EPI_FOR_ROWS { bf16_t* rp = O + (size_t)EPI_ROW * 2048 + u.pn * 1024 + grp * 256;
	s_waitcnt lgkmcnt(0)
	s_setprio 1
	s_waitcnt lgkmcnt(0)
	v_mfma_f32_16x16x32_bf16 v[18:21], v[224:227], v[144:147], v[18:21]
	v_mfma_f32_16x16x32_bf16 v[58:61], v[96:99], v[144:147], v[120:123]
	v_mfma_f32_16x16x32_bf16 v[144:147], v[228:231], v[148:151], v[18:21]
	v_mfma_f32_16x16x32_bf16 v[18:21], v[96:99], v[176:179], v[22:25]
	v_mfma_f32_16x16x32_bf16 v[120:123], v[100:103], v[148:151], v[58:61]
	v_mfma_f32_16x16x32_bf16 v[148:151], v[100:103], v[180:183], v[18:21]
	v_mfma_f32_16x16x32_bf16 v[18:21], v[224:227], v[176:179], v[26:29]
	v_mfma_f32_16x16x32_bf16 v[176:179], v[228:231], v[180:183], v[18:21]
	v_mfma_f32_16x16x32_bf16 v[18:21], v[96:99], v[184:187], v[30:33]
	v_mfma_f32_16x16x32_bf16 v[180:183], v[100:103], v[188:191], v[18:21]
	v_mfma_f32_16x16x32_bf16 v[18:21], v[224:227], v[184:187], v[34:37]
	v_mfma_f32_16x16x32_bf16 v[184:187], v[228:231], v[188:191], v[18:21]
	v_mfma_f32_16x16x32_bf16 v[18:21], v[96:99], v[192:195], v[38:41]
	v_mfma_f32_16x16x32_bf16 v[70:73], v[100:103], v[196:199], v[18:21]
	v_mfma_f32_16x16x32_bf16 v[18:21], v[224:227], v[192:195], v[42:45]
	v_mfma_f32_16x16x32_bf16 v[62:65], v[228:231], v[196:199], v[18:21]
	s_setprio 0
	s_mov_b32 m0, s33
	s_nop 4
	v_lshl_add_u64 v[18:19], v[240:241], 0, s[12:13]
	s_barrier
	ds_read_b128 v[26:29], v93 offset:49152
	ds_read_b128 v[30:33], v93 offset:50176
	ds_read_b128 v[42:45], v93 offset:51200
	ds_read_b128 v[188:191], v93 offset:52224
	ds_read_b128 v[192:195], v93 offset:53248
	ds_read_b128 v[196:199], v93 offset:54272
	ds_read_b128 v[232:235], v93 offset:55296
	ds_read_b128 v[236:239], v93 offset:56320
	global_load_lds_dwordx4 v[18:19], off
	v_lshl_add_u64 v[18:19], v[242:243], 0, s[12:13]
	s_mov_b32 m0, s34
	s_nop 0
	global_load_lds_dwordx4 v[18:19], off
	s_barrier
	s_waitcnt lgkmcnt(0)
	s_setprio 1
	s_waitcnt lgkmcnt(0)
	v_mfma_f32_16x16x32_bf16 v[18:21], v[6:9], v[26:29], v[152:155]
	v_mfma_f32_16x16x32_bf16 v[66:69], v[132:135], v[30:33], v[18:21]
	v_mfma_f32_16x16x32_bf16 v[18:21], v[136:139], v[26:29], v[156:159]
	v_mfma_f32_16x16x32_bf16 v[58:61], v[140:143], v[30:33], v[18:21]
	v_mfma_f32_16x16x32_bf16 v[18:21], v[6:9], v[42:45], v[160:163]
	v_mfma_f32_16x16x32_bf16 v[38:41], v[132:135], v[188:191], v[18:21]
	v_mfma_f32_16x16x32_bf16 v[18:21], v[136:139], v[42:45], v[164:167]
	v_mfma_f32_16x16x32_bf16 v[34:37], v[140:143], v[188:191], v[18:21]
	v_mfma_f32_16x16x32_bf16 v[18:21], v[6:9], v[192:195], v[168:171]
	v_mfma_f32_16x16x32_bf16 v[2:5], v[6:9], v[232:235], v[2:5]
	v_mfma_f32_16x16x32_bf16 v[22:25], v[132:135], v[196:199], v[18:21]
	v_mfma_f32_16x16x32_bf16 v[18:21], v[136:139], v[192:195], v[172:175]
	v_mfma_f32_16x16x32_bf16 v[6:9], v[132:135], v[236:239], v[2:5]
	v_mfma_f32_16x16x32_bf16 v[2:5], v[136:139], v[232:235], v[128:131]
	v_mfma_f32_16x16x32_bf16 v[18:21], v[140:143], v[196:199], v[18:21]
	v_mfma_f32_16x16x32_bf16 v[2:5], v[140:143], v[236:239], v[2:5]
	s_setprio 0
	s_barrier
	s_add_u32 s24, s22, 0x10080
	s_addc_u32 s25, s23, 0
	s_mov_b32 m0, s27
	s_nop 0
	global_load_lds_dwordx4 v78, s[24:25]
	s_mov_b32 m0, s26
	s_nop 0
	global_load_lds_dwordx4 v74, s[24:25]
	s_waitcnt vmcnt(6)
	s_barrier
	s_setprio 1
	v_mfma_f32_16x16x32_bf16 v[10:13], v[96:99], v[26:29], v[10:13]
	v_mfma_f32_16x16x32_bf16 v[128:131], v[100:103], v[30:33], v[10:13]
	v_mfma_f32_16x16x32_bf16 v[10:13], v[224:227], v[26:29], v[14:17]
	v_mfma_f32_16x16x32_bf16 v[132:135], v[228:231], v[30:33], v[10:13]
	v_mfma_f32_16x16x32_bf16 v[10:13], v[96:99], v[42:45], v[46:49]
	v_mfma_f32_16x16x32_bf16 v[46:49], v[100:103], v[188:191], v[10:13]
	v_mfma_f32_16x16x32_bf16 v[10:13], v[224:227], v[42:45], v[112:115]
	v_mfma_f32_16x16x32_bf16 v[42:45], v[228:231], v[188:191], v[10:13]
	v_mfma_f32_16x16x32_bf16 v[10:13], v[96:99], v[192:195], v[116:119]
	v_mfma_f32_16x16x32_bf16 v[30:33], v[100:103], v[196:199], v[10:13]
	v_mfma_f32_16x16x32_bf16 v[10:13], v[224:227], v[192:195], v[124:127]
	v_mfma_f32_16x16x32_bf16 v[26:29], v[228:231], v[196:199], v[10:13]
	v_mfma_f32_16x16x32_bf16 v[10:13], v[96:99], v[232:235], v[104:107]
	v_mfma_f32_16x16x32_bf16 v[14:17], v[100:103], v[236:239], v[10:13]
	v_mfma_f32_16x16x32_bf16 v[10:13], v[224:227], v[232:235], v[108:111]
	v_mfma_f32_16x16x32_bf16 v[10:13], v[228:231], v[236:239], v[10:13]
	s_setprio 0
	s_ashr_i32 s24, s4, 2
	s_mul_hi_i32 s25, s24, 0x6e22000
	s_mul_i32 s24, s24, 0x6e22000
	s_add_u32 s24, s6, s24
	s_addc_u32 s25, s7, s25
	s_add_u32 s24, s24, 0x4a00000
	v_add_u32_e32 v96, s35, v1
	s_addc_u32 s25, s25, 0
	v_ashrrev_i32_e32 v97, 31, v96
	s_lshl_b32 s26, s19, 10
	v_lshlrev_b64 v[96:97], 12, v[96:97]
	s_ashr_i32 s27, s26, 31
	v_lshl_add_u64 v[96:97], s[24:25], 0, v[96:97]
	s_lshl_b64 s[26:27], s[26:27], 1
	s_lshl_b32 s4, s4, 9
	v_lshl_add_u64 v[96:97], v[96:97], 0, s[26:27]
	s_and_b32 s4, s4, 0x600
	v_lshl_add_u64 v[96:97], v[96:97], 0, s[4:5]
	s_mov_b32 s19, s5
	v_lshl_add_u64 v[96:97], v[96:97], 0, s[18:19]
	s_barrier
; __device__ __forceinline__ unsigned cvt_pk_bf16(float lo, float hi) { unsigned r; asm volatile("v_cvt_pk_bf16_f32 %0, %1, %2" : "=v"(r) : "v"(lo), "v"(hi)); return r; }
; #define EPI_FOR_ROWS _Pragma("unroll") for (int ai = 0; ai < 2; ++ai) if (ai == 0 || !u.half) _Pragma("unroll") for (int m = 0; m < 4; ++m)
;     __device__ __forceinline__ void operator()(EPI_ARGS) const {
;     ...
;         EPI_FOR_ROWS { bf16_t* rp = O + (size_t)EPI_ROW * 2048 + u.pn * 1024 + grp * 256;
; #pragma unroll
;             for (int bj = 0; bj < 2; ++bj) { const f32x4 v0 = acc[ai][bj][m][0], v1 = acc[ai][bj][m][1]; u32x4 o;
;                 o[0] = cvt_pk_bf16(v0[0], v0[1]); o[1] = cvt_pk_bf16(v0[2], v0[3]); o[2] = cvt_pk_bf16(v1[0], v1[1]); o[3] = cvt_pk_bf16(v1[2], v1[3]);
;                 *(u32x4*)(rp + wc * 32 + 8 * fq + bj * 128) = o; } }
	v_lshl_add_u64 v[100:101], v[96:97], 0, v[82:83]
	v_cvt_pk_bf16_f32 v96, v200, v201
	v_cvt_pk_bf16_f32 v97, v202, v203
	v_cvt_pk_bf16_f32 v98, v204, v205
	v_cvt_pk_bf16_f32 v99, v206, v207
	global_store_dwordx4 v[100:101], v[96:99], off
	s_add_i32 s37, s37, s31
	s_add_u32 s14, s14, s39
	v_cvt_pk_bf16_f32 v96, v120, v121
	v_cvt_pk_bf16_f32 v97, v122, v123
	v_cvt_pk_bf16_f32 v98, v144, v145
	v_cvt_pk_bf16_f32 v99, v146, v147
	global_store_dwordx4 v[100:101], v[96:99], off offset:256
	s_addc_u32 s15, s15, s40
	s_add_u32 s0, s0, s31
	v_add_u32_e32 v96, s35, v85
	v_ashrrev_i32_e32 v97, 31, v96
	v_lshlrev_b64 v[96:97], 12, v[96:97]
	v_lshl_add_u64 v[96:97], s[24:25], 0, v[96:97]
	v_lshl_add_u64 v[96:97], v[96:97], 0, s[26:27]
	v_lshl_add_u64 v[96:97], v[96:97], 0, s[4:5]
	v_lshl_add_u64 v[96:97], v[96:97], 0, s[18:19]
	v_lshl_add_u64 v[100:101], v[96:97], 0, v[82:83]
	v_cvt_pk_bf16_f32 v96, v208, v209
	v_cvt_pk_bf16_f32 v97, v210, v211
	v_cvt_pk_bf16_f32 v98, v212, v213
	v_cvt_pk_bf16_f32 v99, v214, v215
	global_store_dwordx4 v[100:101], v[96:99], off
	s_addc_u32 s38, s38, s36
	s_nop 0
	v_cvt_pk_bf16_f32 v96, v148, v149
	v_cvt_pk_bf16_f32 v97, v150, v151
	v_cvt_pk_bf16_f32 v98, v176, v177
	v_cvt_pk_bf16_f32 v99, v178, v179
	global_store_dwordx4 v[100:101], v[96:99], off offset:256
	s_nop 1
	v_add_u32_e32 v96, s35, v86
	v_ashrrev_i32_e32 v97, 31, v96
	v_lshlrev_b64 v[96:97], 12, v[96:97]
	v_lshl_add_u64 v[96:97], s[24:25], 0, v[96:97]
	v_lshl_add_u64 v[96:97], v[96:97], 0, s[26:27]
	v_lshl_add_u64 v[96:97], v[96:97], 0, s[4:5]
	v_lshl_add_u64 v[96:97], v[96:97], 0, s[18:19]
	v_lshl_add_u64 v[100:101], v[96:97], 0, v[82:83]
	v_cvt_pk_bf16_f32 v96, v216, v217
	v_cvt_pk_bf16_f32 v97, v218, v219
	v_cvt_pk_bf16_f32 v98, v220, v221
	v_cvt_pk_bf16_f32 v99, v222, v223
	global_store_dwordx4 v[100:101], v[96:99], off
	s_nop 1
	v_cvt_pk_bf16_f32 v96, v180, v181
	v_cvt_pk_bf16_f32 v97, v182, v183
	v_cvt_pk_bf16_f32 v98, v184, v185
	v_cvt_pk_bf16_f32 v99, v186, v187
	global_store_dwordx4 v[100:101], v[96:99], off offset:256
	v_cvt_pk_bf16_f32 v54, v54, v55
	v_cvt_pk_bf16_f32 v55, v56, v57
	v_cvt_pk_bf16_f32 v56, v50, v51
	v_cvt_pk_bf16_f32 v57, v52, v53
	s_nop 1
	v_add_u32_e32 v96, s35, v87
	v_ashrrev_i32_e32 v97, 31, v96
	v_lshlrev_b64 v[96:97], 12, v[96:97]
	v_lshl_add_u64 v[96:97], s[24:25], 0, v[96:97]
	v_lshl_add_u64 v[96:97], v[96:97], 0, s[26:27]
	v_lshl_add_u64 v[96:97], v[96:97], 0, s[4:5]
	v_lshl_add_u64 v[96:97], v[96:97], 0, s[18:19]
	v_lshl_add_u64 v[96:97], v[96:97], 0, v[82:83]
	global_store_dwordx4 v[96:97], v[54:57], off
	v_cvt_pk_bf16_f32 v50, v70, v71
	v_cvt_pk_bf16_f32 v51, v72, v73
	v_cvt_pk_bf16_f32 v52, v62, v63
	v_cvt_pk_bf16_f32 v53, v64, v65
	global_store_dwordx4 v[96:97], v[50:53], off offset:256
	s_nop 1
	v_add_u32_e32 v50, s35, v88
	v_ashrrev_i32_e32 v51, 31, v50
	v_lshlrev_b64 v[50:51], 12, v[50:51]
	v_lshl_add_u64 v[50:51], s[24:25], 0, v[50:51]
	v_lshl_add_u64 v[50:51], v[50:51], 0, s[26:27]
	v_lshl_add_u64 v[50:51], v[50:51], 0, s[4:5]
	v_lshl_add_u64 v[50:51], v[50:51], 0, s[18:19]
	v_lshl_add_u64 v[54:55], v[50:51], 0, v[82:83]
	v_cvt_pk_bf16_f32 v50, v66, v67
	v_cvt_pk_bf16_f32 v51, v68, v69
	v_cvt_pk_bf16_f32 v52, v58, v59
	v_cvt_pk_bf16_f32 v53, v60, v61
	global_store_dwordx4 v[54:55], v[50:53], off
	s_nop 1
	v_cvt_pk_bf16_f32 v50, v128, v129
	v_cvt_pk_bf16_f32 v51, v130, v131
	v_cvt_pk_bf16_f32 v52, v132, v133
	v_cvt_pk_bf16_f32 v53, v134, v135
	global_store_dwordx4 v[54:55], v[50:53], off offset:256
	v_cvt_pk_bf16_f32 v38, v38, v39
	v_cvt_pk_bf16_f32 v39, v40, v41
	v_cvt_pk_bf16_f32 v40, v34, v35
	v_cvt_pk_bf16_f32 v41, v36, v37
	s_nop 1
	v_add_u32_e32 v50, s35, v89
	v_ashrrev_i32_e32 v51, 31, v50
	v_lshlrev_b64 v[50:51], 12, v[50:51]
	v_lshl_add_u64 v[50:51], s[24:25], 0, v[50:51]
	v_lshl_add_u64 v[50:51], v[50:51], 0, s[26:27]
	v_lshl_add_u64 v[50:51], v[50:51], 0, s[4:5]
	v_lshl_add_u64 v[50:51], v[50:51], 0, s[18:19]
	v_lshl_add_u64 v[50:51], v[50:51], 0, v[82:83]
	global_store_dwordx4 v[50:51], v[38:41], off
	v_cvt_pk_bf16_f32 v34, v46, v47
	v_cvt_pk_bf16_f32 v35, v48, v49
	v_cvt_pk_bf16_f32 v36, v42, v43
	v_cvt_pk_bf16_f32 v37, v44, v45
	global_store_dwordx4 v[50:51], v[34:37], off offset:256
	v_cvt_pk_bf16_f32 v22, v22, v23
	v_cvt_pk_bf16_f32 v23, v24, v25
	v_cvt_pk_bf16_f32 v24, v18, v19
	v_cvt_pk_bf16_f32 v25, v20, v21
	s_nop 1
	v_add_u32_e32 v34, s35, v90
	v_ashrrev_i32_e32 v35, 31, v34
	v_lshlrev_b64 v[34:35], 12, v[34:35]
	v_lshl_add_u64 v[34:35], s[24:25], 0, v[34:35]
	v_lshl_add_u64 v[34:35], v[34:35], 0, s[26:27]
	v_lshl_add_u64 v[34:35], v[34:35], 0, s[4:5]
	v_lshl_add_u64 v[34:35], v[34:35], 0, s[18:19]
	v_lshl_add_u64 v[34:35], v[34:35], 0, v[82:83]
	global_store_dwordx4 v[34:35], v[22:25], off
	v_cvt_pk_bf16_f32 v18, v30, v31
	v_cvt_pk_bf16_f32 v19, v32, v33
	v_cvt_pk_bf16_f32 v20, v26, v27
	v_cvt_pk_bf16_f32 v21, v28, v29
	global_store_dwordx4 v[34:35], v[18:21], off offset:256
	v_cvt_pk_bf16_f32 v6, v6, v7
	v_cvt_pk_bf16_f32 v7, v8, v9
	v_cvt_pk_bf16_f32 v8, v2, v3
	v_cvt_pk_bf16_f32 v9, v4, v5
	s_nop 1
	v_add_u32_e32 v18, s35, v91
	v_ashrrev_i32_e32 v19, 31, v18
	v_lshlrev_b64 v[18:19], 12, v[18:19]
	v_lshl_add_u64 v[18:19], s[24:25], 0, v[18:19]
	v_lshl_add_u64 v[18:19], v[18:19], 0, s[26:27]
	s_add_u32 s24, s43, s0
	v_lshl_add_u64 v[18:19], v[18:19], 0, s[4:5]
	s_addc_u32 s25, s44, s38
	v_lshl_add_u64 v[18:19], v[18:19], 0, s[18:19]
	v_cmp_lt_i64_e64 s[24:25], s[24:25], 64
	v_lshl_add_u64 v[18:19], v[18:19], 0, v[82:83]
	s_and_b64 vcc, exec, s[24:25]
	s_mov_b32 s4, s51
	s_mov_b32 s19, s49
	s_mov_b32 s35, s50
	s_mov_b64 s[26:27], s[22:23]
	s_mov_b64 s[24:25], s[20:21]
	global_store_dwordx4 v[18:19], v[6:9], off
	v_cvt_pk_bf16_f32 v2, v14, v15
	v_cvt_pk_bf16_f32 v3, v16, v17
	v_cvt_pk_bf16_f32 v4, v10, v11
	v_cvt_pk_bf16_f32 v5, v12, v13
	global_store_dwordx4 v[18:19], v[2:5], off offset:256
	s_cbranch_vccz .LBB0_433

; #define PG8_STAGE(bufoff, gbase, voff) do { _Pragma("unroll") for (int _i = 0; _i < 2; ++_i) \
;         __builtin_amdgcn_global_load_lds((const unsigned*)((const char*)(gbase) + (voff)[_i]), (LAS unsigned*)(lds + (bufoff) + ldsw + _i * 8192), 16, 0, 0); } while (0)
; #define PG8_LDA(dst, b, h) do { _Pragma("unroll") for (int m = 0; m < 4; ++m) _Pragma("unroll") for (int k = 0; k < 2; ++k) dst[m][k] = *(const LAS bf16x8*)(lds + PG8_SA(b, h) + aoff + m * 2048 + k * 1024); } while (0)
; #define PG8_LDB(dst, b, h) do { _Pragma("unroll") for (int n = 0; n < 2; ++n) _Pragma("unroll") for (int k = 0; k < 2; ++k) dst[n][k] = *(const LAS bf16x8*)(lds + PG8_SB(b, h) + boff + n * 2048 + k * 1024); } while (0)
; #define PG8_MMA(ai, bj, At, Bt) do { __builtin_amdgcn_s_setprio(1); _Pragma("unroll") for (int m = 0; m < 4; ++m) _Pragma("unroll") for (int n = 0; n < 2; ++n) _Pragma("unroll") for (int k = 0; k < 2; ++k) \
;         acc[ai][bj][m][n] = __builtin_amdgcn_mfma_f32_16x16x32_bf16(Bt[n][k], At[m][k], acc[ai][bj][m][n], 0, 0, 0); __builtin_amdgcn_s_setprio(0); } while (0)
; #define PG8_WAIT_L(n) asm volatile("s_waitcnt lgkmcnt(" #n ")" ::: "memory")
; #define PG8_BAR __builtin_amdgcn_s_barrier()
; #define PG8_SCHED __builtin_amdgcn_sched_barrier(0)
; template <class Sched, class Epi>
; __device__ __forceinline__ void gemm_phase(LAS unsigned char* lds, const Sched& S, const Epi& E, const int K, const int lda, const int ldb) {
;     ...
;             PG8_LDB(B0, 0, 0); PG8_SCHED; PG8_LDA(At, 0, 0); PG8_STAGE(PG8_SA(1, 1), a1 + hstepA, voffA);
;             PG8_WAIT_L(8); PG8_BAR; PG8_WAIT_L(0); PG8_MMA(0, 0, At, B0); PG8_BAR; PG8_SCHED;
;             PG8_LDB(B1, 0, 1); PG8_STAGE(PG8_SB(0, 0), b2, voffB);
;             PG8_BAR; PG8_WAIT_L(0); PG8_MMA(0, 1, At, B1); PG8_BAR;
;             PG8_LDA(At, 0, 1); PG8_STAGE(PG8_SA(0, 0), a2, voffA);
;             PG8_BAR; PG8_WAIT_L(0); if (!chalf) PG8_MMA(1, 0, At, B0); PG8_BAR; PG8_SCHED;
.LBB0_736:
	s_add_u32 s22, s18, s20
	ds_read_b128 v[148:151], v143
	ds_read_b128 v[152:155], v143 offset:1024
	ds_read_b128 v[156:159], v143 offset:2048
	ds_read_b128 v[160:163], v143 offset:3072
	s_addc_u32 s23, s19, s21
	s_add_u32 s22, s22, 0x294d8100
	s_addc_u32 s23, s23, 0
	s_add_u32 s41, s26, s20
	s_addc_u32 s42, s27, s21
	s_cmpk_eq_i32 s20, 0xf00
	s_cselect_b32 s25, s13, s23
	s_cselect_b32 s24, s12, s22
	s_cselect_b32 s23, s15, s42
	s_cselect_b32 s22, s14, s41
	s_mov_b32 m0, s29
	v_lshl_add_u64 v[196:197], v[140:141], 0, s[20:21]
	ds_read_b128 v[164:167], v144
	ds_read_b128 v[168:171], v144 offset:1024
	ds_read_b128 v[172:175], v144 offset:2048
	ds_read_b128 v[176:179], v144 offset:3072
	ds_read_b128 v[180:183], v144 offset:4096
	ds_read_b128 v[184:187], v144 offset:5120
	ds_read_b128 v[188:191], v144 offset:6144
	ds_read_b128 v[192:195], v144 offset:7168
	global_load_lds_dwordx4 v[196:197], off
	v_lshl_add_u64 v[196:197], v[138:139], 0, s[20:21]
	s_mov_b32 m0, s30
	s_nop 0
	global_load_lds_dwordx4 v[196:197], off
	s_waitcnt lgkmcnt(8)
	s_barrier
	s_waitcnt lgkmcnt(0)
	s_setprio 1
	s_waitcnt lgkmcnt(0)
	v_mfma_f32_16x16x32_bf16 v[126:129], v[148:151], v[164:167], v[126:129]
	v_mfma_f32_16x16x32_bf16 v[122:125], v[156:159], v[164:167], v[122:125]
	v_mfma_f32_16x16x32_bf16 v[110:113], v[148:151], v[172:175], v[110:113]
	v_mfma_f32_16x16x32_bf16 v[106:109], v[156:159], v[172:175], v[106:109]
	v_mfma_f32_16x16x32_bf16 v[94:97], v[148:151], v[180:183], v[94:97]
	v_mfma_f32_16x16x32_bf16 v[90:93], v[156:159], v[180:183], v[90:93]
	v_mfma_f32_16x16x32_bf16 v[78:81], v[148:151], v[188:191], v[78:81]
	v_mfma_f32_16x16x32_bf16 v[74:77], v[156:159], v[188:191], v[74:77]
	v_mfma_f32_16x16x32_bf16 v[126:129], v[152:155], v[168:171], v[126:129]
	v_mfma_f32_16x16x32_bf16 v[122:125], v[160:163], v[168:171], v[122:125]
	v_mfma_f32_16x16x32_bf16 v[110:113], v[152:155], v[176:179], v[110:113]
	v_mfma_f32_16x16x32_bf16 v[106:109], v[160:163], v[176:179], v[106:109]
	v_mfma_f32_16x16x32_bf16 v[94:97], v[152:155], v[184:187], v[94:97]
	v_mfma_f32_16x16x32_bf16 v[90:93], v[160:163], v[184:187], v[90:93]
	v_mfma_f32_16x16x32_bf16 v[78:81], v[152:155], v[192:195], v[78:81]
	v_mfma_f32_16x16x32_bf16 v[74:77], v[160:163], v[192:195], v[74:77]
	s_setprio 0
	s_barrier
	s_mov_b32 m0, s31
	v_lshl_add_u64 v[212:213], s[22:23], 0, v[132:133]
	ds_read_b128 v[196:199], v145
	ds_read_b128 v[200:203], v145 offset:1024
	ds_read_b128 v[204:207], v145 offset:2048
	ds_read_b128 v[208:211], v145 offset:3072
	global_load_lds_dwordx4 v[212:213], off
	v_lshl_add_u64 v[214:215], s[22:23], 0, v[136:137]
	s_mov_b32 m0, s34
	s_nop 0
	global_load_lds_dwordx4 v[214:215], off
	s_barrier
	s_waitcnt lgkmcnt(0)
	s_setprio 1
	s_waitcnt lgkmcnt(0)
	v_mfma_f32_16x16x32_bf16 v[118:121], v[196:199], v[164:167], v[118:121]
	v_mfma_f32_16x16x32_bf16 v[114:117], v[204:207], v[164:167], v[114:117]
	v_mfma_f32_16x16x32_bf16 v[102:105], v[196:199], v[172:175], v[102:105]
	v_mfma_f32_16x16x32_bf16 v[98:101], v[204:207], v[172:175], v[98:101]
	v_mfma_f32_16x16x32_bf16 v[86:89], v[196:199], v[180:183], v[86:89]
	v_mfma_f32_16x16x32_bf16 v[82:85], v[204:207], v[180:183], v[82:85]
	v_mfma_f32_16x16x32_bf16 v[70:73], v[196:199], v[188:191], v[70:73]
	v_mfma_f32_16x16x32_bf16 v[66:69], v[204:207], v[188:191], v[66:69]
	v_mfma_f32_16x16x32_bf16 v[118:121], v[200:203], v[168:171], v[118:121]
	v_mfma_f32_16x16x32_bf16 v[114:117], v[208:211], v[168:171], v[114:117]
	v_mfma_f32_16x16x32_bf16 v[102:105], v[200:203], v[176:179], v[102:105]
	v_mfma_f32_16x16x32_bf16 v[98:101], v[208:211], v[176:179], v[98:101]
	v_mfma_f32_16x16x32_bf16 v[86:89], v[200:203], v[184:187], v[86:89]
	v_mfma_f32_16x16x32_bf16 v[82:85], v[208:211], v[184:187], v[82:85]
	v_mfma_f32_16x16x32_bf16 v[70:73], v[200:203], v[192:195], v[70:73]
	v_mfma_f32_16x16x32_bf16 v[66:69], v[208:211], v[192:195], v[66:69]
	s_setprio 0
	s_mov_b32 m0, s1
	v_lshl_add_u64 v[216:217], s[24:25], 0, v[130:131]
	s_barrier
	ds_read_b128 v[164:167], v144 offset:16384
	ds_read_b128 v[168:171], v144 offset:17408
	ds_read_b128 v[172:175], v144 offset:18432
	ds_read_b128 v[176:179], v144 offset:19456
	ds_read_b128 v[180:183], v144 offset:20480
	ds_read_b128 v[184:187], v144 offset:21504
	ds_read_b128 v[188:191], v144 offset:22528
	ds_read_b128 v[192:195], v144 offset:23552
	global_load_lds_dwordx4 v[216:217], off
	v_lshl_add_u64 v[218:219], s[24:25], 0, v[134:135]
	s_mov_b32 m0, s2
	s_nop 0
	global_load_lds_dwordx4 v[218:219], off
	s_barrier
	s_waitcnt lgkmcnt(0)
	s_setprio 1
	s_waitcnt lgkmcnt(0)
	v_mfma_f32_16x16x32_bf16 v[62:65], v[148:151], v[164:167], v[62:65]
	v_mfma_f32_16x16x32_bf16 v[58:61], v[156:159], v[164:167], v[58:61]
	v_mfma_f32_16x16x32_bf16 v[46:49], v[148:151], v[172:175], v[46:49]
	v_mfma_f32_16x16x32_bf16 v[42:45], v[156:159], v[172:175], v[42:45]
	v_mfma_f32_16x16x32_bf16 v[30:33], v[148:151], v[180:183], v[30:33]
	v_mfma_f32_16x16x32_bf16 v[26:29], v[156:159], v[180:183], v[26:29]
	v_mfma_f32_16x16x32_bf16 v[14:17], v[148:151], v[188:191], v[14:17]
	v_mfma_f32_16x16x32_bf16 v[10:13], v[156:159], v[188:191], v[10:13]
	v_mfma_f32_16x16x32_bf16 v[62:65], v[152:155], v[168:171], v[62:65]
	v_mfma_f32_16x16x32_bf16 v[58:61], v[160:163], v[168:171], v[58:61]
	v_mfma_f32_16x16x32_bf16 v[46:49], v[152:155], v[176:179], v[46:49]
	v_mfma_f32_16x16x32_bf16 v[42:45], v[160:163], v[176:179], v[42:45]
	v_mfma_f32_16x16x32_bf16 v[30:33], v[152:155], v[184:187], v[30:33]
	v_mfma_f32_16x16x32_bf16 v[26:29], v[160:163], v[184:187], v[26:29]
	v_mfma_f32_16x16x32_bf16 v[14:17], v[152:155], v[192:195], v[14:17]
	v_mfma_f32_16x16x32_bf16 v[10:13], v[160:163], v[192:195], v[10:13]
	s_setprio 0
	s_barrier
; #define PG8_STAGE(bufoff, gbase, voff) do { _Pragma("unroll") for (int _i = 0; _i < 2; ++_i) \
;         __builtin_amdgcn_global_load_lds((const unsigned*)((const char*)(gbase) + (voff)[_i]), (LAS unsigned*)(lds + (bufoff) + ldsw + _i * 8192), 16, 0, 0); } while (0)
; #define PG8_LDA(dst, b, h) do { _Pragma("unroll") for (int m = 0; m < 4; ++m) _Pragma("unroll") for (int k = 0; k < 2; ++k) dst[m][k] = *(const LAS bf16x8*)(lds + PG8_SA(b, h) + aoff + m * 2048 + k * 1024); } while (0)
; #define PG8_LDB(dst, b, h) do { _Pragma("unroll") for (int n = 0; n < 2; ++n) _Pragma("unroll") for (int k = 0; k < 2; ++k) dst[n][k] = *(const LAS bf16x8*)(lds + PG8_SB(b, h) + boff + n * 2048 + k * 1024); } while (0)
; #define PG8_MMA(ai, bj, At, Bt) do { __builtin_amdgcn_s_setprio(1); _Pragma("unroll") for (int m = 0; m < 4; ++m) _Pragma("unroll") for (int n = 0; n < 2; ++n) _Pragma("unroll") for (int k = 0; k < 2; ++k) \
;         acc[ai][bj][m][n] = __builtin_amdgcn_mfma_f32_16x16x32_bf16(Bt[n][k], At[m][k], acc[ai][bj][m][n], 0, 0, 0); __builtin_amdgcn_s_setprio(0); } while (0)
; #define PG8_WAIT_V(n) asm volatile("s_waitcnt vmcnt(" #n ")" ::: "memory")
; #define PG8_WAIT_L(n) asm volatile("s_waitcnt lgkmcnt(" #n ")" ::: "memory")
; #define PG8_BAR __builtin_amdgcn_s_barrier()
; #define PG8_SCHED __builtin_amdgcn_sched_barrier(0)
; template <class Sched, class Epi>
; __device__ __forceinline__ void gemm_phase(LAS unsigned char* lds, const Sched& S, const Epi& E, const int K, const int lda, const int ldb) {
;     ...
;             PG8_BAR; PG8_WAIT_L(0); if (!chalf) PG8_MMA(1, 0, At, B0); PG8_BAR; PG8_SCHED;
;             PG8_STAGE(PG8_SB(0, 1), b2 + hstepB, voffB);
;             PG8_WAIT_V(6); PG8_BAR; if (!chalf) PG8_MMA(1, 1, At, B1); PG8_BAR;
;             PG8_LDB(B0, 1, 0); PG8_SCHED; PG8_LDA(At, 1, 0); PG8_STAGE(PG8_SA(0, 1), a2 + hstepA, voffA);
;             PG8_WAIT_L(8); PG8_BAR; PG8_WAIT_L(0); PG8_MMA(0, 0, At, B0); PG8_BAR; PG8_SCHED;
;             PG8_LDB(B1, 1, 1); PG8_STAGE(PG8_SB(1, 0), b3, voffB);
;             PG8_BAR; PG8_WAIT_L(0); PG8_MMA(0, 1, At, B1); PG8_BAR;
;             PG8_LDA(At, 1, 1); PG8_STAGE(PG8_SA(1, 0), a3, voffA);
;             PG8_BAR; PG8_WAIT_L(0); if (!chalf) PG8_MMA(1, 0, At, B0); PG8_BAR; PG8_SCHED;
	s_add_u32 s42, s22, 0x80000
	s_addc_u32 s43, s23, 0
	s_mov_b32 m0, s35
	s_nop 0
	global_load_lds_dwordx4 v132, s[42:43]
	s_mov_b32 m0, s36
	s_nop 0
	global_load_lds_dwordx4 v136, s[42:43]
	s_waitcnt vmcnt(6)
	s_barrier
	s_setprio 1
	v_mfma_f32_16x16x32_bf16 v[54:57], v[196:199], v[164:167], v[54:57]
	v_mfma_f32_16x16x32_bf16 v[50:53], v[204:207], v[164:167], v[50:53]
	v_mfma_f32_16x16x32_bf16 v[38:41], v[196:199], v[172:175], v[38:41]
	v_mfma_f32_16x16x32_bf16 v[34:37], v[204:207], v[172:175], v[34:37]
	v_mfma_f32_16x16x32_bf16 v[22:25], v[196:199], v[180:183], v[22:25]
	v_mfma_f32_16x16x32_bf16 v[18:21], v[204:207], v[180:183], v[18:21]
	v_mfma_f32_16x16x32_bf16 v[6:9], v[196:199], v[188:191], v[6:9]
	v_mfma_f32_16x16x32_bf16 v[2:5], v[204:207], v[188:191], v[2:5]
	v_mfma_f32_16x16x32_bf16 v[54:57], v[200:203], v[168:171], v[54:57]
	v_mfma_f32_16x16x32_bf16 v[50:53], v[208:211], v[168:171], v[50:53]
	v_mfma_f32_16x16x32_bf16 v[38:41], v[200:203], v[176:179], v[38:41]
	v_mfma_f32_16x16x32_bf16 v[34:37], v[208:211], v[176:179], v[34:37]
	v_mfma_f32_16x16x32_bf16 v[22:25], v[200:203], v[184:187], v[22:25]
	v_mfma_f32_16x16x32_bf16 v[18:21], v[208:211], v[184:187], v[18:21]
	v_mfma_f32_16x16x32_bf16 v[6:9], v[200:203], v[192:195], v[6:9]
	v_mfma_f32_16x16x32_bf16 v[2:5], v[208:211], v[192:195], v[2:5]
	s_setprio 0
	s_barrier
	ds_read_b128 v[148:151], v146
	ds_read_b128 v[152:155], v146 offset:1024
	ds_read_b128 v[156:159], v146 offset:2048
	ds_read_b128 v[160:163], v146 offset:3072
	s_add_u32 s24, s24, 0x80000
	s_addc_u32 s25, s25, 0
	s_mov_b32 m0, s3
	ds_read_b128 v[164:167], v144 offset:32768
	ds_read_b128 v[168:171], v144 offset:33792
	ds_read_b128 v[172:175], v144 offset:34816
	ds_read_b128 v[176:179], v144 offset:35840
	ds_read_b128 v[180:183], v144 offset:36864
	ds_read_b128 v[184:187], v144 offset:37888
	ds_read_b128 v[188:191], v144 offset:38912
	ds_read_b128 v[192:195], v144 offset:39936
	global_load_lds_dwordx4 v130, s[24:25]
	s_mov_b32 m0, s5
	s_nop 0
	global_load_lds_dwordx4 v134, s[24:25]
	s_waitcnt lgkmcnt(8)
	s_barrier
	s_waitcnt lgkmcnt(0)
	s_setprio 1
	s_waitcnt lgkmcnt(0)
	v_mfma_f32_16x16x32_bf16 v[126:129], v[148:151], v[164:167], v[126:129]
	v_mfma_f32_16x16x32_bf16 v[122:125], v[156:159], v[164:167], v[122:125]
	v_mfma_f32_16x16x32_bf16 v[110:113], v[148:151], v[172:175], v[110:113]
	v_mfma_f32_16x16x32_bf16 v[106:109], v[156:159], v[172:175], v[106:109]
	v_mfma_f32_16x16x32_bf16 v[94:97], v[148:151], v[180:183], v[94:97]
	v_mfma_f32_16x16x32_bf16 v[90:93], v[156:159], v[180:183], v[90:93]
	v_mfma_f32_16x16x32_bf16 v[78:81], v[148:151], v[188:191], v[78:81]
	v_mfma_f32_16x16x32_bf16 v[74:77], v[156:159], v[188:191], v[74:77]
	v_mfma_f32_16x16x32_bf16 v[126:129], v[152:155], v[168:171], v[126:129]
	v_mfma_f32_16x16x32_bf16 v[122:125], v[160:163], v[168:171], v[122:125]
	v_mfma_f32_16x16x32_bf16 v[110:113], v[152:155], v[176:179], v[110:113]
	v_mfma_f32_16x16x32_bf16 v[106:109], v[160:163], v[176:179], v[106:109]
	v_mfma_f32_16x16x32_bf16 v[94:97], v[152:155], v[184:187], v[94:97]
	v_mfma_f32_16x16x32_bf16 v[90:93], v[160:163], v[184:187], v[90:93]
	v_mfma_f32_16x16x32_bf16 v[78:81], v[152:155], v[192:195], v[78:81]
	v_mfma_f32_16x16x32_bf16 v[74:77], v[160:163], v[192:195], v[74:77]
	s_setprio 0
	s_barrier
	s_mov_b32 m0, s37
	v_lshl_add_u64 v[212:213], v[212:213], 0, s[16:17]
	ds_read_b128 v[196:199], v147
	ds_read_b128 v[200:203], v147 offset:1024
	ds_read_b128 v[204:207], v147 offset:2048
	ds_read_b128 v[208:211], v147 offset:3072
	global_load_lds_dwordx4 v[212:213], off
	v_lshl_add_u64 v[212:213], v[214:215], 0, s[16:17]
	s_mov_b32 m0, s38
	s_nop 0
	global_load_lds_dwordx4 v[212:213], off
	s_barrier
	s_waitcnt lgkmcnt(0)
	s_setprio 1
	s_waitcnt lgkmcnt(0)
	v_mfma_f32_16x16x32_bf16 v[118:121], v[196:199], v[164:167], v[118:121]
	v_mfma_f32_16x16x32_bf16 v[114:117], v[204:207], v[164:167], v[114:117]
	v_mfma_f32_16x16x32_bf16 v[102:105], v[196:199], v[172:175], v[102:105]
	v_mfma_f32_16x16x32_bf16 v[98:101], v[204:207], v[172:175], v[98:101]
	v_mfma_f32_16x16x32_bf16 v[86:89], v[196:199], v[180:183], v[86:89]
	v_mfma_f32_16x16x32_bf16 v[82:85], v[204:207], v[180:183], v[82:85]
	v_mfma_f32_16x16x32_bf16 v[70:73], v[196:199], v[188:191], v[70:73]
	v_mfma_f32_16x16x32_bf16 v[66:69], v[204:207], v[188:191], v[66:69]
	v_mfma_f32_16x16x32_bf16 v[118:121], v[200:203], v[168:171], v[118:121]
	v_mfma_f32_16x16x32_bf16 v[114:117], v[208:211], v[168:171], v[114:117]
	v_mfma_f32_16x16x32_bf16 v[102:105], v[200:203], v[176:179], v[102:105]
	v_mfma_f32_16x16x32_bf16 v[98:101], v[208:211], v[176:179], v[98:101]
	v_mfma_f32_16x16x32_bf16 v[86:89], v[200:203], v[184:187], v[86:89]
	v_mfma_f32_16x16x32_bf16 v[82:85], v[208:211], v[184:187], v[82:85]
	v_mfma_f32_16x16x32_bf16 v[70:73], v[200:203], v[192:195], v[70:73]
	v_mfma_f32_16x16x32_bf16 v[66:69], v[208:211], v[192:195], v[66:69]
	s_setprio 0
	s_mov_b32 m0, s10
	v_lshl_add_u64 v[212:213], v[216:217], 0, s[16:17]
	s_barrier
	ds_read_b128 v[164:167], v144 offset:49152
	ds_read_b128 v[168:171], v144 offset:50176
	ds_read_b128 v[172:175], v144 offset:51200
	ds_read_b128 v[176:179], v144 offset:52224
	ds_read_b128 v[180:183], v144 offset:53248
	ds_read_b128 v[184:187], v144 offset:54272
	ds_read_b128 v[188:191], v144 offset:55296
	ds_read_b128 v[192:195], v144 offset:56320
	global_load_lds_dwordx4 v[212:213], off
	v_lshl_add_u64 v[212:213], v[218:219], 0, s[16:17]
	s_mov_b32 m0, s11
	s_nop 0
	global_load_lds_dwordx4 v[212:213], off
	s_barrier
; #define PG8_STAGE(bufoff, gbase, voff) do { _Pragma("unroll") for (int _i = 0; _i < 2; ++_i) \
;         __builtin_amdgcn_global_load_lds((const unsigned*)((const char*)(gbase) + (voff)[_i]), (LAS unsigned*)(lds + (bufoff) + ldsw + _i * 8192), 16, 0, 0); } while (0)
; #define PG8_MMA(ai, bj, At, Bt) do { __builtin_amdgcn_s_setprio(1); _Pragma("unroll") for (int m = 0; m < 4; ++m) _Pragma("unroll") for (int n = 0; n < 2; ++n) _Pragma("unroll") for (int k = 0; k < 2; ++k) \
;         acc[ai][bj][m][n] = __builtin_amdgcn_mfma_f32_16x16x32_bf16(Bt[n][k], At[m][k], acc[ai][bj][m][n], 0, 0, 0); __builtin_amdgcn_s_setprio(0); } while (0)
; #define PG8_WAIT_V(n) asm volatile("s_waitcnt vmcnt(" #n ")" ::: "memory")
; #define PG8_WAIT_L(n) asm volatile("s_waitcnt lgkmcnt(" #n ")" ::: "memory")
; #define PG8_BAR __builtin_amdgcn_s_barrier()
; #define PG8_SCHED __builtin_amdgcn_sched_barrier(0)
; template <class Sched, class Epi>
; __device__ __forceinline__ void gemm_phase(LAS unsigned char* lds, const Sched& S, const Epi& E, const int K, const int lda, const int ldb) {
;     ...
;             PG8_BAR; PG8_WAIT_L(0); if (!chalf) PG8_MMA(1, 0, At, B0); PG8_BAR; PG8_SCHED;
;             PG8_STAGE(PG8_SB(1, 1), b3 + hstepB, voffB);
;             PG8_WAIT_V(6); PG8_BAR; if (!chalf) PG8_MMA(1, 1, At, B1); PG8_BAR;
;         }
;         E(acc, cur, wr, wc, fr, fq);
;     __device__ __forceinline__ void operator()(EPI_ARGS) const {
;     ...
;         for (int ai = 0; ai < 2; ++ai) if (ai == 0 || !u.half) { u32x4 zz[4][2];
; #pragma unroll
;             for (int m = 0; m < 4; ++m)
; #pragma unroll
;                 for (int bj = 0; bj < 2; ++bj) zz[m][bj] = *(const u32x4*)(parts + E_PZC + (size_t)EPI_ROW * 1024 + EPI_COL(bj));
	s_waitcnt lgkmcnt(0)
	s_setprio 1
	s_waitcnt lgkmcnt(0)
	v_mfma_f32_16x16x32_bf16 v[62:65], v[148:151], v[164:167], v[62:65]
	v_mfma_f32_16x16x32_bf16 v[58:61], v[156:159], v[164:167], v[58:61]
	v_mfma_f32_16x16x32_bf16 v[46:49], v[148:151], v[172:175], v[46:49]
	v_mfma_f32_16x16x32_bf16 v[42:45], v[156:159], v[172:175], v[42:45]
	v_mfma_f32_16x16x32_bf16 v[30:33], v[148:151], v[180:183], v[30:33]
	v_mfma_f32_16x16x32_bf16 v[26:29], v[156:159], v[180:183], v[26:29]
	v_mfma_f32_16x16x32_bf16 v[14:17], v[148:151], v[188:191], v[14:17]
	v_mfma_f32_16x16x32_bf16 v[10:13], v[156:159], v[188:191], v[10:13]
	v_mfma_f32_16x16x32_bf16 v[62:65], v[152:155], v[168:171], v[62:65]
	v_mfma_f32_16x16x32_bf16 v[58:61], v[160:163], v[168:171], v[58:61]
	v_mfma_f32_16x16x32_bf16 v[46:49], v[152:155], v[176:179], v[46:49]
	v_mfma_f32_16x16x32_bf16 v[42:45], v[160:163], v[176:179], v[42:45]
	v_mfma_f32_16x16x32_bf16 v[30:33], v[152:155], v[184:187], v[30:33]
	v_mfma_f32_16x16x32_bf16 v[26:29], v[160:163], v[184:187], v[26:29]
	v_mfma_f32_16x16x32_bf16 v[14:17], v[152:155], v[192:195], v[14:17]
	v_mfma_f32_16x16x32_bf16 v[10:13], v[160:163], v[192:195], v[10:13]
	s_setprio 0
	s_barrier
	s_add_u32 s22, s22, 0x80080
	s_addc_u32 s23, s23, 0
	s_mov_b32 m0, s39
	s_nop 0
	global_load_lds_dwordx4 v132, s[22:23]
	s_mov_b32 m0, s40
	s_nop 0
	global_load_lds_dwordx4 v136, s[22:23]
	s_waitcnt vmcnt(6)
	s_barrier
	s_setprio 1
	v_mfma_f32_16x16x32_bf16 v[54:57], v[196:199], v[164:167], v[54:57]
	v_mfma_f32_16x16x32_bf16 v[50:53], v[204:207], v[164:167], v[50:53]
	v_mfma_f32_16x16x32_bf16 v[38:41], v[196:199], v[172:175], v[38:41]
	v_mfma_f32_16x16x32_bf16 v[34:37], v[204:207], v[172:175], v[34:37]
	v_mfma_f32_16x16x32_bf16 v[22:25], v[196:199], v[180:183], v[22:25]
	v_mfma_f32_16x16x32_bf16 v[18:21], v[204:207], v[180:183], v[18:21]
	v_mfma_f32_16x16x32_bf16 v[6:9], v[196:199], v[188:191], v[6:9]
	v_mfma_f32_16x16x32_bf16 v[2:5], v[204:207], v[188:191], v[2:5]
	v_mfma_f32_16x16x32_bf16 v[54:57], v[200:203], v[168:171], v[54:57]
	v_mfma_f32_16x16x32_bf16 v[50:53], v[208:211], v[168:171], v[50:53]
	v_mfma_f32_16x16x32_bf16 v[38:41], v[200:203], v[176:179], v[38:41]
	v_mfma_f32_16x16x32_bf16 v[34:37], v[208:211], v[176:179], v[34:37]
	v_mfma_f32_16x16x32_bf16 v[22:25], v[200:203], v[184:187], v[22:25]
	v_mfma_f32_16x16x32_bf16 v[18:21], v[208:211], v[184:187], v[18:21]
	v_mfma_f32_16x16x32_bf16 v[6:9], v[200:203], v[192:195], v[6:9]
	v_mfma_f32_16x16x32_bf16 v[2:5], v[208:211], v[192:195], v[2:5]
	s_setprio 0
	s_add_i32 s28, s28, 2
	s_add_u32 s20, s20, 0x100
	s_addc_u32 s21, s21, 0
	s_cmp_gt_u32 s28, 29
	s_barrier
	s_cbranch_scc0 .LBB0_736
	s_sext_i32_i8 s1, s4
	v_add_u32_e32 v152, s8, v1
	v_lshl_or_b32 v1, s1, 8, v142
	s_add_u32 s12, s6, 0x1b9d8000
	v_or_b32_e32 v130, s9, v1
	v_ashrrev_i32_e32 v153, 31, v152
	s_addc_u32 s13, s7, 0
	v_ashrrev_i32_e32 v131, 31, v130
	v_lshlrev_b64 v[132:133], 11, v[152:153]
	v_lshl_add_u64 v[134:135], s[12:13], 0, v[132:133]
	v_lshlrev_b64 v[150:151], 1, v[130:131]
	v_lshl_add_u64 v[130:131], v[134:135], 0, v[150:151]
	global_load_dwordx4 v[154:157], v[130:131], off
	global_load_dwordx4 v[158:161], v[130:131], off offset:256
	v_or_b32_e32 v130, 16, v152
	v_or_b32_e32 v134, 32, v152
	v_or_b32_e32 v136, 48, v152
	v_ashrrev_i32_e32 v131, 31, v130
	v_ashrrev_i32_e32 v135, 31, v134
	s_add_u32 s4, s6, 0x252d8000
	v_ashrrev_i32_e32 v137, 31, v136
	v_lshlrev_b64 v[130:131], 11, v[130:131]
	v_lshlrev_b64 v[134:135], 11, v[134:135]
	s_addc_u32 s5, s7, 0
	v_lshlrev_b64 v[136:137], 11, v[136:137]
	v_lshl_add_u64 v[130:131], s[12:13], 0, v[130:131]
	v_lshl_add_u64 v[134:135], s[12:13], 0, v[134:135]
	v_lshl_add_u64 v[136:137], s[12:13], 0, v[136:137]
	v_lshl_add_u64 v[132:133], s[4:5], 0, v[132:133]
	v_lshl_add_u64 v[130:131], v[130:131], 0, v[150:151]
	v_lshl_add_u64 v[134:135], v[134:135], 0, v[150:151]
	v_lshl_add_u64 v[166:167], v[136:137], 0, v[150:151]
	v_lshl_add_u64 v[168:169], v[132:133], 0, v[150:151]
	global_load_dwordx4 v[162:165], v[130:131], off
	global_load_dwordx4 v[146:149], v[130:131], off offset:256
	global_load_dwordx4 v[142:145], v[134:135], off
	global_load_dwordx4 v[138:141], v[134:135], off offset:256
	s_nop 0
	global_load_dwordx4 v[134:137], v[166:167], off
	global_load_dwordx4 v[130:133], v[166:167], off offset:256
	s_cmpk_lt_u32 s0, 0x100
	s_waitcnt vmcnt(0)
; __device__ __forceinline__ float siluf_(float x) { return x * __builtin_amdgcn_rcpf(1.0f + __expf(-x)); }
; __device__ __forceinline__ u32x4 pack8(const float (&f)[8]) { u32x4 r; r[0] = cvt_pk_bf16(f[0], f[1]); r[1] = cvt_pk_bf16(f[2], f[3]); r[2] = cvt_pk_bf16(f[4], f[5]); r[3] = cvt_pk_bf16(f[6], f[7]); return r; }
;     __device__ __forceinline__ void operator()(EPI_ARGS) const {
;     ...
;                 for (int bj = 0; bj < 2; ++bj) zz[m][bj] = *(const u32x4*)(parts + E_PZC + (size_t)EPI_ROW * 1024 + EPI_COL(bj));
; #pragma unroll
;             for (int m = 0; m < 4; ++m)
; #pragma unroll
;                 for (int bj = 0; bj < 2; ++bj) { const f32x4 v0 = acc[ai][bj][m][0], v1 = acc[ai][bj][m][1]; float z[8]; unpack8(zz[m][bj], z); float o[8];
; #pragma unroll
;                     for (int j = 0; j < 4; ++j) { o[j] = v0[j] * siluf_(z[j]); o[4 + j] = v1[j] * siluf_(z[4 + j]); }
;                     *(u32x4*)(O + (size_t)EPI_ROW * 1024 + EPI_COL(bj)) = pack8(o); } }
	v_lshlrev_b32_e32 v1, 16, v154
	v_and_b32_e32 v153, 0xffff0000, v154
	v_lshlrev_b32_e32 v154, 16, v155
	v_and_b32_e32 v155, 0xffff0000, v155
	v_lshlrev_b32_e32 v166, 16, v156
	v_and_b32_e32 v156, 0xffff0000, v156
	v_lshlrev_b32_e32 v167, 16, v157
	v_and_b32_e32 v157, 0xffff0000, v157
	v_mul_f32_e32 v171, 0xbfb8aa3b, v1
	v_mul_f32_e32 v172, 0xbfb8aa3b, v166
	v_mul_f32_e32 v173, 0xbfb8aa3b, v153
	v_mul_f32_e32 v174, 0xbfb8aa3b, v156
	v_mul_f32_e32 v175, 0xbfb8aa3b, v154
	v_mul_f32_e32 v176, 0xbfb8aa3b, v167
	v_mul_f32_e32 v177, 0xbfb8aa3b, v155
	v_mul_f32_e32 v178, 0xbfb8aa3b, v157
	v_exp_f32_e32 v171, v171
	v_exp_f32_e32 v172, v172
	v_exp_f32_e32 v173, v173
	v_exp_f32_e32 v174, v174
	v_exp_f32_e32 v175, v175
	v_exp_f32_e32 v176, v176
	v_exp_f32_e32 v177, v177
	v_exp_f32_e32 v178, v178
	v_add_f32_e32 v171, 1.0, v171
	v_add_f32_e32 v172, 1.0, v172
	v_add_f32_e32 v173, 1.0, v173
	v_add_f32_e32 v174, 1.0, v174
	v_add_f32_e32 v175, 1.0, v175
	v_add_f32_e32 v176, 1.0, v176
	v_add_f32_e32 v177, 1.0, v177
	v_add_f32_e32 v178, 1.0, v178
	v_rcp_f32_e32 v171, v171
	v_rcp_f32_e32 v172, v172
	v_rcp_f32_e32 v173, v173
	v_rcp_f32_e32 v174, v174
	v_rcp_f32_e32 v175, v175
	v_rcp_f32_e32 v176, v176
	v_rcp_f32_e32 v177, v177
	v_rcp_f32_e32 v178, v178
	v_mul_f32_e32 v1, v171, v1
	v_mul_f32_e32 v166, v172, v166
	v_mul_f32_e32 v153, v173, v153
	v_mul_f32_e32 v156, v174, v156
	v_mul_f32_e32 v154, v175, v154
	v_mul_f32_e32 v167, v176, v167
	v_mul_f32_e32 v155, v177, v155
	v_lshlrev_b32_e32 v170, 16, v158
	v_mul_f32_e32 v157, v178, v157
	v_mul_f32_e32 v1, v126, v1
	v_mul_f32_e32 v126, v122, v166
	v_mul_f32_e32 v122, v127, v153
	v_mul_f32_e32 v127, v123, v156
	v_mul_f32_e32 v123, v128, v154
	v_mul_f32_e32 v128, v124, v167
	v_mul_f32_e32 v124, v129, v155
	v_mul_f32_e32 v125, v125, v157
	v_cvt_pk_bf16_f32 v122, v1, v122
	v_cvt_pk_bf16_f32 v123, v123, v124
	v_cvt_pk_bf16_f32 v124, v126, v127
	v_mul_f32_e32 v126, 0xbfb8aa3b, v170
	v_cvt_pk_bf16_f32 v125, v128, v125
	global_store_dwordx4 v[168:169], v[122:125], off
	v_exp_f32_e32 v126, v126
	v_and_b32_e32 v1, 0xffff0000, v158
	v_lshlrev_b32_e32 v124, 16, v160
	v_mul_f32_e32 v127, 0xbfb8aa3b, v124
	v_exp_f32_e32 v127, v127
	v_add_f32_e32 v126, 1.0, v126
	v_rcp_f32_e32 v126, v126
	v_and_b32_e32 v125, 0xffff0000, v160
	v_add_f32_e32 v127, 1.0, v127
	v_rcp_f32_e32 v127, v127
	v_mul_f32_e32 v126, v126, v170
	v_mul_f32_e32 v118, v118, v126
	v_mul_f32_e32 v126, 0xbfb8aa3b, v1
	v_mul_f32_e32 v124, v127, v124
	v_exp_f32_e32 v126, v126
	v_mul_f32_e32 v127, 0xbfb8aa3b, v125
	v_exp_f32_e32 v127, v127
	v_lshlrev_b32_e32 v122, 16, v159
	v_mul_f32_e32 v124, v114, v124
	v_add_f32_e32 v114, 1.0, v126
	v_rcp_f32_e32 v114, v114
	v_add_f32_e32 v126, 1.0, v127
	v_mul_f32_e32 v127, 0xbfb8aa3b, v122
	v_exp_f32_e32 v127, v127
	v_mul_f32_e32 v1, v114, v1
	v_rcp_f32_e32 v126, v126
	v_mul_f32_e32 v1, v119, v1
	v_add_f32_e32 v119, 1.0, v127
	v_rcp_f32_e32 v119, v119
	v_lshlrev_b32_e32 v128, 16, v161
	v_and_b32_e32 v123, 0xffff0000, v159
	v_mul_f32_e32 v114, v126, v125
	v_mul_f32_e32 v125, 0xbfb8aa3b, v128
	v_and_b32_e32 v129, 0xffff0000, v161
	v_exp_f32_e32 v125, v125
	v_mul_f32_e32 v126, v115, v114
	v_mul_f32_e32 v114, v119, v122
	v_mul_f32_e32 v119, 0xbfb8aa3b, v123
	v_mul_f32_e32 v115, v120, v114
	v_exp_f32_e32 v119, v119
	v_mul_f32_e32 v120, 0xbfb8aa3b, v129
	v_exp_f32_e32 v120, v120
	v_add_f32_e32 v114, 1.0, v125
	v_rcp_f32_e32 v114, v114
	v_add_f32_e32 v119, 1.0, v119
	v_rcp_f32_e32 v119, v119
	v_add_f32_e32 v120, 1.0, v120
	v_rcp_f32_e32 v120, v120
	v_mul_f32_e32 v114, v114, v128
	v_mul_f32_e32 v122, v116, v114
	v_mul_f32_e32 v114, v119, v123
	v_mul_f32_e32 v116, v121, v114
	v_mul_f32_e32 v114, v120, v129
	v_mul_f32_e32 v117, v117, v114
	v_cvt_pk_bf16_f32 v114, v118, v1
	v_cvt_pk_bf16_f32 v115, v115, v116
	v_cvt_pk_bf16_f32 v116, v124, v126
	v_cvt_pk_bf16_f32 v117, v122, v117
	v_lshlrev_b32_e32 v1, 16, v162
	global_store_dwordx4 v[168:169], v[114:117], off offset:256
	v_mul_f32_e32 v119, 0xbfb8aa3b, v1
	v_exp_f32_e32 v119, v119
	v_lshlrev_b32_e32 v117, 16, v164
	v_mul_f32_e32 v120, 0xbfb8aa3b, v117
	v_exp_f32_e32 v120, v120
	v_add_f32_e32 v119, 1.0, v119
	v_rcp_f32_e32 v119, v119
	v_and_b32_e32 v114, 0xffff0000, v162
	v_add_f32_e32 v120, 1.0, v120
	v_rcp_f32_e32 v120, v120
	v_and_b32_e32 v118, 0xffff0000, v164
	v_mul_f32_e32 v1, v119, v1
	v_mul_f32_e32 v1, v110, v1
	v_mul_f32_e32 v110, v120, v117
	v_mul_f32_e32 v117, 0xbfb8aa3b, v114
	v_mul_f32_e32 v119, 0xbfb8aa3b, v118
	v_exp_f32_e32 v117, v117
	v_exp_f32_e32 v119, v119
	v_lshlrev_b32_e32 v115, 16, v163
	v_mul_f32_e32 v110, v106, v110
	v_add_f32_e32 v106, 1.0, v117
	v_add_f32_e32 v117, 1.0, v119
	v_mul_f32_e32 v119, 0xbfb8aa3b, v115
	v_rcp_f32_e32 v106, v106
	v_exp_f32_e32 v119, v119
	v_rcp_f32_e32 v117, v117
	v_lshlrev_b32_e32 v121, 16, v165
	v_mul_f32_e32 v106, v106, v114
	v_add_f32_e32 v114, 1.0, v119
	v_rcp_f32_e32 v114, v114
	v_and_b32_e32 v116, 0xffff0000, v163
	v_mul_f32_e32 v106, v111, v106
	v_mul_f32_e32 v111, v117, v118
	v_mul_f32_e32 v117, 0xbfb8aa3b, v121
	v_exp_f32_e32 v117, v117
	v_mul_f32_e32 v111, v107, v111
	v_mul_f32_e32 v107, v114, v115
	v_mul_f32_e32 v114, 0xbfb8aa3b, v116
	v_exp_f32_e32 v114, v114
	v_and_b32_e32 v122, 0xffff0000, v165
	v_mul_f32_e32 v107, v112, v107
	v_add_f32_e32 v112, 1.0, v117
	v_mul_f32_e32 v115, 0xbfb8aa3b, v122
	v_rcp_f32_e32 v112, v112
	v_exp_f32_e32 v115, v115
	v_add_f32_e32 v114, 1.0, v114
	v_rcp_f32_e32 v114, v114
	v_mul_f32_e32 v112, v112, v121
	v_add_f32_e32 v115, 1.0, v115
	v_rcp_f32_e32 v115, v115
	v_mul_f32_e32 v112, v108, v112
	v_mul_f32_e32 v108, v114, v116
	v_mul_f32_e32 v108, v113, v108
	v_cvt_pk_bf16_f32 v106, v1, v106
; __device__ __forceinline__ float siluf_(float x) { return x * __builtin_amdgcn_rcpf(1.0f + __expf(-x)); }
; __device__ __forceinline__ u32x4 pack8(const float (&f)[8]) { u32x4 r; r[0] = cvt_pk_bf16(f[0], f[1]); r[1] = cvt_pk_bf16(f[2], f[3]); r[2] = cvt_pk_bf16(f[4], f[5]); r[3] = cvt_pk_bf16(f[6], f[7]); return r; }
;     __device__ __forceinline__ void operator()(EPI_ARGS) const {
;     ...
;                 for (int bj = 0; bj < 2; ++bj) zz[m][bj] = *(const u32x4*)(parts + E_PZC + (size_t)EPI_ROW * 1024 + EPI_COL(bj));
; #pragma unroll
;             for (int m = 0; m < 4; ++m)
; #pragma unroll
;                 for (int bj = 0; bj < 2; ++bj) { const f32x4 v0 = acc[ai][bj][m][0], v1 = acc[ai][bj][m][1]; float z[8]; unpack8(zz[m][bj], z); float o[8];
; #pragma unroll
;                     for (int j = 0; j < 4; ++j) { o[j] = v0[j] * siluf_(z[j]); o[4 + j] = v1[j] * siluf_(z[4 + j]); }
;                     *(u32x4*)(O + (size_t)EPI_ROW * 1024 + EPI_COL(bj)) = pack8(o); } }
	v_cvt_pk_bf16_f32 v107, v107, v108
	v_cvt_pk_bf16_f32 v108, v110, v111
	v_add_u32_e32 v110, 16, v152
	v_ashrrev_i32_e32 v111, 31, v110
	v_mul_f32_e32 v113, v115, v122
	v_lshlrev_b64 v[110:111], 11, v[110:111]
	v_mul_f32_e32 v109, v109, v113
	v_lshl_add_u64 v[110:111], s[4:5], 0, v[110:111]
	v_cvt_pk_bf16_f32 v109, v112, v109
	v_lshl_add_u64 v[110:111], v[110:111], 0, v[150:151]
	v_lshlrev_b32_e32 v1, 16, v146
	global_store_dwordx4 v[110:111], v[106:109], off
	v_mul_f32_e32 v113, 0xbfb8aa3b, v1
	v_exp_f32_e32 v113, v113
	v_lshlrev_b32_e32 v109, 16, v148
	v_mul_f32_e32 v114, 0xbfb8aa3b, v109
	v_exp_f32_e32 v114, v114
	v_add_f32_e32 v113, 1.0, v113
	v_rcp_f32_e32 v113, v113
	v_and_b32_e32 v106, 0xffff0000, v146
	v_add_f32_e32 v114, 1.0, v114
	v_rcp_f32_e32 v114, v114
	v_and_b32_e32 v112, 0xffff0000, v148
	v_mul_f32_e32 v1, v113, v1
	v_mul_f32_e32 v1, v102, v1
	v_mul_f32_e32 v102, v114, v109
	v_mul_f32_e32 v109, 0xbfb8aa3b, v106
	v_mul_f32_e32 v113, 0xbfb8aa3b, v112
	v_exp_f32_e32 v109, v109
	v_exp_f32_e32 v113, v113
	v_lshlrev_b32_e32 v107, 16, v147
	v_mul_f32_e32 v102, v98, v102
	v_add_f32_e32 v98, 1.0, v109
	v_add_f32_e32 v109, 1.0, v113
	v_mul_f32_e32 v113, 0xbfb8aa3b, v107
	v_rcp_f32_e32 v98, v98
	v_exp_f32_e32 v113, v113
	v_rcp_f32_e32 v109, v109
	v_lshlrev_b32_e32 v115, 16, v149
	v_mul_f32_e32 v98, v98, v106
	v_add_f32_e32 v106, 1.0, v113
	v_rcp_f32_e32 v106, v106
	v_and_b32_e32 v108, 0xffff0000, v147
	v_mul_f32_e32 v98, v103, v98
	v_mul_f32_e32 v103, v109, v112
	v_mul_f32_e32 v109, 0xbfb8aa3b, v115
	v_and_b32_e32 v116, 0xffff0000, v149
	v_exp_f32_e32 v109, v109
	v_mul_f32_e32 v103, v99, v103
	v_mul_f32_e32 v99, v106, v107
	v_mul_f32_e32 v106, 0xbfb8aa3b, v108
	v_exp_f32_e32 v106, v106
	v_mul_f32_e32 v107, 0xbfb8aa3b, v116
	v_exp_f32_e32 v107, v107
	v_mul_f32_e32 v99, v104, v99
	v_add_f32_e32 v104, 1.0, v109
	v_rcp_f32_e32 v104, v104
	v_add_f32_e32 v106, 1.0, v106
	v_rcp_f32_e32 v106, v106
	v_add_f32_e32 v107, 1.0, v107
	v_rcp_f32_e32 v107, v107
	v_mul_f32_e32 v104, v104, v115
	v_mul_f32_e32 v104, v100, v104
	v_mul_f32_e32 v100, v106, v108
	v_mul_f32_e32 v100, v105, v100
	v_mul_f32_e32 v105, v107, v116
	v_mul_f32_e32 v101, v101, v105
	v_cvt_pk_bf16_f32 v98, v1, v98
	v_cvt_pk_bf16_f32 v99, v99, v100
	v_cvt_pk_bf16_f32 v100, v102, v103
	v_cvt_pk_bf16_f32 v101, v104, v101
	v_lshlrev_b32_e32 v1, 16, v142
	global_store_dwordx4 v[110:111], v[98:101], off offset:256
	v_mul_f32_e32 v103, 0xbfb8aa3b, v1
	v_exp_f32_e32 v103, v103
	v_lshlrev_b32_e32 v101, 16, v144
	v_mul_f32_e32 v104, 0xbfb8aa3b, v101
	v_exp_f32_e32 v104, v104
	v_add_f32_e32 v103, 1.0, v103
	v_rcp_f32_e32 v103, v103
	v_and_b32_e32 v98, 0xffff0000, v142
	v_add_f32_e32 v104, 1.0, v104
	v_rcp_f32_e32 v104, v104
	v_and_b32_e32 v102, 0xffff0000, v144
	v_mul_f32_e32 v1, v103, v1
	v_mul_f32_e32 v1, v94, v1
	v_mul_f32_e32 v94, v104, v101
	v_mul_f32_e32 v101, 0xbfb8aa3b, v98
	v_mul_f32_e32 v103, 0xbfb8aa3b, v102
	v_exp_f32_e32 v101, v101
	v_exp_f32_e32 v103, v103
	v_lshlrev_b32_e32 v99, 16, v143
	v_mul_f32_e32 v94, v90, v94
	v_add_f32_e32 v90, 1.0, v101
	v_add_f32_e32 v101, 1.0, v103
	v_mul_f32_e32 v103, 0xbfb8aa3b, v99
	v_rcp_f32_e32 v90, v90
	v_exp_f32_e32 v103, v103
	v_rcp_f32_e32 v101, v101
	v_lshlrev_b32_e32 v105, 16, v145
	v_mul_f32_e32 v90, v90, v98
	v_add_f32_e32 v98, 1.0, v103
	v_rcp_f32_e32 v98, v98
	v_and_b32_e32 v100, 0xffff0000, v143
	v_mul_f32_e32 v90, v95, v90
	v_mul_f32_e32 v95, v101, v102
	v_mul_f32_e32 v101, 0xbfb8aa3b, v105
	v_exp_f32_e32 v101, v101
	v_mul_f32_e32 v95, v91, v95
	v_mul_f32_e32 v91, v98, v99
	v_mul_f32_e32 v98, 0xbfb8aa3b, v100
	v_exp_f32_e32 v98, v98
	v_and_b32_e32 v106, 0xffff0000, v145
	v_mul_f32_e32 v91, v96, v91
	v_add_f32_e32 v96, 1.0, v101
	v_mul_f32_e32 v99, 0xbfb8aa3b, v106
	v_rcp_f32_e32 v96, v96
	v_exp_f32_e32 v99, v99
	v_add_f32_e32 v98, 1.0, v98
	v_rcp_f32_e32 v98, v98
	v_mul_f32_e32 v96, v96, v105
	v_add_f32_e32 v99, 1.0, v99
	v_rcp_f32_e32 v99, v99
	v_mul_f32_e32 v96, v92, v96
	v_mul_f32_e32 v92, v98, v100
	v_mul_f32_e32 v92, v97, v92
	v_cvt_pk_bf16_f32 v90, v1, v90
	v_cvt_pk_bf16_f32 v91, v91, v92
	v_cvt_pk_bf16_f32 v92, v94, v95
	v_add_u32_e32 v94, 32, v152
	v_ashrrev_i32_e32 v95, 31, v94
	v_mul_f32_e32 v97, v99, v106
	v_lshlrev_b64 v[94:95], 11, v[94:95]
	v_mul_f32_e32 v93, v93, v97
	v_lshl_add_u64 v[94:95], s[4:5], 0, v[94:95]
	v_cvt_pk_bf16_f32 v93, v96, v93
	v_lshl_add_u64 v[94:95], v[94:95], 0, v[150:151]
	v_lshlrev_b32_e32 v1, 16, v138
	global_store_dwordx4 v[94:95], v[90:93], off
	v_mul_f32_e32 v97, 0xbfb8aa3b, v1
	v_exp_f32_e32 v97, v97
	v_lshlrev_b32_e32 v93, 16, v140
	v_mul_f32_e32 v98, 0xbfb8aa3b, v93
	v_exp_f32_e32 v98, v98
	v_add_f32_e32 v97, 1.0, v97
	v_rcp_f32_e32 v97, v97
	v_and_b32_e32 v90, 0xffff0000, v138
	v_add_f32_e32 v98, 1.0, v98
	v_rcp_f32_e32 v98, v98
	v_and_b32_e32 v96, 0xffff0000, v140
	v_mul_f32_e32 v1, v97, v1
	v_mul_f32_e32 v1, v86, v1
	v_mul_f32_e32 v86, v98, v93
	v_mul_f32_e32 v93, 0xbfb8aa3b, v90
	v_mul_f32_e32 v97, 0xbfb8aa3b, v96
	v_exp_f32_e32 v93, v93
	v_exp_f32_e32 v97, v97
	v_lshlrev_b32_e32 v91, 16, v139
	v_mul_f32_e32 v86, v82, v86
	v_add_f32_e32 v82, 1.0, v93
	v_add_f32_e32 v93, 1.0, v97
	v_mul_f32_e32 v97, 0xbfb8aa3b, v91
	v_rcp_f32_e32 v82, v82
	v_exp_f32_e32 v97, v97
	v_rcp_f32_e32 v93, v93
	v_lshlrev_b32_e32 v99, 16, v141
	v_mul_f32_e32 v82, v82, v90
	v_add_f32_e32 v90, 1.0, v97
	v_rcp_f32_e32 v90, v90
	v_and_b32_e32 v92, 0xffff0000, v139
	v_mul_f32_e32 v82, v87, v82
	v_mul_f32_e32 v87, v93, v96
	v_mul_f32_e32 v93, 0xbfb8aa3b, v99
	v_and_b32_e32 v100, 0xffff0000, v141
	v_exp_f32_e32 v93, v93
	v_mul_f32_e32 v87, v83, v87
	v_mul_f32_e32 v83, v90, v91
	v_mul_f32_e32 v90, 0xbfb8aa3b, v92
; __device__ __forceinline__ float siluf_(float x) { return x * __builtin_amdgcn_rcpf(1.0f + __expf(-x)); }
; __device__ __forceinline__ u32x4 pack8(const float (&f)[8]) { u32x4 r; r[0] = cvt_pk_bf16(f[0], f[1]); r[1] = cvt_pk_bf16(f[2], f[3]); r[2] = cvt_pk_bf16(f[4], f[5]); r[3] = cvt_pk_bf16(f[6], f[7]); return r; }
;     __device__ __forceinline__ void operator()(EPI_ARGS) const {
;     ...
;                 for (int bj = 0; bj < 2; ++bj) zz[m][bj] = *(const u32x4*)(parts + E_PZC + (size_t)EPI_ROW * 1024 + EPI_COL(bj));
; #pragma unroll
;             for (int m = 0; m < 4; ++m)
; #pragma unroll
;                 for (int bj = 0; bj < 2; ++bj) { const f32x4 v0 = acc[ai][bj][m][0], v1 = acc[ai][bj][m][1]; float z[8]; unpack8(zz[m][bj], z); float o[8];
; #pragma unroll
;                     for (int j = 0; j < 4; ++j) { o[j] = v0[j] * siluf_(z[j]); o[4 + j] = v1[j] * siluf_(z[4 + j]); }
;                     *(u32x4*)(O + (size_t)EPI_ROW * 1024 + EPI_COL(bj)) = pack8(o); } }
	v_exp_f32_e32 v90, v90
	v_mul_f32_e32 v91, 0xbfb8aa3b, v100
	v_exp_f32_e32 v91, v91
	v_mul_f32_e32 v83, v88, v83
	v_add_f32_e32 v88, 1.0, v93
	v_rcp_f32_e32 v88, v88
	v_add_f32_e32 v90, 1.0, v90
	v_rcp_f32_e32 v90, v90
	v_add_f32_e32 v91, 1.0, v91
	v_rcp_f32_e32 v91, v91
	v_mul_f32_e32 v88, v88, v99
	v_mul_f32_e32 v88, v84, v88
	v_mul_f32_e32 v84, v90, v92
	v_mul_f32_e32 v84, v89, v84
	v_mul_f32_e32 v89, v91, v100
	v_mul_f32_e32 v85, v85, v89
	v_cvt_pk_bf16_f32 v82, v1, v82
	v_cvt_pk_bf16_f32 v83, v83, v84
	v_cvt_pk_bf16_f32 v84, v86, v87
	v_cvt_pk_bf16_f32 v85, v88, v85
	v_lshlrev_b32_e32 v1, 16, v134
	global_store_dwordx4 v[94:95], v[82:85], off offset:256
	v_mul_f32_e32 v87, 0xbfb8aa3b, v1
	v_exp_f32_e32 v87, v87
	v_lshlrev_b32_e32 v85, 16, v136
	v_mul_f32_e32 v88, 0xbfb8aa3b, v85
	v_exp_f32_e32 v88, v88
	v_add_f32_e32 v87, 1.0, v87
	v_rcp_f32_e32 v87, v87
	v_and_b32_e32 v82, 0xffff0000, v134
	v_add_f32_e32 v88, 1.0, v88
	v_rcp_f32_e32 v88, v88
	v_and_b32_e32 v86, 0xffff0000, v136
	v_mul_f32_e32 v1, v87, v1
	v_mul_f32_e32 v1, v78, v1
	v_mul_f32_e32 v78, v88, v85
	v_mul_f32_e32 v85, 0xbfb8aa3b, v82
	v_mul_f32_e32 v87, 0xbfb8aa3b, v86
	v_exp_f32_e32 v85, v85
	v_exp_f32_e32 v87, v87
	v_lshlrev_b32_e32 v83, 16, v135
	v_mul_f32_e32 v78, v74, v78
	v_add_f32_e32 v74, 1.0, v85
	v_add_f32_e32 v85, 1.0, v87
	v_mul_f32_e32 v87, 0xbfb8aa3b, v83
	v_rcp_f32_e32 v74, v74
	v_exp_f32_e32 v87, v87
	v_rcp_f32_e32 v85, v85
	v_lshlrev_b32_e32 v89, 16, v137
	v_mul_f32_e32 v74, v74, v82
	v_add_f32_e32 v82, 1.0, v87
	v_rcp_f32_e32 v82, v82
	v_and_b32_e32 v84, 0xffff0000, v135
	v_mul_f32_e32 v74, v79, v74
	v_mul_f32_e32 v79, v85, v86
	v_mul_f32_e32 v85, 0xbfb8aa3b, v89
	v_exp_f32_e32 v85, v85
	v_mul_f32_e32 v79, v75, v79
	v_mul_f32_e32 v75, v82, v83
	v_mul_f32_e32 v82, 0xbfb8aa3b, v84
	v_exp_f32_e32 v82, v82
	v_and_b32_e32 v90, 0xffff0000, v137
	v_mul_f32_e32 v75, v80, v75
	v_add_f32_e32 v80, 1.0, v85
	v_mul_f32_e32 v83, 0xbfb8aa3b, v90
	v_rcp_f32_e32 v80, v80
	v_exp_f32_e32 v83, v83
	v_add_f32_e32 v82, 1.0, v82
	v_rcp_f32_e32 v82, v82
	v_mul_f32_e32 v80, v80, v89
	v_add_f32_e32 v83, 1.0, v83
	v_rcp_f32_e32 v83, v83
	v_mul_f32_e32 v80, v76, v80
	v_mul_f32_e32 v76, v82, v84
	v_mul_f32_e32 v76, v81, v76
	v_cvt_pk_bf16_f32 v74, v1, v74
	v_cvt_pk_bf16_f32 v75, v75, v76
	v_cvt_pk_bf16_f32 v76, v78, v79
	v_add_u32_e32 v78, 48, v152
	v_ashrrev_i32_e32 v79, 31, v78
	v_mul_f32_e32 v81, v83, v90
	v_lshlrev_b64 v[78:79], 11, v[78:79]
	v_mul_f32_e32 v77, v77, v81
	v_lshl_add_u64 v[78:79], s[4:5], 0, v[78:79]
	v_cvt_pk_bf16_f32 v77, v80, v77
	v_lshl_add_u64 v[78:79], v[78:79], 0, v[150:151]
	v_lshlrev_b32_e32 v1, 16, v130
	global_store_dwordx4 v[78:79], v[74:77], off
	v_mul_f32_e32 v81, 0xbfb8aa3b, v1
	v_exp_f32_e32 v81, v81
	v_lshlrev_b32_e32 v77, 16, v132
	v_mul_f32_e32 v82, 0xbfb8aa3b, v77
	v_exp_f32_e32 v82, v82
	v_add_f32_e32 v81, 1.0, v81
	v_rcp_f32_e32 v81, v81
	v_and_b32_e32 v74, 0xffff0000, v130
	v_add_f32_e32 v82, 1.0, v82
	v_rcp_f32_e32 v82, v82
	v_and_b32_e32 v80, 0xffff0000, v132
	v_mul_f32_e32 v1, v81, v1
	v_mul_f32_e32 v1, v70, v1
	v_mul_f32_e32 v70, v82, v77
	v_mul_f32_e32 v77, 0xbfb8aa3b, v74
	v_mul_f32_e32 v81, 0xbfb8aa3b, v80
	v_exp_f32_e32 v77, v77
	v_exp_f32_e32 v81, v81
	v_lshlrev_b32_e32 v75, 16, v131
	v_mul_f32_e32 v70, v66, v70
	v_add_f32_e32 v66, 1.0, v77
	v_add_f32_e32 v77, 1.0, v81
	v_mul_f32_e32 v81, 0xbfb8aa3b, v75
	v_rcp_f32_e32 v66, v66
	v_exp_f32_e32 v81, v81
	v_rcp_f32_e32 v77, v77
	v_lshlrev_b32_e32 v83, 16, v133
	v_mul_f32_e32 v66, v66, v74
	v_add_f32_e32 v74, 1.0, v81
	v_rcp_f32_e32 v74, v74
	v_and_b32_e32 v76, 0xffff0000, v131
	v_mul_f32_e32 v66, v71, v66
	v_mul_f32_e32 v71, v77, v80
	v_mul_f32_e32 v77, 0xbfb8aa3b, v83
	v_exp_f32_e32 v77, v77
	v_mul_f32_e32 v71, v67, v71
	v_mul_f32_e32 v67, v74, v75
	v_mul_f32_e32 v74, 0xbfb8aa3b, v76
	v_exp_f32_e32 v74, v74
	v_and_b32_e32 v84, 0xffff0000, v133
	v_mul_f32_e32 v67, v72, v67
	v_add_f32_e32 v72, 1.0, v77
	v_rcp_f32_e32 v72, v72
	v_mul_f32_e32 v75, 0xbfb8aa3b, v84
	v_add_f32_e32 v74, 1.0, v74
	v_exp_f32_e32 v75, v75
	v_rcp_f32_e32 v74, v74
	v_mul_f32_e32 v72, v72, v83
	v_mul_f32_e32 v72, v68, v72
	v_add_f32_e32 v75, 1.0, v75
	v_mul_f32_e32 v68, v74, v76
	v_rcp_f32_e32 v75, v75
	v_mul_f32_e32 v68, v73, v68
	v_cvt_pk_bf16_f32 v66, v1, v66
	v_cvt_pk_bf16_f32 v67, v67, v68
	v_cvt_pk_bf16_f32 v68, v70, v71
	v_add_u32_e32 v70, 0x80, v152
	v_ashrrev_i32_e32 v71, 31, v70
	v_lshlrev_b64 v[104:105], 11, v[70:71]
	v_mul_f32_e32 v73, v75, v84
	v_lshl_add_u64 v[70:71], s[12:13], 0, v[104:105]
	v_mul_f32_e32 v69, v69, v73
	v_lshl_add_u64 v[70:71], v[70:71], 0, v[150:151]
	v_cvt_pk_bf16_f32 v69, v72, v69
	global_load_dwordx4 v[92:95], v[70:71], off
	s_nop 0
	global_store_dwordx4 v[78:79], v[66:69], off offset:256
	global_load_dwordx4 v[96:99], v[70:71], off offset:256
	s_waitcnt vmcnt(0)
; __device__ __forceinline__ float siluf_(float x) { return x * __builtin_amdgcn_rcpf(1.0f + __expf(-x)); }
; __device__ __forceinline__ u32x4 pack8(const float (&f)[8]) { u32x4 r; r[0] = cvt_pk_bf16(f[0], f[1]); r[1] = cvt_pk_bf16(f[2], f[3]); r[2] = cvt_pk_bf16(f[4], f[5]); r[3] = cvt_pk_bf16(f[6], f[7]); return r; }
;     __device__ __forceinline__ void operator()(EPI_ARGS) const {
;     ...
;                 for (int bj = 0; bj < 2; ++bj) zz[m][bj] = *(const u32x4*)(parts + E_PZC + (size_t)EPI_ROW * 1024 + EPI_COL(bj));
; #pragma unroll
;             for (int m = 0; m < 4; ++m)
; #pragma unroll
;                 for (int bj = 0; bj < 2; ++bj) { const f32x4 v0 = acc[ai][bj][m][0], v1 = acc[ai][bj][m][1]; float z[8]; unpack8(zz[m][bj], z); float o[8];
; #pragma unroll
;                     for (int j = 0; j < 4; ++j) { o[j] = v0[j] * siluf_(z[j]); o[4 + j] = v1[j] * siluf_(z[4 + j]); }
;                     *(u32x4*)(O + (size_t)EPI_ROW * 1024 + EPI_COL(bj)) = pack8(o); } }
	v_lshlrev_b32_e32 v1, 16, v92
	v_add_u32_e32 v66, 0x90, v152
	v_ashrrev_i32_e32 v67, 31, v66
	v_lshlrev_b64 v[90:91], 11, v[66:67]
	v_lshl_add_u64 v[66:67], s[12:13], 0, v[90:91]
	v_lshl_add_u64 v[66:67], v[66:67], 0, v[150:151]
	global_load_dwordx4 v[100:103], v[66:67], off
	global_load_dwordx4 v[82:85], v[66:67], off offset:256
	v_add_u32_e32 v66, 0xa0, v152
	v_ashrrev_i32_e32 v67, 31, v66
	v_lshlrev_b64 v[88:89], 11, v[66:67]
	v_lshl_add_u64 v[66:67], s[12:13], 0, v[88:89]
	v_lshl_add_u64 v[66:67], v[66:67], 0, v[150:151]
	global_load_dwordx4 v[78:81], v[66:67], off
	global_load_dwordx4 v[74:77], v[66:67], off offset:256
	v_add_u32_e32 v66, 0xb0, v152
	v_ashrrev_i32_e32 v67, 31, v66
	v_lshlrev_b64 v[86:87], 11, v[66:67]
	v_lshl_add_u64 v[66:67], s[12:13], 0, v[86:87]
	v_lshl_add_u64 v[106:107], v[66:67], 0, v[150:151]
	global_load_dwordx4 v[70:73], v[106:107], off
	global_load_dwordx4 v[66:69], v[106:107], off offset:256
	v_lshlrev_b32_e32 v107, 16, v94
	v_mul_f32_e32 v108, 0xbfb8aa3b, v1
	v_exp_f32_e32 v108, v108
	v_mul_f32_e32 v109, 0xbfb8aa3b, v107
	v_exp_f32_e32 v109, v109
	v_and_b32_e32 v92, 0xffff0000, v92
	v_add_f32_e32 v108, 1.0, v108
	v_rcp_f32_e32 v108, v108
	v_add_f32_e32 v109, 1.0, v109
	v_rcp_f32_e32 v109, v109
	v_and_b32_e32 v94, 0xffff0000, v94
	v_mul_f32_e32 v1, v108, v1
	v_mul_f32_e32 v1, v62, v1
	v_mul_f32_e32 v62, v109, v107
	v_mul_f32_e32 v107, 0xbfb8aa3b, v92
	v_mul_f32_e32 v108, 0xbfb8aa3b, v94
	v_exp_f32_e32 v107, v107
	v_exp_f32_e32 v108, v108
	v_lshlrev_b32_e32 v106, 16, v93
	v_mul_f32_e32 v62, v58, v62
	v_add_f32_e32 v58, 1.0, v107
	v_add_f32_e32 v107, 1.0, v108
	v_mul_f32_e32 v108, 0xbfb8aa3b, v106
	v_rcp_f32_e32 v58, v58
	v_exp_f32_e32 v108, v108
	v_rcp_f32_e32 v107, v107
	v_lshlrev_b32_e32 v110, 16, v95
	v_mul_f32_e32 v58, v58, v92
	v_add_f32_e32 v92, 1.0, v108
	v_mul_f32_e32 v58, v63, v58
	v_mul_f32_e32 v63, v107, v94
	v_rcp_f32_e32 v92, v92
	v_mul_f32_e32 v94, 0xbfb8aa3b, v110
	v_exp_f32_e32 v94, v94
	v_and_b32_e32 v93, 0xffff0000, v93
	v_and_b32_e32 v95, 0xffff0000, v95
	v_mul_f32_e32 v63, v59, v63
	v_mul_f32_e32 v59, v92, v106
	v_mul_f32_e32 v92, 0xbfb8aa3b, v93
	v_mul_f32_e32 v59, v64, v59
	v_add_f32_e32 v64, 1.0, v94
	v_exp_f32_e32 v92, v92
	v_mul_f32_e32 v94, 0xbfb8aa3b, v95
	v_exp_f32_e32 v94, v94
	v_rcp_f32_e32 v64, v64
	v_add_f32_e32 v92, 1.0, v92
	v_rcp_f32_e32 v92, v92
	v_add_f32_e32 v94, 1.0, v94
	v_rcp_f32_e32 v94, v94
	v_mul_f32_e32 v64, v64, v110
	v_mul_f32_e32 v64, v60, v64
	v_mul_f32_e32 v60, v92, v93
	v_mul_f32_e32 v60, v65, v60
	v_mul_f32_e32 v65, v94, v95
	v_mul_f32_e32 v61, v61, v65
	v_cvt_pk_bf16_f32 v58, v1, v58
	v_cvt_pk_bf16_f32 v59, v59, v60
	v_cvt_pk_bf16_f32 v60, v62, v63
	v_lshl_add_u64 v[62:63], s[4:5], 0, v[104:105]
	v_cvt_pk_bf16_f32 v61, v64, v61
	v_lshl_add_u64 v[62:63], v[62:63], 0, v[150:151]
	v_lshlrev_b32_e32 v1, 16, v96
	global_store_dwordx4 v[62:63], v[58:61], off
	v_mul_f32_e32 v65, 0xbfb8aa3b, v1
	v_exp_f32_e32 v65, v65
	v_lshlrev_b32_e32 v61, 16, v98
	v_mul_f32_e32 v92, 0xbfb8aa3b, v61
	v_exp_f32_e32 v92, v92
	v_add_f32_e32 v65, 1.0, v65
	v_rcp_f32_e32 v65, v65
	v_and_b32_e32 v58, 0xffff0000, v96
	v_add_f32_e32 v92, 1.0, v92
	v_rcp_f32_e32 v92, v92
	v_and_b32_e32 v64, 0xffff0000, v98
	v_mul_f32_e32 v1, v65, v1
	v_mul_f32_e32 v1, v54, v1
	v_mul_f32_e32 v54, v92, v61
	v_mul_f32_e32 v61, 0xbfb8aa3b, v58
	v_mul_f32_e32 v65, 0xbfb8aa3b, v64
	v_exp_f32_e32 v61, v61
	v_exp_f32_e32 v65, v65
	v_lshlrev_b32_e32 v59, 16, v97
	v_mul_f32_e32 v54, v50, v54
	v_add_f32_e32 v50, 1.0, v61
	v_add_f32_e32 v61, 1.0, v65
	v_mul_f32_e32 v65, 0xbfb8aa3b, v59
	v_rcp_f32_e32 v50, v50
	v_exp_f32_e32 v65, v65
	v_rcp_f32_e32 v61, v61
	v_lshlrev_b32_e32 v93, 16, v99
	v_mul_f32_e32 v50, v50, v58
	v_add_f32_e32 v58, 1.0, v65
	v_rcp_f32_e32 v58, v58
	v_and_b32_e32 v60, 0xffff0000, v97
	v_mul_f32_e32 v50, v55, v50
	v_mul_f32_e32 v55, v61, v64
	v_mul_f32_e32 v61, 0xbfb8aa3b, v93
	v_and_b32_e32 v94, 0xffff0000, v99
	v_exp_f32_e32 v61, v61
	v_mul_f32_e32 v55, v51, v55
	v_mul_f32_e32 v51, v58, v59
	v_mul_f32_e32 v58, 0xbfb8aa3b, v60
	v_exp_f32_e32 v58, v58
	v_mul_f32_e32 v59, 0xbfb8aa3b, v94
	v_exp_f32_e32 v59, v59
	v_mul_f32_e32 v51, v56, v51
	v_add_f32_e32 v56, 1.0, v61
	v_rcp_f32_e32 v56, v56
	v_add_f32_e32 v58, 1.0, v58
	v_rcp_f32_e32 v58, v58
	v_add_f32_e32 v59, 1.0, v59
	v_rcp_f32_e32 v59, v59
	v_mul_f32_e32 v56, v56, v93
	v_mul_f32_e32 v56, v52, v56
	v_mul_f32_e32 v52, v58, v60
	v_mul_f32_e32 v52, v57, v52
	v_mul_f32_e32 v57, v59, v94
	v_mul_f32_e32 v53, v53, v57
	v_cvt_pk_bf16_f32 v50, v1, v50
	v_cvt_pk_bf16_f32 v51, v51, v52
	v_cvt_pk_bf16_f32 v52, v54, v55
	v_cvt_pk_bf16_f32 v53, v56, v53
	s_waitcnt vmcnt(0)
; __device__ __forceinline__ float siluf_(float x) { return x * __builtin_amdgcn_rcpf(1.0f + __expf(-x)); }
; __device__ __forceinline__ u32x4 pack8(const float (&f)[8]) { u32x4 r; r[0] = cvt_pk_bf16(f[0], f[1]); r[1] = cvt_pk_bf16(f[2], f[3]); r[2] = cvt_pk_bf16(f[4], f[5]); r[3] = cvt_pk_bf16(f[6], f[7]); return r; }
;     __device__ __forceinline__ void operator()(EPI_ARGS) const {
;     ...
;                 for (int bj = 0; bj < 2; ++bj) zz[m][bj] = *(const u32x4*)(parts + E_PZC + (size_t)EPI_ROW * 1024 + EPI_COL(bj));
; #pragma unroll
;             for (int m = 0; m < 4; ++m)
; #pragma unroll
;                 for (int bj = 0; bj < 2; ++bj) { const f32x4 v0 = acc[ai][bj][m][0], v1 = acc[ai][bj][m][1]; float z[8]; unpack8(zz[m][bj], z); float o[8];
; #pragma unroll
;                     for (int j = 0; j < 4; ++j) { o[j] = v0[j] * siluf_(z[j]); o[4 + j] = v1[j] * siluf_(z[4 + j]); }
;                     *(u32x4*)(O + (size_t)EPI_ROW * 1024 + EPI_COL(bj)) = pack8(o); } }
	v_lshlrev_b32_e32 v1, 16, v100
	global_store_dwordx4 v[62:63], v[50:53], off offset:256
	v_mul_f32_e32 v55, 0xbfb8aa3b, v1
	v_exp_f32_e32 v55, v55
	v_lshlrev_b32_e32 v53, 16, v102
	v_mul_f32_e32 v56, 0xbfb8aa3b, v53
	v_exp_f32_e32 v56, v56
	v_add_f32_e32 v55, 1.0, v55
	v_rcp_f32_e32 v55, v55
	v_and_b32_e32 v50, 0xffff0000, v100
	v_add_f32_e32 v56, 1.0, v56
	v_rcp_f32_e32 v56, v56
	v_and_b32_e32 v54, 0xffff0000, v102
	v_mul_f32_e32 v1, v55, v1
	v_mul_f32_e32 v1, v46, v1
	v_mul_f32_e32 v46, v56, v53
	v_mul_f32_e32 v53, 0xbfb8aa3b, v50
	v_mul_f32_e32 v55, 0xbfb8aa3b, v54
	v_exp_f32_e32 v53, v53
	v_exp_f32_e32 v55, v55
	v_lshlrev_b32_e32 v51, 16, v101
	v_mul_f32_e32 v46, v42, v46
	v_add_f32_e32 v42, 1.0, v53
	v_add_f32_e32 v53, 1.0, v55
	v_mul_f32_e32 v55, 0xbfb8aa3b, v51
	v_rcp_f32_e32 v42, v42
	v_exp_f32_e32 v55, v55
	v_rcp_f32_e32 v53, v53
	v_lshlrev_b32_e32 v57, 16, v103
	v_mul_f32_e32 v42, v42, v50
	v_add_f32_e32 v50, 1.0, v55
	v_rcp_f32_e32 v50, v50
	v_and_b32_e32 v52, 0xffff0000, v101
	v_mul_f32_e32 v42, v47, v42
	v_mul_f32_e32 v47, v53, v54
	v_mul_f32_e32 v53, 0xbfb8aa3b, v57
	v_and_b32_e32 v58, 0xffff0000, v103
	v_exp_f32_e32 v53, v53
	v_mul_f32_e32 v47, v43, v47
	v_mul_f32_e32 v43, v50, v51
	v_mul_f32_e32 v50, 0xbfb8aa3b, v52
	v_exp_f32_e32 v50, v50
	v_mul_f32_e32 v51, 0xbfb8aa3b, v58
	v_exp_f32_e32 v51, v51
	v_mul_f32_e32 v43, v48, v43
	v_add_f32_e32 v48, 1.0, v53
	v_rcp_f32_e32 v48, v48
	v_add_f32_e32 v50, 1.0, v50
	v_rcp_f32_e32 v50, v50
	v_add_f32_e32 v51, 1.0, v51
	v_rcp_f32_e32 v51, v51
	v_mul_f32_e32 v48, v48, v57
	v_mul_f32_e32 v48, v44, v48
	v_mul_f32_e32 v44, v50, v52
	v_mul_f32_e32 v44, v49, v44
	v_mul_f32_e32 v49, v51, v58
	v_mul_f32_e32 v45, v45, v49
	v_cvt_pk_bf16_f32 v42, v1, v42
	v_cvt_pk_bf16_f32 v43, v43, v44
	v_cvt_pk_bf16_f32 v44, v46, v47
	v_lshl_add_u64 v[46:47], s[4:5], 0, v[90:91]
	v_cvt_pk_bf16_f32 v45, v48, v45
	v_lshl_add_u64 v[46:47], v[46:47], 0, v[150:151]
	v_lshlrev_b32_e32 v1, 16, v82
	global_store_dwordx4 v[46:47], v[42:45], off
	v_mul_f32_e32 v49, 0xbfb8aa3b, v1
	v_exp_f32_e32 v49, v49
	v_lshlrev_b32_e32 v45, 16, v84
	v_mul_f32_e32 v50, 0xbfb8aa3b, v45
	v_exp_f32_e32 v50, v50
	v_add_f32_e32 v49, 1.0, v49
	v_rcp_f32_e32 v49, v49
	v_and_b32_e32 v42, 0xffff0000, v82
	v_add_f32_e32 v50, 1.0, v50
	v_rcp_f32_e32 v50, v50
	v_and_b32_e32 v48, 0xffff0000, v84
	v_mul_f32_e32 v1, v49, v1
	v_mul_f32_e32 v1, v38, v1
	v_mul_f32_e32 v38, v50, v45
	v_mul_f32_e32 v45, 0xbfb8aa3b, v42
	v_mul_f32_e32 v49, 0xbfb8aa3b, v48
	v_exp_f32_e32 v45, v45
	v_exp_f32_e32 v49, v49
	v_lshlrev_b32_e32 v43, 16, v83
	v_mul_f32_e32 v38, v34, v38
	v_add_f32_e32 v34, 1.0, v45
	v_add_f32_e32 v45, 1.0, v49
	v_mul_f32_e32 v49, 0xbfb8aa3b, v43
	v_rcp_f32_e32 v34, v34
	v_exp_f32_e32 v49, v49
	v_rcp_f32_e32 v45, v45
	v_lshlrev_b32_e32 v51, 16, v85
	v_mul_f32_e32 v34, v34, v42
	v_add_f32_e32 v42, 1.0, v49
	v_rcp_f32_e32 v42, v42
	v_and_b32_e32 v44, 0xffff0000, v83
	v_mul_f32_e32 v34, v39, v34
	v_mul_f32_e32 v39, v45, v48
	v_mul_f32_e32 v45, 0xbfb8aa3b, v51
	v_and_b32_e32 v52, 0xffff0000, v85
	v_exp_f32_e32 v45, v45
	v_mul_f32_e32 v39, v35, v39
	v_mul_f32_e32 v35, v42, v43
	v_mul_f32_e32 v42, 0xbfb8aa3b, v44
	v_exp_f32_e32 v42, v42
	v_mul_f32_e32 v43, 0xbfb8aa3b, v52
	v_exp_f32_e32 v43, v43
	v_mul_f32_e32 v35, v40, v35
	v_add_f32_e32 v40, 1.0, v45
	v_rcp_f32_e32 v40, v40
	v_add_f32_e32 v42, 1.0, v42
	v_rcp_f32_e32 v42, v42
	v_add_f32_e32 v43, 1.0, v43
	v_rcp_f32_e32 v43, v43
	v_mul_f32_e32 v40, v40, v51
	v_mul_f32_e32 v40, v36, v40
	v_mul_f32_e32 v36, v42, v44
	v_mul_f32_e32 v36, v41, v36
	v_mul_f32_e32 v41, v43, v52
	v_mul_f32_e32 v37, v37, v41
	v_cvt_pk_bf16_f32 v34, v1, v34
	v_cvt_pk_bf16_f32 v35, v35, v36
	v_cvt_pk_bf16_f32 v36, v38, v39
	v_cvt_pk_bf16_f32 v37, v40, v37
	v_lshlrev_b32_e32 v1, 16, v78
	global_store_dwordx4 v[46:47], v[34:37], off offset:256
	v_mul_f32_e32 v39, 0xbfb8aa3b, v1
	v_exp_f32_e32 v39, v39
	v_lshlrev_b32_e32 v37, 16, v80
	v_mul_f32_e32 v40, 0xbfb8aa3b, v37
	v_exp_f32_e32 v40, v40
	v_add_f32_e32 v39, 1.0, v39
	v_rcp_f32_e32 v39, v39
	v_and_b32_e32 v34, 0xffff0000, v78
	v_add_f32_e32 v40, 1.0, v40
	v_rcp_f32_e32 v40, v40
	v_and_b32_e32 v38, 0xffff0000, v80
	v_mul_f32_e32 v1, v39, v1
	v_mul_f32_e32 v1, v30, v1
	v_mul_f32_e32 v30, v40, v37
	v_mul_f32_e32 v37, 0xbfb8aa3b, v34
	v_mul_f32_e32 v39, 0xbfb8aa3b, v38
	v_exp_f32_e32 v37, v37
	v_exp_f32_e32 v39, v39
	v_lshlrev_b32_e32 v35, 16, v79
	v_mul_f32_e32 v30, v26, v30
	v_add_f32_e32 v26, 1.0, v37
	v_add_f32_e32 v37, 1.0, v39
	v_mul_f32_e32 v39, 0xbfb8aa3b, v35
	v_rcp_f32_e32 v26, v26
	v_exp_f32_e32 v39, v39
	v_rcp_f32_e32 v37, v37
	v_lshlrev_b32_e32 v41, 16, v81
	v_mul_f32_e32 v26, v26, v34
	v_add_f32_e32 v34, 1.0, v39
	v_rcp_f32_e32 v34, v34
	v_and_b32_e32 v36, 0xffff0000, v79
	v_mul_f32_e32 v26, v31, v26
	v_mul_f32_e32 v31, v37, v38
	v_mul_f32_e32 v37, 0xbfb8aa3b, v41
	v_and_b32_e32 v42, 0xffff0000, v81
	v_exp_f32_e32 v37, v37
	v_mul_f32_e32 v31, v27, v31
	v_mul_f32_e32 v27, v34, v35
	v_mul_f32_e32 v34, 0xbfb8aa3b, v36
	v_exp_f32_e32 v34, v34
	v_mul_f32_e32 v35, 0xbfb8aa3b, v42
	v_exp_f32_e32 v35, v35
	v_mul_f32_e32 v27, v32, v27
	v_add_f32_e32 v32, 1.0, v37
	v_rcp_f32_e32 v32, v32
	v_add_f32_e32 v34, 1.0, v34
	v_rcp_f32_e32 v34, v34
	v_add_f32_e32 v35, 1.0, v35
	v_rcp_f32_e32 v35, v35
	v_mul_f32_e32 v32, v32, v41
	v_mul_f32_e32 v32, v28, v32
	v_mul_f32_e32 v28, v34, v36
	v_mul_f32_e32 v28, v33, v28
	v_mul_f32_e32 v33, v35, v42
	v_mul_f32_e32 v29, v29, v33
	v_cvt_pk_bf16_f32 v26, v1, v26
	v_cvt_pk_bf16_f32 v27, v27, v28
	v_cvt_pk_bf16_f32 v28, v30, v31
	v_lshl_add_u64 v[30:31], s[4:5], 0, v[88:89]
	v_cvt_pk_bf16_f32 v29, v32, v29
; __device__ __forceinline__ float siluf_(float x) { return x * __builtin_amdgcn_rcpf(1.0f + __expf(-x)); }
; __device__ __forceinline__ u32x4 pack8(const float (&f)[8]) { u32x4 r; r[0] = cvt_pk_bf16(f[0], f[1]); r[1] = cvt_pk_bf16(f[2], f[3]); r[2] = cvt_pk_bf16(f[4], f[5]); r[3] = cvt_pk_bf16(f[6], f[7]); return r; }
; #define PG8_WAIT_V(n) asm volatile("s_waitcnt vmcnt(" #n ")" ::: "memory")
; #define PG8_BAR __builtin_amdgcn_s_barrier()
; template <class Sched, class Epi>
; __device__ __forceinline__ void gemm_phase(LAS unsigned char* lds, const Sched& S, const Epi& E, const int K, const int lda, const int ldb) {
;     ...
;     PG8_WAIT_V(0);
;     if (wr == 0) PG8_BAR;
;     PG8_BAR;
;     __device__ __forceinline__ void operator()(EPI_ARGS) const {
;     ...
;                 for (int bj = 0; bj < 2; ++bj) { const f32x4 v0 = acc[ai][bj][m][0], v1 = acc[ai][bj][m][1]; float z[8]; unpack8(zz[m][bj], z); float o[8];
; #pragma unroll
;                     for (int j = 0; j < 4; ++j) { o[j] = v0[j] * siluf_(z[j]); o[4 + j] = v1[j] * siluf_(z[4 + j]); }
;                     *(u32x4*)(O + (size_t)EPI_ROW * 1024 + EPI_COL(bj)) = pack8(o); } }
	v_lshl_add_u64 v[30:31], v[30:31], 0, v[150:151]
	v_lshlrev_b32_e32 v1, 16, v74
	global_store_dwordx4 v[30:31], v[26:29], off
	v_mul_f32_e32 v33, 0xbfb8aa3b, v1
	v_exp_f32_e32 v33, v33
	v_lshlrev_b32_e32 v29, 16, v76
	v_mul_f32_e32 v34, 0xbfb8aa3b, v29
	v_exp_f32_e32 v34, v34
	v_add_f32_e32 v33, 1.0, v33
	v_rcp_f32_e32 v33, v33
	v_and_b32_e32 v26, 0xffff0000, v74
	v_add_f32_e32 v34, 1.0, v34
	v_rcp_f32_e32 v34, v34
	v_and_b32_e32 v32, 0xffff0000, v76
	v_mul_f32_e32 v1, v33, v1
	v_mul_f32_e32 v1, v22, v1
	v_mul_f32_e32 v22, v34, v29
	v_mul_f32_e32 v29, 0xbfb8aa3b, v26
	v_mul_f32_e32 v33, 0xbfb8aa3b, v32
	v_exp_f32_e32 v29, v29
	v_exp_f32_e32 v33, v33
	v_lshlrev_b32_e32 v27, 16, v75
	v_mul_f32_e32 v22, v18, v22
	v_add_f32_e32 v18, 1.0, v29
	v_add_f32_e32 v29, 1.0, v33
	v_mul_f32_e32 v33, 0xbfb8aa3b, v27
	v_rcp_f32_e32 v18, v18
	v_exp_f32_e32 v33, v33
	v_rcp_f32_e32 v29, v29
	v_lshlrev_b32_e32 v35, 16, v77
	v_mul_f32_e32 v18, v18, v26
	v_add_f32_e32 v26, 1.0, v33
	v_rcp_f32_e32 v26, v26
	v_and_b32_e32 v28, 0xffff0000, v75
	v_mul_f32_e32 v18, v23, v18
	v_mul_f32_e32 v23, v29, v32
	v_mul_f32_e32 v29, 0xbfb8aa3b, v35
	v_and_b32_e32 v36, 0xffff0000, v77
	v_exp_f32_e32 v29, v29
	v_mul_f32_e32 v23, v19, v23
	v_mul_f32_e32 v19, v26, v27
	v_mul_f32_e32 v26, 0xbfb8aa3b, v28
	v_exp_f32_e32 v26, v26
	v_mul_f32_e32 v27, 0xbfb8aa3b, v36
	v_exp_f32_e32 v27, v27
	v_mul_f32_e32 v19, v24, v19
	v_add_f32_e32 v24, 1.0, v29
	v_rcp_f32_e32 v24, v24
	v_add_f32_e32 v26, 1.0, v26
	v_rcp_f32_e32 v26, v26
	v_add_f32_e32 v27, 1.0, v27
	v_rcp_f32_e32 v27, v27
	v_mul_f32_e32 v24, v24, v35
	v_mul_f32_e32 v24, v20, v24
	v_mul_f32_e32 v20, v26, v28
	v_mul_f32_e32 v20, v25, v20
	v_mul_f32_e32 v25, v27, v36
	v_mul_f32_e32 v21, v21, v25
	v_cvt_pk_bf16_f32 v18, v1, v18
	v_cvt_pk_bf16_f32 v19, v19, v20
	v_cvt_pk_bf16_f32 v20, v22, v23
	v_cvt_pk_bf16_f32 v21, v24, v21
	v_lshlrev_b32_e32 v1, 16, v70
	global_store_dwordx4 v[30:31], v[18:21], off offset:256
	v_mul_f32_e32 v23, 0xbfb8aa3b, v1
	v_exp_f32_e32 v23, v23
	v_lshlrev_b32_e32 v21, 16, v72
	v_mul_f32_e32 v24, 0xbfb8aa3b, v21
	v_exp_f32_e32 v24, v24
	v_add_f32_e32 v23, 1.0, v23
	v_rcp_f32_e32 v23, v23
	v_and_b32_e32 v18, 0xffff0000, v70
	v_add_f32_e32 v24, 1.0, v24
	v_rcp_f32_e32 v24, v24
	v_and_b32_e32 v22, 0xffff0000, v72
	v_mul_f32_e32 v1, v23, v1
	v_mul_f32_e32 v1, v14, v1
	v_mul_f32_e32 v14, v24, v21
	v_mul_f32_e32 v21, 0xbfb8aa3b, v18
	v_mul_f32_e32 v23, 0xbfb8aa3b, v22
	v_exp_f32_e32 v21, v21
	v_exp_f32_e32 v23, v23
	v_lshlrev_b32_e32 v19, 16, v71
	v_mul_f32_e32 v14, v10, v14
	v_add_f32_e32 v10, 1.0, v21
	v_add_f32_e32 v21, 1.0, v23
	v_mul_f32_e32 v23, 0xbfb8aa3b, v19
	v_rcp_f32_e32 v10, v10
	v_exp_f32_e32 v23, v23
	v_rcp_f32_e32 v21, v21
	v_lshlrev_b32_e32 v25, 16, v73
	v_mul_f32_e32 v10, v10, v18
	v_add_f32_e32 v18, 1.0, v23
	v_rcp_f32_e32 v18, v18
	v_and_b32_e32 v20, 0xffff0000, v71
	v_mul_f32_e32 v10, v15, v10
	v_mul_f32_e32 v15, v21, v22
	v_mul_f32_e32 v21, 0xbfb8aa3b, v25
	v_and_b32_e32 v26, 0xffff0000, v73
	v_exp_f32_e32 v21, v21
	v_mul_f32_e32 v15, v11, v15
	v_mul_f32_e32 v11, v18, v19
	v_mul_f32_e32 v18, 0xbfb8aa3b, v20
	v_exp_f32_e32 v18, v18
	v_mul_f32_e32 v19, 0xbfb8aa3b, v26
	v_exp_f32_e32 v19, v19
	v_mul_f32_e32 v11, v16, v11
	v_add_f32_e32 v16, 1.0, v21
	v_rcp_f32_e32 v16, v16
	v_add_f32_e32 v18, 1.0, v18
	v_rcp_f32_e32 v18, v18
	v_add_f32_e32 v19, 1.0, v19
	v_rcp_f32_e32 v19, v19
	v_mul_f32_e32 v16, v16, v25
	v_mul_f32_e32 v16, v12, v16
	v_mul_f32_e32 v12, v18, v20
	v_mul_f32_e32 v12, v17, v12
	v_mul_f32_e32 v17, v19, v26
	v_mul_f32_e32 v13, v13, v17
	v_cvt_pk_bf16_f32 v10, v1, v10
	v_cvt_pk_bf16_f32 v11, v11, v12
	v_cvt_pk_bf16_f32 v12, v14, v15
	v_lshl_add_u64 v[14:15], s[4:5], 0, v[86:87]
	v_cvt_pk_bf16_f32 v13, v16, v13
	v_lshl_add_u64 v[14:15], v[14:15], 0, v[150:151]
	v_lshlrev_b32_e32 v1, 16, v66
	global_store_dwordx4 v[14:15], v[10:13], off
	v_mul_f32_e32 v17, 0xbfb8aa3b, v1
	v_exp_f32_e32 v17, v17
	v_lshlrev_b32_e32 v13, 16, v68
	v_mul_f32_e32 v18, 0xbfb8aa3b, v13
	v_exp_f32_e32 v18, v18
	v_add_f32_e32 v17, 1.0, v17
	v_rcp_f32_e32 v17, v17
	v_and_b32_e32 v10, 0xffff0000, v66
	v_add_f32_e32 v18, 1.0, v18
	v_rcp_f32_e32 v18, v18
	v_and_b32_e32 v16, 0xffff0000, v68
	v_mul_f32_e32 v1, v17, v1
	v_mul_f32_e32 v1, v6, v1
	v_mul_f32_e32 v6, v18, v13
	v_mul_f32_e32 v13, 0xbfb8aa3b, v10
	v_mul_f32_e32 v17, 0xbfb8aa3b, v16
	v_exp_f32_e32 v13, v13
	v_exp_f32_e32 v17, v17
	v_lshlrev_b32_e32 v11, 16, v67
	v_mul_f32_e32 v6, v2, v6
	v_add_f32_e32 v2, 1.0, v13
	v_add_f32_e32 v13, 1.0, v17
	v_mul_f32_e32 v17, 0xbfb8aa3b, v11
	v_rcp_f32_e32 v2, v2
	v_exp_f32_e32 v17, v17
	v_rcp_f32_e32 v13, v13
	v_lshlrev_b32_e32 v19, 16, v69
	v_mul_f32_e32 v2, v2, v10
	v_add_f32_e32 v10, 1.0, v17
	v_rcp_f32_e32 v10, v10
	v_and_b32_e32 v12, 0xffff0000, v67
	v_mul_f32_e32 v2, v7, v2
	v_mul_f32_e32 v7, v13, v16
	v_mul_f32_e32 v13, 0xbfb8aa3b, v19
	v_and_b32_e32 v20, 0xffff0000, v69
	v_exp_f32_e32 v13, v13
	v_mul_f32_e32 v7, v3, v7
	v_mul_f32_e32 v3, v10, v11
	v_mul_f32_e32 v10, 0xbfb8aa3b, v12
	v_exp_f32_e32 v10, v10
	v_mul_f32_e32 v11, 0xbfb8aa3b, v20
	v_exp_f32_e32 v11, v11
	v_mul_f32_e32 v3, v8, v3
	v_add_f32_e32 v8, 1.0, v13
	v_rcp_f32_e32 v8, v8
	v_add_f32_e32 v10, 1.0, v10
	v_rcp_f32_e32 v10, v10
	v_add_f32_e32 v11, 1.0, v11
	v_rcp_f32_e32 v11, v11
	v_mul_f32_e32 v8, v8, v19
	v_mul_f32_e32 v8, v4, v8
	v_mul_f32_e32 v4, v10, v12
	v_mul_f32_e32 v4, v9, v4
	v_mul_f32_e32 v9, v11, v20
	v_mul_f32_e32 v5, v5, v9
	v_cvt_pk_bf16_f32 v2, v1, v2
	v_cvt_pk_bf16_f32 v3, v3, v4
	v_cvt_pk_bf16_f32 v4, v6, v7
	v_cvt_pk_bf16_f32 v5, v8, v5
	global_store_dwordx4 v[14:15], v[2:5], off offset:256
	s_waitcnt vmcnt(0)
	s_cbranch_scc0 .LBB0_739
	s_barrier

; #define PG8_STAGE(bufoff, gbase, voff) do { _Pragma("unroll") for (int _i = 0; _i < 2; ++_i) \
;         __builtin_amdgcn_global_load_lds((const unsigned*)((const char*)(gbase) + (voff)[_i]), (LAS unsigned*)(lds + (bufoff) + ldsw + _i * 8192), 16, 0, 0); } while (0)
; #define PG8_LDA(dst, b, h) do { _Pragma("unroll") for (int m = 0; m < 4; ++m) _Pragma("unroll") for (int k = 0; k < 2; ++k) dst[m][k] = *(const LAS bf16x8*)(lds + PG8_SA(b, h) + aoff + m * 2048 + k * 1024); } while (0)
; #define PG8_LDB(dst, b, h) do { _Pragma("unroll") for (int n = 0; n < 2; ++n) _Pragma("unroll") for (int k = 0; k < 2; ++k) dst[n][k] = *(const LAS bf16x8*)(lds + PG8_SB(b, h) + boff + n * 2048 + k * 1024); } while (0)
; #define PG8_MMA(ai, bj, At, Bt) do { __builtin_amdgcn_s_setprio(1); _Pragma("unroll") for (int m = 0; m < 4; ++m) _Pragma("unroll") for (int n = 0; n < 2; ++n) _Pragma("unroll") for (int k = 0; k < 2; ++k) \
;         acc[ai][bj][m][n] = __builtin_amdgcn_mfma_f32_16x16x32_bf16(Bt[n][k], At[m][k], acc[ai][bj][m][n], 0, 0, 0); __builtin_amdgcn_s_setprio(0); } while (0)
; #define PG8_WAIT_V(n) asm volatile("s_waitcnt vmcnt(" #n ")" ::: "memory")
; #define PG8_WAIT_L(n) asm volatile("s_waitcnt lgkmcnt(" #n ")" ::: "memory")
; #define PG8_BAR __builtin_amdgcn_s_barrier()
; #define PG8_SCHED __builtin_amdgcn_sched_barrier(0)
; template <class Sched, class Epi>
; __device__ __forceinline__ void gemm_phase(LAS unsigned char* lds, const Sched& S, const Epi& E, const int K, const int lda, const int ldb) {
;     ...
;             PG8_LDB(B0, 0, 0); PG8_SCHED; PG8_LDA(At, 0, 0); PG8_STAGE(PG8_SA(1, 1), a1 + hstepA, voffA);
;             PG8_WAIT_L(8); PG8_BAR; PG8_WAIT_L(0); PG8_MMA(0, 0, At, B0); PG8_BAR; PG8_SCHED;
;             PG8_LDB(B1, 0, 1); PG8_STAGE(PG8_SB(0, 0), b2, voffB);
;             PG8_BAR; PG8_WAIT_L(0); PG8_MMA(0, 1, At, B1); PG8_BAR;
;             PG8_LDA(At, 0, 1); PG8_STAGE(PG8_SA(0, 0), a2, voffA);
;             PG8_BAR; PG8_WAIT_L(0); if (!chalf) PG8_MMA(1, 0, At, B0); PG8_BAR; PG8_SCHED;
;             PG8_STAGE(PG8_SB(0, 1), b2 + hstepB, voffB);
;             PG8_WAIT_V(6); PG8_BAR; if (!chalf) PG8_MMA(1, 1, At, B1); PG8_BAR;
.LBB0_761:
	ds_read_b128 v[144:147], v155
	ds_read_b128 v[158:161], v155 offset:1024
	ds_read_b128 v[162:165], v155 offset:2048
	ds_read_b128 v[166:169], v155 offset:3072
	s_add_u32 s34, s28, 0xfffc0080
	s_addc_u32 s35, s29, -1
	s_cmp_eq_u32 s49, 12
	s_cselect_b32 s37, s25, s35
	s_cselect_b32 s36, s24, s34
	s_cselect_b32 s35, s27, s17
	s_cselect_b32 s34, s26, s15
	s_add_i32 m0, s23, 0xc000
	ds_read_b128 v[170:173], v156
	ds_read_b128 v[174:177], v156 offset:1024
	ds_read_b128 v[178:181], v156 offset:2048
	ds_read_b128 v[182:185], v156 offset:3072
	ds_read_b128 v[186:189], v156 offset:4096
	ds_read_b128 v[190:193], v156 offset:5120
	ds_read_b128 v[194:197], v156 offset:6144
	ds_read_b128 v[198:201], v156 offset:7168
	global_load_lds_dwordx4 v140, s[28:29]
	s_add_i32 m0, s23, 0xe000
	s_nop 0
	global_load_lds_dwordx4 v138, s[28:29]
	s_waitcnt lgkmcnt(8)
	s_barrier
	s_waitcnt lgkmcnt(0)
	s_setprio 1
	s_waitcnt lgkmcnt(0)
	v_mfma_f32_16x16x32_bf16 v[118:121], v[144:147], v[170:173], v[118:121]
	v_mfma_f32_16x16x32_bf16 v[114:117], v[162:165], v[170:173], v[114:117]
	v_mfma_f32_16x16x32_bf16 v[110:113], v[144:147], v[178:181], v[110:113]
	v_mfma_f32_16x16x32_bf16 v[106:109], v[162:165], v[178:181], v[106:109]
	v_mfma_f32_16x16x32_bf16 v[94:97], v[144:147], v[186:189], v[94:97]
	v_mfma_f32_16x16x32_bf16 v[90:93], v[162:165], v[186:189], v[90:93]
	v_mfma_f32_16x16x32_bf16 v[78:81], v[144:147], v[194:197], v[78:81]
	v_mfma_f32_16x16x32_bf16 v[74:77], v[162:165], v[194:197], v[74:77]
	v_mfma_f32_16x16x32_bf16 v[118:121], v[158:161], v[174:177], v[118:121]
	v_mfma_f32_16x16x32_bf16 v[114:117], v[166:169], v[174:177], v[114:117]
	v_mfma_f32_16x16x32_bf16 v[110:113], v[158:161], v[182:185], v[110:113]
	v_mfma_f32_16x16x32_bf16 v[106:109], v[166:169], v[182:185], v[106:109]
	v_mfma_f32_16x16x32_bf16 v[94:97], v[158:161], v[190:193], v[94:97]
	v_mfma_f32_16x16x32_bf16 v[90:93], v[166:169], v[190:193], v[90:93]
	v_mfma_f32_16x16x32_bf16 v[78:81], v[158:161], v[198:201], v[78:81]
	v_mfma_f32_16x16x32_bf16 v[74:77], v[166:169], v[198:201], v[74:77]
	s_setprio 0
	s_barrier
	s_add_i32 s50, s46, s38
	v_lshl_add_u64 v[148:149], s[34:35], 0, v[132:133]
	s_mov_b32 m0, s50
	ds_read_b128 v[202:205], v157
	ds_read_b128 v[206:209], v157 offset:1024
	ds_read_b128 v[210:213], v157 offset:2048
	ds_read_b128 v[214:217], v157 offset:3072
	global_load_lds_dwordx4 v[148:149], off
	v_lshl_add_u64 v[218:219], s[34:35], 0, v[136:137]
	s_add_i32 m0, s50, 0x2000
	s_nop 0
	global_load_lds_dwordx4 v[218:219], off
	s_barrier
	s_waitcnt lgkmcnt(0)
	s_setprio 1
	s_waitcnt lgkmcnt(0)
	v_mfma_f32_16x16x32_bf16 v[126:129], v[202:205], v[170:173], v[126:129]
	v_mfma_f32_16x16x32_bf16 v[122:125], v[210:213], v[170:173], v[122:125]
	v_mfma_f32_16x16x32_bf16 v[102:105], v[202:205], v[178:181], v[102:105]
	v_mfma_f32_16x16x32_bf16 v[98:101], v[210:213], v[178:181], v[98:101]
	v_mfma_f32_16x16x32_bf16 v[86:89], v[202:205], v[186:189], v[86:89]
	v_mfma_f32_16x16x32_bf16 v[82:85], v[210:213], v[186:189], v[82:85]
	v_mfma_f32_16x16x32_bf16 v[70:73], v[202:205], v[194:197], v[70:73]
	v_mfma_f32_16x16x32_bf16 v[66:69], v[210:213], v[194:197], v[66:69]
	v_mfma_f32_16x16x32_bf16 v[126:129], v[206:209], v[174:177], v[126:129]
	v_mfma_f32_16x16x32_bf16 v[122:125], v[214:217], v[174:177], v[122:125]
	v_mfma_f32_16x16x32_bf16 v[102:105], v[206:209], v[182:185], v[102:105]
	v_mfma_f32_16x16x32_bf16 v[98:101], v[214:217], v[182:185], v[98:101]
	v_mfma_f32_16x16x32_bf16 v[86:89], v[206:209], v[190:193], v[86:89]
	v_mfma_f32_16x16x32_bf16 v[82:85], v[214:217], v[190:193], v[82:85]
	v_mfma_f32_16x16x32_bf16 v[70:73], v[206:209], v[198:201], v[70:73]
	v_mfma_f32_16x16x32_bf16 v[66:69], v[214:217], v[198:201], v[66:69]
	s_setprio 0
	s_mov_b32 m0, s23
	v_lshl_add_u64 v[220:221], s[36:37], 0, v[130:131]
	s_barrier
	ds_read_b128 v[170:173], v156 offset:16384
	ds_read_b128 v[174:177], v156 offset:17408
	ds_read_b128 v[178:181], v156 offset:18432
	ds_read_b128 v[182:185], v156 offset:19456
	ds_read_b128 v[186:189], v156 offset:20480
	ds_read_b128 v[190:193], v156 offset:21504
	ds_read_b128 v[194:197], v156 offset:22528
	ds_read_b128 v[198:201], v156 offset:23552
	global_load_lds_dwordx4 v[220:221], off
	v_lshl_add_u64 v[222:223], s[36:37], 0, v[134:135]
	s_mov_b32 m0, s39
	s_nop 0
	global_load_lds_dwordx4 v[222:223], off
	s_barrier
	s_waitcnt lgkmcnt(0)
	s_setprio 1
	s_waitcnt lgkmcnt(0)
	v_mfma_f32_16x16x32_bf16 v[62:65], v[144:147], v[170:173], v[62:65]
	v_mfma_f32_16x16x32_bf16 v[58:61], v[162:165], v[170:173], v[58:61]
	v_mfma_f32_16x16x32_bf16 v[46:49], v[144:147], v[178:181], v[46:49]
	v_mfma_f32_16x16x32_bf16 v[42:45], v[162:165], v[178:181], v[42:45]
	v_mfma_f32_16x16x32_bf16 v[30:33], v[144:147], v[186:189], v[30:33]
	v_mfma_f32_16x16x32_bf16 v[26:29], v[162:165], v[186:189], v[26:29]
	v_mfma_f32_16x16x32_bf16 v[14:17], v[144:147], v[194:197], v[14:17]
	v_mfma_f32_16x16x32_bf16 v[10:13], v[162:165], v[194:197], v[10:13]
	v_mfma_f32_16x16x32_bf16 v[62:65], v[158:161], v[174:177], v[62:65]
	v_mfma_f32_16x16x32_bf16 v[58:61], v[166:169], v[174:177], v[58:61]
	v_mfma_f32_16x16x32_bf16 v[46:49], v[158:161], v[182:185], v[46:49]
	v_mfma_f32_16x16x32_bf16 v[42:45], v[166:169], v[182:185], v[42:45]
	v_mfma_f32_16x16x32_bf16 v[30:33], v[158:161], v[190:193], v[30:33]
	v_mfma_f32_16x16x32_bf16 v[26:29], v[166:169], v[190:193], v[26:29]
	v_mfma_f32_16x16x32_bf16 v[14:17], v[158:161], v[198:201], v[14:17]
	v_mfma_f32_16x16x32_bf16 v[10:13], v[166:169], v[198:201], v[10:13]
	s_setprio 0
	s_barrier
; #define PG8_STAGE(bufoff, gbase, voff) do { _Pragma("unroll") for (int _i = 0; _i < 2; ++_i) \
;         __builtin_amdgcn_global_load_lds((const unsigned*)((const char*)(gbase) + (voff)[_i]), (LAS unsigned*)(lds + (bufoff) + ldsw + _i * 8192), 16, 0, 0); } while (0)
; #define PG8_LDA(dst, b, h) do { _Pragma("unroll") for (int m = 0; m < 4; ++m) _Pragma("unroll") for (int k = 0; k < 2; ++k) dst[m][k] = *(const LAS bf16x8*)(lds + PG8_SA(b, h) + aoff + m * 2048 + k * 1024); } while (0)
; #define PG8_LDB(dst, b, h) do { _Pragma("unroll") for (int n = 0; n < 2; ++n) _Pragma("unroll") for (int k = 0; k < 2; ++k) dst[n][k] = *(const LAS bf16x8*)(lds + PG8_SB(b, h) + boff + n * 2048 + k * 1024); } while (0)
; #define PG8_MMA(ai, bj, At, Bt) do { __builtin_amdgcn_s_setprio(1); _Pragma("unroll") for (int m = 0; m < 4; ++m) _Pragma("unroll") for (int n = 0; n < 2; ++n) _Pragma("unroll") for (int k = 0; k < 2; ++k) \
;         acc[ai][bj][m][n] = __builtin_amdgcn_mfma_f32_16x16x32_bf16(Bt[n][k], At[m][k], acc[ai][bj][m][n], 0, 0, 0); __builtin_amdgcn_s_setprio(0); } while (0)
; #define PG8_WAIT_V(n) asm volatile("s_waitcnt vmcnt(" #n ")" ::: "memory")
; #define PG8_WAIT_L(n) asm volatile("s_waitcnt lgkmcnt(" #n ")" ::: "memory")
; #define PG8_BAR __builtin_amdgcn_s_barrier()
; #define PG8_SCHED __builtin_amdgcn_sched_barrier(0)
; template <class Sched, class Epi>
; __device__ __forceinline__ void gemm_phase(LAS unsigned char* lds, const Sched& S, const Epi& E, const int K, const int lda, const int ldb) {
;     ...
;             PG8_STAGE(PG8_SB(0, 1), b2 + hstepB, voffB);
;             PG8_WAIT_V(6); PG8_BAR; if (!chalf) PG8_MMA(1, 1, At, B1); PG8_BAR;
;             PG8_LDB(B0, 1, 0); PG8_SCHED; PG8_LDA(At, 1, 0); PG8_STAGE(PG8_SA(0, 1), a2 + hstepA, voffA);
;             PG8_WAIT_L(8); PG8_BAR; PG8_WAIT_L(0); PG8_MMA(0, 0, At, B0); PG8_BAR; PG8_SCHED;
;             PG8_LDB(B1, 1, 1); PG8_STAGE(PG8_SB(1, 0), b3, voffB);
;             PG8_BAR; PG8_WAIT_L(0); PG8_MMA(0, 1, At, B1); PG8_BAR;
;             PG8_LDA(At, 1, 1); PG8_STAGE(PG8_SA(1, 0), a3, voffA);
;             PG8_BAR; PG8_WAIT_L(0); if (!chalf) PG8_MMA(1, 0, At, B0); PG8_BAR; PG8_SCHED;
	s_add_u32 s50, s34, 0x40000
	s_addc_u32 s51, s35, 0
	s_add_i32 s52, s47, s38
	s_mov_b32 m0, s52
	s_nop 0
	global_load_lds_dwordx4 v132, s[50:51]
	s_add_i32 m0, s52, 0x2000
	s_nop 0
	global_load_lds_dwordx4 v136, s[50:51]
	s_waitcnt vmcnt(6)
	s_barrier
	s_setprio 1
	v_mfma_f32_16x16x32_bf16 v[54:57], v[202:205], v[170:173], v[54:57]
	v_mfma_f32_16x16x32_bf16 v[50:53], v[210:213], v[170:173], v[50:53]
	v_mfma_f32_16x16x32_bf16 v[38:41], v[202:205], v[178:181], v[38:41]
	v_mfma_f32_16x16x32_bf16 v[34:37], v[210:213], v[178:181], v[34:37]
	v_mfma_f32_16x16x32_bf16 v[22:25], v[202:205], v[186:189], v[22:25]
	v_mfma_f32_16x16x32_bf16 v[18:21], v[210:213], v[186:189], v[18:21]
	v_mfma_f32_16x16x32_bf16 v[6:9], v[202:205], v[194:197], v[6:9]
	v_mfma_f32_16x16x32_bf16 v[2:5], v[210:213], v[194:197], v[2:5]
	v_mfma_f32_16x16x32_bf16 v[54:57], v[206:209], v[174:177], v[54:57]
	v_mfma_f32_16x16x32_bf16 v[50:53], v[214:217], v[174:177], v[50:53]
	v_mfma_f32_16x16x32_bf16 v[38:41], v[206:209], v[182:185], v[38:41]
	v_mfma_f32_16x16x32_bf16 v[34:37], v[214:217], v[182:185], v[34:37]
	v_mfma_f32_16x16x32_bf16 v[22:25], v[206:209], v[190:193], v[22:25]
	v_mfma_f32_16x16x32_bf16 v[18:21], v[214:217], v[190:193], v[18:21]
	v_mfma_f32_16x16x32_bf16 v[6:9], v[206:209], v[198:201], v[6:9]
	v_mfma_f32_16x16x32_bf16 v[2:5], v[214:217], v[198:201], v[2:5]
	s_setprio 0
	s_add_i32 s50, 16, 0x18000
	v_add_u32_e32 v166, s50, v150
	s_barrier
	ds_read_b128 v[144:147], v166
	ds_read_b128 v[158:161], v166 offset:1024
	ds_read_b128 v[162:165], v166 offset:2048
	ds_read_b128 v[166:169], v166 offset:3072
	s_add_u32 s36, s36, 0x40000
	s_addc_u32 s37, s37, 0
	s_mov_b32 m0, s40
	ds_read_b128 v[170:173], v156 offset:32768
	ds_read_b128 v[174:177], v156 offset:33792
	ds_read_b128 v[178:181], v156 offset:34816
	ds_read_b128 v[182:185], v156 offset:35840
	ds_read_b128 v[186:189], v156 offset:36864
	ds_read_b128 v[190:193], v156 offset:37888
	ds_read_b128 v[194:197], v156 offset:38912
	ds_read_b128 v[198:201], v156 offset:39936
	global_load_lds_dwordx4 v130, s[36:37]
	s_mov_b32 m0, s41
	s_nop 0
	global_load_lds_dwordx4 v134, s[36:37]
	s_waitcnt lgkmcnt(8)
	s_barrier
	s_waitcnt lgkmcnt(0)
	s_setprio 1
	s_waitcnt lgkmcnt(0)
	v_mfma_f32_16x16x32_bf16 v[118:121], v[144:147], v[170:173], v[118:121]
	v_mfma_f32_16x16x32_bf16 v[114:117], v[162:165], v[170:173], v[114:117]
	v_mfma_f32_16x16x32_bf16 v[110:113], v[144:147], v[178:181], v[110:113]
	v_mfma_f32_16x16x32_bf16 v[106:109], v[162:165], v[178:181], v[106:109]
	v_mfma_f32_16x16x32_bf16 v[94:97], v[144:147], v[186:189], v[94:97]
	v_mfma_f32_16x16x32_bf16 v[90:93], v[162:165], v[186:189], v[90:93]
	v_mfma_f32_16x16x32_bf16 v[78:81], v[144:147], v[194:197], v[78:81]
	v_mfma_f32_16x16x32_bf16 v[74:77], v[162:165], v[194:197], v[74:77]
	v_mfma_f32_16x16x32_bf16 v[118:121], v[158:161], v[174:177], v[118:121]
	v_mfma_f32_16x16x32_bf16 v[114:117], v[166:169], v[174:177], v[114:117]
	v_mfma_f32_16x16x32_bf16 v[110:113], v[158:161], v[182:185], v[110:113]
	v_mfma_f32_16x16x32_bf16 v[106:109], v[166:169], v[182:185], v[106:109]
	v_mfma_f32_16x16x32_bf16 v[94:97], v[158:161], v[190:193], v[94:97]
	v_mfma_f32_16x16x32_bf16 v[90:93], v[166:169], v[190:193], v[90:93]
	v_mfma_f32_16x16x32_bf16 v[78:81], v[158:161], v[198:201], v[78:81]
	v_mfma_f32_16x16x32_bf16 v[74:77], v[166:169], v[198:201], v[74:77]
	s_setprio 0
	s_barrier
	s_add_i32 s36, 16, 0x1c000
	s_add_i32 s37, s50, s38
	v_add_u32_e32 v214, s36, v150
	v_lshl_add_u64 v[148:149], v[148:149], 0, s[8:9]
	s_mov_b32 m0, s37
	ds_read_b128 v[202:205], v214
	ds_read_b128 v[206:209], v214 offset:1024
	ds_read_b128 v[210:213], v214 offset:2048
	ds_read_b128 v[214:217], v214 offset:3072
	global_load_lds_dwordx4 v[148:149], off
	v_lshl_add_u64 v[148:149], v[218:219], 0, s[8:9]
	s_add_i32 m0, s37, 0x2000
	s_nop 0
	global_load_lds_dwordx4 v[148:149], off
	s_barrier
	s_waitcnt lgkmcnt(0)
	s_setprio 1
	s_waitcnt lgkmcnt(0)
	v_mfma_f32_16x16x32_bf16 v[126:129], v[202:205], v[170:173], v[126:129]
	v_mfma_f32_16x16x32_bf16 v[122:125], v[210:213], v[170:173], v[122:125]
	v_mfma_f32_16x16x32_bf16 v[102:105], v[202:205], v[178:181], v[102:105]
	v_mfma_f32_16x16x32_bf16 v[98:101], v[210:213], v[178:181], v[98:101]
	v_mfma_f32_16x16x32_bf16 v[86:89], v[202:205], v[186:189], v[86:89]
	v_mfma_f32_16x16x32_bf16 v[82:85], v[210:213], v[186:189], v[82:85]
	v_mfma_f32_16x16x32_bf16 v[70:73], v[202:205], v[194:197], v[70:73]
	v_mfma_f32_16x16x32_bf16 v[66:69], v[210:213], v[194:197], v[66:69]
	v_mfma_f32_16x16x32_bf16 v[126:129], v[206:209], v[174:177], v[126:129]
	v_mfma_f32_16x16x32_bf16 v[122:125], v[214:217], v[174:177], v[122:125]
	v_mfma_f32_16x16x32_bf16 v[102:105], v[206:209], v[182:185], v[102:105]
	v_mfma_f32_16x16x32_bf16 v[98:101], v[214:217], v[182:185], v[98:101]
	v_mfma_f32_16x16x32_bf16 v[86:89], v[206:209], v[190:193], v[86:89]
	v_mfma_f32_16x16x32_bf16 v[82:85], v[214:217], v[190:193], v[82:85]
	v_mfma_f32_16x16x32_bf16 v[70:73], v[206:209], v[198:201], v[70:73]
	v_mfma_f32_16x16x32_bf16 v[66:69], v[214:217], v[198:201], v[66:69]
	s_setprio 0
	s_mov_b32 m0, s42
	v_lshl_add_u64 v[148:149], v[220:221], 0, s[8:9]
	s_barrier
	ds_read_b128 v[170:173], v156 offset:49152
	ds_read_b128 v[174:177], v156 offset:50176
	ds_read_b128 v[178:181], v156 offset:51200
	ds_read_b128 v[182:185], v156 offset:52224
	ds_read_b128 v[186:189], v156 offset:53248
	ds_read_b128 v[190:193], v156 offset:54272
	ds_read_b128 v[194:197], v156 offset:55296
	ds_read_b128 v[198:201], v156 offset:56320
	global_load_lds_dwordx4 v[148:149], off
	v_lshl_add_u64 v[148:149], v[222:223], 0, s[8:9]
	s_mov_b32 m0, s43
	s_nop 0
	global_load_lds_dwordx4 v[148:149], off
	s_barrier
; #define PG8_STAGE(bufoff, gbase, voff) do { _Pragma("unroll") for (int _i = 0; _i < 2; ++_i) \
;         __builtin_amdgcn_global_load_lds((const unsigned*)((const char*)(gbase) + (voff)[_i]), (LAS unsigned*)(lds + (bufoff) + ldsw + _i * 8192), 16, 0, 0); } while (0)
; #define PG8_MMA(ai, bj, At, Bt) do { __builtin_amdgcn_s_setprio(1); _Pragma("unroll") for (int m = 0; m < 4; ++m) _Pragma("unroll") for (int n = 0; n < 2; ++n) _Pragma("unroll") for (int k = 0; k < 2; ++k) \
;         acc[ai][bj][m][n] = __builtin_amdgcn_mfma_f32_16x16x32_bf16(Bt[n][k], At[m][k], acc[ai][bj][m][n], 0, 0, 0); __builtin_amdgcn_s_setprio(0); } while (0)
; #define PG8_WAIT_V(n) asm volatile("s_waitcnt vmcnt(" #n ")" ::: "memory")
; #define PG8_WAIT_L(n) asm volatile("s_waitcnt lgkmcnt(" #n ")" ::: "memory")
; #define PG8_BAR __builtin_amdgcn_s_barrier()
; #define PG8_SCHED __builtin_amdgcn_sched_barrier(0)
; template <class Sched, class Epi>
; __device__ __forceinline__ void gemm_phase(LAS unsigned char* lds, const Sched& S, const Epi& E, const int K, const int lda, const int ldb) {
;     ...
;             PG8_BAR; PG8_WAIT_L(0); if (!chalf) PG8_MMA(1, 0, At, B0); PG8_BAR; PG8_SCHED;
;             PG8_STAGE(PG8_SB(1, 1), b3 + hstepB, voffB);
;             PG8_WAIT_V(6); PG8_BAR; if (!chalf) PG8_MMA(1, 1, At, B1); PG8_BAR;
;     __device__ __forceinline__ void operator()(EPI_ARGS) const {
;     ...
;         for (int ai = 0; ai < 2; ++ai) if (ai == 0 || !u.half) { u32x4 zz[4];
; #pragma unroll
;             for (int m = 0; m < 4; ++m) zz[m] = *(const u32x4*)(parts + E_PZB + (size_t)EPI_ROW * 1024 + col);
; #pragma unroll
;             for (int m = 0; m < 4; ++m) { float z[8]; unpack8(zz[m], z);
;                 const f32x4 a0 = acc[ai][0][m][0], a1 = acc[ai][0][m][1], b0 = acc[ai][1][m][0], b1 = acc[ai][1][m][1]; float o[8];
; #pragma unroll
;                 for (int j = 0; j < 4; ++j) { o[j] = a0[j] * z[j] * __builtin_amdgcn_rcpf((1.0f + __expf(-b0[j])) * (1.0f + __expf(-z[j]))); o[4 + j] = a1[j] * z[4 + j] * __builtin_amdgcn_rcpf((1.0f + __expf(-b1[j])) * (1.0f + __expf(-z[4 + j]))); }
	s_waitcnt lgkmcnt(0)
	s_setprio 1
	s_waitcnt lgkmcnt(0)
	v_mfma_f32_16x16x32_bf16 v[62:65], v[144:147], v[170:173], v[62:65]
	v_mfma_f32_16x16x32_bf16 v[58:61], v[162:165], v[170:173], v[58:61]
	v_mfma_f32_16x16x32_bf16 v[46:49], v[144:147], v[178:181], v[46:49]
	v_mfma_f32_16x16x32_bf16 v[42:45], v[162:165], v[178:181], v[42:45]
	v_mfma_f32_16x16x32_bf16 v[30:33], v[144:147], v[186:189], v[30:33]
	v_mfma_f32_16x16x32_bf16 v[26:29], v[162:165], v[186:189], v[26:29]
	v_mfma_f32_16x16x32_bf16 v[14:17], v[144:147], v[194:197], v[14:17]
	v_mfma_f32_16x16x32_bf16 v[10:13], v[162:165], v[194:197], v[10:13]
	v_mfma_f32_16x16x32_bf16 v[62:65], v[158:161], v[174:177], v[62:65]
	v_mfma_f32_16x16x32_bf16 v[58:61], v[166:169], v[174:177], v[58:61]
	v_mfma_f32_16x16x32_bf16 v[46:49], v[158:161], v[182:185], v[46:49]
	v_mfma_f32_16x16x32_bf16 v[42:45], v[166:169], v[182:185], v[42:45]
	v_mfma_f32_16x16x32_bf16 v[30:33], v[158:161], v[190:193], v[30:33]
	v_mfma_f32_16x16x32_bf16 v[26:29], v[166:169], v[190:193], v[26:29]
	v_mfma_f32_16x16x32_bf16 v[14:17], v[158:161], v[198:201], v[14:17]
	v_mfma_f32_16x16x32_bf16 v[10:13], v[166:169], v[198:201], v[10:13]
	s_setprio 0
	s_barrier
	s_add_u32 s34, s34, 0x40080
	s_addc_u32 s35, s35, 0
	s_add_i32 s36, s36, s38
	s_mov_b32 m0, s36
	s_nop 0
	global_load_lds_dwordx4 v132, s[34:35]
	s_add_i32 m0, s36, 0x2000
	s_nop 0
	global_load_lds_dwordx4 v136, s[34:35]
	s_waitcnt vmcnt(6)
	s_barrier
	s_setprio 1
	v_mfma_f32_16x16x32_bf16 v[54:57], v[202:205], v[170:173], v[54:57]
	v_mfma_f32_16x16x32_bf16 v[50:53], v[210:213], v[170:173], v[50:53]
	v_mfma_f32_16x16x32_bf16 v[38:41], v[202:205], v[178:181], v[38:41]
	v_mfma_f32_16x16x32_bf16 v[34:37], v[210:213], v[178:181], v[34:37]
	v_mfma_f32_16x16x32_bf16 v[22:25], v[202:205], v[186:189], v[22:25]
	v_mfma_f32_16x16x32_bf16 v[18:21], v[210:213], v[186:189], v[18:21]
	v_mfma_f32_16x16x32_bf16 v[6:9], v[202:205], v[194:197], v[6:9]
	v_mfma_f32_16x16x32_bf16 v[2:5], v[210:213], v[194:197], v[2:5]
	v_mfma_f32_16x16x32_bf16 v[54:57], v[206:209], v[174:177], v[54:57]
	v_mfma_f32_16x16x32_bf16 v[50:53], v[214:217], v[174:177], v[50:53]
	v_mfma_f32_16x16x32_bf16 v[38:41], v[206:209], v[182:185], v[38:41]
	v_mfma_f32_16x16x32_bf16 v[34:37], v[214:217], v[182:185], v[34:37]
	v_mfma_f32_16x16x32_bf16 v[22:25], v[206:209], v[190:193], v[22:25]
	v_mfma_f32_16x16x32_bf16 v[18:21], v[214:217], v[190:193], v[18:21]
	v_mfma_f32_16x16x32_bf16 v[6:9], v[206:209], v[198:201], v[6:9]
	v_mfma_f32_16x16x32_bf16 v[2:5], v[214:217], v[198:201], v[2:5]
	s_setprio 0
	s_add_i32 s49, s49, 2
	s_add_u32 s15, s15, 0x100
	s_addc_u32 s17, s17, 0
	s_add_u32 s28, s28, 0x100
	s_addc_u32 s29, s29, 0
	s_cmp_gt_u32 s49, 13
	s_barrier
	s_cbranch_scc0 .LBB0_761
	v_lshl_or_b32 v144, s48, 7, v154
	v_ashrrev_i32_e32 v145, 31, v144
	v_add_u32_e32 v148, s22, v1
	v_lshlrev_b64 v[144:145], 1, v[144:145]
	v_ashrrev_i32_e32 v149, 31, v148
	v_lshl_add_u64 v[146:147], s[6:7], 0, v[144:145]
	v_lshlrev_b64 v[166:167], 11, v[148:149]
	v_lshl_add_u64 v[158:159], v[146:147], 0, v[166:167]
	global_load_dwordx4 v[158:161], v[158:159], off
	v_mul_f32_e32 v149, 0xbfb8aa3b, v122
	v_mul_f32_e32 v123, 0xbfb8aa3b, v123
	v_add_u32_e32 v122, 16, v148
	v_exp_f32_e32 v174, v123
	v_ashrrev_i32_e32 v123, 31, v122
	v_lshlrev_b64 v[122:123], 11, v[122:123]
	v_mul_f32_e32 v126, 0xbfb8aa3b, v126
	v_mul_f32_e32 v127, 0xbfb8aa3b, v127
	v_mul_f32_e32 v128, 0xbfb8aa3b, v128
	v_mul_f32_e32 v129, 0xbfb8aa3b, v129
	v_lshl_add_u64 v[122:123], v[146:147], 0, v[122:123]
	v_exp_f32_e32 v168, v126
	v_exp_f32_e32 v172, v127
	v_exp_f32_e32 v176, v128
	v_exp_f32_e32 v180, v129
	global_load_dwordx4 v[126:129], v[122:123], off
	v_mul_f32_e32 v163, 0xbfb8aa3b, v124
	v_mul_f32_e32 v125, 0xbfb8aa3b, v125
	v_add_u32_e32 v124, 32, v148
	v_add_u32_e32 v162, 48, v148
	v_exp_f32_e32 v178, v163
	v_exp_f32_e32 v182, v125
	v_ashrrev_i32_e32 v125, 31, v124
	v_ashrrev_i32_e32 v163, 31, v162
	v_lshlrev_b64 v[122:123], 11, v[124:125]
	v_lshlrev_b64 v[124:125], 11, v[162:163]
	v_lshl_add_u64 v[122:123], v[146:147], 0, v[122:123]
	v_lshl_add_u64 v[124:125], v[146:147], 0, v[124:125]
	global_load_dwordx4 v[162:165], v[122:123], off
	s_nop 0
	global_load_dwordx4 v[122:125], v[124:125], off
	v_exp_f32_e32 v170, v149
	v_mul_f32_e32 v102, 0xbfb8aa3b, v102
	v_mul_f32_e32 v98, 0xbfb8aa3b, v98
	v_mul_f32_e32 v100, 0xbfb8aa3b, v100
	v_mul_f32_e32 v86, 0xbfb8aa3b, v86
	v_mul_f32_e32 v82, 0xbfb8aa3b, v82
	v_mul_f32_e32 v84, 0xbfb8aa3b, v84
	v_mul_f32_e32 v70, 0xbfb8aa3b, v70
	v_mul_f32_e32 v66, 0xbfb8aa3b, v66
	v_mul_f32_e32 v68, 0xbfb8aa3b, v68
	v_mul_f32_e32 v54, 0xbfb8aa3b, v54
	v_mul_f32_e32 v50, 0xbfb8aa3b, v50
	v_mul_f32_e32 v52, 0xbfb8aa3b, v52
	v_mul_f32_e32 v38, 0xbfb8aa3b, v38
	v_mul_f32_e32 v34, 0xbfb8aa3b, v34
	v_mul_f32_e32 v36, 0xbfb8aa3b, v36
	v_mul_f32_e32 v22, 0xbfb8aa3b, v22
	v_mul_f32_e32 v18, 0xbfb8aa3b, v18
	v_mul_f32_e32 v20, 0xbfb8aa3b, v20
	v_mul_f32_e32 v6, 0xbfb8aa3b, v6
	v_mul_f32_e32 v2, 0xbfb8aa3b, v2
	v_mul_f32_e32 v4, 0xbfb8aa3b, v4
	s_and_b64 vcc, exec, s[12:13]
	s_mov_b32 s48, s14
	s_mov_b64 s[34:35], s[20:21]
	s_mov_b64 s[28:29], s[18:19]
	s_waitcnt vmcnt(0)
; __device__ __forceinline__ u32x4 pack8(const float (&f)[8]) { u32x4 r; r[0] = cvt_pk_bf16(f[0], f[1]); r[1] = cvt_pk_bf16(f[2], f[3]); r[2] = cvt_pk_bf16(f[4], f[5]); r[3] = cvt_pk_bf16(f[6], f[7]); return r; }
;     __device__ __forceinline__ void operator()(EPI_ARGS) const {
;     ...
;         for (int ai = 0; ai < 2; ++ai) if (ai == 0 || !u.half) { u32x4 zz[4];
; #pragma unroll
;             for (int m = 0; m < 4; ++m) zz[m] = *(const u32x4*)(parts + E_PZB + (size_t)EPI_ROW * 1024 + col);
; #pragma unroll
;             for (int m = 0; m < 4; ++m) { float z[8]; unpack8(zz[m], z);
;                 const f32x4 a0 = acc[ai][0][m][0], a1 = acc[ai][0][m][1], b0 = acc[ai][1][m][0], b1 = acc[ai][1][m][1]; float o[8];
; #pragma unroll
;                 for (int j = 0; j < 4; ++j) { o[j] = a0[j] * z[j] * __builtin_amdgcn_rcpf((1.0f + __expf(-b0[j])) * (1.0f + __expf(-z[j]))); o[4 + j] = a1[j] * z[4 + j] * __builtin_amdgcn_rcpf((1.0f + __expf(-b1[j])) * (1.0f + __expf(-z[4 + j]))); }
;                 *(u32x4*)(O + (size_t)EPI_ROW * 1024 + col) = pack8(o); } }
	v_lshlrev_b32_e32 v149, 16, v158
	v_and_b32_e32 v158, 0xffff0000, v158
	v_lshlrev_b32_e32 v169, 16, v159
	v_and_b32_e32 v184, 0xffff0000, v159
	v_lshlrev_b32_e32 v159, 16, v160
	v_and_b32_e32 v160, 0xffff0000, v160
	v_lshlrev_b32_e32 v171, 16, v161
	v_mul_f32_e32 v186, v118, v149
	v_mul_f32_e32 v118, 0xbfb8aa3b, v149
	v_mul_f32_e32 v149, v114, v159
	v_mul_f32_e32 v114, 0xbfb8aa3b, v159
	v_mul_f32_e32 v187, v119, v158
	v_mul_f32_e32 v119, 0xbfb8aa3b, v158
	v_mul_f32_e32 v188, v115, v160
	v_mul_f32_e32 v115, 0xbfb8aa3b, v160
	v_mul_f32_e32 v158, 0xbfb8aa3b, v169
	v_mul_f32_e32 v159, 0xbfb8aa3b, v171
	v_mul_f32_e32 v120, v120, v169
	v_mul_f32_e32 v116, v116, v171
	v_exp_f32_e32 v169, v118
	v_exp_f32_e32 v171, v114
	v_exp_f32_e32 v173, v119
	v_exp_f32_e32 v175, v115
	v_exp_f32_e32 v177, v158
	v_exp_f32_e32 v179, v159
	v_and_b32_e32 v185, 0xffff0000, v161
	v_mul_f32_e32 v160, 0xbfb8aa3b, v184
	v_mul_f32_e32 v161, 0xbfb8aa3b, v185
	v_exp_f32_e32 v181, v160
	v_exp_f32_e32 v183, v161
	v_pk_add_f32 v[114:115], v[168:169], 1.0 op_sel_hi:[1,0]
	v_pk_add_f32 v[118:119], v[170:171], 1.0 op_sel_hi:[1,0]
	v_pk_add_f32 v[158:159], v[172:173], 1.0 op_sel_hi:[1,0]
	v_pk_add_f32 v[160:161], v[174:175], 1.0 op_sel_hi:[1,0]
	v_pk_add_f32 v[168:169], v[176:177], 1.0 op_sel_hi:[1,0]
	v_pk_add_f32 v[170:171], v[178:179], 1.0 op_sel_hi:[1,0]
	v_mul_f32_e32 v114, v114, v115
	v_mul_f32_e32 v115, v118, v119
	v_mul_f32_e32 v118, v158, v159
	v_mul_f32_e32 v119, v160, v161
	v_mul_f32_e32 v158, v168, v169
	v_mul_f32_e32 v159, v170, v171
	v_rcp_f32_e32 v115, v115
	v_rcp_f32_e32 v118, v118
	v_rcp_f32_e32 v119, v119
	v_rcp_f32_e32 v158, v158
	v_rcp_f32_e32 v159, v159
	v_pk_add_f32 v[172:173], v[180:181], 1.0 op_sel_hi:[1,0]
	v_pk_add_f32 v[174:175], v[182:183], 1.0 op_sel_hi:[1,0]
	v_mul_f32_e32 v160, v172, v173
	v_rcp_f32_e32 v114, v114
	v_mul_f32_e32 v149, v149, v115
	v_mul_f32_e32 v115, v187, v118
	v_mul_f32_e32 v118, v188, v119
	v_mul_f32_e32 v119, v120, v158
	v_mul_f32_e32 v120, v116, v159
	v_mul_f32_e32 v116, v174, v175
	v_rcp_f32_e32 v160, v160
	v_rcp_f32_e32 v116, v116
	v_mul_f32_e32 v114, v186, v114
	v_mul_f32_e32 v121, v121, v184
	v_mul_f32_e32 v117, v117, v185
	v_mul_f32_e32 v121, v121, v160
	v_mul_f32_e32 v117, v117, v116
	v_cvt_pk_bf16_f32 v114, v114, v115
	v_cvt_pk_bf16_f32 v115, v119, v121
	v_cvt_pk_bf16_f32 v116, v149, v118
	v_lshl_add_u64 v[118:119], s[4:5], 0, v[166:167]
	v_lshl_add_u64 v[118:119], v[118:119], 0, v[144:145]
	v_cvt_pk_bf16_f32 v117, v120, v117
	global_store_dwordx4 v[118:119], v[114:117], off
	v_lshlrev_b32_e32 v118, 16, v126
	v_and_b32_e32 v119, 0xffff0000, v126
	v_lshlrev_b32_e32 v126, 16, v128
	v_exp_f32_e32 v114, v102
	v_mul_f32_e32 v102, 0xbfb8aa3b, v118
	v_exp_f32_e32 v115, v102
	v_exp_f32_e32 v116, v98
	v_mul_f32_e32 v98, 0xbfb8aa3b, v126
	v_exp_f32_e32 v117, v98
	v_pk_add_f32 v[114:115], v[114:115], 1.0 op_sel_hi:[1,0]
	v_mul_f32_e32 v110, v110, v118
	v_mul_f32_e32 v98, v114, v115
	v_pk_add_f32 v[114:115], v[116:117], 1.0 op_sel_hi:[1,0]
	v_rcp_f32_e32 v98, v98
	v_mul_f32_e32 v102, v114, v115
	v_rcp_f32_e32 v102, v102
	v_lshlrev_b32_e32 v120, 16, v127
	v_mul_f32_e32 v110, v110, v98
	v_mul_f32_e32 v98, v106, v126
	v_mul_f32_e32 v106, v98, v102
	v_mul_f32_e32 v98, 0xbfb8aa3b, v103
	v_and_b32_e32 v121, 0xffff0000, v127
	v_and_b32_e32 v127, 0xffff0000, v128
	v_exp_f32_e32 v102, v98
	v_mul_f32_e32 v98, 0xbfb8aa3b, v119
	v_exp_f32_e32 v103, v98
	v_mul_f32_e32 v98, 0xbfb8aa3b, v99
	v_mul_f32_e32 v99, 0xbfb8aa3b, v127
	v_exp_f32_e32 v98, v98
	v_exp_f32_e32 v99, v99
	v_pk_add_f32 v[102:103], v[102:103], 1.0 op_sel_hi:[1,0]
	v_lshlrev_b32_e32 v128, 16, v129
	v_mul_f32_e32 v102, v102, v103
	v_pk_add_f32 v[98:99], v[98:99], 1.0 op_sel_hi:[1,0]
	v_rcp_f32_e32 v102, v102
	v_mul_f32_e32 v98, v98, v99
	v_rcp_f32_e32 v98, v98
	v_mul_f32_e32 v99, v111, v119
	v_mul_f32_e32 v111, v99, v102
	v_mul_f32_e32 v99, v107, v127
	v_mul_f32_e32 v107, v99, v98
	v_mul_f32_e32 v98, 0xbfb8aa3b, v104
	v_mul_f32_e32 v99, 0xbfb8aa3b, v120
	v_exp_f32_e32 v98, v98
	v_exp_f32_e32 v99, v99
	v_exp_f32_e32 v102, v100
	v_mul_f32_e32 v100, 0xbfb8aa3b, v128
	v_exp_f32_e32 v103, v100
	v_pk_add_f32 v[98:99], v[98:99], 1.0 op_sel_hi:[1,0]
	v_and_b32_e32 v129, 0xffff0000, v129
	v_mul_f32_e32 v98, v98, v99
	v_rcp_f32_e32 v100, v98
	v_pk_add_f32 v[98:99], v[102:103], 1.0 op_sel_hi:[1,0]
	s_nop 0
	v_mul_f32_e32 v98, v98, v99
	v_rcp_f32_e32 v98, v98
	v_mul_f32_e32 v99, v112, v120
	v_mul_f32_e32 v102, v99, v100
	v_mul_f32_e32 v99, v108, v128
	v_mul_f32_e32 v103, v99, v98
	v_mul_f32_e32 v98, 0xbfb8aa3b, v105
	v_mul_f32_e32 v99, 0xbfb8aa3b, v121
	v_exp_f32_e32 v98, v98
	v_exp_f32_e32 v99, v99
	v_mul_f32_e32 v100, 0xbfb8aa3b, v101
	v_mul_f32_e32 v101, 0xbfb8aa3b, v129
	v_exp_f32_e32 v100, v100
	v_exp_f32_e32 v101, v101
	v_pk_add_f32 v[98:99], v[98:99], 1.0 op_sel_hi:[1,0]
	v_lshlrev_b32_e32 v108, 16, v165
	v_mul_f32_e32 v98, v98, v99
	v_rcp_f32_e32 v104, v98
	v_pk_add_f32 v[98:99], v[100:101], 1.0 op_sel_hi:[1,0]
	v_mul_f32_e32 v100, v109, v129
	v_mul_f32_e32 v98, v98, v99
	v_rcp_f32_e32 v98, v98
	v_mul_f32_e32 v99, v113, v121
	v_mul_f32_e32 v99, v99, v104
	v_lshlrev_b32_e32 v104, 16, v163
	v_mul_f32_e32 v101, v100, v98
	v_cvt_pk_bf16_f32 v98, v110, v111
	v_cvt_pk_bf16_f32 v99, v102, v99
	v_add_u32_e32 v102, s22, v151
	v_cvt_pk_bf16_f32 v100, v106, v107
	v_cvt_pk_bf16_f32 v101, v103, v101
	v_ashrrev_i32_e32 v103, 31, v102
	v_lshlrev_b64 v[102:103], 11, v[102:103]
	v_lshl_add_u64 v[102:103], s[4:5], 0, v[102:103]
	v_lshl_add_u64 v[102:103], v[102:103], 0, v[144:145]
	global_store_dwordx4 v[102:103], v[98:101], off
	v_lshlrev_b32_e32 v102, 16, v162
	v_lshlrev_b32_e32 v106, 16, v164
; __device__ __forceinline__ u32x4 pack8(const float (&f)[8]) { u32x4 r; r[0] = cvt_pk_bf16(f[0], f[1]); r[1] = cvt_pk_bf16(f[2], f[3]); r[2] = cvt_pk_bf16(f[4], f[5]); r[3] = cvt_pk_bf16(f[6], f[7]); return r; }
;     __device__ __forceinline__ void operator()(EPI_ARGS) const {
;     ...
;         for (int ai = 0; ai < 2; ++ai) if (ai == 0 || !u.half) { u32x4 zz[4];
; #pragma unroll
;             for (int m = 0; m < 4; ++m) zz[m] = *(const u32x4*)(parts + E_PZB + (size_t)EPI_ROW * 1024 + col);
; #pragma unroll
;             for (int m = 0; m < 4; ++m) { float z[8]; unpack8(zz[m], z);
;                 const f32x4 a0 = acc[ai][0][m][0], a1 = acc[ai][0][m][1], b0 = acc[ai][1][m][0], b1 = acc[ai][1][m][1]; float o[8];
; #pragma unroll
;                 for (int j = 0; j < 4; ++j) { o[j] = a0[j] * z[j] * __builtin_amdgcn_rcpf((1.0f + __expf(-b0[j])) * (1.0f + __expf(-z[j]))); o[4 + j] = a1[j] * z[4 + j] * __builtin_amdgcn_rcpf((1.0f + __expf(-b1[j])) * (1.0f + __expf(-z[4 + j]))); }
;                 *(u32x4*)(O + (size_t)EPI_ROW * 1024 + col) = pack8(o); } }
	v_exp_f32_e32 v98, v86
	v_mul_f32_e32 v86, 0xbfb8aa3b, v102
	v_exp_f32_e32 v99, v86
	v_exp_f32_e32 v100, v82
	v_mul_f32_e32 v82, 0xbfb8aa3b, v106
	v_exp_f32_e32 v101, v82
	v_pk_add_f32 v[98:99], v[98:99], 1.0 op_sel_hi:[1,0]
	v_mul_f32_e32 v94, v94, v102
	v_mul_f32_e32 v82, v98, v99
	v_pk_add_f32 v[98:99], v[100:101], 1.0 op_sel_hi:[1,0]
	v_rcp_f32_e32 v82, v82
	v_mul_f32_e32 v86, v98, v99
	v_rcp_f32_e32 v86, v86
	v_and_b32_e32 v103, 0xffff0000, v162
	v_mul_f32_e32 v94, v94, v82
	v_mul_f32_e32 v82, v90, v106
	v_mul_f32_e32 v90, v82, v86
	v_mul_f32_e32 v82, 0xbfb8aa3b, v87
	v_and_b32_e32 v107, 0xffff0000, v164
	v_exp_f32_e32 v86, v82
	v_mul_f32_e32 v82, 0xbfb8aa3b, v103
	v_exp_f32_e32 v87, v82
	v_mul_f32_e32 v82, 0xbfb8aa3b, v83
	v_mul_f32_e32 v83, 0xbfb8aa3b, v107
	v_exp_f32_e32 v82, v82
	v_exp_f32_e32 v83, v83
	v_pk_add_f32 v[86:87], v[86:87], 1.0 op_sel_hi:[1,0]
	v_and_b32_e32 v105, 0xffff0000, v163
	v_mul_f32_e32 v86, v86, v87
	v_pk_add_f32 v[82:83], v[82:83], 1.0 op_sel_hi:[1,0]
	v_rcp_f32_e32 v86, v86
	v_mul_f32_e32 v82, v82, v83
	v_rcp_f32_e32 v82, v82
	v_mul_f32_e32 v83, v95, v103
	v_mul_f32_e32 v95, v83, v86
	v_mul_f32_e32 v83, v91, v107
	v_mul_f32_e32 v91, v83, v82
	v_mul_f32_e32 v82, 0xbfb8aa3b, v88
	v_mul_f32_e32 v83, 0xbfb8aa3b, v104
	v_exp_f32_e32 v82, v82
	v_exp_f32_e32 v83, v83
	v_exp_f32_e32 v86, v84
	v_mul_f32_e32 v84, 0xbfb8aa3b, v108
	v_exp_f32_e32 v87, v84
	v_pk_add_f32 v[82:83], v[82:83], 1.0 op_sel_hi:[1,0]
	v_and_b32_e32 v109, 0xffff0000, v165
	v_mul_f32_e32 v82, v82, v83
	v_rcp_f32_e32 v84, v82
	v_pk_add_f32 v[82:83], v[86:87], 1.0 op_sel_hi:[1,0]
	s_nop 0
	v_mul_f32_e32 v82, v82, v83
	v_rcp_f32_e32 v82, v82
	v_mul_f32_e32 v83, v96, v104
	v_mul_f32_e32 v86, v83, v84
	v_mul_f32_e32 v83, v92, v108
	v_mul_f32_e32 v87, v83, v82
	v_mul_f32_e32 v82, 0xbfb8aa3b, v89
	v_mul_f32_e32 v83, 0xbfb8aa3b, v105
	v_exp_f32_e32 v82, v82
	v_exp_f32_e32 v83, v83
	v_mul_f32_e32 v84, 0xbfb8aa3b, v85
	v_mul_f32_e32 v85, 0xbfb8aa3b, v109
	v_exp_f32_e32 v84, v84
	v_exp_f32_e32 v85, v85
	v_pk_add_f32 v[82:83], v[82:83], 1.0 op_sel_hi:[1,0]
	v_lshlrev_b32_e32 v92, 16, v125
	v_mul_f32_e32 v82, v82, v83
	v_rcp_f32_e32 v88, v82
	v_pk_add_f32 v[82:83], v[84:85], 1.0 op_sel_hi:[1,0]
	v_mul_f32_e32 v84, v93, v109
	v_mul_f32_e32 v82, v82, v83
	v_rcp_f32_e32 v82, v82
	v_mul_f32_e32 v83, v97, v105
	v_mul_f32_e32 v83, v83, v88
	v_lshlrev_b32_e32 v88, 16, v123
	v_mul_f32_e32 v85, v84, v82
	v_cvt_pk_bf16_f32 v82, v94, v95
	v_cvt_pk_bf16_f32 v83, v86, v83
	v_add_u32_e32 v86, s22, v152
	v_cvt_pk_bf16_f32 v84, v90, v91
	v_cvt_pk_bf16_f32 v85, v87, v85
	v_ashrrev_i32_e32 v87, 31, v86
	v_lshlrev_b64 v[86:87], 11, v[86:87]
	v_lshl_add_u64 v[86:87], s[4:5], 0, v[86:87]
	v_lshl_add_u64 v[86:87], v[86:87], 0, v[144:145]
	global_store_dwordx4 v[86:87], v[82:85], off
	v_lshlrev_b32_e32 v86, 16, v122
	v_lshlrev_b32_e32 v90, 16, v124
	v_exp_f32_e32 v82, v70
	v_mul_f32_e32 v70, 0xbfb8aa3b, v86
	v_exp_f32_e32 v83, v70
	v_exp_f32_e32 v84, v66
	v_mul_f32_e32 v66, 0xbfb8aa3b, v90
	v_exp_f32_e32 v85, v66
	v_pk_add_f32 v[82:83], v[82:83], 1.0 op_sel_hi:[1,0]
	v_mul_f32_e32 v78, v78, v86
	v_mul_f32_e32 v66, v82, v83
	v_pk_add_f32 v[82:83], v[84:85], 1.0 op_sel_hi:[1,0]
	v_rcp_f32_e32 v66, v66
	v_mul_f32_e32 v70, v82, v83
	v_rcp_f32_e32 v70, v70
	v_and_b32_e32 v87, 0xffff0000, v122
	v_mul_f32_e32 v78, v78, v66
	v_mul_f32_e32 v66, v74, v90
	v_mul_f32_e32 v74, v66, v70
	v_mul_f32_e32 v66, 0xbfb8aa3b, v71
	v_and_b32_e32 v91, 0xffff0000, v124
	v_exp_f32_e32 v70, v66
	v_mul_f32_e32 v66, 0xbfb8aa3b, v87
	v_exp_f32_e32 v71, v66
	v_mul_f32_e32 v66, 0xbfb8aa3b, v67
	v_mul_f32_e32 v67, 0xbfb8aa3b, v91
	v_exp_f32_e32 v66, v66
	v_exp_f32_e32 v67, v67
	v_pk_add_f32 v[70:71], v[70:71], 1.0 op_sel_hi:[1,0]
	v_and_b32_e32 v89, 0xffff0000, v123
	v_mul_f32_e32 v70, v70, v71
	v_pk_add_f32 v[66:67], v[66:67], 1.0 op_sel_hi:[1,0]
	v_rcp_f32_e32 v70, v70
	v_mul_f32_e32 v66, v66, v67
	v_rcp_f32_e32 v66, v66
	v_mul_f32_e32 v67, v79, v87
	v_mul_f32_e32 v79, v67, v70
	v_mul_f32_e32 v67, v75, v91
	v_mul_f32_e32 v75, v67, v66
	v_mul_f32_e32 v66, 0xbfb8aa3b, v72
	v_mul_f32_e32 v67, 0xbfb8aa3b, v88
	v_exp_f32_e32 v66, v66
	v_exp_f32_e32 v67, v67
	v_exp_f32_e32 v70, v68
	v_mul_f32_e32 v68, 0xbfb8aa3b, v92
	v_exp_f32_e32 v71, v68
	v_pk_add_f32 v[66:67], v[66:67], 1.0 op_sel_hi:[1,0]
	v_and_b32_e32 v93, 0xffff0000, v125
	v_mul_f32_e32 v66, v66, v67
	v_rcp_f32_e32 v68, v66
	v_pk_add_f32 v[66:67], v[70:71], 1.0 op_sel_hi:[1,0]
	s_nop 0
	v_mul_f32_e32 v66, v66, v67
	v_rcp_f32_e32 v66, v66
	v_mul_f32_e32 v67, v80, v88
	v_mul_f32_e32 v70, v67, v68
	v_mul_f32_e32 v67, v76, v92
	v_mul_f32_e32 v71, v67, v66
	v_mul_f32_e32 v66, 0xbfb8aa3b, v73
	v_mul_f32_e32 v67, 0xbfb8aa3b, v89
	v_exp_f32_e32 v66, v66
	v_exp_f32_e32 v67, v67
	v_mul_f32_e32 v68, 0xbfb8aa3b, v69
	v_mul_f32_e32 v69, 0xbfb8aa3b, v93
	v_exp_f32_e32 v68, v68
	v_exp_f32_e32 v69, v69
	v_pk_add_f32 v[66:67], v[66:67], 1.0 op_sel_hi:[1,0]
	s_nop 0
	v_mul_f32_e32 v66, v66, v67
	v_rcp_f32_e32 v72, v66
	v_pk_add_f32 v[66:67], v[68:69], 1.0 op_sel_hi:[1,0]
	v_mul_f32_e32 v68, v77, v93
	v_mul_f32_e32 v66, v66, v67
	v_rcp_f32_e32 v66, v66
	v_mul_f32_e32 v67, v81, v89
	v_mul_f32_e32 v67, v67, v72
	v_mul_f32_e32 v69, v68, v66
	v_cvt_pk_bf16_f32 v66, v78, v79
	v_cvt_pk_bf16_f32 v67, v70, v67
	v_add_u32_e32 v70, s22, v153
	v_cvt_pk_bf16_f32 v68, v74, v75
	v_cvt_pk_bf16_f32 v69, v71, v69
	v_ashrrev_i32_e32 v71, 31, v70
	v_lshlrev_b64 v[70:71], 11, v[70:71]
	v_lshl_add_u64 v[70:71], s[4:5], 0, v[70:71]
	v_lshl_add_u64 v[70:71], v[70:71], 0, v[144:145]
	global_store_dwordx4 v[70:71], v[66:69], off
	s_mov_b32 s22, s16
	s_nop 0
	v_add_u32_e32 v66, 0x80, v148
	v_ashrrev_i32_e32 v67, 31, v66
	v_lshlrev_b64 v[88:89], 11, v[66:67]
	v_lshl_add_u64 v[66:67], v[146:147], 0, v[88:89]
	global_load_dwordx4 v[80:83], v[66:67], off
	v_add_u32_e32 v66, 0x90, v148
	v_ashrrev_i32_e32 v67, 31, v66
	v_lshlrev_b64 v[78:79], 11, v[66:67]
	v_lshl_add_u64 v[66:67], v[146:147], 0, v[78:79]
	global_load_dwordx4 v[84:87], v[66:67], off
	v_add_u32_e32 v66, 0xa0, v148
	v_ashrrev_i32_e32 v67, 31, v66
	v_lshlrev_b64 v[76:77], 11, v[66:67]
	v_add_u32_e32 v66, 0xb0, v148
	v_ashrrev_i32_e32 v67, 31, v66
	v_lshl_add_u64 v[90:91], v[146:147], 0, v[76:77]
	v_lshlrev_b64 v[74:75], 11, v[66:67]
	v_lshl_add_u64 v[92:93], v[146:147], 0, v[74:75]
	global_load_dwordx4 v[70:73], v[90:91], off
	global_load_dwordx4 v[66:69], v[92:93], off
	s_waitcnt vmcnt(0)
; __device__ __forceinline__ u32x4 pack8(const float (&f)[8]) { u32x4 r; r[0] = cvt_pk_bf16(f[0], f[1]); r[1] = cvt_pk_bf16(f[2], f[3]); r[2] = cvt_pk_bf16(f[4], f[5]); r[3] = cvt_pk_bf16(f[6], f[7]); return r; }
;     __device__ __forceinline__ void operator()(EPI_ARGS) const {
;     ...
;         for (int ai = 0; ai < 2; ++ai) if (ai == 0 || !u.half) { u32x4 zz[4];
; #pragma unroll
;             for (int m = 0; m < 4; ++m) zz[m] = *(const u32x4*)(parts + E_PZB + (size_t)EPI_ROW * 1024 + col);
; #pragma unroll
;             for (int m = 0; m < 4; ++m) { float z[8]; unpack8(zz[m], z);
;                 const f32x4 a0 = acc[ai][0][m][0], a1 = acc[ai][0][m][1], b0 = acc[ai][1][m][0], b1 = acc[ai][1][m][1]; float o[8];
; #pragma unroll
;                 for (int j = 0; j < 4; ++j) { o[j] = a0[j] * z[j] * __builtin_amdgcn_rcpf((1.0f + __expf(-b0[j])) * (1.0f + __expf(-z[j]))); o[4 + j] = a1[j] * z[4 + j] * __builtin_amdgcn_rcpf((1.0f + __expf(-b1[j])) * (1.0f + __expf(-z[4 + j]))); }
;                 *(u32x4*)(O + (size_t)EPI_ROW * 1024 + col) = pack8(o); } }
	v_lshlrev_b32_e32 v90, 16, v80
	v_and_b32_e32 v91, 0xffff0000, v80
	v_lshlrev_b32_e32 v94, 16, v82
	v_exp_f32_e32 v80, v54
	v_mul_f32_e32 v54, 0xbfb8aa3b, v90
	v_lshlrev_b32_e32 v92, 16, v81
	v_and_b32_e32 v93, 0xffff0000, v81
	v_and_b32_e32 v95, 0xffff0000, v82
	v_exp_f32_e32 v81, v54
	v_exp_f32_e32 v82, v50
	v_mul_f32_e32 v50, 0xbfb8aa3b, v94
	v_lshlrev_b32_e32 v96, 16, v83
	v_and_b32_e32 v97, 0xffff0000, v83
	v_exp_f32_e32 v83, v50
	v_pk_add_f32 v[80:81], v[80:81], 1.0 op_sel_hi:[1,0]
	v_mul_f32_e32 v62, v62, v90
	v_mul_f32_e32 v50, v80, v81
	v_pk_add_f32 v[80:81], v[82:83], 1.0 op_sel_hi:[1,0]
	v_rcp_f32_e32 v50, v50
	v_mul_f32_e32 v54, v80, v81
	v_rcp_f32_e32 v54, v54
	v_mul_f32_e32 v62, v62, v50
	v_mul_f32_e32 v50, v58, v94
	v_mul_f32_e32 v58, v50, v54
	v_mul_f32_e32 v50, 0xbfb8aa3b, v55
	v_exp_f32_e32 v54, v50
	v_mul_f32_e32 v50, 0xbfb8aa3b, v91
	v_exp_f32_e32 v55, v50
	v_mul_f32_e32 v50, 0xbfb8aa3b, v51
	v_mul_f32_e32 v51, 0xbfb8aa3b, v95
	v_exp_f32_e32 v50, v50
	v_exp_f32_e32 v51, v51
	v_pk_add_f32 v[54:55], v[54:55], 1.0 op_sel_hi:[1,0]
	v_pk_add_f32 v[50:51], v[50:51], 1.0 op_sel_hi:[1,0]
	v_mul_f32_e32 v54, v54, v55
	v_rcp_f32_e32 v54, v54
	v_mul_f32_e32 v50, v50, v51
	v_rcp_f32_e32 v50, v50
	v_mul_f32_e32 v51, v63, v91
	v_mul_f32_e32 v63, v51, v54
	v_mul_f32_e32 v51, v59, v95
	v_mul_f32_e32 v59, v51, v50
	v_mul_f32_e32 v50, 0xbfb8aa3b, v56
	v_mul_f32_e32 v51, 0xbfb8aa3b, v92
	v_exp_f32_e32 v50, v50
	v_exp_f32_e32 v51, v51
	v_exp_f32_e32 v54, v52
	v_mul_f32_e32 v52, 0xbfb8aa3b, v96
	v_exp_f32_e32 v55, v52
	v_pk_add_f32 v[50:51], v[50:51], 1.0 op_sel_hi:[1,0]
	s_nop 0
	v_mul_f32_e32 v50, v50, v51
	v_rcp_f32_e32 v52, v50
	v_pk_add_f32 v[50:51], v[54:55], 1.0 op_sel_hi:[1,0]
	s_nop 0
	v_mul_f32_e32 v50, v50, v51
	v_rcp_f32_e32 v50, v50
	v_mul_f32_e32 v51, v64, v92
	v_mul_f32_e32 v54, v51, v52
	v_mul_f32_e32 v51, v60, v96
	v_mul_f32_e32 v55, v51, v50
	v_mul_f32_e32 v50, 0xbfb8aa3b, v57
	v_mul_f32_e32 v51, 0xbfb8aa3b, v93
	v_exp_f32_e32 v50, v50
	v_exp_f32_e32 v51, v51
	v_mul_f32_e32 v52, 0xbfb8aa3b, v53
	v_mul_f32_e32 v53, 0xbfb8aa3b, v97
	v_exp_f32_e32 v52, v52
	v_exp_f32_e32 v53, v53
	v_pk_add_f32 v[50:51], v[50:51], 1.0 op_sel_hi:[1,0]
	v_lshlrev_b32_e32 v60, 16, v87
	v_mul_f32_e32 v50, v50, v51
	v_rcp_f32_e32 v56, v50
	v_pk_add_f32 v[50:51], v[52:53], 1.0 op_sel_hi:[1,0]
	v_mul_f32_e32 v52, v61, v97
	v_mul_f32_e32 v50, v50, v51
	v_rcp_f32_e32 v50, v50
	v_mul_f32_e32 v51, v65, v93
	v_mul_f32_e32 v51, v51, v56
	v_lshlrev_b32_e32 v56, 16, v85
	v_mul_f32_e32 v53, v52, v50
	v_cvt_pk_bf16_f32 v50, v62, v63
	v_cvt_pk_bf16_f32 v51, v54, v51
	v_cvt_pk_bf16_f32 v52, v58, v59
	v_cvt_pk_bf16_f32 v53, v55, v53
	v_lshl_add_u64 v[54:55], s[4:5], 0, v[88:89]
	v_lshl_add_u64 v[54:55], v[54:55], 0, v[144:145]
	global_store_dwordx4 v[54:55], v[50:53], off
	v_lshlrev_b32_e32 v54, 16, v84
	v_lshlrev_b32_e32 v58, 16, v86
	v_exp_f32_e32 v50, v38
	v_mul_f32_e32 v38, 0xbfb8aa3b, v54
	v_exp_f32_e32 v51, v38
	v_exp_f32_e32 v52, v34
	v_mul_f32_e32 v34, 0xbfb8aa3b, v58
	v_exp_f32_e32 v53, v34
	v_pk_add_f32 v[50:51], v[50:51], 1.0 op_sel_hi:[1,0]
	v_mul_f32_e32 v46, v46, v54
	v_mul_f32_e32 v34, v50, v51
	v_pk_add_f32 v[50:51], v[52:53], 1.0 op_sel_hi:[1,0]
	v_rcp_f32_e32 v34, v34
	v_mul_f32_e32 v38, v50, v51
	v_rcp_f32_e32 v38, v38
	v_and_b32_e32 v55, 0xffff0000, v84
	v_mul_f32_e32 v46, v46, v34
	v_mul_f32_e32 v34, v42, v58
	v_mul_f32_e32 v42, v34, v38
	v_mul_f32_e32 v34, 0xbfb8aa3b, v39
	v_and_b32_e32 v59, 0xffff0000, v86
	v_exp_f32_e32 v38, v34
	v_mul_f32_e32 v34, 0xbfb8aa3b, v55
	v_exp_f32_e32 v39, v34
	v_mul_f32_e32 v34, 0xbfb8aa3b, v35
	v_mul_f32_e32 v35, 0xbfb8aa3b, v59
	v_exp_f32_e32 v34, v34
	v_exp_f32_e32 v35, v35
	v_pk_add_f32 v[38:39], v[38:39], 1.0 op_sel_hi:[1,0]
	v_and_b32_e32 v57, 0xffff0000, v85
	v_mul_f32_e32 v38, v38, v39
	v_pk_add_f32 v[34:35], v[34:35], 1.0 op_sel_hi:[1,0]
	v_rcp_f32_e32 v38, v38
	v_mul_f32_e32 v34, v34, v35
	v_rcp_f32_e32 v34, v34
	v_mul_f32_e32 v35, v47, v55
	v_mul_f32_e32 v47, v35, v38
	v_mul_f32_e32 v35, v43, v59
	v_mul_f32_e32 v43, v35, v34
	v_mul_f32_e32 v34, 0xbfb8aa3b, v40
	v_mul_f32_e32 v35, 0xbfb8aa3b, v56
	v_exp_f32_e32 v34, v34
	v_exp_f32_e32 v35, v35
	v_exp_f32_e32 v38, v36
	v_mul_f32_e32 v36, 0xbfb8aa3b, v60
	v_exp_f32_e32 v39, v36
	v_pk_add_f32 v[34:35], v[34:35], 1.0 op_sel_hi:[1,0]
	v_and_b32_e32 v61, 0xffff0000, v87
	v_mul_f32_e32 v34, v34, v35
	v_rcp_f32_e32 v36, v34
	v_pk_add_f32 v[34:35], v[38:39], 1.0 op_sel_hi:[1,0]
	s_nop 0
	v_mul_f32_e32 v34, v34, v35
	v_rcp_f32_e32 v34, v34
	v_mul_f32_e32 v35, v48, v56
	v_mul_f32_e32 v38, v35, v36
	v_mul_f32_e32 v35, v44, v60
	v_mul_f32_e32 v39, v35, v34
	v_mul_f32_e32 v34, 0xbfb8aa3b, v41
	v_mul_f32_e32 v35, 0xbfb8aa3b, v57
	v_exp_f32_e32 v34, v34
	v_exp_f32_e32 v35, v35
	v_mul_f32_e32 v36, 0xbfb8aa3b, v37
	v_mul_f32_e32 v37, 0xbfb8aa3b, v61
	v_exp_f32_e32 v36, v36
	v_exp_f32_e32 v37, v37
	v_pk_add_f32 v[34:35], v[34:35], 1.0 op_sel_hi:[1,0]
	v_lshlrev_b32_e32 v44, 16, v73
	v_mul_f32_e32 v34, v34, v35
	v_rcp_f32_e32 v40, v34
	v_pk_add_f32 v[34:35], v[36:37], 1.0 op_sel_hi:[1,0]
	v_mul_f32_e32 v36, v45, v61
	v_mul_f32_e32 v34, v34, v35
	v_rcp_f32_e32 v34, v34
	v_mul_f32_e32 v35, v49, v57
	v_mul_f32_e32 v35, v35, v40
	v_lshlrev_b32_e32 v40, 16, v71
	v_mul_f32_e32 v37, v36, v34
	v_cvt_pk_bf16_f32 v34, v46, v47
	v_cvt_pk_bf16_f32 v35, v38, v35
	v_cvt_pk_bf16_f32 v36, v42, v43
	v_cvt_pk_bf16_f32 v37, v39, v37
	v_lshl_add_u64 v[38:39], s[4:5], 0, v[78:79]
; __device__ __forceinline__ u32x4 pack8(const float (&f)[8]) { u32x4 r; r[0] = cvt_pk_bf16(f[0], f[1]); r[1] = cvt_pk_bf16(f[2], f[3]); r[2] = cvt_pk_bf16(f[4], f[5]); r[3] = cvt_pk_bf16(f[6], f[7]); return r; }
; #define PG8_WAIT_V(n) asm volatile("s_waitcnt vmcnt(" #n ")" ::: "memory")
; #define PG8_BAR __builtin_amdgcn_s_barrier()
; template <class Sched, class Epi>
; __device__ __forceinline__ void gemm_phase(LAS unsigned char* lds, const Sched& S, const Epi& E, const int K, const int lda, const int ldb) {
;     ...
;         if (!has_next) break;
; #pragma unroll
;         for (int a = 0; a < 2; ++a)
; #pragma unroll
;             for (int b = 0; b < 2; ++b)
; #pragma unroll
;                 for (int m = 0; m < 4; ++m)
; #pragma unroll
;                     for (int n = 0; n < 2; ++n) acc[a][b][m][n] = (f32x4){0.f, 0.f, 0.f, 0.f};
;         cur = nxt; cA = nA; cB = nB; ++ui;
;     }
;     PG8_WAIT_V(0);
;     if (wr == 0) PG8_BAR;
;     __device__ __forceinline__ void operator()(EPI_ARGS) const {
;     ...
;         for (int ai = 0; ai < 2; ++ai) if (ai == 0 || !u.half) { u32x4 zz[4];
; #pragma unroll
;             for (int m = 0; m < 4; ++m) zz[m] = *(const u32x4*)(parts + E_PZB + (size_t)EPI_ROW * 1024 + col);
; #pragma unroll
;             for (int m = 0; m < 4; ++m) { float z[8]; unpack8(zz[m], z);
;                 const f32x4 a0 = acc[ai][0][m][0], a1 = acc[ai][0][m][1], b0 = acc[ai][1][m][0], b1 = acc[ai][1][m][1]; float o[8];
; #pragma unroll
;                 for (int j = 0; j < 4; ++j) { o[j] = a0[j] * z[j] * __builtin_amdgcn_rcpf((1.0f + __expf(-b0[j])) * (1.0f + __expf(-z[j]))); o[4 + j] = a1[j] * z[4 + j] * __builtin_amdgcn_rcpf((1.0f + __expf(-b1[j])) * (1.0f + __expf(-z[4 + j]))); }
;                 *(u32x4*)(O + (size_t)EPI_ROW * 1024 + col) = pack8(o); } }
	v_lshl_add_u64 v[38:39], v[38:39], 0, v[144:145]
	global_store_dwordx4 v[38:39], v[34:37], off
	v_lshlrev_b32_e32 v38, 16, v70
	v_lshlrev_b32_e32 v42, 16, v72
	v_exp_f32_e32 v34, v22
	v_mul_f32_e32 v22, 0xbfb8aa3b, v38
	v_exp_f32_e32 v35, v22
	v_exp_f32_e32 v36, v18
	v_mul_f32_e32 v18, 0xbfb8aa3b, v42
	v_exp_f32_e32 v37, v18
	v_pk_add_f32 v[34:35], v[34:35], 1.0 op_sel_hi:[1,0]
	v_mul_f32_e32 v30, v30, v38
	v_mul_f32_e32 v18, v34, v35
	v_pk_add_f32 v[34:35], v[36:37], 1.0 op_sel_hi:[1,0]
	v_rcp_f32_e32 v18, v18
	v_mul_f32_e32 v22, v34, v35
	v_rcp_f32_e32 v22, v22
	v_and_b32_e32 v39, 0xffff0000, v70
	v_mul_f32_e32 v30, v30, v18
	v_mul_f32_e32 v18, v26, v42
	v_mul_f32_e32 v26, v18, v22
	v_mul_f32_e32 v18, 0xbfb8aa3b, v23
	v_and_b32_e32 v43, 0xffff0000, v72
	v_exp_f32_e32 v22, v18
	v_mul_f32_e32 v18, 0xbfb8aa3b, v39
	v_exp_f32_e32 v23, v18
	v_mul_f32_e32 v18, 0xbfb8aa3b, v19
	v_mul_f32_e32 v19, 0xbfb8aa3b, v43
	v_exp_f32_e32 v18, v18
	v_exp_f32_e32 v19, v19
	v_pk_add_f32 v[22:23], v[22:23], 1.0 op_sel_hi:[1,0]
	v_and_b32_e32 v41, 0xffff0000, v71
	v_mul_f32_e32 v22, v22, v23
	v_pk_add_f32 v[18:19], v[18:19], 1.0 op_sel_hi:[1,0]
	v_rcp_f32_e32 v22, v22
	v_mul_f32_e32 v18, v18, v19
	v_rcp_f32_e32 v18, v18
	v_mul_f32_e32 v19, v31, v39
	v_mul_f32_e32 v31, v19, v22
	v_mul_f32_e32 v19, v27, v43
	v_mul_f32_e32 v27, v19, v18
	v_mul_f32_e32 v18, 0xbfb8aa3b, v24
	v_mul_f32_e32 v19, 0xbfb8aa3b, v40
	v_exp_f32_e32 v18, v18
	v_exp_f32_e32 v19, v19
	v_exp_f32_e32 v22, v20
	v_mul_f32_e32 v20, 0xbfb8aa3b, v44
	v_exp_f32_e32 v23, v20
	v_pk_add_f32 v[18:19], v[18:19], 1.0 op_sel_hi:[1,0]
	v_and_b32_e32 v45, 0xffff0000, v73
	v_mul_f32_e32 v18, v18, v19
	v_rcp_f32_e32 v20, v18
	v_pk_add_f32 v[18:19], v[22:23], 1.0 op_sel_hi:[1,0]
	s_nop 0
	v_mul_f32_e32 v18, v18, v19
	v_rcp_f32_e32 v18, v18
	v_mul_f32_e32 v19, v32, v40
	v_mul_f32_e32 v22, v19, v20
	v_mul_f32_e32 v19, v28, v44
	v_mul_f32_e32 v23, v19, v18
	v_mul_f32_e32 v18, 0xbfb8aa3b, v25
	v_mul_f32_e32 v19, 0xbfb8aa3b, v41
	v_exp_f32_e32 v18, v18
	v_exp_f32_e32 v19, v19
	v_mul_f32_e32 v20, 0xbfb8aa3b, v21
	v_mul_f32_e32 v21, 0xbfb8aa3b, v45
	v_exp_f32_e32 v20, v20
	v_exp_f32_e32 v21, v21
	v_pk_add_f32 v[18:19], v[18:19], 1.0 op_sel_hi:[1,0]
	v_lshlrev_b32_e32 v28, 16, v69
	v_mul_f32_e32 v18, v18, v19
	v_rcp_f32_e32 v24, v18
	v_pk_add_f32 v[18:19], v[20:21], 1.0 op_sel_hi:[1,0]
	v_mul_f32_e32 v20, v29, v45
	v_mul_f32_e32 v18, v18, v19
	v_rcp_f32_e32 v18, v18
	v_mul_f32_e32 v19, v33, v41
	v_mul_f32_e32 v19, v19, v24
	v_lshlrev_b32_e32 v24, 16, v67
	v_mul_f32_e32 v21, v20, v18
	v_cvt_pk_bf16_f32 v18, v30, v31
	v_cvt_pk_bf16_f32 v19, v22, v19
	v_cvt_pk_bf16_f32 v20, v26, v27
	v_cvt_pk_bf16_f32 v21, v23, v21
	v_lshl_add_u64 v[22:23], s[4:5], 0, v[76:77]
	v_lshl_add_u64 v[22:23], v[22:23], 0, v[144:145]
	global_store_dwordx4 v[22:23], v[18:21], off
	v_lshlrev_b32_e32 v22, 16, v66
	v_lshlrev_b32_e32 v26, 16, v68
	v_exp_f32_e32 v18, v6
	v_mul_f32_e32 v6, 0xbfb8aa3b, v22
	v_exp_f32_e32 v19, v6
	v_exp_f32_e32 v20, v2
	v_mul_f32_e32 v2, 0xbfb8aa3b, v26
	v_exp_f32_e32 v21, v2
	v_pk_add_f32 v[18:19], v[18:19], 1.0 op_sel_hi:[1,0]
	v_mul_f32_e32 v14, v14, v22
	v_mul_f32_e32 v2, v18, v19
	v_pk_add_f32 v[18:19], v[20:21], 1.0 op_sel_hi:[1,0]
	v_rcp_f32_e32 v2, v2
	v_mul_f32_e32 v6, v18, v19
	v_rcp_f32_e32 v6, v6
	v_and_b32_e32 v23, 0xffff0000, v66
	v_mul_f32_e32 v14, v14, v2
	v_mul_f32_e32 v2, v10, v26
	v_mul_f32_e32 v10, v2, v6
	v_mul_f32_e32 v2, 0xbfb8aa3b, v7
	v_and_b32_e32 v27, 0xffff0000, v68
	v_exp_f32_e32 v6, v2
	v_mul_f32_e32 v2, 0xbfb8aa3b, v23
	v_exp_f32_e32 v7, v2
	v_mul_f32_e32 v2, 0xbfb8aa3b, v3
	v_mul_f32_e32 v3, 0xbfb8aa3b, v27
	v_exp_f32_e32 v2, v2
	v_exp_f32_e32 v3, v3
	v_pk_add_f32 v[6:7], v[6:7], 1.0 op_sel_hi:[1,0]
	v_and_b32_e32 v25, 0xffff0000, v67
	v_mul_f32_e32 v6, v6, v7
	v_pk_add_f32 v[2:3], v[2:3], 1.0 op_sel_hi:[1,0]
	v_rcp_f32_e32 v6, v6
	v_mul_f32_e32 v2, v2, v3
	v_rcp_f32_e32 v2, v2
	v_mul_f32_e32 v3, v15, v23
	v_mul_f32_e32 v15, v3, v6
	v_mul_f32_e32 v3, v11, v27
	v_mul_f32_e32 v11, v3, v2
	v_mul_f32_e32 v2, 0xbfb8aa3b, v8
	v_mul_f32_e32 v3, 0xbfb8aa3b, v24
	v_exp_f32_e32 v2, v2
	v_exp_f32_e32 v3, v3
	v_exp_f32_e32 v6, v4
	v_mul_f32_e32 v4, 0xbfb8aa3b, v28
	v_exp_f32_e32 v7, v4
	v_pk_add_f32 v[2:3], v[2:3], 1.0 op_sel_hi:[1,0]
	v_and_b32_e32 v29, 0xffff0000, v69
	v_mul_f32_e32 v2, v2, v3
	v_rcp_f32_e32 v4, v2
	v_pk_add_f32 v[2:3], v[6:7], 1.0 op_sel_hi:[1,0]
	s_nop 0
	v_mul_f32_e32 v2, v2, v3
	v_rcp_f32_e32 v2, v2
	v_mul_f32_e32 v3, v16, v24
	v_mul_f32_e32 v6, v3, v4
	v_mul_f32_e32 v3, v12, v28
	v_mul_f32_e32 v7, v3, v2
	v_mul_f32_e32 v2, 0xbfb8aa3b, v9
	v_mul_f32_e32 v3, 0xbfb8aa3b, v25
	v_exp_f32_e32 v2, v2
	v_exp_f32_e32 v3, v3
	v_mul_f32_e32 v4, 0xbfb8aa3b, v5
	v_mul_f32_e32 v5, 0xbfb8aa3b, v29
	v_exp_f32_e32 v4, v4
	v_exp_f32_e32 v5, v5
	v_pk_add_f32 v[2:3], v[2:3], 1.0 op_sel_hi:[1,0]
	s_nop 0
	v_mul_f32_e32 v2, v2, v3
	v_rcp_f32_e32 v8, v2
	v_pk_add_f32 v[2:3], v[4:5], 1.0 op_sel_hi:[1,0]
	v_mul_f32_e32 v4, v13, v29
	v_mul_f32_e32 v2, v2, v3
	v_rcp_f32_e32 v2, v2
	v_mul_f32_e32 v3, v17, v25
	v_mul_f32_e32 v3, v3, v8
	v_mul_f32_e32 v5, v4, v2
	v_cvt_pk_bf16_f32 v2, v14, v15
	v_cvt_pk_bf16_f32 v3, v6, v3
	v_cvt_pk_bf16_f32 v4, v10, v11
	v_cvt_pk_bf16_f32 v5, v7, v5
	v_lshl_add_u64 v[6:7], s[4:5], 0, v[74:75]
	v_lshl_add_u64 v[6:7], v[6:7], 0, v[144:145]
	global_store_dwordx4 v[6:7], v[2:5], off
	s_cbranch_vccz .LBB0_754
	s_waitcnt vmcnt(0)
	s_cmpk_gt_u32 s2, 0xff
	s_cbranch_scc1 .LBB0_765
	s_barrier

; #define PG8_STAGE(bufoff, gbase, voff) do { _Pragma("unroll") for (int _i = 0; _i < 2; ++_i) \
;         __builtin_amdgcn_global_load_lds((const unsigned*)((const char*)(gbase) + (voff)[_i]), (LAS unsigned*)(lds + (bufoff) + ldsw + _i * 8192), 16, 0, 0); } while (0)
; #define PG8_LDA(dst, b, h) do { _Pragma("unroll") for (int m = 0; m < 4; ++m) _Pragma("unroll") for (int k = 0; k < 2; ++k) dst[m][k] = *(const LAS bf16x8*)(lds + PG8_SA(b, h) + aoff + m * 2048 + k * 1024); } while (0)
; #define PG8_LDB(dst, b, h) do { _Pragma("unroll") for (int n = 0; n < 2; ++n) _Pragma("unroll") for (int k = 0; k < 2; ++k) dst[n][k] = *(const LAS bf16x8*)(lds + PG8_SB(b, h) + boff + n * 2048 + k * 1024); } while (0)
; #define PG8_MMA(ai, bj, At, Bt) do { __builtin_amdgcn_s_setprio(1); _Pragma("unroll") for (int m = 0; m < 4; ++m) _Pragma("unroll") for (int n = 0; n < 2; ++n) _Pragma("unroll") for (int k = 0; k < 2; ++k) \
;         acc[ai][bj][m][n] = __builtin_amdgcn_mfma_f32_16x16x32_bf16(Bt[n][k], At[m][k], acc[ai][bj][m][n], 0, 0, 0); __builtin_amdgcn_s_setprio(0); } while (0)
; #define PG8_WAIT_V(n) asm volatile("s_waitcnt vmcnt(" #n ")" ::: "memory")
; #define PG8_WAIT_L(n) asm volatile("s_waitcnt lgkmcnt(" #n ")" ::: "memory")
; #define PG8_BAR __builtin_amdgcn_s_barrier()
; #define PG8_SCHED __builtin_amdgcn_sched_barrier(0)
; template <class Sched, class Epi>
; __device__ __forceinline__ void gemm_phase(LAS unsigned char* lds, const Sched& S, const Epi& E, const int K, const int lda, const int ldb) {
;     ...
;             PG8_LDB(B0, 0, 0); PG8_SCHED; PG8_LDA(At, 0, 0); PG8_STAGE(PG8_SA(1, 1), a1 + hstepA, voffA);
;             PG8_WAIT_L(8); PG8_BAR; PG8_WAIT_L(0); PG8_MMA(0, 0, At, B0); PG8_BAR; PG8_SCHED;
;             PG8_LDB(B1, 0, 1); PG8_STAGE(PG8_SB(0, 0), b2, voffB);
;             PG8_BAR; PG8_WAIT_L(0); PG8_MMA(0, 1, At, B1); PG8_BAR;
;             PG8_LDA(At, 0, 1); PG8_STAGE(PG8_SA(0, 0), a2, voffA);
;             PG8_BAR; PG8_WAIT_L(0); if (!chalf) PG8_MMA(1, 0, At, B0); PG8_BAR; PG8_SCHED;
;             PG8_STAGE(PG8_SB(0, 1), b2 + hstepB, voffB);
;             PG8_WAIT_V(6); PG8_BAR; if (!chalf) PG8_MMA(1, 1, At, B1); PG8_BAR;
.LBB0_842:
	ds_read_b128 v[130:133], v233
	ds_read_b128 v[134:137], v233 offset:1024
	ds_read_b128 v[138:141], v233 offset:2048
	ds_read_b128 v[142:145], v233 offset:3072
	s_add_u32 s28, s6, 0xfffc0080
	s_addc_u32 s29, s7, -1
	s_cmp_eq_u32 s21, 12
	s_cselect_b32 s35, s23, s29
	s_cselect_b32 s34, s22, s28
	s_cselect_b32 s29, s25, s19
	s_cselect_b32 s28, s24, s17
	s_add_i32 m0, s31, 0xc000
	ds_read_b128 v[146:149], v234
	ds_read_b128 v[150:153], v234 offset:1024
	ds_read_b128 v[154:157], v234 offset:2048
	ds_read_b128 v[158:161], v234 offset:3072
	ds_read_b128 v[162:165], v234 offset:4096
	ds_read_b128 v[166:169], v234 offset:5120
	ds_read_b128 v[170:173], v234 offset:6144
	ds_read_b128 v[174:177], v234 offset:7168
	global_load_lds_dwordx4 v208, s[6:7]
	s_add_i32 m0, s31, 0xe000
	s_nop 0
	global_load_lds_dwordx4 v206, s[6:7]
	s_waitcnt lgkmcnt(8)
	s_barrier
	s_waitcnt lgkmcnt(0)
	s_setprio 1
	s_waitcnt lgkmcnt(0)
	v_mfma_f32_16x16x32_bf16 v[126:129], v[130:133], v[146:149], v[126:129]
	v_mfma_f32_16x16x32_bf16 v[122:125], v[138:141], v[146:149], v[122:125]
	v_mfma_f32_16x16x32_bf16 v[118:121], v[130:133], v[154:157], v[118:121]
	v_mfma_f32_16x16x32_bf16 v[114:117], v[138:141], v[154:157], v[114:117]
	v_mfma_f32_16x16x32_bf16 v[110:113], v[130:133], v[162:165], v[110:113]
	v_mfma_f32_16x16x32_bf16 v[106:109], v[138:141], v[162:165], v[106:109]
	v_mfma_f32_16x16x32_bf16 v[102:105], v[130:133], v[170:173], v[102:105]
	v_mfma_f32_16x16x32_bf16 v[98:101], v[138:141], v[170:173], v[98:101]
	v_mfma_f32_16x16x32_bf16 v[126:129], v[134:137], v[150:153], v[126:129]
	v_mfma_f32_16x16x32_bf16 v[122:125], v[142:145], v[150:153], v[122:125]
	v_mfma_f32_16x16x32_bf16 v[118:121], v[134:137], v[158:161], v[118:121]
	v_mfma_f32_16x16x32_bf16 v[114:117], v[142:145], v[158:161], v[114:117]
	v_mfma_f32_16x16x32_bf16 v[110:113], v[134:137], v[166:169], v[110:113]
	v_mfma_f32_16x16x32_bf16 v[106:109], v[142:145], v[166:169], v[106:109]
	v_mfma_f32_16x16x32_bf16 v[102:105], v[134:137], v[174:177], v[102:105]
	v_mfma_f32_16x16x32_bf16 v[98:101], v[142:145], v[174:177], v[98:101]
	s_setprio 0
	s_barrier
	s_add_i32 s49, s43, s27
	v_lshl_add_u64 v[194:195], s[28:29], 0, v[200:201]
	s_mov_b32 m0, s49
	ds_read_b128 v[178:181], v235
	ds_read_b128 v[182:185], v235 offset:1024
	ds_read_b128 v[186:189], v235 offset:2048
	ds_read_b128 v[190:193], v235 offset:3072
	global_load_lds_dwordx4 v[194:195], off
	v_lshl_add_u64 v[196:197], s[28:29], 0, v[204:205]
	s_add_i32 m0, s49, 0x2000
	s_nop 0
	global_load_lds_dwordx4 v[196:197], off
	s_barrier
	s_waitcnt lgkmcnt(0)
	s_setprio 1
	s_waitcnt lgkmcnt(0)
	v_mfma_f32_16x16x32_bf16 v[94:97], v[178:181], v[146:149], v[94:97]
	v_mfma_f32_16x16x32_bf16 v[90:93], v[186:189], v[146:149], v[90:93]
	v_mfma_f32_16x16x32_bf16 v[86:89], v[178:181], v[154:157], v[86:89]
	v_mfma_f32_16x16x32_bf16 v[82:85], v[186:189], v[154:157], v[82:85]
	v_mfma_f32_16x16x32_bf16 v[78:81], v[178:181], v[162:165], v[78:81]
	v_mfma_f32_16x16x32_bf16 v[74:77], v[186:189], v[162:165], v[74:77]
	v_mfma_f32_16x16x32_bf16 v[70:73], v[178:181], v[170:173], v[70:73]
	v_mfma_f32_16x16x32_bf16 v[66:69], v[186:189], v[170:173], v[66:69]
	v_mfma_f32_16x16x32_bf16 v[94:97], v[182:185], v[150:153], v[94:97]
	v_mfma_f32_16x16x32_bf16 v[90:93], v[190:193], v[150:153], v[90:93]
	v_mfma_f32_16x16x32_bf16 v[86:89], v[182:185], v[158:161], v[86:89]
	v_mfma_f32_16x16x32_bf16 v[82:85], v[190:193], v[158:161], v[82:85]
	v_mfma_f32_16x16x32_bf16 v[78:81], v[182:185], v[166:169], v[78:81]
	v_mfma_f32_16x16x32_bf16 v[74:77], v[190:193], v[166:169], v[74:77]
	v_mfma_f32_16x16x32_bf16 v[70:73], v[182:185], v[174:177], v[70:73]
	v_mfma_f32_16x16x32_bf16 v[66:69], v[190:193], v[174:177], v[66:69]
	s_setprio 0
	s_mov_b32 m0, s31
	v_lshl_add_u64 v[212:213], s[34:35], 0, v[198:199]
	s_barrier
	ds_read_b128 v[146:149], v234 offset:16384
	ds_read_b128 v[150:153], v234 offset:17408
	ds_read_b128 v[154:157], v234 offset:18432
	ds_read_b128 v[158:161], v234 offset:19456
	ds_read_b128 v[162:165], v234 offset:20480
	ds_read_b128 v[166:169], v234 offset:21504
	ds_read_b128 v[170:173], v234 offset:22528
	ds_read_b128 v[174:177], v234 offset:23552
	global_load_lds_dwordx4 v[212:213], off
	v_lshl_add_u64 v[214:215], s[34:35], 0, v[202:203]
	s_mov_b32 m0, s33
	s_nop 0
	global_load_lds_dwordx4 v[214:215], off
	s_barrier
	s_waitcnt lgkmcnt(0)
	s_setprio 1
	s_waitcnt lgkmcnt(0)
	v_mfma_f32_16x16x32_bf16 v[62:65], v[130:133], v[146:149], v[62:65]
	v_mfma_f32_16x16x32_bf16 v[58:61], v[138:141], v[146:149], v[58:61]
	v_mfma_f32_16x16x32_bf16 v[54:57], v[130:133], v[154:157], v[54:57]
	v_mfma_f32_16x16x32_bf16 v[50:53], v[138:141], v[154:157], v[50:53]
	v_mfma_f32_16x16x32_bf16 v[46:49], v[130:133], v[162:165], v[46:49]
	v_mfma_f32_16x16x32_bf16 v[42:45], v[138:141], v[162:165], v[42:45]
	v_mfma_f32_16x16x32_bf16 v[38:41], v[130:133], v[170:173], v[38:41]
	v_mfma_f32_16x16x32_bf16 v[34:37], v[138:141], v[170:173], v[34:37]
	v_mfma_f32_16x16x32_bf16 v[62:65], v[134:137], v[150:153], v[62:65]
	v_mfma_f32_16x16x32_bf16 v[58:61], v[142:145], v[150:153], v[58:61]
	v_mfma_f32_16x16x32_bf16 v[54:57], v[134:137], v[158:161], v[54:57]
	v_mfma_f32_16x16x32_bf16 v[50:53], v[142:145], v[158:161], v[50:53]
	v_mfma_f32_16x16x32_bf16 v[46:49], v[134:137], v[166:169], v[46:49]
	v_mfma_f32_16x16x32_bf16 v[42:45], v[142:145], v[166:169], v[42:45]
	v_mfma_f32_16x16x32_bf16 v[38:41], v[134:137], v[174:177], v[38:41]
	v_mfma_f32_16x16x32_bf16 v[34:37], v[142:145], v[174:177], v[34:37]
	s_setprio 0
	s_barrier
; #define PG8_STAGE(bufoff, gbase, voff) do { _Pragma("unroll") for (int _i = 0; _i < 2; ++_i) \
;         __builtin_amdgcn_global_load_lds((const unsigned*)((const char*)(gbase) + (voff)[_i]), (LAS unsigned*)(lds + (bufoff) + ldsw + _i * 8192), 16, 0, 0); } while (0)
; #define PG8_LDA(dst, b, h) do { _Pragma("unroll") for (int m = 0; m < 4; ++m) _Pragma("unroll") for (int k = 0; k < 2; ++k) dst[m][k] = *(const LAS bf16x8*)(lds + PG8_SA(b, h) + aoff + m * 2048 + k * 1024); } while (0)
; #define PG8_LDB(dst, b, h) do { _Pragma("unroll") for (int n = 0; n < 2; ++n) _Pragma("unroll") for (int k = 0; k < 2; ++k) dst[n][k] = *(const LAS bf16x8*)(lds + PG8_SB(b, h) + boff + n * 2048 + k * 1024); } while (0)
; #define PG8_MMA(ai, bj, At, Bt) do { __builtin_amdgcn_s_setprio(1); _Pragma("unroll") for (int m = 0; m < 4; ++m) _Pragma("unroll") for (int n = 0; n < 2; ++n) _Pragma("unroll") for (int k = 0; k < 2; ++k) \
;         acc[ai][bj][m][n] = __builtin_amdgcn_mfma_f32_16x16x32_bf16(Bt[n][k], At[m][k], acc[ai][bj][m][n], 0, 0, 0); __builtin_amdgcn_s_setprio(0); } while (0)
; #define PG8_WAIT_V(n) asm volatile("s_waitcnt vmcnt(" #n ")" ::: "memory")
; #define PG8_WAIT_L(n) asm volatile("s_waitcnt lgkmcnt(" #n ")" ::: "memory")
; #define PG8_BAR __builtin_amdgcn_s_barrier()
; #define PG8_SCHED __builtin_amdgcn_sched_barrier(0)
; template <class Sched, class Epi>
; __device__ __forceinline__ void gemm_phase(LAS unsigned char* lds, const Sched& S, const Epi& E, const int K, const int lda, const int ldb) {
;     ...
;             PG8_STAGE(PG8_SB(0, 1), b2 + hstepB, voffB);
;             PG8_WAIT_V(6); PG8_BAR; if (!chalf) PG8_MMA(1, 1, At, B1); PG8_BAR;
;             PG8_LDB(B0, 1, 0); PG8_SCHED; PG8_LDA(At, 1, 0); PG8_STAGE(PG8_SA(0, 1), a2 + hstepA, voffA);
;             PG8_WAIT_L(8); PG8_BAR; PG8_WAIT_L(0); PG8_MMA(0, 0, At, B0); PG8_BAR; PG8_SCHED;
;             PG8_LDB(B1, 1, 1); PG8_STAGE(PG8_SB(1, 0), b3, voffB);
;             PG8_BAR; PG8_WAIT_L(0); PG8_MMA(0, 1, At, B1); PG8_BAR;
;             PG8_LDA(At, 1, 1); PG8_STAGE(PG8_SA(1, 0), a3, voffA);
;             PG8_BAR; PG8_WAIT_L(0); if (!chalf) PG8_MMA(1, 0, At, B0); PG8_BAR; PG8_SCHED;
	s_add_u32 s50, s28, 0x40000
	s_addc_u32 s51, s29, 0
	s_add_i32 s49, s44, s27
	s_mov_b32 m0, s49
	s_nop 0
	global_load_lds_dwordx4 v200, s[50:51]
	s_add_i32 m0, s49, 0x2000
	s_nop 0
	global_load_lds_dwordx4 v204, s[50:51]
	s_waitcnt vmcnt(6)
	s_barrier
	s_setprio 1
	v_mfma_f32_16x16x32_bf16 v[30:33], v[178:181], v[146:149], v[30:33]
	v_mfma_f32_16x16x32_bf16 v[26:29], v[186:189], v[146:149], v[26:29]
	v_mfma_f32_16x16x32_bf16 v[22:25], v[178:181], v[154:157], v[22:25]
	v_mfma_f32_16x16x32_bf16 v[18:21], v[186:189], v[154:157], v[18:21]
	v_mfma_f32_16x16x32_bf16 v[14:17], v[178:181], v[162:165], v[14:17]
	v_mfma_f32_16x16x32_bf16 v[10:13], v[186:189], v[162:165], v[10:13]
	v_mfma_f32_16x16x32_bf16 v[6:9], v[178:181], v[170:173], v[6:9]
	v_mfma_f32_16x16x32_bf16 v[2:5], v[186:189], v[170:173], v[2:5]
	v_mfma_f32_16x16x32_bf16 v[30:33], v[182:185], v[150:153], v[30:33]
	v_mfma_f32_16x16x32_bf16 v[26:29], v[190:193], v[150:153], v[26:29]
	v_mfma_f32_16x16x32_bf16 v[22:25], v[182:185], v[158:161], v[22:25]
	v_mfma_f32_16x16x32_bf16 v[18:21], v[190:193], v[158:161], v[18:21]
	v_mfma_f32_16x16x32_bf16 v[14:17], v[182:185], v[166:169], v[14:17]
	v_mfma_f32_16x16x32_bf16 v[10:13], v[190:193], v[166:169], v[10:13]
	v_mfma_f32_16x16x32_bf16 v[6:9], v[182:185], v[174:177], v[6:9]
	v_mfma_f32_16x16x32_bf16 v[2:5], v[190:193], v[174:177], v[2:5]
	s_setprio 0
	s_add_i32 s49, 16, 0x18000
	v_add_u32_e32 v142, s49, v224
	s_barrier
	ds_read_b128 v[130:133], v142
	ds_read_b128 v[134:137], v142 offset:1024
	ds_read_b128 v[138:141], v142 offset:2048
	ds_read_b128 v[142:145], v142 offset:3072
	s_add_u32 s34, s34, 0x40000
	s_addc_u32 s35, s35, 0
	s_mov_b32 m0, s36
	ds_read_b128 v[146:149], v234 offset:32768
	ds_read_b128 v[150:153], v234 offset:33792
	ds_read_b128 v[154:157], v234 offset:34816
	ds_read_b128 v[158:161], v234 offset:35840
	ds_read_b128 v[162:165], v234 offset:36864
	ds_read_b128 v[166:169], v234 offset:37888
	ds_read_b128 v[170:173], v234 offset:38912
	ds_read_b128 v[174:177], v234 offset:39936
	global_load_lds_dwordx4 v198, s[34:35]
	s_mov_b32 m0, s37
	s_nop 0
	global_load_lds_dwordx4 v202, s[34:35]
	s_waitcnt lgkmcnt(8)
	s_barrier
	s_waitcnt lgkmcnt(0)
	s_setprio 1
	s_waitcnt lgkmcnt(0)
	v_mfma_f32_16x16x32_bf16 v[126:129], v[130:133], v[146:149], v[126:129]
	v_mfma_f32_16x16x32_bf16 v[122:125], v[138:141], v[146:149], v[122:125]
	v_mfma_f32_16x16x32_bf16 v[118:121], v[130:133], v[154:157], v[118:121]
	v_mfma_f32_16x16x32_bf16 v[114:117], v[138:141], v[154:157], v[114:117]
	v_mfma_f32_16x16x32_bf16 v[110:113], v[130:133], v[162:165], v[110:113]
	v_mfma_f32_16x16x32_bf16 v[106:109], v[138:141], v[162:165], v[106:109]
	v_mfma_f32_16x16x32_bf16 v[102:105], v[130:133], v[170:173], v[102:105]
	v_mfma_f32_16x16x32_bf16 v[98:101], v[138:141], v[170:173], v[98:101]
	v_mfma_f32_16x16x32_bf16 v[126:129], v[134:137], v[150:153], v[126:129]
	v_mfma_f32_16x16x32_bf16 v[122:125], v[142:145], v[150:153], v[122:125]
	v_mfma_f32_16x16x32_bf16 v[118:121], v[134:137], v[158:161], v[118:121]
	v_mfma_f32_16x16x32_bf16 v[114:117], v[142:145], v[158:161], v[114:117]
	v_mfma_f32_16x16x32_bf16 v[110:113], v[134:137], v[166:169], v[110:113]
	v_mfma_f32_16x16x32_bf16 v[106:109], v[142:145], v[166:169], v[106:109]
	v_mfma_f32_16x16x32_bf16 v[102:105], v[134:137], v[174:177], v[102:105]
	v_mfma_f32_16x16x32_bf16 v[98:101], v[142:145], v[174:177], v[98:101]
	s_setprio 0
	s_barrier
	s_add_i32 s34, 16, 0x1c000
	s_add_i32 s35, s49, s27
	v_add_u32_e32 v190, s34, v224
	v_lshl_add_u64 v[194:195], v[194:195], 0, s[14:15]
	s_mov_b32 m0, s35
	ds_read_b128 v[178:181], v190
	ds_read_b128 v[182:185], v190 offset:1024
	ds_read_b128 v[186:189], v190 offset:2048
	ds_read_b128 v[190:193], v190 offset:3072
	global_load_lds_dwordx4 v[194:195], off
	v_lshl_add_u64 v[194:195], v[196:197], 0, s[14:15]
	s_add_i32 m0, s35, 0x2000
	s_nop 0
	global_load_lds_dwordx4 v[194:195], off
	s_barrier
	s_waitcnt lgkmcnt(0)
	s_setprio 1
	s_waitcnt lgkmcnt(0)
	v_mfma_f32_16x16x32_bf16 v[94:97], v[178:181], v[146:149], v[94:97]
	v_mfma_f32_16x16x32_bf16 v[90:93], v[186:189], v[146:149], v[90:93]
	v_mfma_f32_16x16x32_bf16 v[86:89], v[178:181], v[154:157], v[86:89]
	v_mfma_f32_16x16x32_bf16 v[82:85], v[186:189], v[154:157], v[82:85]
	v_mfma_f32_16x16x32_bf16 v[78:81], v[178:181], v[162:165], v[78:81]
	v_mfma_f32_16x16x32_bf16 v[74:77], v[186:189], v[162:165], v[74:77]
	v_mfma_f32_16x16x32_bf16 v[70:73], v[178:181], v[170:173], v[70:73]
	v_mfma_f32_16x16x32_bf16 v[66:69], v[186:189], v[170:173], v[66:69]
	v_mfma_f32_16x16x32_bf16 v[94:97], v[182:185], v[150:153], v[94:97]
	v_mfma_f32_16x16x32_bf16 v[90:93], v[190:193], v[150:153], v[90:93]
	v_mfma_f32_16x16x32_bf16 v[86:89], v[182:185], v[158:161], v[86:89]
	v_mfma_f32_16x16x32_bf16 v[82:85], v[190:193], v[158:161], v[82:85]
	v_mfma_f32_16x16x32_bf16 v[78:81], v[182:185], v[166:169], v[78:81]
	v_mfma_f32_16x16x32_bf16 v[74:77], v[190:193], v[166:169], v[74:77]
	v_mfma_f32_16x16x32_bf16 v[70:73], v[182:185], v[174:177], v[70:73]
	v_mfma_f32_16x16x32_bf16 v[66:69], v[190:193], v[174:177], v[66:69]
	s_setprio 0
	s_mov_b32 m0, s39
	v_lshl_add_u64 v[194:195], v[212:213], 0, s[14:15]
	s_barrier
; #define PG8_STAGE(bufoff, gbase, voff) do { _Pragma("unroll") for (int _i = 0; _i < 2; ++_i) \
;         __builtin_amdgcn_global_load_lds((const unsigned*)((const char*)(gbase) + (voff)[_i]), (LAS unsigned*)(lds + (bufoff) + ldsw + _i * 8192), 16, 0, 0); } while (0)
; #define PG8_MMA(ai, bj, At, Bt) do { __builtin_amdgcn_s_setprio(1); _Pragma("unroll") for (int m = 0; m < 4; ++m) _Pragma("unroll") for (int n = 0; n < 2; ++n) _Pragma("unroll") for (int k = 0; k < 2; ++k) \
;         acc[ai][bj][m][n] = __builtin_amdgcn_mfma_f32_16x16x32_bf16(Bt[n][k], At[m][k], acc[ai][bj][m][n], 0, 0, 0); __builtin_amdgcn_s_setprio(0); } while (0)
; #define PG8_WAIT_V(n) asm volatile("s_waitcnt vmcnt(" #n ")" ::: "memory")
; #define PG8_WAIT_L(n) asm volatile("s_waitcnt lgkmcnt(" #n ")" ::: "memory")
; #define PG8_BAR __builtin_amdgcn_s_barrier()
; #define PG8_SCHED __builtin_amdgcn_sched_barrier(0)
; template <class Sched, class Epi>
; __device__ __forceinline__ void gemm_phase(LAS unsigned char* lds, const Sched& S, const Epi& E, const int K, const int lda, const int ldb) {
;     ...
;             PG8_BAR; PG8_WAIT_L(0); if (!chalf) PG8_MMA(1, 0, At, B0); PG8_BAR; PG8_SCHED;
;             PG8_STAGE(PG8_SB(1, 1), b3 + hstepB, voffB);
;             PG8_WAIT_V(6); PG8_BAR; if (!chalf) PG8_MMA(1, 1, At, B1); PG8_BAR;
;         }
	ds_read_b128 v[146:149], v234 offset:49152
	ds_read_b128 v[150:153], v234 offset:50176
	ds_read_b128 v[154:157], v234 offset:51200
	ds_read_b128 v[158:161], v234 offset:52224
	ds_read_b128 v[162:165], v234 offset:53248
	ds_read_b128 v[166:169], v234 offset:54272
	ds_read_b128 v[170:173], v234 offset:55296
	ds_read_b128 v[174:177], v234 offset:56320
	global_load_lds_dwordx4 v[194:195], off
	v_lshl_add_u64 v[194:195], v[214:215], 0, s[14:15]
	s_mov_b32 m0, s40
	s_nop 0
	global_load_lds_dwordx4 v[194:195], off
	s_barrier
	s_waitcnt lgkmcnt(0)
	s_setprio 1
	s_waitcnt lgkmcnt(0)
	v_mfma_f32_16x16x32_bf16 v[62:65], v[130:133], v[146:149], v[62:65]
	v_mfma_f32_16x16x32_bf16 v[58:61], v[138:141], v[146:149], v[58:61]
	v_mfma_f32_16x16x32_bf16 v[54:57], v[130:133], v[154:157], v[54:57]
	v_mfma_f32_16x16x32_bf16 v[50:53], v[138:141], v[154:157], v[50:53]
	v_mfma_f32_16x16x32_bf16 v[46:49], v[130:133], v[162:165], v[46:49]
	v_mfma_f32_16x16x32_bf16 v[42:45], v[138:141], v[162:165], v[42:45]
	v_mfma_f32_16x16x32_bf16 v[38:41], v[130:133], v[170:173], v[38:41]
	v_mfma_f32_16x16x32_bf16 v[34:37], v[138:141], v[170:173], v[34:37]
	v_mfma_f32_16x16x32_bf16 v[62:65], v[134:137], v[150:153], v[62:65]
	v_mfma_f32_16x16x32_bf16 v[58:61], v[142:145], v[150:153], v[58:61]
	v_mfma_f32_16x16x32_bf16 v[54:57], v[134:137], v[158:161], v[54:57]
	v_mfma_f32_16x16x32_bf16 v[50:53], v[142:145], v[158:161], v[50:53]
	v_mfma_f32_16x16x32_bf16 v[46:49], v[134:137], v[166:169], v[46:49]
	v_mfma_f32_16x16x32_bf16 v[42:45], v[142:145], v[166:169], v[42:45]
	v_mfma_f32_16x16x32_bf16 v[38:41], v[134:137], v[174:177], v[38:41]
	v_mfma_f32_16x16x32_bf16 v[34:37], v[142:145], v[174:177], v[34:37]
	s_setprio 0
	s_barrier
	s_add_u32 s28, s28, 0x40080
	s_addc_u32 s29, s29, 0
	s_add_i32 s34, s34, s27
	s_mov_b32 m0, s34
	s_nop 0
	global_load_lds_dwordx4 v200, s[28:29]
	s_add_i32 m0, s34, 0x2000
	s_nop 0
	global_load_lds_dwordx4 v204, s[28:29]
	s_waitcnt vmcnt(6)
	s_barrier
	s_setprio 1
	v_mfma_f32_16x16x32_bf16 v[30:33], v[178:181], v[146:149], v[30:33]
	v_mfma_f32_16x16x32_bf16 v[26:29], v[186:189], v[146:149], v[26:29]
	v_mfma_f32_16x16x32_bf16 v[22:25], v[178:181], v[154:157], v[22:25]
	v_mfma_f32_16x16x32_bf16 v[18:21], v[186:189], v[154:157], v[18:21]
	v_mfma_f32_16x16x32_bf16 v[14:17], v[178:181], v[162:165], v[14:17]
	v_mfma_f32_16x16x32_bf16 v[10:13], v[186:189], v[162:165], v[10:13]
	v_mfma_f32_16x16x32_bf16 v[6:9], v[178:181], v[170:173], v[6:9]
	v_mfma_f32_16x16x32_bf16 v[2:5], v[186:189], v[170:173], v[2:5]
	v_mfma_f32_16x16x32_bf16 v[30:33], v[182:185], v[150:153], v[30:33]
	v_mfma_f32_16x16x32_bf16 v[26:29], v[190:193], v[150:153], v[26:29]
	v_mfma_f32_16x16x32_bf16 v[22:25], v[182:185], v[158:161], v[22:25]
	v_mfma_f32_16x16x32_bf16 v[18:21], v[190:193], v[158:161], v[18:21]
	v_mfma_f32_16x16x32_bf16 v[14:17], v[182:185], v[166:169], v[14:17]
	v_mfma_f32_16x16x32_bf16 v[10:13], v[190:193], v[166:169], v[10:13]
	v_mfma_f32_16x16x32_bf16 v[6:9], v[182:185], v[174:177], v[6:9]
	v_mfma_f32_16x16x32_bf16 v[2:5], v[190:193], v[174:177], v[2:5]
	s_setprio 0
	s_add_i32 s21, s21, 2
	s_add_u32 s17, s17, 0x100
	s_addc_u32 s19, s19, 0
	s_add_u32 s6, s6, 0x100
	s_addc_u32 s7, s7, 0
	s_cmp_gt_u32 s21, 13
	s_barrier
	s_cbranch_scc0 .LBB0_842
	s_lshl_b32 s6, s48, 11
	s_ashr_i32 s7, s6, 31
	s_lshl_b64 s[28:29], s[6:7], 1
	v_lshl_or_b32 v134, s47, 8, v232
	s_add_u32 s6, s41, s28
	v_ashrrev_i32_e32 v135, 31, v134
	s_addc_u32 s7, s42, s29
	v_lshlrev_b64 v[212:213], 1, v[134:135]
	v_add_u32_e32 v130, s26, v1
	v_lshl_add_u64 v[216:217], s[6:7], 0, v[212:213]
	v_mad_i64_i32 v[132:133], s[6:7], v130, s45, v[216:217]
	global_load_dwordx4 v[194:197], v[132:133], off
	v_ashrrev_i32_e32 v131, 31, v130
	s_cmp_gt_i32 s48, 0
	v_lshl_add_u64 v[218:219], s[12:13], 0, v[212:213]
	v_lshlrev_b64 v[132:133], 12, v[130:131]
	s_cselect_b64 s[34:35], -1, 0
	s_cmp_lt_i32 s48, 1
	v_lshl_add_u64 v[136:137], v[218:219], 0, v[132:133]
	s_cbranch_scc1 .LBB0_845
	global_load_dwordx4 v[190:193], v[136:137], off
	s_branch .LBB0_846

; #define PG8_STAGE(bufoff, gbase, voff) do { _Pragma("unroll") for (int _i = 0; _i < 2; ++_i) \
;         __builtin_amdgcn_global_load_lds((const unsigned*)((const char*)(gbase) + (voff)[_i]), (LAS unsigned*)(lds + (bufoff) + ldsw + _i * 8192), 16, 0, 0); } while (0)
; #define PG8_LDA(dst, b, h) do { _Pragma("unroll") for (int m = 0; m < 4; ++m) _Pragma("unroll") for (int k = 0; k < 2; ++k) dst[m][k] = *(const LAS bf16x8*)(lds + PG8_SA(b, h) + aoff + m * 2048 + k * 1024); } while (0)
; #define PG8_LDB(dst, b, h) do { _Pragma("unroll") for (int n = 0; n < 2; ++n) _Pragma("unroll") for (int k = 0; k < 2; ++k) dst[n][k] = *(const LAS bf16x8*)(lds + PG8_SB(b, h) + boff + n * 2048 + k * 1024); } while (0)
; #define PG8_MMA(ai, bj, At, Bt) do { __builtin_amdgcn_s_setprio(1); _Pragma("unroll") for (int m = 0; m < 4; ++m) _Pragma("unroll") for (int n = 0; n < 2; ++n) _Pragma("unroll") for (int k = 0; k < 2; ++k) \
;         acc[ai][bj][m][n] = __builtin_amdgcn_mfma_f32_16x16x32_bf16(Bt[n][k], At[m][k], acc[ai][bj][m][n], 0, 0, 0); __builtin_amdgcn_s_setprio(0); } while (0)
; #define PG8_WAIT_V(n) asm volatile("s_waitcnt vmcnt(" #n ")" ::: "memory")
; #define PG8_WAIT_L(n) asm volatile("s_waitcnt lgkmcnt(" #n ")" ::: "memory")
; #define PG8_BAR __builtin_amdgcn_s_barrier()
; #define PG8_SCHED __builtin_amdgcn_sched_barrier(0)
; template <class Sched, class Epi>
; __device__ __forceinline__ void gemm_phase(LAS unsigned char* lds, const Sched& S, const Epi& E, const int K, const int lda, const int ldb) {
;     ...
;             PG8_LDB(B0, 0, 0); PG8_SCHED; PG8_LDA(At, 0, 0); PG8_STAGE(PG8_SA(1, 1), a1 + hstepA, voffA);
;             PG8_WAIT_L(8); PG8_BAR; PG8_WAIT_L(0); PG8_MMA(0, 0, At, B0); PG8_BAR; PG8_SCHED;
;             PG8_LDB(B1, 0, 1); PG8_STAGE(PG8_SB(0, 0), b2, voffB);
;             PG8_BAR; PG8_WAIT_L(0); PG8_MMA(0, 1, At, B1); PG8_BAR;
;             PG8_LDA(At, 0, 1); PG8_STAGE(PG8_SA(0, 0), a2, voffA);
;             PG8_BAR; PG8_WAIT_L(0); if (!chalf) PG8_MMA(1, 0, At, B0); PG8_BAR; PG8_SCHED;
;             PG8_STAGE(PG8_SB(0, 1), b2 + hstepB, voffB);
;             PG8_WAIT_V(6); PG8_BAR; if (!chalf) PG8_MMA(1, 1, At, B1); PG8_BAR;
.LBB0_957:
	ds_read_b128 v[156:159], v153
	ds_read_b128 v[160:163], v153 offset:1024
	ds_read_b128 v[164:167], v153 offset:2048
	ds_read_b128 v[168:171], v153 offset:3072
	s_add_u32 s28, s26, 0xfff80080
	s_addc_u32 s29, s27, -1
	s_cmp_eq_u32 s46, 28
	s_cselect_b32 s35, s23, s29
	s_cselect_b32 s34, s22, s28
	s_cselect_b32 s29, s25, s17
	s_cselect_b32 s28, s24, s15
	s_add_i32 m0, s5, 0xc000
	ds_read_b128 v[172:175], v154
	ds_read_b128 v[176:179], v154 offset:1024
	ds_read_b128 v[180:183], v154 offset:2048
	ds_read_b128 v[184:187], v154 offset:3072
	ds_read_b128 v[188:191], v154 offset:4096
	ds_read_b128 v[192:195], v154 offset:5120
	ds_read_b128 v[196:199], v154 offset:6144
	ds_read_b128 v[200:203], v154 offset:7168
	global_load_lds_dwordx4 v140, s[26:27]
	s_add_i32 m0, s5, 0xe000
	s_nop 0
	global_load_lds_dwordx4 v138, s[26:27]
	s_waitcnt lgkmcnt(8)
	s_barrier
	s_waitcnt lgkmcnt(0)
	s_setprio 1
	s_waitcnt lgkmcnt(0)
	v_mfma_f32_16x16x32_bf16 v[126:129], v[156:159], v[172:175], v[126:129]
	v_mfma_f32_16x16x32_bf16 v[122:125], v[164:167], v[172:175], v[122:125]
	v_mfma_f32_16x16x32_bf16 v[114:117], v[156:159], v[180:183], v[114:117]
	v_mfma_f32_16x16x32_bf16 v[106:109], v[164:167], v[180:183], v[106:109]
	v_mfma_f32_16x16x32_bf16 v[98:101], v[156:159], v[188:191], v[98:101]
	v_mfma_f32_16x16x32_bf16 v[90:93], v[164:167], v[188:191], v[90:93]
	v_mfma_f32_16x16x32_bf16 v[82:85], v[156:159], v[196:199], v[82:85]
	v_mfma_f32_16x16x32_bf16 v[74:77], v[164:167], v[196:199], v[74:77]
	v_mfma_f32_16x16x32_bf16 v[126:129], v[160:163], v[176:179], v[126:129]
	v_mfma_f32_16x16x32_bf16 v[122:125], v[168:171], v[176:179], v[122:125]
	v_mfma_f32_16x16x32_bf16 v[114:117], v[160:163], v[184:187], v[114:117]
	v_mfma_f32_16x16x32_bf16 v[106:109], v[168:171], v[184:187], v[106:109]
	v_mfma_f32_16x16x32_bf16 v[98:101], v[160:163], v[192:195], v[98:101]
	v_mfma_f32_16x16x32_bf16 v[90:93], v[168:171], v[192:195], v[90:93]
	v_mfma_f32_16x16x32_bf16 v[82:85], v[160:163], v[200:203], v[82:85]
	v_mfma_f32_16x16x32_bf16 v[74:77], v[168:171], v[200:203], v[74:77]
	s_setprio 0
	s_barrier
	s_add_i32 s47, s43, s33
	v_lshl_add_u64 v[220:221], s[28:29], 0, v[132:133]
	s_mov_b32 m0, s47
	ds_read_b128 v[204:207], v155
	ds_read_b128 v[208:211], v155 offset:1024
	ds_read_b128 v[212:215], v155 offset:2048
	ds_read_b128 v[216:219], v155 offset:3072
	global_load_lds_dwordx4 v[220:221], off
	v_lshl_add_u64 v[222:223], s[28:29], 0, v[136:137]
	s_add_i32 m0, s47, 0x2000
	s_nop 0
	global_load_lds_dwordx4 v[222:223], off
	s_barrier
	s_waitcnt lgkmcnt(0)
	s_setprio 1
	s_waitcnt lgkmcnt(0)
	v_mfma_f32_16x16x32_bf16 v[118:121], v[204:207], v[172:175], v[118:121]
	v_mfma_f32_16x16x32_bf16 v[110:113], v[212:215], v[172:175], v[110:113]
	v_mfma_f32_16x16x32_bf16 v[102:105], v[204:207], v[180:183], v[102:105]
	v_mfma_f32_16x16x32_bf16 v[94:97], v[212:215], v[180:183], v[94:97]
	v_mfma_f32_16x16x32_bf16 v[86:89], v[204:207], v[188:191], v[86:89]
	v_mfma_f32_16x16x32_bf16 v[78:81], v[212:215], v[188:191], v[78:81]
	v_mfma_f32_16x16x32_bf16 v[70:73], v[204:207], v[196:199], v[70:73]
	v_mfma_f32_16x16x32_bf16 v[66:69], v[212:215], v[196:199], v[66:69]
	v_mfma_f32_16x16x32_bf16 v[118:121], v[208:211], v[176:179], v[118:121]
	v_mfma_f32_16x16x32_bf16 v[110:113], v[216:219], v[176:179], v[110:113]
	v_mfma_f32_16x16x32_bf16 v[102:105], v[208:211], v[184:187], v[102:105]
	v_mfma_f32_16x16x32_bf16 v[94:97], v[216:219], v[184:187], v[94:97]
	v_mfma_f32_16x16x32_bf16 v[86:89], v[208:211], v[192:195], v[86:89]
	v_mfma_f32_16x16x32_bf16 v[78:81], v[216:219], v[192:195], v[78:81]
	v_mfma_f32_16x16x32_bf16 v[70:73], v[208:211], v[200:203], v[70:73]
	v_mfma_f32_16x16x32_bf16 v[66:69], v[216:219], v[200:203], v[66:69]
	s_setprio 0
	s_mov_b32 m0, s5
	v_lshl_add_u64 v[224:225], s[34:35], 0, v[130:131]
	s_barrier
	ds_read_b128 v[172:175], v154 offset:16384
	ds_read_b128 v[176:179], v154 offset:17408
	ds_read_b128 v[180:183], v154 offset:18432
	ds_read_b128 v[184:187], v154 offset:19456
	ds_read_b128 v[188:191], v154 offset:20480
	ds_read_b128 v[192:195], v154 offset:21504
	ds_read_b128 v[196:199], v154 offset:22528
	ds_read_b128 v[200:203], v154 offset:23552
	global_load_lds_dwordx4 v[224:225], off
	v_lshl_add_u64 v[226:227], s[34:35], 0, v[134:135]
	s_mov_b32 m0, s36
	s_nop 0
	global_load_lds_dwordx4 v[226:227], off
	s_barrier
	s_waitcnt lgkmcnt(0)
	s_setprio 1
	s_waitcnt lgkmcnt(0)
	v_mfma_f32_16x16x32_bf16 v[62:65], v[156:159], v[172:175], v[62:65]
	v_mfma_f32_16x16x32_bf16 v[58:61], v[164:167], v[172:175], v[58:61]
	v_mfma_f32_16x16x32_bf16 v[54:57], v[156:159], v[180:183], v[54:57]
	v_mfma_f32_16x16x32_bf16 v[46:49], v[164:167], v[180:183], v[46:49]
	v_mfma_f32_16x16x32_bf16 v[38:41], v[156:159], v[188:191], v[38:41]
	v_mfma_f32_16x16x32_bf16 v[30:33], v[164:167], v[188:191], v[30:33]
	v_mfma_f32_16x16x32_bf16 v[22:25], v[156:159], v[196:199], v[22:25]
	v_mfma_f32_16x16x32_bf16 v[14:17], v[164:167], v[196:199], v[14:17]
	v_mfma_f32_16x16x32_bf16 v[62:65], v[160:163], v[176:179], v[62:65]
	v_mfma_f32_16x16x32_bf16 v[58:61], v[168:171], v[176:179], v[58:61]
	v_mfma_f32_16x16x32_bf16 v[54:57], v[160:163], v[184:187], v[54:57]
	v_mfma_f32_16x16x32_bf16 v[46:49], v[168:171], v[184:187], v[46:49]
	v_mfma_f32_16x16x32_bf16 v[38:41], v[160:163], v[192:195], v[38:41]
	v_mfma_f32_16x16x32_bf16 v[30:33], v[168:171], v[192:195], v[30:33]
	v_mfma_f32_16x16x32_bf16 v[22:25], v[160:163], v[200:203], v[22:25]
	v_mfma_f32_16x16x32_bf16 v[14:17], v[168:171], v[200:203], v[14:17]
	s_setprio 0
	s_barrier
; #define PG8_STAGE(bufoff, gbase, voff) do { _Pragma("unroll") for (int _i = 0; _i < 2; ++_i) \
;         __builtin_amdgcn_global_load_lds((const unsigned*)((const char*)(gbase) + (voff)[_i]), (LAS unsigned*)(lds + (bufoff) + ldsw + _i * 8192), 16, 0, 0); } while (0)
; #define PG8_LDA(dst, b, h) do { _Pragma("unroll") for (int m = 0; m < 4; ++m) _Pragma("unroll") for (int k = 0; k < 2; ++k) dst[m][k] = *(const LAS bf16x8*)(lds + PG8_SA(b, h) + aoff + m * 2048 + k * 1024); } while (0)
; #define PG8_LDB(dst, b, h) do { _Pragma("unroll") for (int n = 0; n < 2; ++n) _Pragma("unroll") for (int k = 0; k < 2; ++k) dst[n][k] = *(const LAS bf16x8*)(lds + PG8_SB(b, h) + boff + n * 2048 + k * 1024); } while (0)
; #define PG8_MMA(ai, bj, At, Bt) do { __builtin_amdgcn_s_setprio(1); _Pragma("unroll") for (int m = 0; m < 4; ++m) _Pragma("unroll") for (int n = 0; n < 2; ++n) _Pragma("unroll") for (int k = 0; k < 2; ++k) \
;         acc[ai][bj][m][n] = __builtin_amdgcn_mfma_f32_16x16x32_bf16(Bt[n][k], At[m][k], acc[ai][bj][m][n], 0, 0, 0); __builtin_amdgcn_s_setprio(0); } while (0)
; #define PG8_WAIT_V(n) asm volatile("s_waitcnt vmcnt(" #n ")" ::: "memory")
; #define PG8_WAIT_L(n) asm volatile("s_waitcnt lgkmcnt(" #n ")" ::: "memory")
; #define PG8_BAR __builtin_amdgcn_s_barrier()
; #define PG8_SCHED __builtin_amdgcn_sched_barrier(0)
; template <class Sched, class Epi>
; __device__ __forceinline__ void gemm_phase(LAS unsigned char* lds, const Sched& S, const Epi& E, const int K, const int lda, const int ldb) {
;     ...
;             PG8_STAGE(PG8_SB(0, 1), b2 + hstepB, voffB);
;             PG8_WAIT_V(6); PG8_BAR; if (!chalf) PG8_MMA(1, 1, At, B1); PG8_BAR;
;             PG8_LDB(B0, 1, 0); PG8_SCHED; PG8_LDA(At, 1, 0); PG8_STAGE(PG8_SA(0, 1), a2 + hstepA, voffA);
;             PG8_WAIT_L(8); PG8_BAR; PG8_WAIT_L(0); PG8_MMA(0, 0, At, B0); PG8_BAR; PG8_SCHED;
;             PG8_LDB(B1, 1, 1); PG8_STAGE(PG8_SB(1, 0), b3, voffB);
;             PG8_BAR; PG8_WAIT_L(0); PG8_MMA(0, 1, At, B1); PG8_BAR;
;             PG8_LDA(At, 1, 1); PG8_STAGE(PG8_SA(1, 0), a3, voffA);
;             PG8_BAR; PG8_WAIT_L(0); if (!chalf) PG8_MMA(1, 0, At, B0); PG8_BAR; PG8_SCHED;
	s_add_u32 s48, s28, 0x80000
	s_addc_u32 s49, s29, 0
	s_add_i32 s47, s44, s33
	s_mov_b32 m0, s47
	s_nop 0
	global_load_lds_dwordx4 v132, s[48:49]
	s_add_i32 m0, s47, 0x2000
	s_nop 0
	global_load_lds_dwordx4 v136, s[48:49]
	s_waitcnt vmcnt(6)
	s_barrier
	s_setprio 1
	v_mfma_f32_16x16x32_bf16 v[50:53], v[204:207], v[172:175], v[50:53]
	v_mfma_f32_16x16x32_bf16 v[42:45], v[212:215], v[172:175], v[42:45]
	v_mfma_f32_16x16x32_bf16 v[34:37], v[204:207], v[180:183], v[34:37]
	v_mfma_f32_16x16x32_bf16 v[26:29], v[212:215], v[180:183], v[26:29]
	v_mfma_f32_16x16x32_bf16 v[18:21], v[204:207], v[188:191], v[18:21]
	v_mfma_f32_16x16x32_bf16 v[10:13], v[212:215], v[188:191], v[10:13]
	v_mfma_f32_16x16x32_bf16 v[6:9], v[204:207], v[196:199], v[6:9]
	v_mfma_f32_16x16x32_bf16 v[2:5], v[212:215], v[196:199], v[2:5]
	v_mfma_f32_16x16x32_bf16 v[50:53], v[208:211], v[176:179], v[50:53]
	v_mfma_f32_16x16x32_bf16 v[42:45], v[216:219], v[176:179], v[42:45]
	v_mfma_f32_16x16x32_bf16 v[34:37], v[208:211], v[184:187], v[34:37]
	v_mfma_f32_16x16x32_bf16 v[26:29], v[216:219], v[184:187], v[26:29]
	v_mfma_f32_16x16x32_bf16 v[18:21], v[208:211], v[192:195], v[18:21]
	v_mfma_f32_16x16x32_bf16 v[10:13], v[216:219], v[192:195], v[10:13]
	v_mfma_f32_16x16x32_bf16 v[6:9], v[208:211], v[200:203], v[6:9]
	v_mfma_f32_16x16x32_bf16 v[2:5], v[216:219], v[200:203], v[2:5]
	s_setprio 0
	s_add_i32 s47, 16, 0x18000
	v_add_u32_e32 v168, s47, v144
	s_barrier
	ds_read_b128 v[156:159], v168
	ds_read_b128 v[160:163], v168 offset:1024
	ds_read_b128 v[164:167], v168 offset:2048
	ds_read_b128 v[168:171], v168 offset:3072
	s_add_u32 s34, s34, 0x80000
	s_addc_u32 s35, s35, 0
	s_mov_b32 m0, s37
	ds_read_b128 v[172:175], v154 offset:32768
	ds_read_b128 v[176:179], v154 offset:33792
	ds_read_b128 v[180:183], v154 offset:34816
	ds_read_b128 v[184:187], v154 offset:35840
	ds_read_b128 v[188:191], v154 offset:36864
	ds_read_b128 v[192:195], v154 offset:37888
	ds_read_b128 v[196:199], v154 offset:38912
	ds_read_b128 v[200:203], v154 offset:39936
	global_load_lds_dwordx4 v130, s[34:35]
	s_mov_b32 m0, s38
	s_nop 0
	global_load_lds_dwordx4 v134, s[34:35]
	s_waitcnt lgkmcnt(8)
	s_barrier
	s_waitcnt lgkmcnt(0)
	s_setprio 1
	s_waitcnt lgkmcnt(0)
	v_mfma_f32_16x16x32_bf16 v[126:129], v[156:159], v[172:175], v[126:129]
	v_mfma_f32_16x16x32_bf16 v[122:125], v[164:167], v[172:175], v[122:125]
	v_mfma_f32_16x16x32_bf16 v[114:117], v[156:159], v[180:183], v[114:117]
	v_mfma_f32_16x16x32_bf16 v[106:109], v[164:167], v[180:183], v[106:109]
	v_mfma_f32_16x16x32_bf16 v[98:101], v[156:159], v[188:191], v[98:101]
	v_mfma_f32_16x16x32_bf16 v[90:93], v[164:167], v[188:191], v[90:93]
	v_mfma_f32_16x16x32_bf16 v[82:85], v[156:159], v[196:199], v[82:85]
	v_mfma_f32_16x16x32_bf16 v[74:77], v[164:167], v[196:199], v[74:77]
	v_mfma_f32_16x16x32_bf16 v[126:129], v[160:163], v[176:179], v[126:129]
	v_mfma_f32_16x16x32_bf16 v[122:125], v[168:171], v[176:179], v[122:125]
	v_mfma_f32_16x16x32_bf16 v[114:117], v[160:163], v[184:187], v[114:117]
	v_mfma_f32_16x16x32_bf16 v[106:109], v[168:171], v[184:187], v[106:109]
	v_mfma_f32_16x16x32_bf16 v[98:101], v[160:163], v[192:195], v[98:101]
	v_mfma_f32_16x16x32_bf16 v[90:93], v[168:171], v[192:195], v[90:93]
	v_mfma_f32_16x16x32_bf16 v[82:85], v[160:163], v[200:203], v[82:85]
	v_mfma_f32_16x16x32_bf16 v[74:77], v[168:171], v[200:203], v[74:77]
	s_setprio 0
	s_barrier
	s_add_i32 s34, 16, 0x1c000
	s_add_i32 s35, s47, s33
	v_add_u32_e32 v216, s34, v144
	v_lshl_add_u64 v[220:221], v[220:221], 0, s[8:9]
	s_mov_b32 m0, s35
	ds_read_b128 v[204:207], v216
	ds_read_b128 v[208:211], v216 offset:1024
	ds_read_b128 v[212:215], v216 offset:2048
	ds_read_b128 v[216:219], v216 offset:3072
	global_load_lds_dwordx4 v[220:221], off
	v_lshl_add_u64 v[220:221], v[222:223], 0, s[8:9]
	s_add_i32 m0, s35, 0x2000
	s_nop 0
	global_load_lds_dwordx4 v[220:221], off
	s_barrier
	s_waitcnt lgkmcnt(0)
	s_setprio 1
	s_waitcnt lgkmcnt(0)
	v_mfma_f32_16x16x32_bf16 v[118:121], v[204:207], v[172:175], v[118:121]
	v_mfma_f32_16x16x32_bf16 v[110:113], v[212:215], v[172:175], v[110:113]
	v_mfma_f32_16x16x32_bf16 v[102:105], v[204:207], v[180:183], v[102:105]
	v_mfma_f32_16x16x32_bf16 v[94:97], v[212:215], v[180:183], v[94:97]
	v_mfma_f32_16x16x32_bf16 v[86:89], v[204:207], v[188:191], v[86:89]
	v_mfma_f32_16x16x32_bf16 v[78:81], v[212:215], v[188:191], v[78:81]
	v_mfma_f32_16x16x32_bf16 v[70:73], v[204:207], v[196:199], v[70:73]
	v_mfma_f32_16x16x32_bf16 v[66:69], v[212:215], v[196:199], v[66:69]
	v_mfma_f32_16x16x32_bf16 v[118:121], v[208:211], v[176:179], v[118:121]
	v_mfma_f32_16x16x32_bf16 v[110:113], v[216:219], v[176:179], v[110:113]
	v_mfma_f32_16x16x32_bf16 v[102:105], v[208:211], v[184:187], v[102:105]
	v_mfma_f32_16x16x32_bf16 v[94:97], v[216:219], v[184:187], v[94:97]
	v_mfma_f32_16x16x32_bf16 v[86:89], v[208:211], v[192:195], v[86:89]
	v_mfma_f32_16x16x32_bf16 v[78:81], v[216:219], v[192:195], v[78:81]
	v_mfma_f32_16x16x32_bf16 v[70:73], v[208:211], v[200:203], v[70:73]
	v_mfma_f32_16x16x32_bf16 v[66:69], v[216:219], v[200:203], v[66:69]
	s_setprio 0
	s_mov_b32 m0, s39
	v_lshl_add_u64 v[220:221], v[224:225], 0, s[8:9]
	s_barrier
	ds_read_b128 v[172:175], v154 offset:49152
	ds_read_b128 v[176:179], v154 offset:50176
	ds_read_b128 v[180:183], v154 offset:51200
	ds_read_b128 v[184:187], v154 offset:52224
	ds_read_b128 v[188:191], v154 offset:53248
	ds_read_b128 v[192:195], v154 offset:54272
	ds_read_b128 v[196:199], v154 offset:55296
	ds_read_b128 v[200:203], v154 offset:56320
	global_load_lds_dwordx4 v[220:221], off
	v_lshl_add_u64 v[220:221], v[226:227], 0, s[8:9]
	s_mov_b32 m0, s40
	s_nop 0
	global_load_lds_dwordx4 v[220:221], off
	s_barrier
; #define PG8_STAGE(bufoff, gbase, voff) do { _Pragma("unroll") for (int _i = 0; _i < 2; ++_i) \
;         __builtin_amdgcn_global_load_lds((const unsigned*)((const char*)(gbase) + (voff)[_i]), (LAS unsigned*)(lds + (bufoff) + ldsw + _i * 8192), 16, 0, 0); } while (0)
; #define PG8_MMA(ai, bj, At, Bt) do { __builtin_amdgcn_s_setprio(1); _Pragma("unroll") for (int m = 0; m < 4; ++m) _Pragma("unroll") for (int n = 0; n < 2; ++n) _Pragma("unroll") for (int k = 0; k < 2; ++k) \
;         acc[ai][bj][m][n] = __builtin_amdgcn_mfma_f32_16x16x32_bf16(Bt[n][k], At[m][k], acc[ai][bj][m][n], 0, 0, 0); __builtin_amdgcn_s_setprio(0); } while (0)
; #define PG8_WAIT_V(n) asm volatile("s_waitcnt vmcnt(" #n ")" ::: "memory")
; #define PG8_WAIT_L(n) asm volatile("s_waitcnt lgkmcnt(" #n ")" ::: "memory")
; #define PG8_BAR __builtin_amdgcn_s_barrier()
; #define PG8_SCHED __builtin_amdgcn_sched_barrier(0)
; template <class Sched, class Epi>
; __device__ __forceinline__ void gemm_phase(LAS unsigned char* lds, const Sched& S, const Epi& E, const int K, const int lda, const int ldb) {
;     ...
;             PG8_BAR; PG8_WAIT_L(0); if (!chalf) PG8_MMA(1, 0, At, B0); PG8_BAR; PG8_SCHED;
;             PG8_STAGE(PG8_SB(1, 1), b3 + hstepB, voffB);
;             PG8_WAIT_V(6); PG8_BAR; if (!chalf) PG8_MMA(1, 1, At, B1); PG8_BAR;
	s_waitcnt lgkmcnt(0)
	s_setprio 1
	s_waitcnt lgkmcnt(0)
	v_mfma_f32_16x16x32_bf16 v[62:65], v[156:159], v[172:175], v[62:65]
	v_mfma_f32_16x16x32_bf16 v[58:61], v[164:167], v[172:175], v[58:61]
	v_mfma_f32_16x16x32_bf16 v[54:57], v[156:159], v[180:183], v[54:57]
	v_mfma_f32_16x16x32_bf16 v[46:49], v[164:167], v[180:183], v[46:49]
	v_mfma_f32_16x16x32_bf16 v[38:41], v[156:159], v[188:191], v[38:41]
	v_mfma_f32_16x16x32_bf16 v[30:33], v[164:167], v[188:191], v[30:33]
	v_mfma_f32_16x16x32_bf16 v[22:25], v[156:159], v[196:199], v[22:25]
	v_mfma_f32_16x16x32_bf16 v[14:17], v[164:167], v[196:199], v[14:17]
	v_mfma_f32_16x16x32_bf16 v[62:65], v[160:163], v[176:179], v[62:65]
	v_mfma_f32_16x16x32_bf16 v[58:61], v[168:171], v[176:179], v[58:61]
	v_mfma_f32_16x16x32_bf16 v[54:57], v[160:163], v[184:187], v[54:57]
	v_mfma_f32_16x16x32_bf16 v[46:49], v[168:171], v[184:187], v[46:49]
	v_mfma_f32_16x16x32_bf16 v[38:41], v[160:163], v[192:195], v[38:41]
	v_mfma_f32_16x16x32_bf16 v[30:33], v[168:171], v[192:195], v[30:33]
	v_mfma_f32_16x16x32_bf16 v[22:25], v[160:163], v[200:203], v[22:25]
	v_mfma_f32_16x16x32_bf16 v[14:17], v[168:171], v[200:203], v[14:17]
	s_setprio 0
	s_barrier
	s_add_u32 s28, s28, 0x80080
	s_addc_u32 s29, s29, 0
	s_add_i32 s34, s34, s33
	s_mov_b32 m0, s34
	s_nop 0
	global_load_lds_dwordx4 v132, s[28:29]
	s_add_i32 m0, s34, 0x2000
	s_nop 0
	global_load_lds_dwordx4 v136, s[28:29]
	s_waitcnt vmcnt(6)
	s_barrier
	s_setprio 1
	v_mfma_f32_16x16x32_bf16 v[50:53], v[204:207], v[172:175], v[50:53]
	v_mfma_f32_16x16x32_bf16 v[42:45], v[212:215], v[172:175], v[42:45]
	v_mfma_f32_16x16x32_bf16 v[34:37], v[204:207], v[180:183], v[34:37]
	v_mfma_f32_16x16x32_bf16 v[26:29], v[212:215], v[180:183], v[26:29]
	v_mfma_f32_16x16x32_bf16 v[18:21], v[204:207], v[188:191], v[18:21]
	v_mfma_f32_16x16x32_bf16 v[10:13], v[212:215], v[188:191], v[10:13]
	v_mfma_f32_16x16x32_bf16 v[6:9], v[204:207], v[196:199], v[6:9]
	v_mfma_f32_16x16x32_bf16 v[2:5], v[212:215], v[196:199], v[2:5]
	v_mfma_f32_16x16x32_bf16 v[50:53], v[208:211], v[176:179], v[50:53]
	v_mfma_f32_16x16x32_bf16 v[42:45], v[216:219], v[176:179], v[42:45]
	v_mfma_f32_16x16x32_bf16 v[34:37], v[208:211], v[184:187], v[34:37]
	v_mfma_f32_16x16x32_bf16 v[26:29], v[216:219], v[184:187], v[26:29]
	v_mfma_f32_16x16x32_bf16 v[18:21], v[208:211], v[192:195], v[18:21]
	v_mfma_f32_16x16x32_bf16 v[10:13], v[216:219], v[192:195], v[10:13]
	v_mfma_f32_16x16x32_bf16 v[6:9], v[208:211], v[200:203], v[6:9]
	v_mfma_f32_16x16x32_bf16 v[2:5], v[216:219], v[200:203], v[2:5]
	s_setprio 0
	s_add_i32 s46, s46, 2
	s_add_u32 s15, s15, 0x100
	s_addc_u32 s17, s17, 0
	s_add_u32 s26, s26, 0x100
	s_addc_u32 s27, s27, 0
	s_cmp_gt_u32 s46, 29
	s_barrier
	s_cbranch_scc0 .LBB0_957
; __device__ __forceinline__ unsigned cvt_pk_bf16(float lo, float hi) { unsigned r; asm volatile("v_cvt_pk_bf16_f32 %0, %1, %2" : "=v"(r) : "v"(lo), "v"(hi)); return r; }
; #define EPI_FOR_ROWS _Pragma("unroll") for (int ai = 0; ai < 2; ++ai) if (ai == 0 || !u.half) _Pragma("unroll") for (int m = 0; m < 4; ++m)
;     __device__ __forceinline__ void operator()(EPI_ARGS) const {
;         EPI_FOR_ROWS { bf16_t* rp = O + (size_t)EPI_ROW * ldc;
; #pragma unroll
;             for (int bj = 0; bj < 2; ++bj) { const f32x4 v0 = acc[ai][bj][m][0], v1 = acc[ai][bj][m][1]; u32x4 o;
;                 o[0] = cvt_pk_bf16(v0[0], v0[1]); o[1] = cvt_pk_bf16(v0[2], v0[3]); o[2] = cvt_pk_bf16(v1[0], v1[1]); o[3] = cvt_pk_bf16(v1[2], v1[3]);
;                 *(u32x4*)(rp + EPI_COL(bj)) = o; } }
;     }
	v_add_u32_e32 v156, s4, v1
	v_ashrrev_i32_e32 v157, 31, v156
	v_cvt_pk_bf16_f32 v126, v126, v127
	v_cvt_pk_bf16_f32 v127, v128, v129
	v_cvt_pk_bf16_f32 v128, v122, v123
	v_lshl_or_b32 v122, s45, 8, v152
	v_lshlrev_b64 v[156:157], 12, v[156:157]
	v_ashrrev_i32_e32 v123, 31, v122
	v_lshl_add_u64 v[156:157], s[6:7], 0, v[156:157]
	v_lshlrev_b64 v[122:123], 1, v[122:123]
	v_cvt_pk_bf16_f32 v129, v124, v125
	v_lshl_add_u64 v[124:125], v[156:157], 0, v[122:123]
	global_store_dwordx4 v[124:125], v[126:129], off
	v_cvt_pk_bf16_f32 v118, v118, v119
	v_cvt_pk_bf16_f32 v119, v120, v121
	v_cvt_pk_bf16_f32 v120, v110, v111
	v_add_u32_e32 v110, s4, v145
	v_ashrrev_i32_e32 v111, 31, v110
	v_lshlrev_b64 v[110:111], 12, v[110:111]
	v_cvt_pk_bf16_f32 v121, v112, v113
	global_store_dwordx4 v[124:125], v[118:121], off offset:256
	s_and_b64 vcc, exec, s[12:13]
	s_mov_b32 s45, s14
	v_lshl_add_u64 v[118:119], s[6:7], 0, v[110:111]
	v_cvt_pk_bf16_f32 v110, v114, v115
	v_cvt_pk_bf16_f32 v111, v116, v117
	v_cvt_pk_bf16_f32 v112, v106, v107
	v_lshl_add_u64 v[106:107], v[118:119], 0, v[122:123]
	v_cvt_pk_bf16_f32 v113, v108, v109
	global_store_dwordx4 v[106:107], v[110:113], off
	v_cvt_pk_bf16_f32 v102, v102, v103
	v_cvt_pk_bf16_f32 v103, v104, v105
	v_cvt_pk_bf16_f32 v104, v94, v95
	v_add_u32_e32 v94, s4, v146
	v_ashrrev_i32_e32 v95, 31, v94
	v_lshlrev_b64 v[94:95], 12, v[94:95]
	v_cvt_pk_bf16_f32 v105, v96, v97
	global_store_dwordx4 v[106:107], v[102:105], off offset:256
	s_mov_b64 s[28:29], s[20:21]
	s_mov_b64 s[26:27], s[18:19]
	v_lshl_add_u64 v[102:103], s[6:7], 0, v[94:95]
	v_cvt_pk_bf16_f32 v94, v98, v99
	v_cvt_pk_bf16_f32 v95, v100, v101
	v_cvt_pk_bf16_f32 v96, v90, v91
	v_lshl_add_u64 v[90:91], v[102:103], 0, v[122:123]
	v_cvt_pk_bf16_f32 v97, v92, v93
	global_store_dwordx4 v[90:91], v[94:97], off
	v_cvt_pk_bf16_f32 v86, v86, v87
	v_cvt_pk_bf16_f32 v87, v88, v89
	v_cvt_pk_bf16_f32 v88, v78, v79
	v_add_u32_e32 v78, s4, v147
	v_ashrrev_i32_e32 v79, 31, v78
	v_lshlrev_b64 v[78:79], 12, v[78:79]
	v_cvt_pk_bf16_f32 v89, v80, v81
	global_store_dwordx4 v[90:91], v[86:89], off offset:256
	s_nop 1
	v_lshl_add_u64 v[86:87], s[6:7], 0, v[78:79]
	v_cvt_pk_bf16_f32 v78, v82, v83
	v_cvt_pk_bf16_f32 v79, v84, v85
	v_cvt_pk_bf16_f32 v80, v74, v75
	v_lshl_add_u64 v[74:75], v[86:87], 0, v[122:123]
	v_cvt_pk_bf16_f32 v81, v76, v77
	global_store_dwordx4 v[74:75], v[78:81], off
	v_cvt_pk_bf16_f32 v70, v70, v71
	v_cvt_pk_bf16_f32 v71, v72, v73
	v_cvt_pk_bf16_f32 v72, v66, v67
	v_add_u32_e32 v66, s4, v148
	v_ashrrev_i32_e32 v67, 31, v66
	v_lshlrev_b64 v[66:67], 12, v[66:67]
	v_lshl_add_u64 v[66:67], s[6:7], 0, v[66:67]
	v_cvt_pk_bf16_f32 v73, v68, v69
	global_store_dwordx4 v[74:75], v[70:73], off offset:256
	v_cvt_pk_bf16_f32 v62, v62, v63
	v_cvt_pk_bf16_f32 v63, v64, v65
	v_cvt_pk_bf16_f32 v64, v58, v59
	v_lshl_add_u64 v[58:59], v[66:67], 0, v[122:123]
	v_cvt_pk_bf16_f32 v65, v60, v61
	global_store_dwordx4 v[58:59], v[62:65], off
	v_cvt_pk_bf16_f32 v50, v50, v51
	v_cvt_pk_bf16_f32 v51, v52, v53
	v_cvt_pk_bf16_f32 v52, v42, v43
	v_add_u32_e32 v42, s4, v149
	v_ashrrev_i32_e32 v43, 31, v42
	v_lshlrev_b64 v[42:43], 12, v[42:43]
	v_cvt_pk_bf16_f32 v53, v44, v45
	global_store_dwordx4 v[58:59], v[50:53], off offset:256
	s_nop 1
	v_lshl_add_u64 v[50:51], s[6:7], 0, v[42:43]
	v_cvt_pk_bf16_f32 v42, v54, v55
	v_cvt_pk_bf16_f32 v43, v56, v57
	v_cvt_pk_bf16_f32 v44, v46, v47
	v_lshl_add_u64 v[46:47], v[50:51], 0, v[122:123]
	v_cvt_pk_bf16_f32 v45, v48, v49
	global_store_dwordx4 v[46:47], v[42:45], off
	v_cvt_pk_bf16_f32 v34, v34, v35
	v_cvt_pk_bf16_f32 v35, v36, v37
	v_cvt_pk_bf16_f32 v36, v26, v27
	v_add_u32_e32 v26, s4, v150
	v_ashrrev_i32_e32 v27, 31, v26
	v_lshlrev_b64 v[26:27], 12, v[26:27]
	v_cvt_pk_bf16_f32 v37, v28, v29
	global_store_dwordx4 v[46:47], v[34:37], off offset:256
	s_nop 1
	v_lshl_add_u64 v[34:35], s[6:7], 0, v[26:27]
	v_cvt_pk_bf16_f32 v26, v38, v39
	v_cvt_pk_bf16_f32 v27, v40, v41
	v_cvt_pk_bf16_f32 v28, v30, v31
	v_lshl_add_u64 v[30:31], v[34:35], 0, v[122:123]
	v_cvt_pk_bf16_f32 v29, v32, v33
	global_store_dwordx4 v[30:31], v[26:29], off
	v_cvt_pk_bf16_f32 v18, v18, v19
	v_cvt_pk_bf16_f32 v19, v20, v21
	v_cvt_pk_bf16_f32 v20, v10, v11
	v_add_u32_e32 v10, s4, v151
	v_ashrrev_i32_e32 v11, 31, v10
	v_lshlrev_b64 v[10:11], 12, v[10:11]
	v_cvt_pk_bf16_f32 v21, v12, v13
	global_store_dwordx4 v[30:31], v[18:21], off offset:256
	s_mov_b32 s4, s16
	s_nop 0
	v_lshl_add_u64 v[18:19], s[6:7], 0, v[10:11]
	v_cvt_pk_bf16_f32 v10, v22, v23
	v_cvt_pk_bf16_f32 v11, v24, v25
	v_cvt_pk_bf16_f32 v12, v14, v15
	v_lshl_add_u64 v[14:15], v[18:19], 0, v[122:123]
	v_cvt_pk_bf16_f32 v13, v16, v17
	global_store_dwordx4 v[14:15], v[10:13], off
	v_cvt_pk_bf16_f32 v6, v6, v7
	v_cvt_pk_bf16_f32 v7, v8, v9
	v_cvt_pk_bf16_f32 v8, v2, v3
	v_cvt_pk_bf16_f32 v9, v4, v5
	global_store_dwordx4 v[14:15], v[6:9], off offset:256
	s_cbranch_vccz .LBB0_950
	s_waitcnt vmcnt(0)
	s_cmpk_gt_u32 s2, 0xff
	s_cbranch_scc1 .LBB0_961
	s_barrier

; #define PG8_STAGE(bufoff, gbase, voff) do { _Pragma("unroll") for (int _i = 0; _i < 2; ++_i) \
;         __builtin_amdgcn_global_load_lds((const unsigned*)((const char*)(gbase) + (voff)[_i]), (LAS unsigned*)(lds + (bufoff) + ldsw + _i * 8192), 16, 0, 0); } while (0)
; #define PG8_LDA(dst, b, h) do { _Pragma("unroll") for (int m = 0; m < 4; ++m) _Pragma("unroll") for (int k = 0; k < 2; ++k) dst[m][k] = *(const LAS bf16x8*)(lds + PG8_SA(b, h) + aoff + m * 2048 + k * 1024); } while (0)
; #define PG8_LDB(dst, b, h) do { _Pragma("unroll") for (int n = 0; n < 2; ++n) _Pragma("unroll") for (int k = 0; k < 2; ++k) dst[n][k] = *(const LAS bf16x8*)(lds + PG8_SB(b, h) + boff + n * 2048 + k * 1024); } while (0)
; #define PG8_MMA(ai, bj, At, Bt) do { __builtin_amdgcn_s_setprio(1); _Pragma("unroll") for (int m = 0; m < 4; ++m) _Pragma("unroll") for (int n = 0; n < 2; ++n) _Pragma("unroll") for (int k = 0; k < 2; ++k) \
;         acc[ai][bj][m][n] = __builtin_amdgcn_mfma_f32_16x16x32_bf16(Bt[n][k], At[m][k], acc[ai][bj][m][n], 0, 0, 0); __builtin_amdgcn_s_setprio(0); } while (0)
; #define PG8_WAIT_V(n) asm volatile("s_waitcnt vmcnt(" #n ")" ::: "memory")
; #define PG8_WAIT_L(n) asm volatile("s_waitcnt lgkmcnt(" #n ")" ::: "memory")
; #define PG8_BAR __builtin_amdgcn_s_barrier()
; #define PG8_SCHED __builtin_amdgcn_sched_barrier(0)
; template <class Sched, class Epi>
; __device__ __forceinline__ void gemm_phase(LAS unsigned char* lds, const Sched& S, const Epi& E, const int K, const int lda, const int ldb) {
;     ...
;             PG8_LDB(B0, 0, 0); PG8_SCHED; PG8_LDA(At, 0, 0); PG8_STAGE(PG8_SA(1, 1), a1 + hstepA, voffA);
;             PG8_WAIT_L(8); PG8_BAR; PG8_WAIT_L(0); PG8_MMA(0, 0, At, B0); PG8_BAR; PG8_SCHED;
;             PG8_LDB(B1, 0, 1); PG8_STAGE(PG8_SB(0, 0), b2, voffB);
;             PG8_BAR; PG8_WAIT_L(0); PG8_MMA(0, 1, At, B1); PG8_BAR;
;             PG8_LDA(At, 0, 1); PG8_STAGE(PG8_SA(0, 0), a2, voffA);
;             PG8_BAR; PG8_WAIT_L(0); if (!chalf) PG8_MMA(1, 0, At, B0); PG8_BAR; PG8_SCHED;
;             PG8_STAGE(PG8_SB(0, 1), b2 + hstepB, voffB);
;             PG8_WAIT_V(6); PG8_BAR; if (!chalf) PG8_MMA(1, 1, At, B1); PG8_BAR;
.LBB0_1092:
	ds_read_b128 v[160:163], v156
	ds_read_b128 v[164:167], v156 offset:1024
	ds_read_b128 v[168:171], v156 offset:2048
	ds_read_b128 v[172:175], v156 offset:3072
	s_add_u32 s26, s24, 0xfff80080
	s_addc_u32 s27, s25, -1
	s_cmp_eq_u32 s48, 28
	s_cselect_b32 s29, s21, s27
	s_cselect_b32 s28, s20, s26
	s_cselect_b32 s27, s23, s15
	s_cselect_b32 s26, s22, s13
	s_add_i32 m0, s5, 0xc000
	ds_read_b128 v[176:179], v157
	ds_read_b128 v[180:183], v157 offset:1024
	ds_read_b128 v[184:187], v157 offset:2048
	ds_read_b128 v[188:191], v157 offset:3072
	ds_read_b128 v[192:195], v157 offset:4096
	ds_read_b128 v[196:199], v157 offset:5120
	ds_read_b128 v[200:203], v157 offset:6144
	ds_read_b128 v[204:207], v157 offset:7168
	global_load_lds_dwordx4 v142, s[24:25]
	s_add_i32 m0, s5, 0xe000
	s_nop 0
	global_load_lds_dwordx4 v140, s[24:25]
	s_waitcnt lgkmcnt(8)
	s_barrier
	s_waitcnt lgkmcnt(0)
	s_setprio 1
	s_waitcnt lgkmcnt(0)
	v_mfma_f32_16x16x32_bf16 v[126:129], v[160:163], v[176:179], v[126:129]
	v_mfma_f32_16x16x32_bf16 v[122:125], v[168:171], v[176:179], v[122:125]
	v_mfma_f32_16x16x32_bf16 v[114:117], v[160:163], v[184:187], v[114:117]
	v_mfma_f32_16x16x32_bf16 v[106:109], v[168:171], v[184:187], v[106:109]
	v_mfma_f32_16x16x32_bf16 v[98:101], v[160:163], v[192:195], v[98:101]
	v_mfma_f32_16x16x32_bf16 v[90:93], v[168:171], v[192:195], v[90:93]
	v_mfma_f32_16x16x32_bf16 v[82:85], v[160:163], v[200:203], v[82:85]
	v_mfma_f32_16x16x32_bf16 v[74:77], v[168:171], v[200:203], v[74:77]
	v_mfma_f32_16x16x32_bf16 v[126:129], v[164:167], v[180:183], v[126:129]
	v_mfma_f32_16x16x32_bf16 v[122:125], v[172:175], v[180:183], v[122:125]
	v_mfma_f32_16x16x32_bf16 v[114:117], v[164:167], v[188:191], v[114:117]
	v_mfma_f32_16x16x32_bf16 v[106:109], v[172:175], v[188:191], v[106:109]
	v_mfma_f32_16x16x32_bf16 v[98:101], v[164:167], v[196:199], v[98:101]
	v_mfma_f32_16x16x32_bf16 v[90:93], v[172:175], v[196:199], v[90:93]
	v_mfma_f32_16x16x32_bf16 v[82:85], v[164:167], v[204:207], v[82:85]
	v_mfma_f32_16x16x32_bf16 v[74:77], v[172:175], v[204:207], v[74:77]
	s_setprio 0
	s_barrier
	s_add_i32 s49, s44, s11
	v_lshl_add_u64 v[146:147], s[26:27], 0, v[134:135]
	s_mov_b32 m0, s49
	ds_read_b128 v[208:211], v158
	ds_read_b128 v[212:215], v158 offset:1024
	ds_read_b128 v[216:219], v158 offset:2048
	ds_read_b128 v[220:223], v158 offset:3072
	global_load_lds_dwordx4 v[146:147], off
	v_lshl_add_u64 v[224:225], s[26:27], 0, v[130:131]
	s_add_i32 m0, s49, 0x2000
	s_nop 0
	global_load_lds_dwordx4 v[224:225], off
	s_barrier
	s_waitcnt lgkmcnt(0)
	s_setprio 1
	s_waitcnt lgkmcnt(0)
	v_mfma_f32_16x16x32_bf16 v[118:121], v[208:211], v[176:179], v[118:121]
	v_mfma_f32_16x16x32_bf16 v[110:113], v[216:219], v[176:179], v[110:113]
	v_mfma_f32_16x16x32_bf16 v[102:105], v[208:211], v[184:187], v[102:105]
	v_mfma_f32_16x16x32_bf16 v[94:97], v[216:219], v[184:187], v[94:97]
	v_mfma_f32_16x16x32_bf16 v[86:89], v[208:211], v[192:195], v[86:89]
	v_mfma_f32_16x16x32_bf16 v[78:81], v[216:219], v[192:195], v[78:81]
	v_mfma_f32_16x16x32_bf16 v[70:73], v[208:211], v[200:203], v[70:73]
	v_mfma_f32_16x16x32_bf16 v[66:69], v[216:219], v[200:203], v[66:69]
	v_mfma_f32_16x16x32_bf16 v[118:121], v[212:215], v[180:183], v[118:121]
	v_mfma_f32_16x16x32_bf16 v[110:113], v[220:223], v[180:183], v[110:113]
	v_mfma_f32_16x16x32_bf16 v[102:105], v[212:215], v[188:191], v[102:105]
	v_mfma_f32_16x16x32_bf16 v[94:97], v[220:223], v[188:191], v[94:97]
	v_mfma_f32_16x16x32_bf16 v[86:89], v[212:215], v[196:199], v[86:89]
	v_mfma_f32_16x16x32_bf16 v[78:81], v[220:223], v[196:199], v[78:81]
	v_mfma_f32_16x16x32_bf16 v[70:73], v[212:215], v[204:207], v[70:73]
	v_mfma_f32_16x16x32_bf16 v[66:69], v[220:223], v[204:207], v[66:69]
	s_setprio 0
	s_mov_b32 m0, s5
	v_lshl_add_u64 v[226:227], s[28:29], 0, v[136:137]
	s_barrier
	ds_read_b128 v[176:179], v157 offset:16384
	ds_read_b128 v[180:183], v157 offset:17408
	ds_read_b128 v[184:187], v157 offset:18432
	ds_read_b128 v[188:191], v157 offset:19456
	ds_read_b128 v[192:195], v157 offset:20480
	ds_read_b128 v[196:199], v157 offset:21504
	ds_read_b128 v[200:203], v157 offset:22528
	ds_read_b128 v[204:207], v157 offset:23552
	global_load_lds_dwordx4 v[226:227], off
	v_lshl_add_u64 v[228:229], s[28:29], 0, v[132:133]
	s_mov_b32 m0, s35
	s_nop 0
	global_load_lds_dwordx4 v[228:229], off
	s_barrier
	s_waitcnt lgkmcnt(0)
	s_setprio 1
	s_waitcnt lgkmcnt(0)
	v_mfma_f32_16x16x32_bf16 v[62:65], v[160:163], v[176:179], v[62:65]
	v_mfma_f32_16x16x32_bf16 v[58:61], v[168:171], v[176:179], v[58:61]
	v_mfma_f32_16x16x32_bf16 v[50:53], v[160:163], v[184:187], v[50:53]
	v_mfma_f32_16x16x32_bf16 v[42:45], v[168:171], v[184:187], v[42:45]
	v_mfma_f32_16x16x32_bf16 v[34:37], v[160:163], v[192:195], v[34:37]
	v_mfma_f32_16x16x32_bf16 v[26:29], v[168:171], v[192:195], v[26:29]
	v_mfma_f32_16x16x32_bf16 v[18:21], v[160:163], v[200:203], v[18:21]
	v_mfma_f32_16x16x32_bf16 v[10:13], v[168:171], v[200:203], v[10:13]
	v_mfma_f32_16x16x32_bf16 v[62:65], v[164:167], v[180:183], v[62:65]
	v_mfma_f32_16x16x32_bf16 v[58:61], v[172:175], v[180:183], v[58:61]
	v_mfma_f32_16x16x32_bf16 v[50:53], v[164:167], v[188:191], v[50:53]
	v_mfma_f32_16x16x32_bf16 v[42:45], v[172:175], v[188:191], v[42:45]
	v_mfma_f32_16x16x32_bf16 v[34:37], v[164:167], v[196:199], v[34:37]
	v_mfma_f32_16x16x32_bf16 v[26:29], v[172:175], v[196:199], v[26:29]
	v_mfma_f32_16x16x32_bf16 v[18:21], v[164:167], v[204:207], v[18:21]
	v_mfma_f32_16x16x32_bf16 v[10:13], v[172:175], v[204:207], v[10:13]
	s_setprio 0
	s_barrier
; #define PG8_STAGE(bufoff, gbase, voff) do { _Pragma("unroll") for (int _i = 0; _i < 2; ++_i) \
;         __builtin_amdgcn_global_load_lds((const unsigned*)((const char*)(gbase) + (voff)[_i]), (LAS unsigned*)(lds + (bufoff) + ldsw + _i * 8192), 16, 0, 0); } while (0)
; #define PG8_LDA(dst, b, h) do { _Pragma("unroll") for (int m = 0; m < 4; ++m) _Pragma("unroll") for (int k = 0; k < 2; ++k) dst[m][k] = *(const LAS bf16x8*)(lds + PG8_SA(b, h) + aoff + m * 2048 + k * 1024); } while (0)
; #define PG8_LDB(dst, b, h) do { _Pragma("unroll") for (int n = 0; n < 2; ++n) _Pragma("unroll") for (int k = 0; k < 2; ++k) dst[n][k] = *(const LAS bf16x8*)(lds + PG8_SB(b, h) + boff + n * 2048 + k * 1024); } while (0)
; #define PG8_MMA(ai, bj, At, Bt) do { __builtin_amdgcn_s_setprio(1); _Pragma("unroll") for (int m = 0; m < 4; ++m) _Pragma("unroll") for (int n = 0; n < 2; ++n) _Pragma("unroll") for (int k = 0; k < 2; ++k) \
;         acc[ai][bj][m][n] = __builtin_amdgcn_mfma_f32_16x16x32_bf16(Bt[n][k], At[m][k], acc[ai][bj][m][n], 0, 0, 0); __builtin_amdgcn_s_setprio(0); } while (0)
; #define PG8_WAIT_V(n) asm volatile("s_waitcnt vmcnt(" #n ")" ::: "memory")
; #define PG8_WAIT_L(n) asm volatile("s_waitcnt lgkmcnt(" #n ")" ::: "memory")
; #define PG8_BAR __builtin_amdgcn_s_barrier()
; #define PG8_SCHED __builtin_amdgcn_sched_barrier(0)
; template <class Sched, class Epi>
; __device__ __forceinline__ void gemm_phase(LAS unsigned char* lds, const Sched& S, const Epi& E, const int K, const int lda, const int ldb) {
;     ...
;             PG8_STAGE(PG8_SB(0, 1), b2 + hstepB, voffB);
;             PG8_WAIT_V(6); PG8_BAR; if (!chalf) PG8_MMA(1, 1, At, B1); PG8_BAR;
;             PG8_LDB(B0, 1, 0); PG8_SCHED; PG8_LDA(At, 1, 0); PG8_STAGE(PG8_SA(0, 1), a2 + hstepA, voffA);
;             PG8_WAIT_L(8); PG8_BAR; PG8_WAIT_L(0); PG8_MMA(0, 0, At, B0); PG8_BAR; PG8_SCHED;
;             PG8_LDB(B1, 1, 1); PG8_STAGE(PG8_SB(1, 0), b3, voffB);
;             PG8_BAR; PG8_WAIT_L(0); PG8_MMA(0, 1, At, B1); PG8_BAR;
	s_add_u32 s50, s26, 0x80000
	s_addc_u32 s51, s27, 0
	s_add_i32 s49, s45, s11
	s_mov_b32 m0, s49
	s_nop 0
	global_load_lds_dwordx4 v134, s[50:51]
	s_add_i32 m0, s49, 0x2000
	s_nop 0
	global_load_lds_dwordx4 v130, s[50:51]
	s_waitcnt vmcnt(6)
	s_barrier
	s_setprio 1
	v_mfma_f32_16x16x32_bf16 v[54:57], v[208:211], v[176:179], v[54:57]
	v_mfma_f32_16x16x32_bf16 v[46:49], v[216:219], v[176:179], v[46:49]
	v_mfma_f32_16x16x32_bf16 v[38:41], v[208:211], v[184:187], v[38:41]
	v_mfma_f32_16x16x32_bf16 v[30:33], v[216:219], v[184:187], v[30:33]
	v_mfma_f32_16x16x32_bf16 v[22:25], v[208:211], v[192:195], v[22:25]
	v_mfma_f32_16x16x32_bf16 v[14:17], v[216:219], v[192:195], v[14:17]
	v_mfma_f32_16x16x32_bf16 v[6:9], v[208:211], v[200:203], v[6:9]
	v_mfma_f32_16x16x32_bf16 v[2:5], v[216:219], v[200:203], v[2:5]
	v_mfma_f32_16x16x32_bf16 v[54:57], v[212:215], v[180:183], v[54:57]
	v_mfma_f32_16x16x32_bf16 v[46:49], v[220:223], v[180:183], v[46:49]
	v_mfma_f32_16x16x32_bf16 v[38:41], v[212:215], v[188:191], v[38:41]
	v_mfma_f32_16x16x32_bf16 v[30:33], v[220:223], v[188:191], v[30:33]
	v_mfma_f32_16x16x32_bf16 v[22:25], v[212:215], v[196:199], v[22:25]
	v_mfma_f32_16x16x32_bf16 v[14:17], v[220:223], v[196:199], v[14:17]
	v_mfma_f32_16x16x32_bf16 v[6:9], v[212:215], v[204:207], v[6:9]
	v_mfma_f32_16x16x32_bf16 v[2:5], v[220:223], v[204:207], v[2:5]
	s_setprio 0
	s_add_i32 s49, 16, 0x18000
	v_add_u32_e32 v159, s49, v148
	s_barrier
	ds_read_b128 v[160:163], v159
	ds_read_b128 v[164:167], v159 offset:1024
	ds_read_b128 v[168:171], v159 offset:2048
	ds_read_b128 v[172:175], v159 offset:3072
	s_add_u32 s28, s28, 0x80000
	s_addc_u32 s29, s29, 0
	s_mov_b32 m0, s36
	ds_read_b128 v[176:179], v157 offset:32768
	ds_read_b128 v[180:183], v157 offset:33792
	ds_read_b128 v[184:187], v157 offset:34816
	ds_read_b128 v[188:191], v157 offset:35840
	ds_read_b128 v[192:195], v157 offset:36864
	ds_read_b128 v[196:199], v157 offset:37888
	ds_read_b128 v[200:203], v157 offset:38912
	ds_read_b128 v[204:207], v157 offset:39936
	global_load_lds_dwordx4 v136, s[28:29]
	s_mov_b32 m0, s37
	s_nop 0
	global_load_lds_dwordx4 v132, s[28:29]
	s_waitcnt lgkmcnt(8)
	s_barrier
	s_waitcnt lgkmcnt(0)
	s_setprio 1
	s_waitcnt lgkmcnt(0)
	v_mfma_f32_16x16x32_bf16 v[126:129], v[160:163], v[176:179], v[126:129]
	v_mfma_f32_16x16x32_bf16 v[122:125], v[168:171], v[176:179], v[122:125]
	v_mfma_f32_16x16x32_bf16 v[114:117], v[160:163], v[184:187], v[114:117]
	v_mfma_f32_16x16x32_bf16 v[106:109], v[168:171], v[184:187], v[106:109]
	v_mfma_f32_16x16x32_bf16 v[98:101], v[160:163], v[192:195], v[98:101]
	v_mfma_f32_16x16x32_bf16 v[90:93], v[168:171], v[192:195], v[90:93]
	v_mfma_f32_16x16x32_bf16 v[82:85], v[160:163], v[200:203], v[82:85]
	v_mfma_f32_16x16x32_bf16 v[74:77], v[168:171], v[200:203], v[74:77]
	v_mfma_f32_16x16x32_bf16 v[126:129], v[164:167], v[180:183], v[126:129]
	v_mfma_f32_16x16x32_bf16 v[122:125], v[172:175], v[180:183], v[122:125]
	v_mfma_f32_16x16x32_bf16 v[114:117], v[164:167], v[188:191], v[114:117]
	v_mfma_f32_16x16x32_bf16 v[106:109], v[172:175], v[188:191], v[106:109]
	v_mfma_f32_16x16x32_bf16 v[98:101], v[164:167], v[196:199], v[98:101]
	v_mfma_f32_16x16x32_bf16 v[90:93], v[172:175], v[196:199], v[90:93]
	v_mfma_f32_16x16x32_bf16 v[82:85], v[164:167], v[204:207], v[82:85]
	v_mfma_f32_16x16x32_bf16 v[74:77], v[172:175], v[204:207], v[74:77]
	s_setprio 0
	s_barrier
	s_add_i32 s28, 16, 0x1c000
	s_add_i32 s29, s49, s11
	v_add_u32_e32 v159, s28, v148
	v_lshl_add_u64 v[146:147], v[146:147], 0, s[6:7]
	s_mov_b32 m0, s29
	ds_read_b128 v[208:211], v159
	ds_read_b128 v[212:215], v159 offset:1024
	ds_read_b128 v[216:219], v159 offset:2048
	ds_read_b128 v[220:223], v159 offset:3072
	global_load_lds_dwordx4 v[146:147], off
	v_lshl_add_u64 v[146:147], v[224:225], 0, s[6:7]
	s_add_i32 m0, s29, 0x2000
	s_nop 0
	global_load_lds_dwordx4 v[146:147], off
	s_barrier
; #define PG8_STAGE(bufoff, gbase, voff) do { _Pragma("unroll") for (int _i = 0; _i < 2; ++_i) \
;         __builtin_amdgcn_global_load_lds((const unsigned*)((const char*)(gbase) + (voff)[_i]), (LAS unsigned*)(lds + (bufoff) + ldsw + _i * 8192), 16, 0, 0); } while (0)
; #define PG8_LDA(dst, b, h) do { _Pragma("unroll") for (int m = 0; m < 4; ++m) _Pragma("unroll") for (int k = 0; k < 2; ++k) dst[m][k] = *(const LAS bf16x8*)(lds + PG8_SA(b, h) + aoff + m * 2048 + k * 1024); } while (0)
; #define PG8_MMA(ai, bj, At, Bt) do { __builtin_amdgcn_s_setprio(1); _Pragma("unroll") for (int m = 0; m < 4; ++m) _Pragma("unroll") for (int n = 0; n < 2; ++n) _Pragma("unroll") for (int k = 0; k < 2; ++k) \
;         acc[ai][bj][m][n] = __builtin_amdgcn_mfma_f32_16x16x32_bf16(Bt[n][k], At[m][k], acc[ai][bj][m][n], 0, 0, 0); __builtin_amdgcn_s_setprio(0); } while (0)
; #define PG8_WAIT_V(n) asm volatile("s_waitcnt vmcnt(" #n ")" ::: "memory")
; #define PG8_WAIT_L(n) asm volatile("s_waitcnt lgkmcnt(" #n ")" ::: "memory")
; #define PG8_BAR __builtin_amdgcn_s_barrier()
; #define PG8_SCHED __builtin_amdgcn_sched_barrier(0)
; template <class Sched, class Epi>
; __device__ __forceinline__ void gemm_phase(LAS unsigned char* lds, const Sched& S, const Epi& E, const int K, const int lda, const int ldb) {
;     ...
;             PG8_BAR; PG8_WAIT_L(0); PG8_MMA(0, 1, At, B1); PG8_BAR;
;             PG8_LDA(At, 1, 1); PG8_STAGE(PG8_SA(1, 0), a3, voffA);
;             PG8_BAR; PG8_WAIT_L(0); if (!chalf) PG8_MMA(1, 0, At, B0); PG8_BAR; PG8_SCHED;
;             PG8_STAGE(PG8_SB(1, 1), b3 + hstepB, voffB);
;             PG8_WAIT_V(6); PG8_BAR; if (!chalf) PG8_MMA(1, 1, At, B1); PG8_BAR;
;         }
;     __device__ __forceinline__ void operator()(EPI_ARGS) const {
;         const int c0 = u.pn * 256; size_t eb; int pitch, cl;
;         if (c0 < C_U) { eb = E_PC; pitch = 4096; cl = c0; } else if (c0 < C_ZB) { eb = E_PU; pitch = 1024; cl = c0 - C_U; } else if (c0 < C_F) { eb = E_PZB; pitch = 1024; cl = c0 - C_ZB; }
;         else if (c0 < C_ZC) { eb = E_PF; pitch = 1024; cl = c0 - C_F; } else if (c0 < C_GL) { eb = E_PZC; pitch = 1024; cl = c0 - C_ZC; } else { eb = E_PGL; pitch = 6144; cl = c0 - C_GL; }
	s_waitcnt lgkmcnt(0)
	s_setprio 1
	s_waitcnt lgkmcnt(0)
	v_mfma_f32_16x16x32_bf16 v[118:121], v[208:211], v[176:179], v[118:121]
	v_mfma_f32_16x16x32_bf16 v[110:113], v[216:219], v[176:179], v[110:113]
	v_mfma_f32_16x16x32_bf16 v[102:105], v[208:211], v[184:187], v[102:105]
	v_mfma_f32_16x16x32_bf16 v[94:97], v[216:219], v[184:187], v[94:97]
	v_mfma_f32_16x16x32_bf16 v[86:89], v[208:211], v[192:195], v[86:89]
	v_mfma_f32_16x16x32_bf16 v[78:81], v[216:219], v[192:195], v[78:81]
	v_mfma_f32_16x16x32_bf16 v[70:73], v[208:211], v[200:203], v[70:73]
	v_mfma_f32_16x16x32_bf16 v[66:69], v[216:219], v[200:203], v[66:69]
	v_mfma_f32_16x16x32_bf16 v[118:121], v[212:215], v[180:183], v[118:121]
	v_mfma_f32_16x16x32_bf16 v[110:113], v[220:223], v[180:183], v[110:113]
	v_mfma_f32_16x16x32_bf16 v[102:105], v[212:215], v[188:191], v[102:105]
	v_mfma_f32_16x16x32_bf16 v[94:97], v[220:223], v[188:191], v[94:97]
	v_mfma_f32_16x16x32_bf16 v[86:89], v[212:215], v[196:199], v[86:89]
	v_mfma_f32_16x16x32_bf16 v[78:81], v[220:223], v[196:199], v[78:81]
	v_mfma_f32_16x16x32_bf16 v[70:73], v[212:215], v[204:207], v[70:73]
	v_mfma_f32_16x16x32_bf16 v[66:69], v[220:223], v[204:207], v[66:69]
	s_setprio 0
	s_mov_b32 m0, s41
	v_lshl_add_u64 v[146:147], v[226:227], 0, s[6:7]
	s_barrier
	ds_read_b128 v[176:179], v157 offset:49152
	ds_read_b128 v[180:183], v157 offset:50176
	ds_read_b128 v[184:187], v157 offset:51200
	ds_read_b128 v[188:191], v157 offset:52224
	ds_read_b128 v[192:195], v157 offset:53248
	ds_read_b128 v[196:199], v157 offset:54272
	ds_read_b128 v[200:203], v157 offset:55296
	ds_read_b128 v[204:207], v157 offset:56320
	global_load_lds_dwordx4 v[146:147], off
	v_lshl_add_u64 v[146:147], v[228:229], 0, s[6:7]
	s_mov_b32 m0, s42
	s_nop 0
	global_load_lds_dwordx4 v[146:147], off
	s_barrier
	s_waitcnt lgkmcnt(0)
	s_setprio 1
	s_waitcnt lgkmcnt(0)
	v_mfma_f32_16x16x32_bf16 v[62:65], v[160:163], v[176:179], v[62:65]
	v_mfma_f32_16x16x32_bf16 v[58:61], v[168:171], v[176:179], v[58:61]
	v_mfma_f32_16x16x32_bf16 v[50:53], v[160:163], v[184:187], v[50:53]
	v_mfma_f32_16x16x32_bf16 v[42:45], v[168:171], v[184:187], v[42:45]
	v_mfma_f32_16x16x32_bf16 v[34:37], v[160:163], v[192:195], v[34:37]
	v_mfma_f32_16x16x32_bf16 v[26:29], v[168:171], v[192:195], v[26:29]
	v_mfma_f32_16x16x32_bf16 v[18:21], v[160:163], v[200:203], v[18:21]
	v_mfma_f32_16x16x32_bf16 v[10:13], v[168:171], v[200:203], v[10:13]
	v_mfma_f32_16x16x32_bf16 v[62:65], v[164:167], v[180:183], v[62:65]
	v_mfma_f32_16x16x32_bf16 v[58:61], v[172:175], v[180:183], v[58:61]
	v_mfma_f32_16x16x32_bf16 v[50:53], v[164:167], v[188:191], v[50:53]
	v_mfma_f32_16x16x32_bf16 v[42:45], v[172:175], v[188:191], v[42:45]
	v_mfma_f32_16x16x32_bf16 v[34:37], v[164:167], v[196:199], v[34:37]
	v_mfma_f32_16x16x32_bf16 v[26:29], v[172:175], v[196:199], v[26:29]
	v_mfma_f32_16x16x32_bf16 v[18:21], v[164:167], v[204:207], v[18:21]
	v_mfma_f32_16x16x32_bf16 v[10:13], v[172:175], v[204:207], v[10:13]
	s_setprio 0
	s_barrier
	s_add_u32 s26, s26, 0x80080
	s_addc_u32 s27, s27, 0
	s_add_i32 s28, s28, s11
	s_mov_b32 m0, s28
	s_nop 0
	global_load_lds_dwordx4 v134, s[26:27]
	s_add_i32 m0, s28, 0x2000
	s_nop 0
	global_load_lds_dwordx4 v130, s[26:27]
	s_waitcnt vmcnt(6)
	s_barrier
	s_setprio 1
	v_mfma_f32_16x16x32_bf16 v[54:57], v[208:211], v[176:179], v[54:57]
	v_mfma_f32_16x16x32_bf16 v[46:49], v[216:219], v[176:179], v[46:49]
	v_mfma_f32_16x16x32_bf16 v[38:41], v[208:211], v[184:187], v[38:41]
	v_mfma_f32_16x16x32_bf16 v[30:33], v[216:219], v[184:187], v[30:33]
	v_mfma_f32_16x16x32_bf16 v[22:25], v[208:211], v[192:195], v[22:25]
	v_mfma_f32_16x16x32_bf16 v[14:17], v[216:219], v[192:195], v[14:17]
	v_mfma_f32_16x16x32_bf16 v[6:9], v[208:211], v[200:203], v[6:9]
	v_mfma_f32_16x16x32_bf16 v[2:5], v[216:219], v[200:203], v[2:5]
	v_mfma_f32_16x16x32_bf16 v[54:57], v[212:215], v[180:183], v[54:57]
	v_mfma_f32_16x16x32_bf16 v[46:49], v[220:223], v[180:183], v[46:49]
	v_mfma_f32_16x16x32_bf16 v[38:41], v[212:215], v[188:191], v[38:41]
	v_mfma_f32_16x16x32_bf16 v[30:33], v[220:223], v[188:191], v[30:33]
	v_mfma_f32_16x16x32_bf16 v[22:25], v[212:215], v[196:199], v[22:25]
	v_mfma_f32_16x16x32_bf16 v[14:17], v[220:223], v[196:199], v[14:17]
	v_mfma_f32_16x16x32_bf16 v[6:9], v[212:215], v[204:207], v[6:9]
	v_mfma_f32_16x16x32_bf16 v[2:5], v[220:223], v[204:207], v[2:5]
	s_setprio 0
	s_add_i32 s48, s48, 2
	s_add_u32 s13, s13, 0x100
	s_addc_u32 s15, s15, 0
	s_add_u32 s24, s24, 0x100
	s_addc_u32 s25, s25, 0
	s_cmp_gt_u32 s48, 29
	s_barrier
	s_cbranch_scc0 .LBB0_1092
	s_lshl_b32 s22, s47, 8
	s_cmp_lt_i32 s47, 16
	s_cbranch_scc1 .LBB0_1109
	s_cmp_gt_u32 s47, 19
	s_mov_b64 s[26:27], -1
	s_cbranch_scc0 .LBB0_1107
	s_cmp_gt_u32 s47, 23
	s_cbranch_scc0 .LBB0_1104
	s_cmp_gt_u32 s47, 27
	s_cbranch_scc0 .LBB0_1101
	s_cmp_gt_u32 s47, 31
	s_mov_b64 s[20:21], -1
	s_cbranch_scc0 .LBB0_1099
	s_add_i32 s13, s22, 0xffffe000
	s_mov_b64 s[20:21], 0

; #define PG8_STAGE(bufoff, gbase, voff) do { _Pragma("unroll") for (int _i = 0; _i < 2; ++_i) \
;         __builtin_amdgcn_global_load_lds((const unsigned*)((const char*)(gbase) + (voff)[_i]), (LAS unsigned*)(lds + (bufoff) + ldsw + _i * 8192), 16, 0, 0); } while (0)
; #define PG8_LDA(dst, b, h) do { _Pragma("unroll") for (int m = 0; m < 4; ++m) _Pragma("unroll") for (int k = 0; k < 2; ++k) dst[m][k] = *(const LAS bf16x8*)(lds + PG8_SA(b, h) + aoff + m * 2048 + k * 1024); } while (0)
; #define PG8_LDB(dst, b, h) do { _Pragma("unroll") for (int n = 0; n < 2; ++n) _Pragma("unroll") for (int k = 0; k < 2; ++k) dst[n][k] = *(const LAS bf16x8*)(lds + PG8_SB(b, h) + boff + n * 2048 + k * 1024); } while (0)
; #define PG8_MMA(ai, bj, At, Bt) do { __builtin_amdgcn_s_setprio(1); _Pragma("unroll") for (int m = 0; m < 4; ++m) _Pragma("unroll") for (int n = 0; n < 2; ++n) _Pragma("unroll") for (int k = 0; k < 2; ++k) \
;         acc[ai][bj][m][n] = __builtin_amdgcn_mfma_f32_16x16x32_bf16(Bt[n][k], At[m][k], acc[ai][bj][m][n], 0, 0, 0); __builtin_amdgcn_s_setprio(0); } while (0)
; #define PG8_WAIT_V(n) asm volatile("s_waitcnt vmcnt(" #n ")" ::: "memory")
; #define PG8_WAIT_L(n) asm volatile("s_waitcnt lgkmcnt(" #n ")" ::: "memory")
; #define PG8_BAR __builtin_amdgcn_s_barrier()
; #define PG8_SCHED __builtin_amdgcn_sched_barrier(0)
; template <class Sched, class Epi>
; __device__ __forceinline__ void gemm_phase(LAS unsigned char* lds, const Sched& S, const Epi& E, const int K, const int lda, const int ldb) {
;     ...
;             PG8_LDB(B0, 0, 0); PG8_SCHED; PG8_LDA(At, 0, 0); PG8_STAGE(PG8_SA(1, 1), a1 + hstepA, voffA);
;             PG8_WAIT_L(8); PG8_BAR; PG8_WAIT_L(0); PG8_MMA(0, 0, At, B0); PG8_BAR; PG8_SCHED;
;             PG8_LDB(B1, 0, 1); PG8_STAGE(PG8_SB(0, 0), b2, voffB);
;             PG8_BAR; PG8_WAIT_L(0); PG8_MMA(0, 1, At, B1); PG8_BAR;
;             PG8_LDA(At, 0, 1); PG8_STAGE(PG8_SA(0, 0), a2, voffA);
;             PG8_BAR; PG8_WAIT_L(0); if (!chalf) PG8_MMA(1, 0, At, B0); PG8_BAR; PG8_SCHED;
;             PG8_STAGE(PG8_SB(0, 1), b2 + hstepB, voffB);
;             PG8_WAIT_V(6); PG8_BAR; if (!chalf) PG8_MMA(1, 1, At, B1); PG8_BAR;
.LBB0_1390:
	s_add_u32 s22, s18, s20
	ds_read_b128 v[148:151], v143
	ds_read_b128 v[152:155], v143 offset:1024
	ds_read_b128 v[156:159], v143 offset:2048
	ds_read_b128 v[160:163], v143 offset:3072
	s_addc_u32 s23, s19, s21
	s_add_u32 s22, s22, 0x294d8100
	s_addc_u32 s23, s23, 0
	s_add_u32 s41, s26, s20
	s_addc_u32 s42, s27, s21
	s_cmpk_eq_i32 s20, 0xf00
	s_cselect_b32 s25, s13, s23
	s_cselect_b32 s24, s12, s22
	s_cselect_b32 s23, s15, s42
	s_cselect_b32 s22, s14, s41
	s_mov_b32 m0, s29
	v_lshl_add_u64 v[196:197], v[140:141], 0, s[20:21]
	ds_read_b128 v[164:167], v144
	ds_read_b128 v[168:171], v144 offset:1024
	ds_read_b128 v[172:175], v144 offset:2048
	ds_read_b128 v[176:179], v144 offset:3072
	ds_read_b128 v[180:183], v144 offset:4096
	ds_read_b128 v[184:187], v144 offset:5120
	ds_read_b128 v[188:191], v144 offset:6144
	ds_read_b128 v[192:195], v144 offset:7168
	global_load_lds_dwordx4 v[196:197], off
	v_lshl_add_u64 v[196:197], v[138:139], 0, s[20:21]
	s_mov_b32 m0, s30
	s_nop 0
	global_load_lds_dwordx4 v[196:197], off
	s_waitcnt lgkmcnt(8)
	s_barrier
	s_waitcnt lgkmcnt(0)
	s_setprio 1
	s_waitcnt lgkmcnt(0)
	v_mfma_f32_16x16x32_bf16 v[126:129], v[148:151], v[164:167], v[126:129]
	v_mfma_f32_16x16x32_bf16 v[122:125], v[156:159], v[164:167], v[122:125]
	v_mfma_f32_16x16x32_bf16 v[110:113], v[148:151], v[172:175], v[110:113]
	v_mfma_f32_16x16x32_bf16 v[106:109], v[156:159], v[172:175], v[106:109]
	v_mfma_f32_16x16x32_bf16 v[94:97], v[148:151], v[180:183], v[94:97]
	v_mfma_f32_16x16x32_bf16 v[90:93], v[156:159], v[180:183], v[90:93]
	v_mfma_f32_16x16x32_bf16 v[78:81], v[148:151], v[188:191], v[78:81]
	v_mfma_f32_16x16x32_bf16 v[74:77], v[156:159], v[188:191], v[74:77]
	v_mfma_f32_16x16x32_bf16 v[126:129], v[152:155], v[168:171], v[126:129]
	v_mfma_f32_16x16x32_bf16 v[122:125], v[160:163], v[168:171], v[122:125]
	v_mfma_f32_16x16x32_bf16 v[110:113], v[152:155], v[176:179], v[110:113]
	v_mfma_f32_16x16x32_bf16 v[106:109], v[160:163], v[176:179], v[106:109]
	v_mfma_f32_16x16x32_bf16 v[94:97], v[152:155], v[184:187], v[94:97]
	v_mfma_f32_16x16x32_bf16 v[90:93], v[160:163], v[184:187], v[90:93]
	v_mfma_f32_16x16x32_bf16 v[78:81], v[152:155], v[192:195], v[78:81]
	v_mfma_f32_16x16x32_bf16 v[74:77], v[160:163], v[192:195], v[74:77]
	s_setprio 0
	s_barrier
	s_mov_b32 m0, s31
	v_lshl_add_u64 v[212:213], s[22:23], 0, v[132:133]
	ds_read_b128 v[196:199], v145
	ds_read_b128 v[200:203], v145 offset:1024
	ds_read_b128 v[204:207], v145 offset:2048
	ds_read_b128 v[208:211], v145 offset:3072
	global_load_lds_dwordx4 v[212:213], off
	v_lshl_add_u64 v[214:215], s[22:23], 0, v[136:137]
	s_mov_b32 m0, s34
	s_nop 0
	global_load_lds_dwordx4 v[214:215], off
	s_barrier
	s_waitcnt lgkmcnt(0)
	s_setprio 1
	s_waitcnt lgkmcnt(0)
	v_mfma_f32_16x16x32_bf16 v[118:121], v[196:199], v[164:167], v[118:121]
	v_mfma_f32_16x16x32_bf16 v[114:117], v[204:207], v[164:167], v[114:117]
	v_mfma_f32_16x16x32_bf16 v[102:105], v[196:199], v[172:175], v[102:105]
	v_mfma_f32_16x16x32_bf16 v[98:101], v[204:207], v[172:175], v[98:101]
	v_mfma_f32_16x16x32_bf16 v[86:89], v[196:199], v[180:183], v[86:89]
	v_mfma_f32_16x16x32_bf16 v[82:85], v[204:207], v[180:183], v[82:85]
	v_mfma_f32_16x16x32_bf16 v[70:73], v[196:199], v[188:191], v[70:73]
	v_mfma_f32_16x16x32_bf16 v[66:69], v[204:207], v[188:191], v[66:69]
	v_mfma_f32_16x16x32_bf16 v[118:121], v[200:203], v[168:171], v[118:121]
	v_mfma_f32_16x16x32_bf16 v[114:117], v[208:211], v[168:171], v[114:117]
	v_mfma_f32_16x16x32_bf16 v[102:105], v[200:203], v[176:179], v[102:105]
	v_mfma_f32_16x16x32_bf16 v[98:101], v[208:211], v[176:179], v[98:101]
	v_mfma_f32_16x16x32_bf16 v[86:89], v[200:203], v[184:187], v[86:89]
	v_mfma_f32_16x16x32_bf16 v[82:85], v[208:211], v[184:187], v[82:85]
	v_mfma_f32_16x16x32_bf16 v[70:73], v[200:203], v[192:195], v[70:73]
	v_mfma_f32_16x16x32_bf16 v[66:69], v[208:211], v[192:195], v[66:69]
	s_setprio 0
	s_mov_b32 m0, s1
	v_lshl_add_u64 v[216:217], s[24:25], 0, v[130:131]
	s_barrier
	ds_read_b128 v[164:167], v144 offset:16384
	ds_read_b128 v[168:171], v144 offset:17408
	ds_read_b128 v[172:175], v144 offset:18432
	ds_read_b128 v[176:179], v144 offset:19456
	ds_read_b128 v[180:183], v144 offset:20480
	ds_read_b128 v[184:187], v144 offset:21504
	ds_read_b128 v[188:191], v144 offset:22528
	ds_read_b128 v[192:195], v144 offset:23552
	global_load_lds_dwordx4 v[216:217], off
	v_lshl_add_u64 v[218:219], s[24:25], 0, v[134:135]
	s_mov_b32 m0, s2
	s_nop 0
	global_load_lds_dwordx4 v[218:219], off
	s_barrier
	s_waitcnt lgkmcnt(0)
	s_setprio 1
	s_waitcnt lgkmcnt(0)
	v_mfma_f32_16x16x32_bf16 v[62:65], v[148:151], v[164:167], v[62:65]
	v_mfma_f32_16x16x32_bf16 v[58:61], v[156:159], v[164:167], v[58:61]
	v_mfma_f32_16x16x32_bf16 v[46:49], v[148:151], v[172:175], v[46:49]
	v_mfma_f32_16x16x32_bf16 v[42:45], v[156:159], v[172:175], v[42:45]
	v_mfma_f32_16x16x32_bf16 v[30:33], v[148:151], v[180:183], v[30:33]
	v_mfma_f32_16x16x32_bf16 v[26:29], v[156:159], v[180:183], v[26:29]
	v_mfma_f32_16x16x32_bf16 v[14:17], v[148:151], v[188:191], v[14:17]
	v_mfma_f32_16x16x32_bf16 v[10:13], v[156:159], v[188:191], v[10:13]
	v_mfma_f32_16x16x32_bf16 v[62:65], v[152:155], v[168:171], v[62:65]
	v_mfma_f32_16x16x32_bf16 v[58:61], v[160:163], v[168:171], v[58:61]
	v_mfma_f32_16x16x32_bf16 v[46:49], v[152:155], v[176:179], v[46:49]
	v_mfma_f32_16x16x32_bf16 v[42:45], v[160:163], v[176:179], v[42:45]
	v_mfma_f32_16x16x32_bf16 v[30:33], v[152:155], v[184:187], v[30:33]
	v_mfma_f32_16x16x32_bf16 v[26:29], v[160:163], v[184:187], v[26:29]
	v_mfma_f32_16x16x32_bf16 v[14:17], v[152:155], v[192:195], v[14:17]
	v_mfma_f32_16x16x32_bf16 v[10:13], v[160:163], v[192:195], v[10:13]
	s_setprio 0
	s_barrier
; #define PG8_STAGE(bufoff, gbase, voff) do { _Pragma("unroll") for (int _i = 0; _i < 2; ++_i) \
;         __builtin_amdgcn_global_load_lds((const unsigned*)((const char*)(gbase) + (voff)[_i]), (LAS unsigned*)(lds + (bufoff) + ldsw + _i * 8192), 16, 0, 0); } while (0)
; #define PG8_LDA(dst, b, h) do { _Pragma("unroll") for (int m = 0; m < 4; ++m) _Pragma("unroll") for (int k = 0; k < 2; ++k) dst[m][k] = *(const LAS bf16x8*)(lds + PG8_SA(b, h) + aoff + m * 2048 + k * 1024); } while (0)
; #define PG8_LDB(dst, b, h) do { _Pragma("unroll") for (int n = 0; n < 2; ++n) _Pragma("unroll") for (int k = 0; k < 2; ++k) dst[n][k] = *(const LAS bf16x8*)(lds + PG8_SB(b, h) + boff + n * 2048 + k * 1024); } while (0)
; #define PG8_MMA(ai, bj, At, Bt) do { __builtin_amdgcn_s_setprio(1); _Pragma("unroll") for (int m = 0; m < 4; ++m) _Pragma("unroll") for (int n = 0; n < 2; ++n) _Pragma("unroll") for (int k = 0; k < 2; ++k) \
;         acc[ai][bj][m][n] = __builtin_amdgcn_mfma_f32_16x16x32_bf16(Bt[n][k], At[m][k], acc[ai][bj][m][n], 0, 0, 0); __builtin_amdgcn_s_setprio(0); } while (0)
; #define PG8_WAIT_V(n) asm volatile("s_waitcnt vmcnt(" #n ")" ::: "memory")
; #define PG8_WAIT_L(n) asm volatile("s_waitcnt lgkmcnt(" #n ")" ::: "memory")
; #define PG8_BAR __builtin_amdgcn_s_barrier()
; #define PG8_SCHED __builtin_amdgcn_sched_barrier(0)
; template <class Sched, class Epi>
; __device__ __forceinline__ void gemm_phase(LAS unsigned char* lds, const Sched& S, const Epi& E, const int K, const int lda, const int ldb) {
;     ...
;             PG8_STAGE(PG8_SB(0, 1), b2 + hstepB, voffB);
;             PG8_WAIT_V(6); PG8_BAR; if (!chalf) PG8_MMA(1, 1, At, B1); PG8_BAR;
;             PG8_LDB(B0, 1, 0); PG8_SCHED; PG8_LDA(At, 1, 0); PG8_STAGE(PG8_SA(0, 1), a2 + hstepA, voffA);
;             PG8_WAIT_L(8); PG8_BAR; PG8_WAIT_L(0); PG8_MMA(0, 0, At, B0); PG8_BAR; PG8_SCHED;
;             PG8_LDB(B1, 1, 1); PG8_STAGE(PG8_SB(1, 0), b3, voffB);
;             PG8_BAR; PG8_WAIT_L(0); PG8_MMA(0, 1, At, B1); PG8_BAR;
;             PG8_LDA(At, 1, 1); PG8_STAGE(PG8_SA(1, 0), a3, voffA);
;             PG8_BAR; PG8_WAIT_L(0); if (!chalf) PG8_MMA(1, 0, At, B0); PG8_BAR; PG8_SCHED;
	s_add_u32 s42, s22, 0x80000
	s_addc_u32 s43, s23, 0
	s_mov_b32 m0, s35
	s_nop 0
	global_load_lds_dwordx4 v132, s[42:43]
	s_mov_b32 m0, s36
	s_nop 0
	global_load_lds_dwordx4 v136, s[42:43]
	s_waitcnt vmcnt(6)
	s_barrier
	s_setprio 1
	v_mfma_f32_16x16x32_bf16 v[54:57], v[196:199], v[164:167], v[54:57]
	v_mfma_f32_16x16x32_bf16 v[50:53], v[204:207], v[164:167], v[50:53]
	v_mfma_f32_16x16x32_bf16 v[38:41], v[196:199], v[172:175], v[38:41]
	v_mfma_f32_16x16x32_bf16 v[34:37], v[204:207], v[172:175], v[34:37]
	v_mfma_f32_16x16x32_bf16 v[22:25], v[196:199], v[180:183], v[22:25]
	v_mfma_f32_16x16x32_bf16 v[18:21], v[204:207], v[180:183], v[18:21]
	v_mfma_f32_16x16x32_bf16 v[6:9], v[196:199], v[188:191], v[6:9]
	v_mfma_f32_16x16x32_bf16 v[2:5], v[204:207], v[188:191], v[2:5]
	v_mfma_f32_16x16x32_bf16 v[54:57], v[200:203], v[168:171], v[54:57]
	v_mfma_f32_16x16x32_bf16 v[50:53], v[208:211], v[168:171], v[50:53]
	v_mfma_f32_16x16x32_bf16 v[38:41], v[200:203], v[176:179], v[38:41]
	v_mfma_f32_16x16x32_bf16 v[34:37], v[208:211], v[176:179], v[34:37]
	v_mfma_f32_16x16x32_bf16 v[22:25], v[200:203], v[184:187], v[22:25]
	v_mfma_f32_16x16x32_bf16 v[18:21], v[208:211], v[184:187], v[18:21]
	v_mfma_f32_16x16x32_bf16 v[6:9], v[200:203], v[192:195], v[6:9]
	v_mfma_f32_16x16x32_bf16 v[2:5], v[208:211], v[192:195], v[2:5]
	s_setprio 0
	s_barrier
	ds_read_b128 v[148:151], v146
	ds_read_b128 v[152:155], v146 offset:1024
	ds_read_b128 v[156:159], v146 offset:2048
	ds_read_b128 v[160:163], v146 offset:3072
	s_add_u32 s24, s24, 0x80000
	s_addc_u32 s25, s25, 0
	s_mov_b32 m0, s3
	ds_read_b128 v[164:167], v144 offset:32768
	ds_read_b128 v[168:171], v144 offset:33792
	ds_read_b128 v[172:175], v144 offset:34816
	ds_read_b128 v[176:179], v144 offset:35840
	ds_read_b128 v[180:183], v144 offset:36864
	ds_read_b128 v[184:187], v144 offset:37888
	ds_read_b128 v[188:191], v144 offset:38912
	ds_read_b128 v[192:195], v144 offset:39936
	global_load_lds_dwordx4 v130, s[24:25]
	s_mov_b32 m0, s7
	s_nop 0
	global_load_lds_dwordx4 v134, s[24:25]
	s_waitcnt lgkmcnt(8)
	s_barrier
	s_waitcnt lgkmcnt(0)
	s_setprio 1
	s_waitcnt lgkmcnt(0)
	v_mfma_f32_16x16x32_bf16 v[126:129], v[148:151], v[164:167], v[126:129]
	v_mfma_f32_16x16x32_bf16 v[122:125], v[156:159], v[164:167], v[122:125]
	v_mfma_f32_16x16x32_bf16 v[110:113], v[148:151], v[172:175], v[110:113]
	v_mfma_f32_16x16x32_bf16 v[106:109], v[156:159], v[172:175], v[106:109]
	v_mfma_f32_16x16x32_bf16 v[94:97], v[148:151], v[180:183], v[94:97]
	v_mfma_f32_16x16x32_bf16 v[90:93], v[156:159], v[180:183], v[90:93]
	v_mfma_f32_16x16x32_bf16 v[78:81], v[148:151], v[188:191], v[78:81]
	v_mfma_f32_16x16x32_bf16 v[74:77], v[156:159], v[188:191], v[74:77]
	v_mfma_f32_16x16x32_bf16 v[126:129], v[152:155], v[168:171], v[126:129]
	v_mfma_f32_16x16x32_bf16 v[122:125], v[160:163], v[168:171], v[122:125]
	v_mfma_f32_16x16x32_bf16 v[110:113], v[152:155], v[176:179], v[110:113]
	v_mfma_f32_16x16x32_bf16 v[106:109], v[160:163], v[176:179], v[106:109]
	v_mfma_f32_16x16x32_bf16 v[94:97], v[152:155], v[184:187], v[94:97]
	v_mfma_f32_16x16x32_bf16 v[90:93], v[160:163], v[184:187], v[90:93]
	v_mfma_f32_16x16x32_bf16 v[78:81], v[152:155], v[192:195], v[78:81]
	v_mfma_f32_16x16x32_bf16 v[74:77], v[160:163], v[192:195], v[74:77]
	s_setprio 0
	s_barrier
	s_mov_b32 m0, s37
	v_lshl_add_u64 v[212:213], v[212:213], 0, s[16:17]
	ds_read_b128 v[196:199], v147
	ds_read_b128 v[200:203], v147 offset:1024
	ds_read_b128 v[204:207], v147 offset:2048
	ds_read_b128 v[208:211], v147 offset:3072
	global_load_lds_dwordx4 v[212:213], off
	v_lshl_add_u64 v[212:213], v[214:215], 0, s[16:17]
	s_mov_b32 m0, s38
	s_nop 0
	global_load_lds_dwordx4 v[212:213], off
	s_barrier
	s_waitcnt lgkmcnt(0)
	s_setprio 1
	s_waitcnt lgkmcnt(0)
	v_mfma_f32_16x16x32_bf16 v[118:121], v[196:199], v[164:167], v[118:121]
	v_mfma_f32_16x16x32_bf16 v[114:117], v[204:207], v[164:167], v[114:117]
	v_mfma_f32_16x16x32_bf16 v[102:105], v[196:199], v[172:175], v[102:105]
	v_mfma_f32_16x16x32_bf16 v[98:101], v[204:207], v[172:175], v[98:101]
	v_mfma_f32_16x16x32_bf16 v[86:89], v[196:199], v[180:183], v[86:89]
	v_mfma_f32_16x16x32_bf16 v[82:85], v[204:207], v[180:183], v[82:85]
	v_mfma_f32_16x16x32_bf16 v[70:73], v[196:199], v[188:191], v[70:73]
	v_mfma_f32_16x16x32_bf16 v[66:69], v[204:207], v[188:191], v[66:69]
	v_mfma_f32_16x16x32_bf16 v[118:121], v[200:203], v[168:171], v[118:121]
	v_mfma_f32_16x16x32_bf16 v[114:117], v[208:211], v[168:171], v[114:117]
	v_mfma_f32_16x16x32_bf16 v[102:105], v[200:203], v[176:179], v[102:105]
	v_mfma_f32_16x16x32_bf16 v[98:101], v[208:211], v[176:179], v[98:101]
	v_mfma_f32_16x16x32_bf16 v[86:89], v[200:203], v[184:187], v[86:89]
	v_mfma_f32_16x16x32_bf16 v[82:85], v[208:211], v[184:187], v[82:85]
	v_mfma_f32_16x16x32_bf16 v[70:73], v[200:203], v[192:195], v[70:73]
	v_mfma_f32_16x16x32_bf16 v[66:69], v[208:211], v[192:195], v[66:69]
	s_setprio 0
	s_mov_b32 m0, s10
	v_lshl_add_u64 v[212:213], v[216:217], 0, s[16:17]
	s_barrier
	ds_read_b128 v[164:167], v144 offset:49152
	ds_read_b128 v[168:171], v144 offset:50176
	ds_read_b128 v[172:175], v144 offset:51200
	ds_read_b128 v[176:179], v144 offset:52224
	ds_read_b128 v[180:183], v144 offset:53248
	ds_read_b128 v[184:187], v144 offset:54272
	ds_read_b128 v[188:191], v144 offset:55296
	ds_read_b128 v[192:195], v144 offset:56320
	global_load_lds_dwordx4 v[212:213], off
	v_lshl_add_u64 v[212:213], v[218:219], 0, s[16:17]
	s_mov_b32 m0, s11
	s_nop 0
	global_load_lds_dwordx4 v[212:213], off
	s_barrier
; #define PG8_STAGE(bufoff, gbase, voff) do { _Pragma("unroll") for (int _i = 0; _i < 2; ++_i) \
;         __builtin_amdgcn_global_load_lds((const unsigned*)((const char*)(gbase) + (voff)[_i]), (LAS unsigned*)(lds + (bufoff) + ldsw + _i * 8192), 16, 0, 0); } while (0)
; #define PG8_MMA(ai, bj, At, Bt) do { __builtin_amdgcn_s_setprio(1); _Pragma("unroll") for (int m = 0; m < 4; ++m) _Pragma("unroll") for (int n = 0; n < 2; ++n) _Pragma("unroll") for (int k = 0; k < 2; ++k) \
;         acc[ai][bj][m][n] = __builtin_amdgcn_mfma_f32_16x16x32_bf16(Bt[n][k], At[m][k], acc[ai][bj][m][n], 0, 0, 0); __builtin_amdgcn_s_setprio(0); } while (0)
; #define PG8_WAIT_V(n) asm volatile("s_waitcnt vmcnt(" #n ")" ::: "memory")
; #define PG8_WAIT_L(n) asm volatile("s_waitcnt lgkmcnt(" #n ")" ::: "memory")
; #define PG8_BAR __builtin_amdgcn_s_barrier()
; #define PG8_SCHED __builtin_amdgcn_sched_barrier(0)
; template <class Sched, class Epi>
; __device__ __forceinline__ void gemm_phase(LAS unsigned char* lds, const Sched& S, const Epi& E, const int K, const int lda, const int ldb) {
;     ...
;             PG8_BAR; PG8_WAIT_L(0); if (!chalf) PG8_MMA(1, 0, At, B0); PG8_BAR; PG8_SCHED;
;             PG8_STAGE(PG8_SB(1, 1), b3 + hstepB, voffB);
;             PG8_WAIT_V(6); PG8_BAR; if (!chalf) PG8_MMA(1, 1, At, B1); PG8_BAR;
;         }
;     __device__ __forceinline__ void operator()(EPI_ARGS) const {
;     ...
;         for (int ai = 0; ai < 2; ++ai) if (ai == 0 || !u.half) { u32x4 zz[4][2];
; #pragma unroll
;             for (int m = 0; m < 4; ++m)
; #pragma unroll
;                 for (int bj = 0; bj < 2; ++bj) zz[m][bj] = *(const u32x4*)(parts + E_PZC + (size_t)EPI_ROW * 1024 + EPI_COL(bj));
	s_waitcnt lgkmcnt(0)
	s_setprio 1
	s_waitcnt lgkmcnt(0)
	v_mfma_f32_16x16x32_bf16 v[62:65], v[148:151], v[164:167], v[62:65]
	v_mfma_f32_16x16x32_bf16 v[58:61], v[156:159], v[164:167], v[58:61]
	v_mfma_f32_16x16x32_bf16 v[46:49], v[148:151], v[172:175], v[46:49]
	v_mfma_f32_16x16x32_bf16 v[42:45], v[156:159], v[172:175], v[42:45]
	v_mfma_f32_16x16x32_bf16 v[30:33], v[148:151], v[180:183], v[30:33]
	v_mfma_f32_16x16x32_bf16 v[26:29], v[156:159], v[180:183], v[26:29]
	v_mfma_f32_16x16x32_bf16 v[14:17], v[148:151], v[188:191], v[14:17]
	v_mfma_f32_16x16x32_bf16 v[10:13], v[156:159], v[188:191], v[10:13]
	v_mfma_f32_16x16x32_bf16 v[62:65], v[152:155], v[168:171], v[62:65]
	v_mfma_f32_16x16x32_bf16 v[58:61], v[160:163], v[168:171], v[58:61]
	v_mfma_f32_16x16x32_bf16 v[46:49], v[152:155], v[176:179], v[46:49]
	v_mfma_f32_16x16x32_bf16 v[42:45], v[160:163], v[176:179], v[42:45]
	v_mfma_f32_16x16x32_bf16 v[30:33], v[152:155], v[184:187], v[30:33]
	v_mfma_f32_16x16x32_bf16 v[26:29], v[160:163], v[184:187], v[26:29]
	v_mfma_f32_16x16x32_bf16 v[14:17], v[152:155], v[192:195], v[14:17]
	v_mfma_f32_16x16x32_bf16 v[10:13], v[160:163], v[192:195], v[10:13]
	s_setprio 0
	s_barrier
	s_add_u32 s22, s22, 0x80080
	s_addc_u32 s23, s23, 0
	s_mov_b32 m0, s39
	s_nop 0
	global_load_lds_dwordx4 v132, s[22:23]
	s_mov_b32 m0, s40
	s_nop 0
	global_load_lds_dwordx4 v136, s[22:23]
	s_waitcnt vmcnt(6)
	s_barrier
	s_setprio 1
	v_mfma_f32_16x16x32_bf16 v[54:57], v[196:199], v[164:167], v[54:57]
	v_mfma_f32_16x16x32_bf16 v[50:53], v[204:207], v[164:167], v[50:53]
	v_mfma_f32_16x16x32_bf16 v[38:41], v[196:199], v[172:175], v[38:41]
	v_mfma_f32_16x16x32_bf16 v[34:37], v[204:207], v[172:175], v[34:37]
	v_mfma_f32_16x16x32_bf16 v[22:25], v[196:199], v[180:183], v[22:25]
	v_mfma_f32_16x16x32_bf16 v[18:21], v[204:207], v[180:183], v[18:21]
	v_mfma_f32_16x16x32_bf16 v[6:9], v[196:199], v[188:191], v[6:9]
	v_mfma_f32_16x16x32_bf16 v[2:5], v[204:207], v[188:191], v[2:5]
	v_mfma_f32_16x16x32_bf16 v[54:57], v[200:203], v[168:171], v[54:57]
	v_mfma_f32_16x16x32_bf16 v[50:53], v[208:211], v[168:171], v[50:53]
	v_mfma_f32_16x16x32_bf16 v[38:41], v[200:203], v[176:179], v[38:41]
	v_mfma_f32_16x16x32_bf16 v[34:37], v[208:211], v[176:179], v[34:37]
	v_mfma_f32_16x16x32_bf16 v[22:25], v[200:203], v[184:187], v[22:25]
	v_mfma_f32_16x16x32_bf16 v[18:21], v[208:211], v[184:187], v[18:21]
	v_mfma_f32_16x16x32_bf16 v[6:9], v[200:203], v[192:195], v[6:9]
	v_mfma_f32_16x16x32_bf16 v[2:5], v[208:211], v[192:195], v[2:5]
	s_setprio 0
	s_add_i32 s28, s28, 2
	s_add_u32 s20, s20, 0x100
	s_addc_u32 s21, s21, 0
	s_cmp_gt_u32 s28, 29
	s_barrier
	s_cbranch_scc0 .LBB0_1390
	s_sext_i32_i8 s1, s6
	v_add_u32_e32 v152, s8, v1
	v_lshl_or_b32 v1, s1, 8, v142
	s_add_u32 s12, s4, 0x1b9d8000
	v_or_b32_e32 v130, s9, v1
	v_ashrrev_i32_e32 v153, 31, v152
	s_addc_u32 s13, s5, 0
	v_ashrrev_i32_e32 v131, 31, v130
	v_lshlrev_b64 v[132:133], 11, v[152:153]
	v_lshl_add_u64 v[134:135], s[12:13], 0, v[132:133]
	v_lshlrev_b64 v[150:151], 1, v[130:131]
	v_lshl_add_u64 v[130:131], v[134:135], 0, v[150:151]
	global_load_dwordx4 v[154:157], v[130:131], off
	global_load_dwordx4 v[158:161], v[130:131], off offset:256
	v_or_b32_e32 v130, 16, v152
	v_or_b32_e32 v134, 32, v152
	v_or_b32_e32 v136, 48, v152
	v_ashrrev_i32_e32 v131, 31, v130
	v_ashrrev_i32_e32 v135, 31, v134
	s_add_u32 s6, s4, 0x252d8000
	v_ashrrev_i32_e32 v137, 31, v136
	v_lshlrev_b64 v[130:131], 11, v[130:131]
	v_lshlrev_b64 v[134:135], 11, v[134:135]
	s_addc_u32 s7, s5, 0
	v_lshlrev_b64 v[136:137], 11, v[136:137]
	v_lshl_add_u64 v[130:131], s[12:13], 0, v[130:131]
	v_lshl_add_u64 v[134:135], s[12:13], 0, v[134:135]
	v_lshl_add_u64 v[136:137], s[12:13], 0, v[136:137]
	v_lshl_add_u64 v[132:133], s[6:7], 0, v[132:133]
	v_lshl_add_u64 v[130:131], v[130:131], 0, v[150:151]
	v_lshl_add_u64 v[134:135], v[134:135], 0, v[150:151]
	v_lshl_add_u64 v[166:167], v[136:137], 0, v[150:151]
	v_lshl_add_u64 v[168:169], v[132:133], 0, v[150:151]
	global_load_dwordx4 v[162:165], v[130:131], off
	global_load_dwordx4 v[146:149], v[130:131], off offset:256
	global_load_dwordx4 v[142:145], v[134:135], off
	global_load_dwordx4 v[138:141], v[134:135], off offset:256
	s_nop 0
	global_load_dwordx4 v[134:137], v[166:167], off
	global_load_dwordx4 v[130:133], v[166:167], off offset:256
	s_cmpk_lt_u32 s0, 0x100
	s_waitcnt vmcnt(0)
; __device__ __forceinline__ float siluf_(float x) { return x * __builtin_amdgcn_rcpf(1.0f + __expf(-x)); }
; __device__ __forceinline__ u32x4 pack8(const float (&f)[8]) { u32x4 r; r[0] = cvt_pk_bf16(f[0], f[1]); r[1] = cvt_pk_bf16(f[2], f[3]); r[2] = cvt_pk_bf16(f[4], f[5]); r[3] = cvt_pk_bf16(f[6], f[7]); return r; }
;     __device__ __forceinline__ void operator()(EPI_ARGS) const {
;     ...
; #pragma unroll
;             for (int m = 0; m < 4; ++m)
; #pragma unroll
;                 for (int bj = 0; bj < 2; ++bj) { const f32x4 v0 = acc[ai][bj][m][0], v1 = acc[ai][bj][m][1]; float z[8]; unpack8(zz[m][bj], z); float o[8];
; #pragma unroll
;                     for (int j = 0; j < 4; ++j) { o[j] = v0[j] * siluf_(z[j]); o[4 + j] = v1[j] * siluf_(z[4 + j]); }
;                     *(u32x4*)(O + (size_t)EPI_ROW * 1024 + EPI_COL(bj)) = pack8(o); } }
	v_lshlrev_b32_e32 v1, 16, v154
	v_and_b32_e32 v153, 0xffff0000, v154
	v_lshlrev_b32_e32 v154, 16, v155
	v_and_b32_e32 v155, 0xffff0000, v155
	v_lshlrev_b32_e32 v166, 16, v156
	v_and_b32_e32 v156, 0xffff0000, v156
	v_lshlrev_b32_e32 v167, 16, v157
	v_and_b32_e32 v157, 0xffff0000, v157
	v_mul_f32_e32 v171, 0xbfb8aa3b, v1
	v_mul_f32_e32 v172, 0xbfb8aa3b, v166
	v_mul_f32_e32 v173, 0xbfb8aa3b, v153
	v_mul_f32_e32 v174, 0xbfb8aa3b, v156
	v_mul_f32_e32 v175, 0xbfb8aa3b, v154
	v_mul_f32_e32 v176, 0xbfb8aa3b, v167
	v_mul_f32_e32 v177, 0xbfb8aa3b, v155
	v_mul_f32_e32 v178, 0xbfb8aa3b, v157
	v_exp_f32_e32 v171, v171
	v_exp_f32_e32 v172, v172
	v_exp_f32_e32 v173, v173
	v_exp_f32_e32 v174, v174
	v_exp_f32_e32 v175, v175
	v_exp_f32_e32 v176, v176
	v_exp_f32_e32 v177, v177
	v_exp_f32_e32 v178, v178
	v_add_f32_e32 v171, 1.0, v171
	v_add_f32_e32 v172, 1.0, v172
	v_add_f32_e32 v173, 1.0, v173
	v_add_f32_e32 v174, 1.0, v174
	v_add_f32_e32 v175, 1.0, v175
	v_add_f32_e32 v176, 1.0, v176
	v_add_f32_e32 v177, 1.0, v177
	v_add_f32_e32 v178, 1.0, v178
	v_rcp_f32_e32 v171, v171
	v_rcp_f32_e32 v172, v172
	v_rcp_f32_e32 v173, v173
	v_rcp_f32_e32 v174, v174
	v_rcp_f32_e32 v175, v175
	v_rcp_f32_e32 v176, v176
	v_rcp_f32_e32 v177, v177
	v_rcp_f32_e32 v178, v178
	v_mul_f32_e32 v1, v171, v1
	v_mul_f32_e32 v166, v172, v166
	v_mul_f32_e32 v153, v173, v153
	v_mul_f32_e32 v156, v174, v156
	v_mul_f32_e32 v154, v175, v154
	v_mul_f32_e32 v167, v176, v167
	v_mul_f32_e32 v155, v177, v155
	v_lshlrev_b32_e32 v170, 16, v158
	v_mul_f32_e32 v157, v178, v157
	v_mul_f32_e32 v1, v126, v1
	v_mul_f32_e32 v126, v122, v166
	v_mul_f32_e32 v122, v127, v153
	v_mul_f32_e32 v127, v123, v156
	v_mul_f32_e32 v123, v128, v154
	v_mul_f32_e32 v128, v124, v167
	v_mul_f32_e32 v124, v129, v155
	v_mul_f32_e32 v125, v125, v157
	v_cvt_pk_bf16_f32 v122, v1, v122
	v_cvt_pk_bf16_f32 v123, v123, v124
	v_cvt_pk_bf16_f32 v124, v126, v127
	v_mul_f32_e32 v126, 0xbfb8aa3b, v170
	v_cvt_pk_bf16_f32 v125, v128, v125
	global_store_dwordx4 v[168:169], v[122:125], off
	v_exp_f32_e32 v126, v126
	v_and_b32_e32 v1, 0xffff0000, v158
	v_lshlrev_b32_e32 v124, 16, v160
	v_mul_f32_e32 v127, 0xbfb8aa3b, v124
	v_exp_f32_e32 v127, v127
	v_add_f32_e32 v126, 1.0, v126
	v_rcp_f32_e32 v126, v126
	v_and_b32_e32 v125, 0xffff0000, v160
	v_add_f32_e32 v127, 1.0, v127
	v_rcp_f32_e32 v127, v127
	v_mul_f32_e32 v126, v126, v170
	v_mul_f32_e32 v118, v118, v126
	v_mul_f32_e32 v126, 0xbfb8aa3b, v1
	v_mul_f32_e32 v124, v127, v124
	v_exp_f32_e32 v126, v126
	v_mul_f32_e32 v127, 0xbfb8aa3b, v125
	v_exp_f32_e32 v127, v127
	v_lshlrev_b32_e32 v122, 16, v159
	v_mul_f32_e32 v124, v114, v124
	v_add_f32_e32 v114, 1.0, v126
	v_rcp_f32_e32 v114, v114
	v_add_f32_e32 v126, 1.0, v127
	v_mul_f32_e32 v127, 0xbfb8aa3b, v122
	v_exp_f32_e32 v127, v127
	v_mul_f32_e32 v1, v114, v1
	v_rcp_f32_e32 v126, v126
	v_mul_f32_e32 v1, v119, v1
	v_add_f32_e32 v119, 1.0, v127
	v_rcp_f32_e32 v119, v119
	v_lshlrev_b32_e32 v128, 16, v161
	v_and_b32_e32 v123, 0xffff0000, v159
	v_mul_f32_e32 v114, v126, v125
	v_mul_f32_e32 v125, 0xbfb8aa3b, v128
	v_and_b32_e32 v129, 0xffff0000, v161
	v_exp_f32_e32 v125, v125
	v_mul_f32_e32 v126, v115, v114
	v_mul_f32_e32 v114, v119, v122
	v_mul_f32_e32 v119, 0xbfb8aa3b, v123
	v_mul_f32_e32 v115, v120, v114
	v_exp_f32_e32 v119, v119
	v_mul_f32_e32 v120, 0xbfb8aa3b, v129
	v_exp_f32_e32 v120, v120
	v_add_f32_e32 v114, 1.0, v125
	v_rcp_f32_e32 v114, v114
	v_add_f32_e32 v119, 1.0, v119
	v_rcp_f32_e32 v119, v119
	v_add_f32_e32 v120, 1.0, v120
	v_rcp_f32_e32 v120, v120
	v_mul_f32_e32 v114, v114, v128
	v_mul_f32_e32 v122, v116, v114
	v_mul_f32_e32 v114, v119, v123
	v_mul_f32_e32 v116, v121, v114
	v_mul_f32_e32 v114, v120, v129
	v_mul_f32_e32 v117, v117, v114
	v_cvt_pk_bf16_f32 v114, v118, v1
	v_cvt_pk_bf16_f32 v115, v115, v116
	v_cvt_pk_bf16_f32 v116, v124, v126
	v_cvt_pk_bf16_f32 v117, v122, v117
	v_lshlrev_b32_e32 v1, 16, v162
	global_store_dwordx4 v[168:169], v[114:117], off offset:256
	v_mul_f32_e32 v119, 0xbfb8aa3b, v1
	v_exp_f32_e32 v119, v119
	v_lshlrev_b32_e32 v117, 16, v164
	v_mul_f32_e32 v120, 0xbfb8aa3b, v117
	v_exp_f32_e32 v120, v120
	v_add_f32_e32 v119, 1.0, v119
	v_rcp_f32_e32 v119, v119
	v_and_b32_e32 v114, 0xffff0000, v162
	v_add_f32_e32 v120, 1.0, v120
	v_rcp_f32_e32 v120, v120
	v_and_b32_e32 v118, 0xffff0000, v164
	v_mul_f32_e32 v1, v119, v1
	v_mul_f32_e32 v1, v110, v1
	v_mul_f32_e32 v110, v120, v117
	v_mul_f32_e32 v117, 0xbfb8aa3b, v114
	v_mul_f32_e32 v119, 0xbfb8aa3b, v118
	v_exp_f32_e32 v117, v117
	v_exp_f32_e32 v119, v119
	v_lshlrev_b32_e32 v115, 16, v163
	v_mul_f32_e32 v110, v106, v110
	v_add_f32_e32 v106, 1.0, v117
	v_add_f32_e32 v117, 1.0, v119
	v_mul_f32_e32 v119, 0xbfb8aa3b, v115
	v_rcp_f32_e32 v106, v106
	v_exp_f32_e32 v119, v119
	v_rcp_f32_e32 v117, v117
	v_lshlrev_b32_e32 v121, 16, v165
	v_mul_f32_e32 v106, v106, v114
	v_add_f32_e32 v114, 1.0, v119
	v_rcp_f32_e32 v114, v114
	v_and_b32_e32 v116, 0xffff0000, v163
	v_mul_f32_e32 v106, v111, v106
	v_mul_f32_e32 v111, v117, v118
	v_mul_f32_e32 v117, 0xbfb8aa3b, v121
	v_exp_f32_e32 v117, v117
	v_mul_f32_e32 v111, v107, v111
	v_mul_f32_e32 v107, v114, v115
	v_mul_f32_e32 v114, 0xbfb8aa3b, v116
	v_exp_f32_e32 v114, v114
	v_and_b32_e32 v122, 0xffff0000, v165
	v_mul_f32_e32 v107, v112, v107
	v_add_f32_e32 v112, 1.0, v117
	v_mul_f32_e32 v115, 0xbfb8aa3b, v122
	v_rcp_f32_e32 v112, v112
	v_exp_f32_e32 v115, v115
	v_add_f32_e32 v114, 1.0, v114
	v_rcp_f32_e32 v114, v114
	v_mul_f32_e32 v112, v112, v121
	v_add_f32_e32 v115, 1.0, v115
	v_rcp_f32_e32 v115, v115
	v_mul_f32_e32 v112, v108, v112
	v_mul_f32_e32 v108, v114, v116
	v_mul_f32_e32 v108, v113, v108
	v_cvt_pk_bf16_f32 v106, v1, v106
; __device__ __forceinline__ float siluf_(float x) { return x * __builtin_amdgcn_rcpf(1.0f + __expf(-x)); }
; __device__ __forceinline__ u32x4 pack8(const float (&f)[8]) { u32x4 r; r[0] = cvt_pk_bf16(f[0], f[1]); r[1] = cvt_pk_bf16(f[2], f[3]); r[2] = cvt_pk_bf16(f[4], f[5]); r[3] = cvt_pk_bf16(f[6], f[7]); return r; }
;     __device__ __forceinline__ void operator()(EPI_ARGS) const {
;     ...
; #pragma unroll
;             for (int m = 0; m < 4; ++m)
; #pragma unroll
;                 for (int bj = 0; bj < 2; ++bj) { const f32x4 v0 = acc[ai][bj][m][0], v1 = acc[ai][bj][m][1]; float z[8]; unpack8(zz[m][bj], z); float o[8];
; #pragma unroll
;                     for (int j = 0; j < 4; ++j) { o[j] = v0[j] * siluf_(z[j]); o[4 + j] = v1[j] * siluf_(z[4 + j]); }
;                     *(u32x4*)(O + (size_t)EPI_ROW * 1024 + EPI_COL(bj)) = pack8(o); } }
	v_cvt_pk_bf16_f32 v107, v107, v108
	v_cvt_pk_bf16_f32 v108, v110, v111
	v_add_u32_e32 v110, 16, v152
	v_ashrrev_i32_e32 v111, 31, v110
	v_mul_f32_e32 v113, v115, v122
	v_lshlrev_b64 v[110:111], 11, v[110:111]
	v_mul_f32_e32 v109, v109, v113
	v_lshl_add_u64 v[110:111], s[6:7], 0, v[110:111]
	v_cvt_pk_bf16_f32 v109, v112, v109
	v_lshl_add_u64 v[110:111], v[110:111], 0, v[150:151]
	v_lshlrev_b32_e32 v1, 16, v146
	global_store_dwordx4 v[110:111], v[106:109], off
	v_mul_f32_e32 v113, 0xbfb8aa3b, v1
	v_exp_f32_e32 v113, v113
	v_lshlrev_b32_e32 v109, 16, v148
	v_mul_f32_e32 v114, 0xbfb8aa3b, v109
	v_exp_f32_e32 v114, v114
	v_add_f32_e32 v113, 1.0, v113
	v_rcp_f32_e32 v113, v113
	v_and_b32_e32 v106, 0xffff0000, v146
	v_add_f32_e32 v114, 1.0, v114
	v_rcp_f32_e32 v114, v114
	v_and_b32_e32 v112, 0xffff0000, v148
	v_mul_f32_e32 v1, v113, v1
	v_mul_f32_e32 v1, v102, v1
	v_mul_f32_e32 v102, v114, v109
	v_mul_f32_e32 v109, 0xbfb8aa3b, v106
	v_mul_f32_e32 v113, 0xbfb8aa3b, v112
	v_exp_f32_e32 v109, v109
	v_exp_f32_e32 v113, v113
	v_lshlrev_b32_e32 v107, 16, v147
	v_mul_f32_e32 v102, v98, v102
	v_add_f32_e32 v98, 1.0, v109
	v_add_f32_e32 v109, 1.0, v113
	v_mul_f32_e32 v113, 0xbfb8aa3b, v107
	v_rcp_f32_e32 v98, v98
	v_exp_f32_e32 v113, v113
	v_rcp_f32_e32 v109, v109
	v_lshlrev_b32_e32 v115, 16, v149
	v_mul_f32_e32 v98, v98, v106
	v_add_f32_e32 v106, 1.0, v113
	v_rcp_f32_e32 v106, v106
	v_and_b32_e32 v108, 0xffff0000, v147
	v_mul_f32_e32 v98, v103, v98
	v_mul_f32_e32 v103, v109, v112
	v_mul_f32_e32 v109, 0xbfb8aa3b, v115
	v_and_b32_e32 v116, 0xffff0000, v149
	v_exp_f32_e32 v109, v109
	v_mul_f32_e32 v103, v99, v103
	v_mul_f32_e32 v99, v106, v107
	v_mul_f32_e32 v106, 0xbfb8aa3b, v108
	v_exp_f32_e32 v106, v106
	v_mul_f32_e32 v107, 0xbfb8aa3b, v116
	v_exp_f32_e32 v107, v107
	v_mul_f32_e32 v99, v104, v99
	v_add_f32_e32 v104, 1.0, v109
	v_rcp_f32_e32 v104, v104
	v_add_f32_e32 v106, 1.0, v106
	v_rcp_f32_e32 v106, v106
	v_add_f32_e32 v107, 1.0, v107
	v_rcp_f32_e32 v107, v107
	v_mul_f32_e32 v104, v104, v115
	v_mul_f32_e32 v104, v100, v104
	v_mul_f32_e32 v100, v106, v108
	v_mul_f32_e32 v100, v105, v100
	v_mul_f32_e32 v105, v107, v116
	v_mul_f32_e32 v101, v101, v105
	v_cvt_pk_bf16_f32 v98, v1, v98
	v_cvt_pk_bf16_f32 v99, v99, v100
	v_cvt_pk_bf16_f32 v100, v102, v103
	v_cvt_pk_bf16_f32 v101, v104, v101
	v_lshlrev_b32_e32 v1, 16, v142
	global_store_dwordx4 v[110:111], v[98:101], off offset:256
	v_mul_f32_e32 v103, 0xbfb8aa3b, v1
	v_exp_f32_e32 v103, v103
	v_lshlrev_b32_e32 v101, 16, v144
	v_mul_f32_e32 v104, 0xbfb8aa3b, v101
	v_exp_f32_e32 v104, v104
	v_add_f32_e32 v103, 1.0, v103
	v_rcp_f32_e32 v103, v103
	v_and_b32_e32 v98, 0xffff0000, v142
	v_add_f32_e32 v104, 1.0, v104
	v_rcp_f32_e32 v104, v104
	v_and_b32_e32 v102, 0xffff0000, v144
	v_mul_f32_e32 v1, v103, v1
	v_mul_f32_e32 v1, v94, v1
	v_mul_f32_e32 v94, v104, v101
	v_mul_f32_e32 v101, 0xbfb8aa3b, v98
	v_mul_f32_e32 v103, 0xbfb8aa3b, v102
	v_exp_f32_e32 v101, v101
	v_exp_f32_e32 v103, v103
	v_lshlrev_b32_e32 v99, 16, v143
	v_mul_f32_e32 v94, v90, v94
	v_add_f32_e32 v90, 1.0, v101
	v_add_f32_e32 v101, 1.0, v103
	v_mul_f32_e32 v103, 0xbfb8aa3b, v99
	v_rcp_f32_e32 v90, v90
	v_exp_f32_e32 v103, v103
	v_rcp_f32_e32 v101, v101
	v_lshlrev_b32_e32 v105, 16, v145
	v_mul_f32_e32 v90, v90, v98
	v_add_f32_e32 v98, 1.0, v103
	v_rcp_f32_e32 v98, v98
	v_and_b32_e32 v100, 0xffff0000, v143
	v_mul_f32_e32 v90, v95, v90
	v_mul_f32_e32 v95, v101, v102
	v_mul_f32_e32 v101, 0xbfb8aa3b, v105
	v_exp_f32_e32 v101, v101
	v_mul_f32_e32 v95, v91, v95
	v_mul_f32_e32 v91, v98, v99
	v_mul_f32_e32 v98, 0xbfb8aa3b, v100
	v_exp_f32_e32 v98, v98
	v_and_b32_e32 v106, 0xffff0000, v145
	v_mul_f32_e32 v91, v96, v91
	v_add_f32_e32 v96, 1.0, v101
	v_mul_f32_e32 v99, 0xbfb8aa3b, v106
	v_rcp_f32_e32 v96, v96
	v_exp_f32_e32 v99, v99
	v_add_f32_e32 v98, 1.0, v98
	v_rcp_f32_e32 v98, v98
	v_mul_f32_e32 v96, v96, v105
	v_add_f32_e32 v99, 1.0, v99
	v_rcp_f32_e32 v99, v99
	v_mul_f32_e32 v96, v92, v96
	v_mul_f32_e32 v92, v98, v100
	v_mul_f32_e32 v92, v97, v92
	v_cvt_pk_bf16_f32 v90, v1, v90
	v_cvt_pk_bf16_f32 v91, v91, v92
	v_cvt_pk_bf16_f32 v92, v94, v95
	v_add_u32_e32 v94, 32, v152
	v_ashrrev_i32_e32 v95, 31, v94
	v_mul_f32_e32 v97, v99, v106
	v_lshlrev_b64 v[94:95], 11, v[94:95]
	v_mul_f32_e32 v93, v93, v97
	v_lshl_add_u64 v[94:95], s[6:7], 0, v[94:95]
	v_cvt_pk_bf16_f32 v93, v96, v93
	v_lshl_add_u64 v[94:95], v[94:95], 0, v[150:151]
	v_lshlrev_b32_e32 v1, 16, v138
	global_store_dwordx4 v[94:95], v[90:93], off
	v_mul_f32_e32 v97, 0xbfb8aa3b, v1
	v_exp_f32_e32 v97, v97
	v_lshlrev_b32_e32 v93, 16, v140
	v_mul_f32_e32 v98, 0xbfb8aa3b, v93
	v_exp_f32_e32 v98, v98
	v_add_f32_e32 v97, 1.0, v97
	v_rcp_f32_e32 v97, v97
	v_and_b32_e32 v90, 0xffff0000, v138
	v_add_f32_e32 v98, 1.0, v98
	v_rcp_f32_e32 v98, v98
	v_and_b32_e32 v96, 0xffff0000, v140
	v_mul_f32_e32 v1, v97, v1
	v_mul_f32_e32 v1, v86, v1
	v_mul_f32_e32 v86, v98, v93
	v_mul_f32_e32 v93, 0xbfb8aa3b, v90
	v_mul_f32_e32 v97, 0xbfb8aa3b, v96
	v_exp_f32_e32 v93, v93
	v_exp_f32_e32 v97, v97
	v_lshlrev_b32_e32 v91, 16, v139
	v_mul_f32_e32 v86, v82, v86
	v_add_f32_e32 v82, 1.0, v93
	v_add_f32_e32 v93, 1.0, v97
	v_mul_f32_e32 v97, 0xbfb8aa3b, v91
	v_rcp_f32_e32 v82, v82
	v_exp_f32_e32 v97, v97
	v_rcp_f32_e32 v93, v93
	v_lshlrev_b32_e32 v99, 16, v141
	v_mul_f32_e32 v82, v82, v90
	v_add_f32_e32 v90, 1.0, v97
	v_rcp_f32_e32 v90, v90
	v_and_b32_e32 v92, 0xffff0000, v139
	v_mul_f32_e32 v82, v87, v82
	v_mul_f32_e32 v87, v93, v96
	v_mul_f32_e32 v93, 0xbfb8aa3b, v99
	v_and_b32_e32 v100, 0xffff0000, v141
	v_exp_f32_e32 v93, v93
	v_mul_f32_e32 v87, v83, v87
	v_mul_f32_e32 v83, v90, v91
	v_mul_f32_e32 v90, 0xbfb8aa3b, v92
; __device__ __forceinline__ float siluf_(float x) { return x * __builtin_amdgcn_rcpf(1.0f + __expf(-x)); }
; __device__ __forceinline__ u32x4 pack8(const float (&f)[8]) { u32x4 r; r[0] = cvt_pk_bf16(f[0], f[1]); r[1] = cvt_pk_bf16(f[2], f[3]); r[2] = cvt_pk_bf16(f[4], f[5]); r[3] = cvt_pk_bf16(f[6], f[7]); return r; }
;     __device__ __forceinline__ void operator()(EPI_ARGS) const {
;     ...
;                 for (int bj = 0; bj < 2; ++bj) zz[m][bj] = *(const u32x4*)(parts + E_PZC + (size_t)EPI_ROW * 1024 + EPI_COL(bj));
; #pragma unroll
;             for (int m = 0; m < 4; ++m)
; #pragma unroll
;                 for (int bj = 0; bj < 2; ++bj) { const f32x4 v0 = acc[ai][bj][m][0], v1 = acc[ai][bj][m][1]; float z[8]; unpack8(zz[m][bj], z); float o[8];
; #pragma unroll
;                     for (int j = 0; j < 4; ++j) { o[j] = v0[j] * siluf_(z[j]); o[4 + j] = v1[j] * siluf_(z[4 + j]); }
;                     *(u32x4*)(O + (size_t)EPI_ROW * 1024 + EPI_COL(bj)) = pack8(o); } }
	v_exp_f32_e32 v90, v90
	v_mul_f32_e32 v91, 0xbfb8aa3b, v100
	v_exp_f32_e32 v91, v91
	v_mul_f32_e32 v83, v88, v83
	v_add_f32_e32 v88, 1.0, v93
	v_rcp_f32_e32 v88, v88
	v_add_f32_e32 v90, 1.0, v90
	v_rcp_f32_e32 v90, v90
	v_add_f32_e32 v91, 1.0, v91
	v_rcp_f32_e32 v91, v91
	v_mul_f32_e32 v88, v88, v99
	v_mul_f32_e32 v88, v84, v88
	v_mul_f32_e32 v84, v90, v92
	v_mul_f32_e32 v84, v89, v84
	v_mul_f32_e32 v89, v91, v100
	v_mul_f32_e32 v85, v85, v89
	v_cvt_pk_bf16_f32 v82, v1, v82
	v_cvt_pk_bf16_f32 v83, v83, v84
	v_cvt_pk_bf16_f32 v84, v86, v87
	v_cvt_pk_bf16_f32 v85, v88, v85
	v_lshlrev_b32_e32 v1, 16, v134
	global_store_dwordx4 v[94:95], v[82:85], off offset:256
	v_mul_f32_e32 v87, 0xbfb8aa3b, v1
	v_exp_f32_e32 v87, v87
	v_lshlrev_b32_e32 v85, 16, v136
	v_mul_f32_e32 v88, 0xbfb8aa3b, v85
	v_exp_f32_e32 v88, v88
	v_add_f32_e32 v87, 1.0, v87
	v_rcp_f32_e32 v87, v87
	v_and_b32_e32 v82, 0xffff0000, v134
	v_add_f32_e32 v88, 1.0, v88
	v_rcp_f32_e32 v88, v88
	v_and_b32_e32 v86, 0xffff0000, v136
	v_mul_f32_e32 v1, v87, v1
	v_mul_f32_e32 v1, v78, v1
	v_mul_f32_e32 v78, v88, v85
	v_mul_f32_e32 v85, 0xbfb8aa3b, v82
	v_mul_f32_e32 v87, 0xbfb8aa3b, v86
	v_exp_f32_e32 v85, v85
	v_exp_f32_e32 v87, v87
	v_lshlrev_b32_e32 v83, 16, v135
	v_mul_f32_e32 v78, v74, v78
	v_add_f32_e32 v74, 1.0, v85
	v_add_f32_e32 v85, 1.0, v87
	v_mul_f32_e32 v87, 0xbfb8aa3b, v83
	v_rcp_f32_e32 v74, v74
	v_exp_f32_e32 v87, v87
	v_rcp_f32_e32 v85, v85
	v_lshlrev_b32_e32 v89, 16, v137
	v_mul_f32_e32 v74, v74, v82
	v_add_f32_e32 v82, 1.0, v87
	v_rcp_f32_e32 v82, v82
	v_and_b32_e32 v84, 0xffff0000, v135
	v_mul_f32_e32 v74, v79, v74
	v_mul_f32_e32 v79, v85, v86
	v_mul_f32_e32 v85, 0xbfb8aa3b, v89
	v_exp_f32_e32 v85, v85
	v_mul_f32_e32 v79, v75, v79
	v_mul_f32_e32 v75, v82, v83
	v_mul_f32_e32 v82, 0xbfb8aa3b, v84
	v_exp_f32_e32 v82, v82
	v_and_b32_e32 v90, 0xffff0000, v137
	v_mul_f32_e32 v75, v80, v75
	v_add_f32_e32 v80, 1.0, v85
	v_mul_f32_e32 v83, 0xbfb8aa3b, v90
	v_rcp_f32_e32 v80, v80
	v_exp_f32_e32 v83, v83
	v_add_f32_e32 v82, 1.0, v82
	v_rcp_f32_e32 v82, v82
	v_mul_f32_e32 v80, v80, v89
	v_add_f32_e32 v83, 1.0, v83
	v_rcp_f32_e32 v83, v83
	v_mul_f32_e32 v80, v76, v80
	v_mul_f32_e32 v76, v82, v84
	v_mul_f32_e32 v76, v81, v76
	v_cvt_pk_bf16_f32 v74, v1, v74
	v_cvt_pk_bf16_f32 v75, v75, v76
	v_cvt_pk_bf16_f32 v76, v78, v79
	v_add_u32_e32 v78, 48, v152
	v_ashrrev_i32_e32 v79, 31, v78
	v_mul_f32_e32 v81, v83, v90
	v_lshlrev_b64 v[78:79], 11, v[78:79]
	v_mul_f32_e32 v77, v77, v81
	v_lshl_add_u64 v[78:79], s[6:7], 0, v[78:79]
	v_cvt_pk_bf16_f32 v77, v80, v77
	v_lshl_add_u64 v[78:79], v[78:79], 0, v[150:151]
	v_lshlrev_b32_e32 v1, 16, v130
	global_store_dwordx4 v[78:79], v[74:77], off
	v_mul_f32_e32 v81, 0xbfb8aa3b, v1
	v_exp_f32_e32 v81, v81
	v_lshlrev_b32_e32 v77, 16, v132
	v_mul_f32_e32 v82, 0xbfb8aa3b, v77
	v_exp_f32_e32 v82, v82
	v_add_f32_e32 v81, 1.0, v81
	v_rcp_f32_e32 v81, v81
	v_and_b32_e32 v74, 0xffff0000, v130
	v_add_f32_e32 v82, 1.0, v82
	v_rcp_f32_e32 v82, v82
	v_and_b32_e32 v80, 0xffff0000, v132
	v_mul_f32_e32 v1, v81, v1
	v_mul_f32_e32 v1, v70, v1
	v_mul_f32_e32 v70, v82, v77
	v_mul_f32_e32 v77, 0xbfb8aa3b, v74
	v_mul_f32_e32 v81, 0xbfb8aa3b, v80
	v_exp_f32_e32 v77, v77
	v_exp_f32_e32 v81, v81
	v_lshlrev_b32_e32 v75, 16, v131
	v_mul_f32_e32 v70, v66, v70
	v_add_f32_e32 v66, 1.0, v77
	v_add_f32_e32 v77, 1.0, v81
	v_mul_f32_e32 v81, 0xbfb8aa3b, v75
	v_rcp_f32_e32 v66, v66
	v_exp_f32_e32 v81, v81
	v_rcp_f32_e32 v77, v77
	v_lshlrev_b32_e32 v83, 16, v133
	v_mul_f32_e32 v66, v66, v74
	v_add_f32_e32 v74, 1.0, v81
	v_rcp_f32_e32 v74, v74
	v_and_b32_e32 v76, 0xffff0000, v131
	v_mul_f32_e32 v66, v71, v66
	v_mul_f32_e32 v71, v77, v80
	v_mul_f32_e32 v77, 0xbfb8aa3b, v83
	v_exp_f32_e32 v77, v77
	v_mul_f32_e32 v71, v67, v71
	v_mul_f32_e32 v67, v74, v75
	v_mul_f32_e32 v74, 0xbfb8aa3b, v76
	v_exp_f32_e32 v74, v74
	v_and_b32_e32 v84, 0xffff0000, v133
	v_mul_f32_e32 v67, v72, v67
	v_add_f32_e32 v72, 1.0, v77
	v_rcp_f32_e32 v72, v72
	v_mul_f32_e32 v75, 0xbfb8aa3b, v84
	v_add_f32_e32 v74, 1.0, v74
	v_exp_f32_e32 v75, v75
	v_rcp_f32_e32 v74, v74
	v_mul_f32_e32 v72, v72, v83
	v_mul_f32_e32 v72, v68, v72
	v_add_f32_e32 v75, 1.0, v75
	v_mul_f32_e32 v68, v74, v76
	v_rcp_f32_e32 v75, v75
	v_mul_f32_e32 v68, v73, v68
	v_cvt_pk_bf16_f32 v66, v1, v66
	v_cvt_pk_bf16_f32 v67, v67, v68
	v_cvt_pk_bf16_f32 v68, v70, v71
	v_add_u32_e32 v70, 0x80, v152
	v_ashrrev_i32_e32 v71, 31, v70
	v_lshlrev_b64 v[104:105], 11, v[70:71]
	v_mul_f32_e32 v73, v75, v84
	v_lshl_add_u64 v[70:71], s[12:13], 0, v[104:105]
	v_mul_f32_e32 v69, v69, v73
	v_lshl_add_u64 v[70:71], v[70:71], 0, v[150:151]
	v_cvt_pk_bf16_f32 v69, v72, v69
	global_load_dwordx4 v[92:95], v[70:71], off
	s_nop 0
	global_store_dwordx4 v[78:79], v[66:69], off offset:256
	global_load_dwordx4 v[96:99], v[70:71], off offset:256
	s_waitcnt vmcnt(0)
; __device__ __forceinline__ float siluf_(float x) { return x * __builtin_amdgcn_rcpf(1.0f + __expf(-x)); }
; __device__ __forceinline__ u32x4 pack8(const float (&f)[8]) { u32x4 r; r[0] = cvt_pk_bf16(f[0], f[1]); r[1] = cvt_pk_bf16(f[2], f[3]); r[2] = cvt_pk_bf16(f[4], f[5]); r[3] = cvt_pk_bf16(f[6], f[7]); return r; }
;     __device__ __forceinline__ void operator()(EPI_ARGS) const {
;     ...
;                 for (int bj = 0; bj < 2; ++bj) zz[m][bj] = *(const u32x4*)(parts + E_PZC + (size_t)EPI_ROW * 1024 + EPI_COL(bj));
; #pragma unroll
;             for (int m = 0; m < 4; ++m)
; #pragma unroll
;                 for (int bj = 0; bj < 2; ++bj) { const f32x4 v0 = acc[ai][bj][m][0], v1 = acc[ai][bj][m][1]; float z[8]; unpack8(zz[m][bj], z); float o[8];
; #pragma unroll
;                     for (int j = 0; j < 4; ++j) { o[j] = v0[j] * siluf_(z[j]); o[4 + j] = v1[j] * siluf_(z[4 + j]); }
;                     *(u32x4*)(O + (size_t)EPI_ROW * 1024 + EPI_COL(bj)) = pack8(o); } }
	v_lshlrev_b32_e32 v1, 16, v92
	v_add_u32_e32 v66, 0x90, v152
	v_ashrrev_i32_e32 v67, 31, v66
	v_lshlrev_b64 v[90:91], 11, v[66:67]
	v_lshl_add_u64 v[66:67], s[12:13], 0, v[90:91]
	v_lshl_add_u64 v[66:67], v[66:67], 0, v[150:151]
	global_load_dwordx4 v[100:103], v[66:67], off
	global_load_dwordx4 v[82:85], v[66:67], off offset:256
	v_add_u32_e32 v66, 0xa0, v152
	v_ashrrev_i32_e32 v67, 31, v66
	v_lshlrev_b64 v[88:89], 11, v[66:67]
	v_lshl_add_u64 v[66:67], s[12:13], 0, v[88:89]
	v_lshl_add_u64 v[66:67], v[66:67], 0, v[150:151]
	global_load_dwordx4 v[78:81], v[66:67], off
	global_load_dwordx4 v[74:77], v[66:67], off offset:256
	v_add_u32_e32 v66, 0xb0, v152
	v_ashrrev_i32_e32 v67, 31, v66
	v_lshlrev_b64 v[86:87], 11, v[66:67]
	v_lshl_add_u64 v[66:67], s[12:13], 0, v[86:87]
	v_lshl_add_u64 v[106:107], v[66:67], 0, v[150:151]
	global_load_dwordx4 v[70:73], v[106:107], off
	global_load_dwordx4 v[66:69], v[106:107], off offset:256
	v_lshlrev_b32_e32 v107, 16, v94
	v_mul_f32_e32 v108, 0xbfb8aa3b, v1
	v_exp_f32_e32 v108, v108
	v_mul_f32_e32 v109, 0xbfb8aa3b, v107
	v_exp_f32_e32 v109, v109
	v_and_b32_e32 v92, 0xffff0000, v92
	v_add_f32_e32 v108, 1.0, v108
	v_rcp_f32_e32 v108, v108
	v_add_f32_e32 v109, 1.0, v109
	v_rcp_f32_e32 v109, v109
	v_and_b32_e32 v94, 0xffff0000, v94
	v_mul_f32_e32 v1, v108, v1
	v_mul_f32_e32 v1, v62, v1
	v_mul_f32_e32 v62, v109, v107
	v_mul_f32_e32 v107, 0xbfb8aa3b, v92
	v_mul_f32_e32 v108, 0xbfb8aa3b, v94
	v_exp_f32_e32 v107, v107
	v_exp_f32_e32 v108, v108
	v_lshlrev_b32_e32 v106, 16, v93
	v_mul_f32_e32 v62, v58, v62
	v_add_f32_e32 v58, 1.0, v107
	v_add_f32_e32 v107, 1.0, v108
	v_mul_f32_e32 v108, 0xbfb8aa3b, v106
	v_rcp_f32_e32 v58, v58
	v_exp_f32_e32 v108, v108
	v_rcp_f32_e32 v107, v107
	v_lshlrev_b32_e32 v110, 16, v95
	v_mul_f32_e32 v58, v58, v92
	v_add_f32_e32 v92, 1.0, v108
	v_mul_f32_e32 v58, v63, v58
	v_mul_f32_e32 v63, v107, v94
	v_rcp_f32_e32 v92, v92
	v_mul_f32_e32 v94, 0xbfb8aa3b, v110
	v_exp_f32_e32 v94, v94
	v_and_b32_e32 v93, 0xffff0000, v93
	v_and_b32_e32 v95, 0xffff0000, v95
	v_mul_f32_e32 v63, v59, v63
	v_mul_f32_e32 v59, v92, v106
	v_mul_f32_e32 v92, 0xbfb8aa3b, v93
	v_mul_f32_e32 v59, v64, v59
	v_add_f32_e32 v64, 1.0, v94
	v_exp_f32_e32 v92, v92
	v_mul_f32_e32 v94, 0xbfb8aa3b, v95
	v_exp_f32_e32 v94, v94
	v_rcp_f32_e32 v64, v64
	v_add_f32_e32 v92, 1.0, v92
	v_rcp_f32_e32 v92, v92
	v_add_f32_e32 v94, 1.0, v94
	v_rcp_f32_e32 v94, v94
	v_mul_f32_e32 v64, v64, v110
	v_mul_f32_e32 v64, v60, v64
	v_mul_f32_e32 v60, v92, v93
	v_mul_f32_e32 v60, v65, v60
	v_mul_f32_e32 v65, v94, v95
	v_mul_f32_e32 v61, v61, v65
	v_cvt_pk_bf16_f32 v58, v1, v58
	v_cvt_pk_bf16_f32 v59, v59, v60
	v_cvt_pk_bf16_f32 v60, v62, v63
	v_lshl_add_u64 v[62:63], s[6:7], 0, v[104:105]
	v_cvt_pk_bf16_f32 v61, v64, v61
	v_lshl_add_u64 v[62:63], v[62:63], 0, v[150:151]
	v_lshlrev_b32_e32 v1, 16, v96
	global_store_dwordx4 v[62:63], v[58:61], off
	v_mul_f32_e32 v65, 0xbfb8aa3b, v1
	v_exp_f32_e32 v65, v65
	v_lshlrev_b32_e32 v61, 16, v98
	v_mul_f32_e32 v92, 0xbfb8aa3b, v61
	v_exp_f32_e32 v92, v92
	v_add_f32_e32 v65, 1.0, v65
	v_rcp_f32_e32 v65, v65
	v_and_b32_e32 v58, 0xffff0000, v96
	v_add_f32_e32 v92, 1.0, v92
	v_rcp_f32_e32 v92, v92
	v_and_b32_e32 v64, 0xffff0000, v98
	v_mul_f32_e32 v1, v65, v1
	v_mul_f32_e32 v1, v54, v1
	v_mul_f32_e32 v54, v92, v61
	v_mul_f32_e32 v61, 0xbfb8aa3b, v58
	v_mul_f32_e32 v65, 0xbfb8aa3b, v64
	v_exp_f32_e32 v61, v61
	v_exp_f32_e32 v65, v65
	v_lshlrev_b32_e32 v59, 16, v97
	v_mul_f32_e32 v54, v50, v54
	v_add_f32_e32 v50, 1.0, v61
	v_add_f32_e32 v61, 1.0, v65
	v_mul_f32_e32 v65, 0xbfb8aa3b, v59
	v_rcp_f32_e32 v50, v50
	v_exp_f32_e32 v65, v65
	v_rcp_f32_e32 v61, v61
	v_lshlrev_b32_e32 v93, 16, v99
	v_mul_f32_e32 v50, v50, v58
	v_add_f32_e32 v58, 1.0, v65
	v_rcp_f32_e32 v58, v58
	v_and_b32_e32 v60, 0xffff0000, v97
	v_mul_f32_e32 v50, v55, v50
	v_mul_f32_e32 v55, v61, v64
	v_mul_f32_e32 v61, 0xbfb8aa3b, v93
	v_and_b32_e32 v94, 0xffff0000, v99
	v_exp_f32_e32 v61, v61
	v_mul_f32_e32 v55, v51, v55
	v_mul_f32_e32 v51, v58, v59
	v_mul_f32_e32 v58, 0xbfb8aa3b, v60
	v_exp_f32_e32 v58, v58
	v_mul_f32_e32 v59, 0xbfb8aa3b, v94
	v_exp_f32_e32 v59, v59
	v_mul_f32_e32 v51, v56, v51
	v_add_f32_e32 v56, 1.0, v61
	v_rcp_f32_e32 v56, v56
	v_add_f32_e32 v58, 1.0, v58
	v_rcp_f32_e32 v58, v58
	v_add_f32_e32 v59, 1.0, v59
	v_rcp_f32_e32 v59, v59
	v_mul_f32_e32 v56, v56, v93
	v_mul_f32_e32 v56, v52, v56
	v_mul_f32_e32 v52, v58, v60
	v_mul_f32_e32 v52, v57, v52
	v_mul_f32_e32 v57, v59, v94
	v_mul_f32_e32 v53, v53, v57
	v_cvt_pk_bf16_f32 v50, v1, v50
	v_cvt_pk_bf16_f32 v51, v51, v52
	v_cvt_pk_bf16_f32 v52, v54, v55
	v_cvt_pk_bf16_f32 v53, v56, v53
	s_waitcnt vmcnt(0)
; __device__ __forceinline__ float siluf_(float x) { return x * __builtin_amdgcn_rcpf(1.0f + __expf(-x)); }
; __device__ __forceinline__ u32x4 pack8(const float (&f)[8]) { u32x4 r; r[0] = cvt_pk_bf16(f[0], f[1]); r[1] = cvt_pk_bf16(f[2], f[3]); r[2] = cvt_pk_bf16(f[4], f[5]); r[3] = cvt_pk_bf16(f[6], f[7]); return r; }
;     __device__ __forceinline__ void operator()(EPI_ARGS) const {
;     ...
;             for (int m = 0; m < 4; ++m)
; #pragma unroll
;                 for (int bj = 0; bj < 2; ++bj) { const f32x4 v0 = acc[ai][bj][m][0], v1 = acc[ai][bj][m][1]; float z[8]; unpack8(zz[m][bj], z); float o[8];
; #pragma unroll
;                     for (int j = 0; j < 4; ++j) { o[j] = v0[j] * siluf_(z[j]); o[4 + j] = v1[j] * siluf_(z[4 + j]); }
;                     *(u32x4*)(O + (size_t)EPI_ROW * 1024 + EPI_COL(bj)) = pack8(o); } }
	v_lshlrev_b32_e32 v1, 16, v100
	global_store_dwordx4 v[62:63], v[50:53], off offset:256
	v_mul_f32_e32 v55, 0xbfb8aa3b, v1
	v_exp_f32_e32 v55, v55
	v_lshlrev_b32_e32 v53, 16, v102
	v_mul_f32_e32 v56, 0xbfb8aa3b, v53
	v_exp_f32_e32 v56, v56
	v_add_f32_e32 v55, 1.0, v55
	v_rcp_f32_e32 v55, v55
	v_and_b32_e32 v50, 0xffff0000, v100
	v_add_f32_e32 v56, 1.0, v56
	v_rcp_f32_e32 v56, v56
	v_and_b32_e32 v54, 0xffff0000, v102
	v_mul_f32_e32 v1, v55, v1
	v_mul_f32_e32 v1, v46, v1
	v_mul_f32_e32 v46, v56, v53
	v_mul_f32_e32 v53, 0xbfb8aa3b, v50
	v_mul_f32_e32 v55, 0xbfb8aa3b, v54
	v_exp_f32_e32 v53, v53
	v_exp_f32_e32 v55, v55
	v_lshlrev_b32_e32 v51, 16, v101
	v_mul_f32_e32 v46, v42, v46
	v_add_f32_e32 v42, 1.0, v53
	v_add_f32_e32 v53, 1.0, v55
	v_mul_f32_e32 v55, 0xbfb8aa3b, v51
	v_rcp_f32_e32 v42, v42
	v_exp_f32_e32 v55, v55
	v_rcp_f32_e32 v53, v53
	v_lshlrev_b32_e32 v57, 16, v103
	v_mul_f32_e32 v42, v42, v50
	v_add_f32_e32 v50, 1.0, v55
	v_rcp_f32_e32 v50, v50
	v_and_b32_e32 v52, 0xffff0000, v101
	v_mul_f32_e32 v42, v47, v42
	v_mul_f32_e32 v47, v53, v54
	v_mul_f32_e32 v53, 0xbfb8aa3b, v57
	v_and_b32_e32 v58, 0xffff0000, v103
	v_exp_f32_e32 v53, v53
	v_mul_f32_e32 v47, v43, v47
	v_mul_f32_e32 v43, v50, v51
	v_mul_f32_e32 v50, 0xbfb8aa3b, v52
	v_exp_f32_e32 v50, v50
	v_mul_f32_e32 v51, 0xbfb8aa3b, v58
	v_exp_f32_e32 v51, v51
	v_mul_f32_e32 v43, v48, v43
	v_add_f32_e32 v48, 1.0, v53
	v_rcp_f32_e32 v48, v48
	v_add_f32_e32 v50, 1.0, v50
	v_rcp_f32_e32 v50, v50
	v_add_f32_e32 v51, 1.0, v51
	v_rcp_f32_e32 v51, v51
	v_mul_f32_e32 v48, v48, v57
	v_mul_f32_e32 v48, v44, v48
	v_mul_f32_e32 v44, v50, v52
	v_mul_f32_e32 v44, v49, v44
	v_mul_f32_e32 v49, v51, v58
	v_mul_f32_e32 v45, v45, v49
	v_cvt_pk_bf16_f32 v42, v1, v42
	v_cvt_pk_bf16_f32 v43, v43, v44
	v_cvt_pk_bf16_f32 v44, v46, v47
	v_lshl_add_u64 v[46:47], s[6:7], 0, v[90:91]
	v_cvt_pk_bf16_f32 v45, v48, v45
	v_lshl_add_u64 v[46:47], v[46:47], 0, v[150:151]
	v_lshlrev_b32_e32 v1, 16, v82
	global_store_dwordx4 v[46:47], v[42:45], off
	v_mul_f32_e32 v49, 0xbfb8aa3b, v1
	v_exp_f32_e32 v49, v49
	v_lshlrev_b32_e32 v45, 16, v84
	v_mul_f32_e32 v50, 0xbfb8aa3b, v45
	v_exp_f32_e32 v50, v50
	v_add_f32_e32 v49, 1.0, v49
	v_rcp_f32_e32 v49, v49
	v_and_b32_e32 v42, 0xffff0000, v82
	v_add_f32_e32 v50, 1.0, v50
	v_rcp_f32_e32 v50, v50
	v_and_b32_e32 v48, 0xffff0000, v84
	v_mul_f32_e32 v1, v49, v1
	v_mul_f32_e32 v1, v38, v1
	v_mul_f32_e32 v38, v50, v45
	v_mul_f32_e32 v45, 0xbfb8aa3b, v42
	v_mul_f32_e32 v49, 0xbfb8aa3b, v48
	v_exp_f32_e32 v45, v45
	v_exp_f32_e32 v49, v49
	v_lshlrev_b32_e32 v43, 16, v83
	v_mul_f32_e32 v38, v34, v38
	v_add_f32_e32 v34, 1.0, v45
	v_add_f32_e32 v45, 1.0, v49
	v_mul_f32_e32 v49, 0xbfb8aa3b, v43
	v_rcp_f32_e32 v34, v34
	v_exp_f32_e32 v49, v49
	v_rcp_f32_e32 v45, v45
	v_lshlrev_b32_e32 v51, 16, v85
	v_mul_f32_e32 v34, v34, v42
	v_add_f32_e32 v42, 1.0, v49
	v_rcp_f32_e32 v42, v42
	v_and_b32_e32 v44, 0xffff0000, v83
	v_mul_f32_e32 v34, v39, v34
	v_mul_f32_e32 v39, v45, v48
	v_mul_f32_e32 v45, 0xbfb8aa3b, v51
	v_and_b32_e32 v52, 0xffff0000, v85
	v_exp_f32_e32 v45, v45
	v_mul_f32_e32 v39, v35, v39
	v_mul_f32_e32 v35, v42, v43
	v_mul_f32_e32 v42, 0xbfb8aa3b, v44
	v_exp_f32_e32 v42, v42
	v_mul_f32_e32 v43, 0xbfb8aa3b, v52
	v_exp_f32_e32 v43, v43
	v_mul_f32_e32 v35, v40, v35
	v_add_f32_e32 v40, 1.0, v45
	v_rcp_f32_e32 v40, v40
	v_add_f32_e32 v42, 1.0, v42
	v_rcp_f32_e32 v42, v42
	v_add_f32_e32 v43, 1.0, v43
	v_rcp_f32_e32 v43, v43
	v_mul_f32_e32 v40, v40, v51
	v_mul_f32_e32 v40, v36, v40
	v_mul_f32_e32 v36, v42, v44
	v_mul_f32_e32 v36, v41, v36
	v_mul_f32_e32 v41, v43, v52
	v_mul_f32_e32 v37, v37, v41
	v_cvt_pk_bf16_f32 v34, v1, v34
	v_cvt_pk_bf16_f32 v35, v35, v36
	v_cvt_pk_bf16_f32 v36, v38, v39
	v_cvt_pk_bf16_f32 v37, v40, v37
	v_lshlrev_b32_e32 v1, 16, v78
	global_store_dwordx4 v[46:47], v[34:37], off offset:256
	v_mul_f32_e32 v39, 0xbfb8aa3b, v1
	v_exp_f32_e32 v39, v39
	v_lshlrev_b32_e32 v37, 16, v80
	v_mul_f32_e32 v40, 0xbfb8aa3b, v37
	v_exp_f32_e32 v40, v40
	v_add_f32_e32 v39, 1.0, v39
	v_rcp_f32_e32 v39, v39
	v_and_b32_e32 v34, 0xffff0000, v78
	v_add_f32_e32 v40, 1.0, v40
	v_rcp_f32_e32 v40, v40
	v_and_b32_e32 v38, 0xffff0000, v80
	v_mul_f32_e32 v1, v39, v1
	v_mul_f32_e32 v1, v30, v1
	v_mul_f32_e32 v30, v40, v37
	v_mul_f32_e32 v37, 0xbfb8aa3b, v34
	v_mul_f32_e32 v39, 0xbfb8aa3b, v38
	v_exp_f32_e32 v37, v37
	v_exp_f32_e32 v39, v39
	v_lshlrev_b32_e32 v35, 16, v79
	v_mul_f32_e32 v30, v26, v30
	v_add_f32_e32 v26, 1.0, v37
	v_add_f32_e32 v37, 1.0, v39
	v_mul_f32_e32 v39, 0xbfb8aa3b, v35
	v_rcp_f32_e32 v26, v26
	v_exp_f32_e32 v39, v39
	v_rcp_f32_e32 v37, v37
	v_lshlrev_b32_e32 v41, 16, v81
	v_mul_f32_e32 v26, v26, v34
	v_add_f32_e32 v34, 1.0, v39
	v_rcp_f32_e32 v34, v34
	v_and_b32_e32 v36, 0xffff0000, v79
	v_mul_f32_e32 v26, v31, v26
	v_mul_f32_e32 v31, v37, v38
	v_mul_f32_e32 v37, 0xbfb8aa3b, v41
	v_and_b32_e32 v42, 0xffff0000, v81
	v_exp_f32_e32 v37, v37
	v_mul_f32_e32 v31, v27, v31
	v_mul_f32_e32 v27, v34, v35
	v_mul_f32_e32 v34, 0xbfb8aa3b, v36
	v_exp_f32_e32 v34, v34
	v_mul_f32_e32 v35, 0xbfb8aa3b, v42
	v_exp_f32_e32 v35, v35
	v_mul_f32_e32 v27, v32, v27
	v_add_f32_e32 v32, 1.0, v37
	v_rcp_f32_e32 v32, v32
	v_add_f32_e32 v34, 1.0, v34
	v_rcp_f32_e32 v34, v34
	v_add_f32_e32 v35, 1.0, v35
	v_rcp_f32_e32 v35, v35
	v_mul_f32_e32 v32, v32, v41
	v_mul_f32_e32 v32, v28, v32
	v_mul_f32_e32 v28, v34, v36
	v_mul_f32_e32 v28, v33, v28
	v_mul_f32_e32 v33, v35, v42
	v_mul_f32_e32 v29, v29, v33
	v_cvt_pk_bf16_f32 v26, v1, v26
	v_cvt_pk_bf16_f32 v27, v27, v28
	v_cvt_pk_bf16_f32 v28, v30, v31
	v_lshl_add_u64 v[30:31], s[6:7], 0, v[88:89]
	v_cvt_pk_bf16_f32 v29, v32, v29
; __device__ __forceinline__ float siluf_(float x) { return x * __builtin_amdgcn_rcpf(1.0f + __expf(-x)); }
; __device__ __forceinline__ u32x4 pack8(const float (&f)[8]) { u32x4 r; r[0] = cvt_pk_bf16(f[0], f[1]); r[1] = cvt_pk_bf16(f[2], f[3]); r[2] = cvt_pk_bf16(f[4], f[5]); r[3] = cvt_pk_bf16(f[6], f[7]); return r; }
; #define PG8_WAIT_V(n) asm volatile("s_waitcnt vmcnt(" #n ")" ::: "memory")
; #define PG8_BAR __builtin_amdgcn_s_barrier()
; template <class Sched, class Epi>
; __device__ __forceinline__ void gemm_phase(LAS unsigned char* lds, const Sched& S, const Epi& E, const int K, const int lda, const int ldb) {
;     ...
;     PG8_WAIT_V(0);
;     if (wr == 0) PG8_BAR;
;     PG8_BAR;
;     __device__ __forceinline__ void operator()(EPI_ARGS) const {
;     ...
;             for (int m = 0; m < 4; ++m)
; #pragma unroll
;                 for (int bj = 0; bj < 2; ++bj) { const f32x4 v0 = acc[ai][bj][m][0], v1 = acc[ai][bj][m][1]; float z[8]; unpack8(zz[m][bj], z); float o[8];
; #pragma unroll
;                     for (int j = 0; j < 4; ++j) { o[j] = v0[j] * siluf_(z[j]); o[4 + j] = v1[j] * siluf_(z[4 + j]); }
;                     *(u32x4*)(O + (size_t)EPI_ROW * 1024 + EPI_COL(bj)) = pack8(o); } }
	v_lshl_add_u64 v[30:31], v[30:31], 0, v[150:151]
	v_lshlrev_b32_e32 v1, 16, v74
	global_store_dwordx4 v[30:31], v[26:29], off
	v_mul_f32_e32 v33, 0xbfb8aa3b, v1
	v_exp_f32_e32 v33, v33
	v_lshlrev_b32_e32 v29, 16, v76
	v_mul_f32_e32 v34, 0xbfb8aa3b, v29
	v_exp_f32_e32 v34, v34
	v_add_f32_e32 v33, 1.0, v33
	v_rcp_f32_e32 v33, v33
	v_and_b32_e32 v26, 0xffff0000, v74
	v_add_f32_e32 v34, 1.0, v34
	v_rcp_f32_e32 v34, v34
	v_and_b32_e32 v32, 0xffff0000, v76
	v_mul_f32_e32 v1, v33, v1
	v_mul_f32_e32 v1, v22, v1
	v_mul_f32_e32 v22, v34, v29
	v_mul_f32_e32 v29, 0xbfb8aa3b, v26
	v_mul_f32_e32 v33, 0xbfb8aa3b, v32
	v_exp_f32_e32 v29, v29
	v_exp_f32_e32 v33, v33
	v_lshlrev_b32_e32 v27, 16, v75
	v_mul_f32_e32 v22, v18, v22
	v_add_f32_e32 v18, 1.0, v29
	v_add_f32_e32 v29, 1.0, v33
	v_mul_f32_e32 v33, 0xbfb8aa3b, v27
	v_rcp_f32_e32 v18, v18
	v_exp_f32_e32 v33, v33
	v_rcp_f32_e32 v29, v29
	v_lshlrev_b32_e32 v35, 16, v77
	v_mul_f32_e32 v18, v18, v26
	v_add_f32_e32 v26, 1.0, v33
	v_rcp_f32_e32 v26, v26
	v_and_b32_e32 v28, 0xffff0000, v75
	v_mul_f32_e32 v18, v23, v18
	v_mul_f32_e32 v23, v29, v32
	v_mul_f32_e32 v29, 0xbfb8aa3b, v35
	v_and_b32_e32 v36, 0xffff0000, v77
	v_exp_f32_e32 v29, v29
	v_mul_f32_e32 v23, v19, v23
	v_mul_f32_e32 v19, v26, v27
	v_mul_f32_e32 v26, 0xbfb8aa3b, v28
	v_exp_f32_e32 v26, v26
	v_mul_f32_e32 v27, 0xbfb8aa3b, v36
	v_exp_f32_e32 v27, v27
	v_mul_f32_e32 v19, v24, v19
	v_add_f32_e32 v24, 1.0, v29
	v_rcp_f32_e32 v24, v24
	v_add_f32_e32 v26, 1.0, v26
	v_rcp_f32_e32 v26, v26
	v_add_f32_e32 v27, 1.0, v27
	v_rcp_f32_e32 v27, v27
	v_mul_f32_e32 v24, v24, v35
	v_mul_f32_e32 v24, v20, v24
	v_mul_f32_e32 v20, v26, v28
	v_mul_f32_e32 v20, v25, v20
	v_mul_f32_e32 v25, v27, v36
	v_mul_f32_e32 v21, v21, v25
	v_cvt_pk_bf16_f32 v18, v1, v18
	v_cvt_pk_bf16_f32 v19, v19, v20
	v_cvt_pk_bf16_f32 v20, v22, v23
	v_cvt_pk_bf16_f32 v21, v24, v21
	v_lshlrev_b32_e32 v1, 16, v70
	global_store_dwordx4 v[30:31], v[18:21], off offset:256
	v_mul_f32_e32 v23, 0xbfb8aa3b, v1
	v_exp_f32_e32 v23, v23
	v_lshlrev_b32_e32 v21, 16, v72
	v_mul_f32_e32 v24, 0xbfb8aa3b, v21
	v_exp_f32_e32 v24, v24
	v_add_f32_e32 v23, 1.0, v23
	v_rcp_f32_e32 v23, v23
	v_and_b32_e32 v18, 0xffff0000, v70
	v_add_f32_e32 v24, 1.0, v24
	v_rcp_f32_e32 v24, v24
	v_and_b32_e32 v22, 0xffff0000, v72
	v_mul_f32_e32 v1, v23, v1
	v_mul_f32_e32 v1, v14, v1
	v_mul_f32_e32 v14, v24, v21
	v_mul_f32_e32 v21, 0xbfb8aa3b, v18
	v_mul_f32_e32 v23, 0xbfb8aa3b, v22
	v_exp_f32_e32 v21, v21
	v_exp_f32_e32 v23, v23
	v_lshlrev_b32_e32 v19, 16, v71
	v_mul_f32_e32 v14, v10, v14
	v_add_f32_e32 v10, 1.0, v21
	v_add_f32_e32 v21, 1.0, v23
	v_mul_f32_e32 v23, 0xbfb8aa3b, v19
	v_rcp_f32_e32 v10, v10
	v_exp_f32_e32 v23, v23
	v_rcp_f32_e32 v21, v21
	v_lshlrev_b32_e32 v25, 16, v73
	v_mul_f32_e32 v10, v10, v18
	v_add_f32_e32 v18, 1.0, v23
	v_rcp_f32_e32 v18, v18
	v_and_b32_e32 v20, 0xffff0000, v71
	v_mul_f32_e32 v10, v15, v10
	v_mul_f32_e32 v15, v21, v22
	v_mul_f32_e32 v21, 0xbfb8aa3b, v25
	v_and_b32_e32 v26, 0xffff0000, v73
	v_exp_f32_e32 v21, v21
	v_mul_f32_e32 v15, v11, v15
	v_mul_f32_e32 v11, v18, v19
	v_mul_f32_e32 v18, 0xbfb8aa3b, v20
	v_exp_f32_e32 v18, v18
	v_mul_f32_e32 v19, 0xbfb8aa3b, v26
	v_exp_f32_e32 v19, v19
	v_mul_f32_e32 v11, v16, v11
	v_add_f32_e32 v16, 1.0, v21
	v_rcp_f32_e32 v16, v16
	v_add_f32_e32 v18, 1.0, v18
	v_rcp_f32_e32 v18, v18
	v_add_f32_e32 v19, 1.0, v19
	v_rcp_f32_e32 v19, v19
	v_mul_f32_e32 v16, v16, v25
	v_mul_f32_e32 v16, v12, v16
	v_mul_f32_e32 v12, v18, v20
	v_mul_f32_e32 v12, v17, v12
	v_mul_f32_e32 v17, v19, v26
	v_mul_f32_e32 v13, v13, v17
	v_cvt_pk_bf16_f32 v10, v1, v10
	v_cvt_pk_bf16_f32 v11, v11, v12
	v_cvt_pk_bf16_f32 v12, v14, v15
	v_lshl_add_u64 v[14:15], s[6:7], 0, v[86:87]
	v_cvt_pk_bf16_f32 v13, v16, v13
	v_lshl_add_u64 v[14:15], v[14:15], 0, v[150:151]
	v_lshlrev_b32_e32 v1, 16, v66
	global_store_dwordx4 v[14:15], v[10:13], off
	v_mul_f32_e32 v17, 0xbfb8aa3b, v1
	v_exp_f32_e32 v17, v17
	v_lshlrev_b32_e32 v13, 16, v68
	v_mul_f32_e32 v18, 0xbfb8aa3b, v13
	v_exp_f32_e32 v18, v18
	v_add_f32_e32 v17, 1.0, v17
	v_rcp_f32_e32 v17, v17
	v_and_b32_e32 v10, 0xffff0000, v66
	v_add_f32_e32 v18, 1.0, v18
	v_rcp_f32_e32 v18, v18
	v_and_b32_e32 v16, 0xffff0000, v68
	v_mul_f32_e32 v1, v17, v1
	v_mul_f32_e32 v1, v6, v1
	v_mul_f32_e32 v6, v18, v13
	v_mul_f32_e32 v13, 0xbfb8aa3b, v10
	v_mul_f32_e32 v17, 0xbfb8aa3b, v16
	v_exp_f32_e32 v13, v13
	v_exp_f32_e32 v17, v17
	v_lshlrev_b32_e32 v11, 16, v67
	v_mul_f32_e32 v6, v2, v6
	v_add_f32_e32 v2, 1.0, v13
	v_add_f32_e32 v13, 1.0, v17
	v_mul_f32_e32 v17, 0xbfb8aa3b, v11
	v_rcp_f32_e32 v2, v2
	v_exp_f32_e32 v17, v17
	v_rcp_f32_e32 v13, v13
	v_lshlrev_b32_e32 v19, 16, v69
	v_mul_f32_e32 v2, v2, v10
	v_add_f32_e32 v10, 1.0, v17
	v_rcp_f32_e32 v10, v10
	v_and_b32_e32 v12, 0xffff0000, v67
	v_mul_f32_e32 v2, v7, v2
	v_mul_f32_e32 v7, v13, v16
	v_mul_f32_e32 v13, 0xbfb8aa3b, v19
	v_and_b32_e32 v20, 0xffff0000, v69
	v_exp_f32_e32 v13, v13
	v_mul_f32_e32 v7, v3, v7
	v_mul_f32_e32 v3, v10, v11
	v_mul_f32_e32 v10, 0xbfb8aa3b, v12
	v_exp_f32_e32 v10, v10
	v_mul_f32_e32 v11, 0xbfb8aa3b, v20
	v_exp_f32_e32 v11, v11
	v_mul_f32_e32 v3, v8, v3
	v_add_f32_e32 v8, 1.0, v13
	v_rcp_f32_e32 v8, v8
	v_add_f32_e32 v10, 1.0, v10
	v_rcp_f32_e32 v10, v10
	v_add_f32_e32 v11, 1.0, v11
	v_rcp_f32_e32 v11, v11
	v_mul_f32_e32 v8, v8, v19
	v_mul_f32_e32 v8, v4, v8
	v_mul_f32_e32 v4, v10, v12
	v_mul_f32_e32 v4, v9, v4
	v_mul_f32_e32 v9, v11, v20
	v_mul_f32_e32 v5, v5, v9
	v_cvt_pk_bf16_f32 v2, v1, v2
	v_cvt_pk_bf16_f32 v3, v3, v4
	v_cvt_pk_bf16_f32 v4, v6, v7
	v_cvt_pk_bf16_f32 v5, v8, v5
	global_store_dwordx4 v[14:15], v[2:5], off offset:256
	s_waitcnt vmcnt(0)
	s_cbranch_scc0 .LBB0_1393
	s_barrier

; #define PG8_STAGE(bufoff, gbase, voff) do { _Pragma("unroll") for (int _i = 0; _i < 2; ++_i) \
;         __builtin_amdgcn_global_load_lds((const unsigned*)((const char*)(gbase) + (voff)[_i]), (LAS unsigned*)(lds + (bufoff) + ldsw + _i * 8192), 16, 0, 0); } while (0)
; #define PG8_LDA(dst, b, h) do { _Pragma("unroll") for (int m = 0; m < 4; ++m) _Pragma("unroll") for (int k = 0; k < 2; ++k) dst[m][k] = *(const LAS bf16x8*)(lds + PG8_SA(b, h) + aoff + m * 2048 + k * 1024); } while (0)
; #define PG8_LDB(dst, b, h) do { _Pragma("unroll") for (int n = 0; n < 2; ++n) _Pragma("unroll") for (int k = 0; k < 2; ++k) dst[n][k] = *(const LAS bf16x8*)(lds + PG8_SB(b, h) + boff + n * 2048 + k * 1024); } while (0)
; #define PG8_MMA(ai, bj, At, Bt) do { __builtin_amdgcn_s_setprio(1); _Pragma("unroll") for (int m = 0; m < 4; ++m) _Pragma("unroll") for (int n = 0; n < 2; ++n) _Pragma("unroll") for (int k = 0; k < 2; ++k) \
;         acc[ai][bj][m][n] = __builtin_amdgcn_mfma_f32_16x16x32_bf16(Bt[n][k], At[m][k], acc[ai][bj][m][n], 0, 0, 0); __builtin_amdgcn_s_setprio(0); } while (0)
; #define PG8_WAIT_V(n) asm volatile("s_waitcnt vmcnt(" #n ")" ::: "memory")
; #define PG8_BAR __builtin_amdgcn_s_barrier()
; template <class Sched, class Epi>
; __device__ __forceinline__ void gemm_phase(LAS unsigned char* lds, const Sched& S, const Epi& E, const int K, const int lda, const int ldb) {
;     ...
;         for (int t = 0; t < nt; t += 2) {
;             const bool last = (t == nt - 2);
;             const char* a1 = cA + (size_t)(t + 1) * kstep;
;             const char* a2 = last ? nA : cA + (size_t)(t + 2) * kstep; const char* b2 = last ? nB : cB + (size_t)(t + 2) * kstep;
;             const char* a3 = a2 + kstep; const char* b3 = b2 + kstep;
;             PG8_LDB(B0, 0, 0); PG8_SCHED; PG8_LDA(At, 0, 0); PG8_STAGE(PG8_SA(1, 1), a1 + hstepA, voffA);
;             PG8_WAIT_L(8); PG8_BAR; PG8_WAIT_L(0); PG8_MMA(0, 0, At, B0); PG8_BAR; PG8_SCHED;
;             PG8_LDB(B1, 0, 1); PG8_STAGE(PG8_SB(0, 0), b2, voffB);
;             PG8_BAR; PG8_WAIT_L(0); PG8_MMA(0, 1, At, B1); PG8_BAR;
;             PG8_LDA(At, 0, 1); PG8_STAGE(PG8_SA(0, 0), a2, voffA);
;             PG8_BAR; PG8_WAIT_L(0); if (!chalf) PG8_MMA(1, 0, At, B0); PG8_BAR; PG8_SCHED;
;             PG8_STAGE(PG8_SB(0, 1), b2 + hstepB, voffB);
;             PG8_WAIT_V(6); PG8_BAR; if (!chalf) PG8_MMA(1, 1, At, B1); PG8_BAR;
.LBB0_1415:
	ds_read_b128 v[144:147], v155
	ds_read_b128 v[158:161], v155 offset:1024
	ds_read_b128 v[162:165], v155 offset:2048
	ds_read_b128 v[166:169], v155 offset:3072
	s_add_u32 s34, s28, 0xfffc0080
	s_addc_u32 s35, s29, -1
	s_cmp_eq_u32 s49, 12
	s_cselect_b32 s37, s25, s35
	s_cselect_b32 s36, s24, s34
	s_cselect_b32 s35, s27, s17
	s_cselect_b32 s34, s26, s15
	s_add_i32 m0, s23, 0xc000
	ds_read_b128 v[170:173], v156
	ds_read_b128 v[174:177], v156 offset:1024
	ds_read_b128 v[178:181], v156 offset:2048
	ds_read_b128 v[182:185], v156 offset:3072
	ds_read_b128 v[186:189], v156 offset:4096
	ds_read_b128 v[190:193], v156 offset:5120
	ds_read_b128 v[194:197], v156 offset:6144
	ds_read_b128 v[198:201], v156 offset:7168
	global_load_lds_dwordx4 v140, s[28:29]
	s_add_i32 m0, s23, 0xe000
	s_nop 0
	global_load_lds_dwordx4 v138, s[28:29]
	s_waitcnt lgkmcnt(8)
	s_barrier
	s_waitcnt lgkmcnt(0)
	s_setprio 1
	s_waitcnt lgkmcnt(0)
	v_mfma_f32_16x16x32_bf16 v[118:121], v[144:147], v[170:173], v[118:121]
	v_mfma_f32_16x16x32_bf16 v[114:117], v[162:165], v[170:173], v[114:117]
	v_mfma_f32_16x16x32_bf16 v[110:113], v[144:147], v[178:181], v[110:113]
	v_mfma_f32_16x16x32_bf16 v[106:109], v[162:165], v[178:181], v[106:109]
	v_mfma_f32_16x16x32_bf16 v[94:97], v[144:147], v[186:189], v[94:97]
	v_mfma_f32_16x16x32_bf16 v[90:93], v[162:165], v[186:189], v[90:93]
	v_mfma_f32_16x16x32_bf16 v[78:81], v[144:147], v[194:197], v[78:81]
	v_mfma_f32_16x16x32_bf16 v[74:77], v[162:165], v[194:197], v[74:77]
	v_mfma_f32_16x16x32_bf16 v[118:121], v[158:161], v[174:177], v[118:121]
	v_mfma_f32_16x16x32_bf16 v[114:117], v[166:169], v[174:177], v[114:117]
	v_mfma_f32_16x16x32_bf16 v[110:113], v[158:161], v[182:185], v[110:113]
	v_mfma_f32_16x16x32_bf16 v[106:109], v[166:169], v[182:185], v[106:109]
	v_mfma_f32_16x16x32_bf16 v[94:97], v[158:161], v[190:193], v[94:97]
	v_mfma_f32_16x16x32_bf16 v[90:93], v[166:169], v[190:193], v[90:93]
	v_mfma_f32_16x16x32_bf16 v[78:81], v[158:161], v[198:201], v[78:81]
	v_mfma_f32_16x16x32_bf16 v[74:77], v[166:169], v[198:201], v[74:77]
	s_setprio 0
	s_barrier
	s_add_i32 s50, s46, s38
	v_lshl_add_u64 v[148:149], s[34:35], 0, v[132:133]
	s_mov_b32 m0, s50
	ds_read_b128 v[202:205], v157
	ds_read_b128 v[206:209], v157 offset:1024
	ds_read_b128 v[210:213], v157 offset:2048
	ds_read_b128 v[214:217], v157 offset:3072
	global_load_lds_dwordx4 v[148:149], off
	v_lshl_add_u64 v[218:219], s[34:35], 0, v[136:137]
	s_add_i32 m0, s50, 0x2000
	s_nop 0
	global_load_lds_dwordx4 v[218:219], off
	s_barrier
	s_waitcnt lgkmcnt(0)
	s_setprio 1
	s_waitcnt lgkmcnt(0)
	v_mfma_f32_16x16x32_bf16 v[126:129], v[202:205], v[170:173], v[126:129]
	v_mfma_f32_16x16x32_bf16 v[122:125], v[210:213], v[170:173], v[122:125]
	v_mfma_f32_16x16x32_bf16 v[102:105], v[202:205], v[178:181], v[102:105]
	v_mfma_f32_16x16x32_bf16 v[98:101], v[210:213], v[178:181], v[98:101]
	v_mfma_f32_16x16x32_bf16 v[86:89], v[202:205], v[186:189], v[86:89]
	v_mfma_f32_16x16x32_bf16 v[82:85], v[210:213], v[186:189], v[82:85]
	v_mfma_f32_16x16x32_bf16 v[70:73], v[202:205], v[194:197], v[70:73]
	v_mfma_f32_16x16x32_bf16 v[66:69], v[210:213], v[194:197], v[66:69]
	v_mfma_f32_16x16x32_bf16 v[126:129], v[206:209], v[174:177], v[126:129]
	v_mfma_f32_16x16x32_bf16 v[122:125], v[214:217], v[174:177], v[122:125]
	v_mfma_f32_16x16x32_bf16 v[102:105], v[206:209], v[182:185], v[102:105]
	v_mfma_f32_16x16x32_bf16 v[98:101], v[214:217], v[182:185], v[98:101]
	v_mfma_f32_16x16x32_bf16 v[86:89], v[206:209], v[190:193], v[86:89]
	v_mfma_f32_16x16x32_bf16 v[82:85], v[214:217], v[190:193], v[82:85]
	v_mfma_f32_16x16x32_bf16 v[70:73], v[206:209], v[198:201], v[70:73]
	v_mfma_f32_16x16x32_bf16 v[66:69], v[214:217], v[198:201], v[66:69]
	s_setprio 0
	s_mov_b32 m0, s23
	v_lshl_add_u64 v[220:221], s[36:37], 0, v[130:131]
	s_barrier
	ds_read_b128 v[170:173], v156 offset:16384
	ds_read_b128 v[174:177], v156 offset:17408
	ds_read_b128 v[178:181], v156 offset:18432
	ds_read_b128 v[182:185], v156 offset:19456
	ds_read_b128 v[186:189], v156 offset:20480
	ds_read_b128 v[190:193], v156 offset:21504
	ds_read_b128 v[194:197], v156 offset:22528
	ds_read_b128 v[198:201], v156 offset:23552
	global_load_lds_dwordx4 v[220:221], off
	v_lshl_add_u64 v[222:223], s[36:37], 0, v[134:135]
	s_mov_b32 m0, s39
	s_nop 0
	global_load_lds_dwordx4 v[222:223], off
	s_barrier
	s_waitcnt lgkmcnt(0)
	s_setprio 1
	s_waitcnt lgkmcnt(0)
	v_mfma_f32_16x16x32_bf16 v[62:65], v[144:147], v[170:173], v[62:65]
	v_mfma_f32_16x16x32_bf16 v[58:61], v[162:165], v[170:173], v[58:61]
	v_mfma_f32_16x16x32_bf16 v[46:49], v[144:147], v[178:181], v[46:49]
	v_mfma_f32_16x16x32_bf16 v[42:45], v[162:165], v[178:181], v[42:45]
	v_mfma_f32_16x16x32_bf16 v[30:33], v[144:147], v[186:189], v[30:33]
	v_mfma_f32_16x16x32_bf16 v[26:29], v[162:165], v[186:189], v[26:29]
	v_mfma_f32_16x16x32_bf16 v[14:17], v[144:147], v[194:197], v[14:17]
	v_mfma_f32_16x16x32_bf16 v[10:13], v[162:165], v[194:197], v[10:13]
	v_mfma_f32_16x16x32_bf16 v[62:65], v[158:161], v[174:177], v[62:65]
	v_mfma_f32_16x16x32_bf16 v[58:61], v[166:169], v[174:177], v[58:61]
	v_mfma_f32_16x16x32_bf16 v[46:49], v[158:161], v[182:185], v[46:49]
	v_mfma_f32_16x16x32_bf16 v[42:45], v[166:169], v[182:185], v[42:45]
	v_mfma_f32_16x16x32_bf16 v[30:33], v[158:161], v[190:193], v[30:33]
	v_mfma_f32_16x16x32_bf16 v[26:29], v[166:169], v[190:193], v[26:29]
	v_mfma_f32_16x16x32_bf16 v[14:17], v[158:161], v[198:201], v[14:17]
	v_mfma_f32_16x16x32_bf16 v[10:13], v[166:169], v[198:201], v[10:13]
	s_setprio 0
	s_barrier
; #define PG8_STAGE(bufoff, gbase, voff) do { _Pragma("unroll") for (int _i = 0; _i < 2; ++_i) \
;         __builtin_amdgcn_global_load_lds((const unsigned*)((const char*)(gbase) + (voff)[_i]), (LAS unsigned*)(lds + (bufoff) + ldsw + _i * 8192), 16, 0, 0); } while (0)
; #define PG8_LDA(dst, b, h) do { _Pragma("unroll") for (int m = 0; m < 4; ++m) _Pragma("unroll") for (int k = 0; k < 2; ++k) dst[m][k] = *(const LAS bf16x8*)(lds + PG8_SA(b, h) + aoff + m * 2048 + k * 1024); } while (0)
; #define PG8_LDB(dst, b, h) do { _Pragma("unroll") for (int n = 0; n < 2; ++n) _Pragma("unroll") for (int k = 0; k < 2; ++k) dst[n][k] = *(const LAS bf16x8*)(lds + PG8_SB(b, h) + boff + n * 2048 + k * 1024); } while (0)
; #define PG8_MMA(ai, bj, At, Bt) do { __builtin_amdgcn_s_setprio(1); _Pragma("unroll") for (int m = 0; m < 4; ++m) _Pragma("unroll") for (int n = 0; n < 2; ++n) _Pragma("unroll") for (int k = 0; k < 2; ++k) \
;         acc[ai][bj][m][n] = __builtin_amdgcn_mfma_f32_16x16x32_bf16(Bt[n][k], At[m][k], acc[ai][bj][m][n], 0, 0, 0); __builtin_amdgcn_s_setprio(0); } while (0)
; #define PG8_WAIT_V(n) asm volatile("s_waitcnt vmcnt(" #n ")" ::: "memory")
; #define PG8_WAIT_L(n) asm volatile("s_waitcnt lgkmcnt(" #n ")" ::: "memory")
; #define PG8_BAR __builtin_amdgcn_s_barrier()
; #define PG8_SCHED __builtin_amdgcn_sched_barrier(0)
; template <class Sched, class Epi>
; __device__ __forceinline__ void gemm_phase(LAS unsigned char* lds, const Sched& S, const Epi& E, const int K, const int lda, const int ldb) {
;     ...
;             PG8_STAGE(PG8_SB(0, 1), b2 + hstepB, voffB);
;             PG8_WAIT_V(6); PG8_BAR; if (!chalf) PG8_MMA(1, 1, At, B1); PG8_BAR;
;             PG8_LDB(B0, 1, 0); PG8_SCHED; PG8_LDA(At, 1, 0); PG8_STAGE(PG8_SA(0, 1), a2 + hstepA, voffA);
;             PG8_WAIT_L(8); PG8_BAR; PG8_WAIT_L(0); PG8_MMA(0, 0, At, B0); PG8_BAR; PG8_SCHED;
;             PG8_LDB(B1, 1, 1); PG8_STAGE(PG8_SB(1, 0), b3, voffB);
;             PG8_BAR; PG8_WAIT_L(0); PG8_MMA(0, 1, At, B1); PG8_BAR;
;             PG8_LDA(At, 1, 1); PG8_STAGE(PG8_SA(1, 0), a3, voffA);
;             PG8_BAR; PG8_WAIT_L(0); if (!chalf) PG8_MMA(1, 0, At, B0); PG8_BAR; PG8_SCHED;
	s_add_u32 s50, s34, 0x40000
	s_addc_u32 s51, s35, 0
	s_add_i32 s52, s47, s38
	s_mov_b32 m0, s52
	s_nop 0
	global_load_lds_dwordx4 v132, s[50:51]
	s_add_i32 m0, s52, 0x2000
	s_nop 0
	global_load_lds_dwordx4 v136, s[50:51]
	s_waitcnt vmcnt(6)
	s_barrier
	s_setprio 1
	v_mfma_f32_16x16x32_bf16 v[54:57], v[202:205], v[170:173], v[54:57]
	v_mfma_f32_16x16x32_bf16 v[50:53], v[210:213], v[170:173], v[50:53]
	v_mfma_f32_16x16x32_bf16 v[38:41], v[202:205], v[178:181], v[38:41]
	v_mfma_f32_16x16x32_bf16 v[34:37], v[210:213], v[178:181], v[34:37]
	v_mfma_f32_16x16x32_bf16 v[22:25], v[202:205], v[186:189], v[22:25]
	v_mfma_f32_16x16x32_bf16 v[18:21], v[210:213], v[186:189], v[18:21]
	v_mfma_f32_16x16x32_bf16 v[6:9], v[202:205], v[194:197], v[6:9]
	v_mfma_f32_16x16x32_bf16 v[2:5], v[210:213], v[194:197], v[2:5]
	v_mfma_f32_16x16x32_bf16 v[54:57], v[206:209], v[174:177], v[54:57]
	v_mfma_f32_16x16x32_bf16 v[50:53], v[214:217], v[174:177], v[50:53]
	v_mfma_f32_16x16x32_bf16 v[38:41], v[206:209], v[182:185], v[38:41]
	v_mfma_f32_16x16x32_bf16 v[34:37], v[214:217], v[182:185], v[34:37]
	v_mfma_f32_16x16x32_bf16 v[22:25], v[206:209], v[190:193], v[22:25]
	v_mfma_f32_16x16x32_bf16 v[18:21], v[214:217], v[190:193], v[18:21]
	v_mfma_f32_16x16x32_bf16 v[6:9], v[206:209], v[198:201], v[6:9]
	v_mfma_f32_16x16x32_bf16 v[2:5], v[214:217], v[198:201], v[2:5]
	s_setprio 0
	s_add_i32 s50, 16, 0x18000
	v_add_u32_e32 v166, s50, v150
	s_barrier
	ds_read_b128 v[144:147], v166
	ds_read_b128 v[158:161], v166 offset:1024
	ds_read_b128 v[162:165], v166 offset:2048
	ds_read_b128 v[166:169], v166 offset:3072
	s_add_u32 s36, s36, 0x40000
	s_addc_u32 s37, s37, 0
	s_mov_b32 m0, s40
	ds_read_b128 v[170:173], v156 offset:32768
	ds_read_b128 v[174:177], v156 offset:33792
	ds_read_b128 v[178:181], v156 offset:34816
	ds_read_b128 v[182:185], v156 offset:35840
	ds_read_b128 v[186:189], v156 offset:36864
	ds_read_b128 v[190:193], v156 offset:37888
	ds_read_b128 v[194:197], v156 offset:38912
	ds_read_b128 v[198:201], v156 offset:39936
	global_load_lds_dwordx4 v130, s[36:37]
	s_mov_b32 m0, s41
	s_nop 0
	global_load_lds_dwordx4 v134, s[36:37]
	s_waitcnt lgkmcnt(8)
	s_barrier
	s_waitcnt lgkmcnt(0)
	s_setprio 1
	s_waitcnt lgkmcnt(0)
	v_mfma_f32_16x16x32_bf16 v[118:121], v[144:147], v[170:173], v[118:121]
	v_mfma_f32_16x16x32_bf16 v[114:117], v[162:165], v[170:173], v[114:117]
	v_mfma_f32_16x16x32_bf16 v[110:113], v[144:147], v[178:181], v[110:113]
	v_mfma_f32_16x16x32_bf16 v[106:109], v[162:165], v[178:181], v[106:109]
	v_mfma_f32_16x16x32_bf16 v[94:97], v[144:147], v[186:189], v[94:97]
	v_mfma_f32_16x16x32_bf16 v[90:93], v[162:165], v[186:189], v[90:93]
	v_mfma_f32_16x16x32_bf16 v[78:81], v[144:147], v[194:197], v[78:81]
	v_mfma_f32_16x16x32_bf16 v[74:77], v[162:165], v[194:197], v[74:77]
	v_mfma_f32_16x16x32_bf16 v[118:121], v[158:161], v[174:177], v[118:121]
	v_mfma_f32_16x16x32_bf16 v[114:117], v[166:169], v[174:177], v[114:117]
	v_mfma_f32_16x16x32_bf16 v[110:113], v[158:161], v[182:185], v[110:113]
	v_mfma_f32_16x16x32_bf16 v[106:109], v[166:169], v[182:185], v[106:109]
	v_mfma_f32_16x16x32_bf16 v[94:97], v[158:161], v[190:193], v[94:97]
	v_mfma_f32_16x16x32_bf16 v[90:93], v[166:169], v[190:193], v[90:93]
	v_mfma_f32_16x16x32_bf16 v[78:81], v[158:161], v[198:201], v[78:81]
	v_mfma_f32_16x16x32_bf16 v[74:77], v[166:169], v[198:201], v[74:77]
	s_setprio 0
	s_barrier
	s_add_i32 s36, 16, 0x1c000
	s_add_i32 s37, s50, s38
	v_add_u32_e32 v214, s36, v150
	v_lshl_add_u64 v[148:149], v[148:149], 0, s[8:9]
	s_mov_b32 m0, s37
	ds_read_b128 v[202:205], v214
	ds_read_b128 v[206:209], v214 offset:1024
	ds_read_b128 v[210:213], v214 offset:2048
	ds_read_b128 v[214:217], v214 offset:3072
	global_load_lds_dwordx4 v[148:149], off
	v_lshl_add_u64 v[148:149], v[218:219], 0, s[8:9]
	s_add_i32 m0, s37, 0x2000
	s_nop 0
	global_load_lds_dwordx4 v[148:149], off
	s_barrier
	s_waitcnt lgkmcnt(0)
	s_setprio 1
	s_waitcnt lgkmcnt(0)
	v_mfma_f32_16x16x32_bf16 v[126:129], v[202:205], v[170:173], v[126:129]
	v_mfma_f32_16x16x32_bf16 v[122:125], v[210:213], v[170:173], v[122:125]
	v_mfma_f32_16x16x32_bf16 v[102:105], v[202:205], v[178:181], v[102:105]
	v_mfma_f32_16x16x32_bf16 v[98:101], v[210:213], v[178:181], v[98:101]
	v_mfma_f32_16x16x32_bf16 v[86:89], v[202:205], v[186:189], v[86:89]
	v_mfma_f32_16x16x32_bf16 v[82:85], v[210:213], v[186:189], v[82:85]
	v_mfma_f32_16x16x32_bf16 v[70:73], v[202:205], v[194:197], v[70:73]
	v_mfma_f32_16x16x32_bf16 v[66:69], v[210:213], v[194:197], v[66:69]
	v_mfma_f32_16x16x32_bf16 v[126:129], v[206:209], v[174:177], v[126:129]
	v_mfma_f32_16x16x32_bf16 v[122:125], v[214:217], v[174:177], v[122:125]
	v_mfma_f32_16x16x32_bf16 v[102:105], v[206:209], v[182:185], v[102:105]
	v_mfma_f32_16x16x32_bf16 v[98:101], v[214:217], v[182:185], v[98:101]
	v_mfma_f32_16x16x32_bf16 v[86:89], v[206:209], v[190:193], v[86:89]
	v_mfma_f32_16x16x32_bf16 v[82:85], v[214:217], v[190:193], v[82:85]
	v_mfma_f32_16x16x32_bf16 v[70:73], v[206:209], v[198:201], v[70:73]
	v_mfma_f32_16x16x32_bf16 v[66:69], v[214:217], v[198:201], v[66:69]
	s_setprio 0
	s_mov_b32 m0, s42
	v_lshl_add_u64 v[148:149], v[220:221], 0, s[8:9]
	s_barrier
	ds_read_b128 v[170:173], v156 offset:49152
	ds_read_b128 v[174:177], v156 offset:50176
	ds_read_b128 v[178:181], v156 offset:51200
	ds_read_b128 v[182:185], v156 offset:52224
	ds_read_b128 v[186:189], v156 offset:53248
	ds_read_b128 v[190:193], v156 offset:54272
	ds_read_b128 v[194:197], v156 offset:55296
	ds_read_b128 v[198:201], v156 offset:56320
	global_load_lds_dwordx4 v[148:149], off
	v_lshl_add_u64 v[148:149], v[222:223], 0, s[8:9]
	s_mov_b32 m0, s43
	s_nop 0
	global_load_lds_dwordx4 v[148:149], off
	s_barrier
; #define PG8_STAGE(bufoff, gbase, voff) do { _Pragma("unroll") for (int _i = 0; _i < 2; ++_i) \
;         __builtin_amdgcn_global_load_lds((const unsigned*)((const char*)(gbase) + (voff)[_i]), (LAS unsigned*)(lds + (bufoff) + ldsw + _i * 8192), 16, 0, 0); } while (0)
; #define PG8_MMA(ai, bj, At, Bt) do { __builtin_amdgcn_s_setprio(1); _Pragma("unroll") for (int m = 0; m < 4; ++m) _Pragma("unroll") for (int n = 0; n < 2; ++n) _Pragma("unroll") for (int k = 0; k < 2; ++k) \
;         acc[ai][bj][m][n] = __builtin_amdgcn_mfma_f32_16x16x32_bf16(Bt[n][k], At[m][k], acc[ai][bj][m][n], 0, 0, 0); __builtin_amdgcn_s_setprio(0); } while (0)
; #define PG8_WAIT_V(n) asm volatile("s_waitcnt vmcnt(" #n ")" ::: "memory")
; #define PG8_WAIT_L(n) asm volatile("s_waitcnt lgkmcnt(" #n ")" ::: "memory")
; #define PG8_BAR __builtin_amdgcn_s_barrier()
; #define PG8_SCHED __builtin_amdgcn_sched_barrier(0)
; template <class Sched, class Epi>
; __device__ __forceinline__ void gemm_phase(LAS unsigned char* lds, const Sched& S, const Epi& E, const int K, const int lda, const int ldb) {
;     ...
;             PG8_BAR; PG8_WAIT_L(0); if (!chalf) PG8_MMA(1, 0, At, B0); PG8_BAR; PG8_SCHED;
;             PG8_STAGE(PG8_SB(1, 1), b3 + hstepB, voffB);
;             PG8_WAIT_V(6); PG8_BAR; if (!chalf) PG8_MMA(1, 1, At, B1); PG8_BAR;
;         }
;     __device__ __forceinline__ void operator()(EPI_ARGS) const {
;         const int col = u.pn * 128 + wc * 32 + 8 * fq;
; #pragma unroll
;         for (int ai = 0; ai < 2; ++ai) if (ai == 0 || !u.half) { u32x4 zz[4];
; #pragma unroll
;             for (int m = 0; m < 4; ++m) zz[m] = *(const u32x4*)(parts + E_PZB + (size_t)EPI_ROW * 1024 + col);
; #pragma unroll
;             for (int m = 0; m < 4; ++m) { float z[8]; unpack8(zz[m], z);
;                 const f32x4 a0 = acc[ai][0][m][0], a1 = acc[ai][0][m][1], b0 = acc[ai][1][m][0], b1 = acc[ai][1][m][1]; float o[8];
; #pragma unroll
;                 for (int j = 0; j < 4; ++j) { o[j] = a0[j] * z[j] * __builtin_amdgcn_rcpf((1.0f + __expf(-b0[j])) * (1.0f + __expf(-z[j]))); o[4 + j] = a1[j] * z[4 + j] * __builtin_amdgcn_rcpf((1.0f + __expf(-b1[j])) * (1.0f + __expf(-z[4 + j]))); }
	s_waitcnt lgkmcnt(0)
	s_setprio 1
	s_waitcnt lgkmcnt(0)
	v_mfma_f32_16x16x32_bf16 v[62:65], v[144:147], v[170:173], v[62:65]
	v_mfma_f32_16x16x32_bf16 v[58:61], v[162:165], v[170:173], v[58:61]
	v_mfma_f32_16x16x32_bf16 v[46:49], v[144:147], v[178:181], v[46:49]
	v_mfma_f32_16x16x32_bf16 v[42:45], v[162:165], v[178:181], v[42:45]
	v_mfma_f32_16x16x32_bf16 v[30:33], v[144:147], v[186:189], v[30:33]
	v_mfma_f32_16x16x32_bf16 v[26:29], v[162:165], v[186:189], v[26:29]
	v_mfma_f32_16x16x32_bf16 v[14:17], v[144:147], v[194:197], v[14:17]
	v_mfma_f32_16x16x32_bf16 v[10:13], v[162:165], v[194:197], v[10:13]
	v_mfma_f32_16x16x32_bf16 v[62:65], v[158:161], v[174:177], v[62:65]
	v_mfma_f32_16x16x32_bf16 v[58:61], v[166:169], v[174:177], v[58:61]
	v_mfma_f32_16x16x32_bf16 v[46:49], v[158:161], v[182:185], v[46:49]
	v_mfma_f32_16x16x32_bf16 v[42:45], v[166:169], v[182:185], v[42:45]
	v_mfma_f32_16x16x32_bf16 v[30:33], v[158:161], v[190:193], v[30:33]
	v_mfma_f32_16x16x32_bf16 v[26:29], v[166:169], v[190:193], v[26:29]
	v_mfma_f32_16x16x32_bf16 v[14:17], v[158:161], v[198:201], v[14:17]
	v_mfma_f32_16x16x32_bf16 v[10:13], v[166:169], v[198:201], v[10:13]
	s_setprio 0
	s_barrier
	s_add_u32 s34, s34, 0x40080
	s_addc_u32 s35, s35, 0
	s_add_i32 s36, s36, s38
	s_mov_b32 m0, s36
	s_nop 0
	global_load_lds_dwordx4 v132, s[34:35]
	s_add_i32 m0, s36, 0x2000
	s_nop 0
	global_load_lds_dwordx4 v136, s[34:35]
	s_waitcnt vmcnt(6)
	s_barrier
	s_setprio 1
	v_mfma_f32_16x16x32_bf16 v[54:57], v[202:205], v[170:173], v[54:57]
	v_mfma_f32_16x16x32_bf16 v[50:53], v[210:213], v[170:173], v[50:53]
	v_mfma_f32_16x16x32_bf16 v[38:41], v[202:205], v[178:181], v[38:41]
	v_mfma_f32_16x16x32_bf16 v[34:37], v[210:213], v[178:181], v[34:37]
	v_mfma_f32_16x16x32_bf16 v[22:25], v[202:205], v[186:189], v[22:25]
	v_mfma_f32_16x16x32_bf16 v[18:21], v[210:213], v[186:189], v[18:21]
	v_mfma_f32_16x16x32_bf16 v[6:9], v[202:205], v[194:197], v[6:9]
	v_mfma_f32_16x16x32_bf16 v[2:5], v[210:213], v[194:197], v[2:5]
	v_mfma_f32_16x16x32_bf16 v[54:57], v[206:209], v[174:177], v[54:57]
	v_mfma_f32_16x16x32_bf16 v[50:53], v[214:217], v[174:177], v[50:53]
	v_mfma_f32_16x16x32_bf16 v[38:41], v[206:209], v[182:185], v[38:41]
	v_mfma_f32_16x16x32_bf16 v[34:37], v[214:217], v[182:185], v[34:37]
	v_mfma_f32_16x16x32_bf16 v[22:25], v[206:209], v[190:193], v[22:25]
	v_mfma_f32_16x16x32_bf16 v[18:21], v[214:217], v[190:193], v[18:21]
	v_mfma_f32_16x16x32_bf16 v[6:9], v[206:209], v[198:201], v[6:9]
	v_mfma_f32_16x16x32_bf16 v[2:5], v[214:217], v[198:201], v[2:5]
	s_setprio 0
	s_add_i32 s49, s49, 2
	s_add_u32 s15, s15, 0x100
	s_addc_u32 s17, s17, 0
	s_add_u32 s28, s28, 0x100
	s_addc_u32 s29, s29, 0
	s_cmp_gt_u32 s49, 13
	s_barrier
	s_cbranch_scc0 .LBB0_1415
	v_lshl_or_b32 v144, s48, 7, v154
	v_ashrrev_i32_e32 v145, 31, v144
	v_add_u32_e32 v148, s22, v1
	v_lshlrev_b64 v[144:145], 1, v[144:145]
	v_ashrrev_i32_e32 v149, 31, v148
	v_lshl_add_u64 v[146:147], s[4:5], 0, v[144:145]
	v_lshlrev_b64 v[166:167], 11, v[148:149]
	v_lshl_add_u64 v[158:159], v[146:147], 0, v[166:167]
	global_load_dwordx4 v[158:161], v[158:159], off
	v_mul_f32_e32 v149, 0xbfb8aa3b, v122
	v_mul_f32_e32 v123, 0xbfb8aa3b, v123
	v_add_u32_e32 v122, 16, v148
	v_exp_f32_e32 v174, v123
	v_ashrrev_i32_e32 v123, 31, v122
	v_lshlrev_b64 v[122:123], 11, v[122:123]
	v_mul_f32_e32 v126, 0xbfb8aa3b, v126
	v_mul_f32_e32 v127, 0xbfb8aa3b, v127
	v_mul_f32_e32 v128, 0xbfb8aa3b, v128
	v_mul_f32_e32 v129, 0xbfb8aa3b, v129
	v_lshl_add_u64 v[122:123], v[146:147], 0, v[122:123]
	v_exp_f32_e32 v168, v126
	v_exp_f32_e32 v172, v127
	v_exp_f32_e32 v176, v128
	v_exp_f32_e32 v180, v129
	global_load_dwordx4 v[126:129], v[122:123], off
	v_mul_f32_e32 v163, 0xbfb8aa3b, v124
	v_mul_f32_e32 v125, 0xbfb8aa3b, v125
	v_add_u32_e32 v124, 32, v148
	v_add_u32_e32 v162, 48, v148
	v_exp_f32_e32 v178, v163
	v_exp_f32_e32 v182, v125
	v_ashrrev_i32_e32 v125, 31, v124
	v_ashrrev_i32_e32 v163, 31, v162
	v_lshlrev_b64 v[122:123], 11, v[124:125]
	v_lshlrev_b64 v[124:125], 11, v[162:163]
	v_lshl_add_u64 v[122:123], v[146:147], 0, v[122:123]
	v_lshl_add_u64 v[124:125], v[146:147], 0, v[124:125]
	global_load_dwordx4 v[162:165], v[122:123], off
	s_nop 0
	global_load_dwordx4 v[122:125], v[124:125], off
	v_exp_f32_e32 v170, v149
	v_mul_f32_e32 v102, 0xbfb8aa3b, v102
	v_mul_f32_e32 v98, 0xbfb8aa3b, v98
	v_mul_f32_e32 v100, 0xbfb8aa3b, v100
	v_mul_f32_e32 v86, 0xbfb8aa3b, v86
	v_mul_f32_e32 v82, 0xbfb8aa3b, v82
	v_mul_f32_e32 v84, 0xbfb8aa3b, v84
	v_mul_f32_e32 v70, 0xbfb8aa3b, v70
	v_mul_f32_e32 v66, 0xbfb8aa3b, v66
	v_mul_f32_e32 v68, 0xbfb8aa3b, v68
	v_mul_f32_e32 v54, 0xbfb8aa3b, v54
	v_mul_f32_e32 v50, 0xbfb8aa3b, v50
	v_mul_f32_e32 v52, 0xbfb8aa3b, v52
	v_mul_f32_e32 v38, 0xbfb8aa3b, v38
	v_mul_f32_e32 v34, 0xbfb8aa3b, v34
	v_mul_f32_e32 v36, 0xbfb8aa3b, v36
	v_mul_f32_e32 v22, 0xbfb8aa3b, v22
	v_mul_f32_e32 v18, 0xbfb8aa3b, v18
	v_mul_f32_e32 v20, 0xbfb8aa3b, v20
	v_mul_f32_e32 v6, 0xbfb8aa3b, v6
	v_mul_f32_e32 v2, 0xbfb8aa3b, v2
	v_mul_f32_e32 v4, 0xbfb8aa3b, v4
	s_and_b64 vcc, exec, s[12:13]
	s_mov_b32 s48, s14
	s_mov_b64 s[34:35], s[20:21]
	s_mov_b64 s[28:29], s[18:19]
	s_waitcnt vmcnt(0)
; __device__ __forceinline__ u32x4 pack8(const float (&f)[8]) { u32x4 r; r[0] = cvt_pk_bf16(f[0], f[1]); r[1] = cvt_pk_bf16(f[2], f[3]); r[2] = cvt_pk_bf16(f[4], f[5]); r[3] = cvt_pk_bf16(f[6], f[7]); return r; }
;     __device__ __forceinline__ void operator()(EPI_ARGS) const {
;     ...
;         for (int ai = 0; ai < 2; ++ai) if (ai == 0 || !u.half) { u32x4 zz[4];
; #pragma unroll
;             for (int m = 0; m < 4; ++m) zz[m] = *(const u32x4*)(parts + E_PZB + (size_t)EPI_ROW * 1024 + col);
; #pragma unroll
;             for (int m = 0; m < 4; ++m) { float z[8]; unpack8(zz[m], z);
;                 const f32x4 a0 = acc[ai][0][m][0], a1 = acc[ai][0][m][1], b0 = acc[ai][1][m][0], b1 = acc[ai][1][m][1]; float o[8];
; #pragma unroll
;                 for (int j = 0; j < 4; ++j) { o[j] = a0[j] * z[j] * __builtin_amdgcn_rcpf((1.0f + __expf(-b0[j])) * (1.0f + __expf(-z[j]))); o[4 + j] = a1[j] * z[4 + j] * __builtin_amdgcn_rcpf((1.0f + __expf(-b1[j])) * (1.0f + __expf(-z[4 + j]))); }
;                 *(u32x4*)(O + (size_t)EPI_ROW * 1024 + col) = pack8(o); } }
	v_lshlrev_b32_e32 v149, 16, v158
	v_and_b32_e32 v158, 0xffff0000, v158
	v_lshlrev_b32_e32 v169, 16, v159
	v_and_b32_e32 v184, 0xffff0000, v159
	v_lshlrev_b32_e32 v159, 16, v160
	v_and_b32_e32 v160, 0xffff0000, v160
	v_lshlrev_b32_e32 v171, 16, v161
	v_mul_f32_e32 v186, v118, v149
	v_mul_f32_e32 v118, 0xbfb8aa3b, v149
	v_mul_f32_e32 v149, v114, v159
	v_mul_f32_e32 v114, 0xbfb8aa3b, v159
	v_mul_f32_e32 v187, v119, v158
	v_mul_f32_e32 v119, 0xbfb8aa3b, v158
	v_mul_f32_e32 v188, v115, v160
	v_mul_f32_e32 v115, 0xbfb8aa3b, v160
	v_mul_f32_e32 v158, 0xbfb8aa3b, v169
	v_mul_f32_e32 v159, 0xbfb8aa3b, v171
	v_mul_f32_e32 v120, v120, v169
	v_mul_f32_e32 v116, v116, v171
	v_exp_f32_e32 v169, v118
	v_exp_f32_e32 v171, v114
	v_exp_f32_e32 v173, v119
	v_exp_f32_e32 v175, v115
	v_exp_f32_e32 v177, v158
	v_exp_f32_e32 v179, v159
	v_and_b32_e32 v185, 0xffff0000, v161
	v_mul_f32_e32 v160, 0xbfb8aa3b, v184
	v_mul_f32_e32 v161, 0xbfb8aa3b, v185
	v_exp_f32_e32 v181, v160
	v_exp_f32_e32 v183, v161
	v_pk_add_f32 v[114:115], v[168:169], 1.0 op_sel_hi:[1,0]
	v_pk_add_f32 v[118:119], v[170:171], 1.0 op_sel_hi:[1,0]
	v_pk_add_f32 v[158:159], v[172:173], 1.0 op_sel_hi:[1,0]
	v_pk_add_f32 v[160:161], v[174:175], 1.0 op_sel_hi:[1,0]
	v_pk_add_f32 v[168:169], v[176:177], 1.0 op_sel_hi:[1,0]
	v_pk_add_f32 v[170:171], v[178:179], 1.0 op_sel_hi:[1,0]
	v_mul_f32_e32 v114, v114, v115
	v_mul_f32_e32 v115, v118, v119
	v_mul_f32_e32 v118, v158, v159
	v_mul_f32_e32 v119, v160, v161
	v_mul_f32_e32 v158, v168, v169
	v_mul_f32_e32 v159, v170, v171
	v_rcp_f32_e32 v115, v115
	v_rcp_f32_e32 v118, v118
	v_rcp_f32_e32 v119, v119
	v_rcp_f32_e32 v158, v158
	v_rcp_f32_e32 v159, v159
	v_pk_add_f32 v[172:173], v[180:181], 1.0 op_sel_hi:[1,0]
	v_pk_add_f32 v[174:175], v[182:183], 1.0 op_sel_hi:[1,0]
	v_mul_f32_e32 v160, v172, v173
	v_rcp_f32_e32 v114, v114
	v_mul_f32_e32 v149, v149, v115
	v_mul_f32_e32 v115, v187, v118
	v_mul_f32_e32 v118, v188, v119
	v_mul_f32_e32 v119, v120, v158
	v_mul_f32_e32 v120, v116, v159
	v_mul_f32_e32 v116, v174, v175
	v_rcp_f32_e32 v160, v160
	v_rcp_f32_e32 v116, v116
	v_mul_f32_e32 v114, v186, v114
	v_mul_f32_e32 v121, v121, v184
	v_mul_f32_e32 v117, v117, v185
	v_mul_f32_e32 v121, v121, v160
	v_mul_f32_e32 v117, v117, v116
	v_cvt_pk_bf16_f32 v114, v114, v115
	v_cvt_pk_bf16_f32 v115, v119, v121
	v_cvt_pk_bf16_f32 v116, v149, v118
	v_lshl_add_u64 v[118:119], s[6:7], 0, v[166:167]
	v_lshl_add_u64 v[118:119], v[118:119], 0, v[144:145]
	v_cvt_pk_bf16_f32 v117, v120, v117
	global_store_dwordx4 v[118:119], v[114:117], off
	v_lshlrev_b32_e32 v118, 16, v126
	v_and_b32_e32 v119, 0xffff0000, v126
	v_lshlrev_b32_e32 v126, 16, v128
	v_exp_f32_e32 v114, v102
	v_mul_f32_e32 v102, 0xbfb8aa3b, v118
	v_exp_f32_e32 v115, v102
	v_exp_f32_e32 v116, v98
	v_mul_f32_e32 v98, 0xbfb8aa3b, v126
	v_exp_f32_e32 v117, v98
	v_pk_add_f32 v[114:115], v[114:115], 1.0 op_sel_hi:[1,0]
	v_mul_f32_e32 v110, v110, v118
	v_mul_f32_e32 v98, v114, v115
	v_pk_add_f32 v[114:115], v[116:117], 1.0 op_sel_hi:[1,0]
	v_rcp_f32_e32 v98, v98
	v_mul_f32_e32 v102, v114, v115
	v_rcp_f32_e32 v102, v102
	v_lshlrev_b32_e32 v120, 16, v127
	v_mul_f32_e32 v110, v110, v98
	v_mul_f32_e32 v98, v106, v126
	v_mul_f32_e32 v106, v98, v102
	v_mul_f32_e32 v98, 0xbfb8aa3b, v103
	v_and_b32_e32 v121, 0xffff0000, v127
	v_and_b32_e32 v127, 0xffff0000, v128
	v_exp_f32_e32 v102, v98
	v_mul_f32_e32 v98, 0xbfb8aa3b, v119
	v_exp_f32_e32 v103, v98
	v_mul_f32_e32 v98, 0xbfb8aa3b, v99
	v_mul_f32_e32 v99, 0xbfb8aa3b, v127
	v_exp_f32_e32 v98, v98
	v_exp_f32_e32 v99, v99
	v_pk_add_f32 v[102:103], v[102:103], 1.0 op_sel_hi:[1,0]
	v_lshlrev_b32_e32 v128, 16, v129
	v_mul_f32_e32 v102, v102, v103
	v_pk_add_f32 v[98:99], v[98:99], 1.0 op_sel_hi:[1,0]
	v_rcp_f32_e32 v102, v102
	v_mul_f32_e32 v98, v98, v99
	v_rcp_f32_e32 v98, v98
	v_mul_f32_e32 v99, v111, v119
	v_mul_f32_e32 v111, v99, v102
	v_mul_f32_e32 v99, v107, v127
	v_mul_f32_e32 v107, v99, v98
	v_mul_f32_e32 v98, 0xbfb8aa3b, v104
	v_mul_f32_e32 v99, 0xbfb8aa3b, v120
	v_exp_f32_e32 v98, v98
	v_exp_f32_e32 v99, v99
	v_exp_f32_e32 v102, v100
	v_mul_f32_e32 v100, 0xbfb8aa3b, v128
	v_exp_f32_e32 v103, v100
	v_pk_add_f32 v[98:99], v[98:99], 1.0 op_sel_hi:[1,0]
	v_and_b32_e32 v129, 0xffff0000, v129
	v_mul_f32_e32 v98, v98, v99
	v_rcp_f32_e32 v100, v98
	v_pk_add_f32 v[98:99], v[102:103], 1.0 op_sel_hi:[1,0]
	s_nop 0
	v_mul_f32_e32 v98, v98, v99
	v_rcp_f32_e32 v98, v98
	v_mul_f32_e32 v99, v112, v120
	v_mul_f32_e32 v102, v99, v100
	v_mul_f32_e32 v99, v108, v128
	v_mul_f32_e32 v103, v99, v98
	v_mul_f32_e32 v98, 0xbfb8aa3b, v105
	v_mul_f32_e32 v99, 0xbfb8aa3b, v121
	v_exp_f32_e32 v98, v98
	v_exp_f32_e32 v99, v99
	v_mul_f32_e32 v100, 0xbfb8aa3b, v101
	v_mul_f32_e32 v101, 0xbfb8aa3b, v129
	v_exp_f32_e32 v100, v100
	v_exp_f32_e32 v101, v101
	v_pk_add_f32 v[98:99], v[98:99], 1.0 op_sel_hi:[1,0]
	v_lshlrev_b32_e32 v108, 16, v165
	v_mul_f32_e32 v98, v98, v99
	v_rcp_f32_e32 v104, v98
	v_pk_add_f32 v[98:99], v[100:101], 1.0 op_sel_hi:[1,0]
	v_mul_f32_e32 v100, v109, v129
	v_mul_f32_e32 v98, v98, v99
	v_rcp_f32_e32 v98, v98
	v_mul_f32_e32 v99, v113, v121
	v_mul_f32_e32 v99, v99, v104
	v_lshlrev_b32_e32 v104, 16, v163
	v_mul_f32_e32 v101, v100, v98
	v_cvt_pk_bf16_f32 v98, v110, v111
	v_cvt_pk_bf16_f32 v99, v102, v99
	v_add_u32_e32 v102, s22, v151
	v_cvt_pk_bf16_f32 v100, v106, v107
	v_cvt_pk_bf16_f32 v101, v103, v101
	v_ashrrev_i32_e32 v103, 31, v102
	v_lshlrev_b64 v[102:103], 11, v[102:103]
	v_lshl_add_u64 v[102:103], s[6:7], 0, v[102:103]
	v_lshl_add_u64 v[102:103], v[102:103], 0, v[144:145]
	global_store_dwordx4 v[102:103], v[98:101], off
	v_lshlrev_b32_e32 v102, 16, v162
	v_lshlrev_b32_e32 v106, 16, v164
; __device__ __forceinline__ u32x4 pack8(const float (&f)[8]) { u32x4 r; r[0] = cvt_pk_bf16(f[0], f[1]); r[1] = cvt_pk_bf16(f[2], f[3]); r[2] = cvt_pk_bf16(f[4], f[5]); r[3] = cvt_pk_bf16(f[6], f[7]); return r; }
;     __device__ __forceinline__ void operator()(EPI_ARGS) const {
;     ...
;         for (int ai = 0; ai < 2; ++ai) if (ai == 0 || !u.half) { u32x4 zz[4];
; #pragma unroll
;             for (int m = 0; m < 4; ++m) zz[m] = *(const u32x4*)(parts + E_PZB + (size_t)EPI_ROW * 1024 + col);
; #pragma unroll
;             for (int m = 0; m < 4; ++m) { float z[8]; unpack8(zz[m], z);
;                 const f32x4 a0 = acc[ai][0][m][0], a1 = acc[ai][0][m][1], b0 = acc[ai][1][m][0], b1 = acc[ai][1][m][1]; float o[8];
; #pragma unroll
;                 for (int j = 0; j < 4; ++j) { o[j] = a0[j] * z[j] * __builtin_amdgcn_rcpf((1.0f + __expf(-b0[j])) * (1.0f + __expf(-z[j]))); o[4 + j] = a1[j] * z[4 + j] * __builtin_amdgcn_rcpf((1.0f + __expf(-b1[j])) * (1.0f + __expf(-z[4 + j]))); }
;                 *(u32x4*)(O + (size_t)EPI_ROW * 1024 + col) = pack8(o); } }
	v_exp_f32_e32 v98, v86
	v_mul_f32_e32 v86, 0xbfb8aa3b, v102
	v_exp_f32_e32 v99, v86
	v_exp_f32_e32 v100, v82
	v_mul_f32_e32 v82, 0xbfb8aa3b, v106
	v_exp_f32_e32 v101, v82
	v_pk_add_f32 v[98:99], v[98:99], 1.0 op_sel_hi:[1,0]
	v_mul_f32_e32 v94, v94, v102
	v_mul_f32_e32 v82, v98, v99
	v_pk_add_f32 v[98:99], v[100:101], 1.0 op_sel_hi:[1,0]
	v_rcp_f32_e32 v82, v82
	v_mul_f32_e32 v86, v98, v99
	v_rcp_f32_e32 v86, v86
	v_and_b32_e32 v103, 0xffff0000, v162
	v_mul_f32_e32 v94, v94, v82
	v_mul_f32_e32 v82, v90, v106
	v_mul_f32_e32 v90, v82, v86
	v_mul_f32_e32 v82, 0xbfb8aa3b, v87
	v_and_b32_e32 v107, 0xffff0000, v164
	v_exp_f32_e32 v86, v82
	v_mul_f32_e32 v82, 0xbfb8aa3b, v103
	v_exp_f32_e32 v87, v82
	v_mul_f32_e32 v82, 0xbfb8aa3b, v83
	v_mul_f32_e32 v83, 0xbfb8aa3b, v107
	v_exp_f32_e32 v82, v82
	v_exp_f32_e32 v83, v83
	v_pk_add_f32 v[86:87], v[86:87], 1.0 op_sel_hi:[1,0]
	v_and_b32_e32 v105, 0xffff0000, v163
	v_mul_f32_e32 v86, v86, v87
	v_pk_add_f32 v[82:83], v[82:83], 1.0 op_sel_hi:[1,0]
	v_rcp_f32_e32 v86, v86
	v_mul_f32_e32 v82, v82, v83
	v_rcp_f32_e32 v82, v82
	v_mul_f32_e32 v83, v95, v103
	v_mul_f32_e32 v95, v83, v86
	v_mul_f32_e32 v83, v91, v107
	v_mul_f32_e32 v91, v83, v82
	v_mul_f32_e32 v82, 0xbfb8aa3b, v88
	v_mul_f32_e32 v83, 0xbfb8aa3b, v104
	v_exp_f32_e32 v82, v82
	v_exp_f32_e32 v83, v83
	v_exp_f32_e32 v86, v84
	v_mul_f32_e32 v84, 0xbfb8aa3b, v108
	v_exp_f32_e32 v87, v84
	v_pk_add_f32 v[82:83], v[82:83], 1.0 op_sel_hi:[1,0]
	v_and_b32_e32 v109, 0xffff0000, v165
	v_mul_f32_e32 v82, v82, v83
	v_rcp_f32_e32 v84, v82
	v_pk_add_f32 v[82:83], v[86:87], 1.0 op_sel_hi:[1,0]
	s_nop 0
	v_mul_f32_e32 v82, v82, v83
	v_rcp_f32_e32 v82, v82
	v_mul_f32_e32 v83, v96, v104
	v_mul_f32_e32 v86, v83, v84
	v_mul_f32_e32 v83, v92, v108
	v_mul_f32_e32 v87, v83, v82
	v_mul_f32_e32 v82, 0xbfb8aa3b, v89
	v_mul_f32_e32 v83, 0xbfb8aa3b, v105
	v_exp_f32_e32 v82, v82
	v_exp_f32_e32 v83, v83
	v_mul_f32_e32 v84, 0xbfb8aa3b, v85
	v_mul_f32_e32 v85, 0xbfb8aa3b, v109
	v_exp_f32_e32 v84, v84
	v_exp_f32_e32 v85, v85
	v_pk_add_f32 v[82:83], v[82:83], 1.0 op_sel_hi:[1,0]
	v_lshlrev_b32_e32 v92, 16, v125
	v_mul_f32_e32 v82, v82, v83
	v_rcp_f32_e32 v88, v82
	v_pk_add_f32 v[82:83], v[84:85], 1.0 op_sel_hi:[1,0]
	v_mul_f32_e32 v84, v93, v109
	v_mul_f32_e32 v82, v82, v83
	v_rcp_f32_e32 v82, v82
	v_mul_f32_e32 v83, v97, v105
	v_mul_f32_e32 v83, v83, v88
	v_lshlrev_b32_e32 v88, 16, v123
	v_mul_f32_e32 v85, v84, v82
	v_cvt_pk_bf16_f32 v82, v94, v95
	v_cvt_pk_bf16_f32 v83, v86, v83
	v_add_u32_e32 v86, s22, v152
	v_cvt_pk_bf16_f32 v84, v90, v91
	v_cvt_pk_bf16_f32 v85, v87, v85
	v_ashrrev_i32_e32 v87, 31, v86
	v_lshlrev_b64 v[86:87], 11, v[86:87]
	v_lshl_add_u64 v[86:87], s[6:7], 0, v[86:87]
	v_lshl_add_u64 v[86:87], v[86:87], 0, v[144:145]
	global_store_dwordx4 v[86:87], v[82:85], off
	v_lshlrev_b32_e32 v86, 16, v122
	v_lshlrev_b32_e32 v90, 16, v124
	v_exp_f32_e32 v82, v70
	v_mul_f32_e32 v70, 0xbfb8aa3b, v86
	v_exp_f32_e32 v83, v70
	v_exp_f32_e32 v84, v66
	v_mul_f32_e32 v66, 0xbfb8aa3b, v90
	v_exp_f32_e32 v85, v66
	v_pk_add_f32 v[82:83], v[82:83], 1.0 op_sel_hi:[1,0]
	v_mul_f32_e32 v78, v78, v86
	v_mul_f32_e32 v66, v82, v83
	v_pk_add_f32 v[82:83], v[84:85], 1.0 op_sel_hi:[1,0]
	v_rcp_f32_e32 v66, v66
	v_mul_f32_e32 v70, v82, v83
	v_rcp_f32_e32 v70, v70
	v_and_b32_e32 v87, 0xffff0000, v122
	v_mul_f32_e32 v78, v78, v66
	v_mul_f32_e32 v66, v74, v90
	v_mul_f32_e32 v74, v66, v70
	v_mul_f32_e32 v66, 0xbfb8aa3b, v71
	v_and_b32_e32 v91, 0xffff0000, v124
	v_exp_f32_e32 v70, v66
	v_mul_f32_e32 v66, 0xbfb8aa3b, v87
	v_exp_f32_e32 v71, v66
	v_mul_f32_e32 v66, 0xbfb8aa3b, v67
	v_mul_f32_e32 v67, 0xbfb8aa3b, v91
	v_exp_f32_e32 v66, v66
	v_exp_f32_e32 v67, v67
	v_pk_add_f32 v[70:71], v[70:71], 1.0 op_sel_hi:[1,0]
	v_and_b32_e32 v89, 0xffff0000, v123
	v_mul_f32_e32 v70, v70, v71
	v_pk_add_f32 v[66:67], v[66:67], 1.0 op_sel_hi:[1,0]
	v_rcp_f32_e32 v70, v70
	v_mul_f32_e32 v66, v66, v67
	v_rcp_f32_e32 v66, v66
	v_mul_f32_e32 v67, v79, v87
	v_mul_f32_e32 v79, v67, v70
	v_mul_f32_e32 v67, v75, v91
	v_mul_f32_e32 v75, v67, v66
	v_mul_f32_e32 v66, 0xbfb8aa3b, v72
	v_mul_f32_e32 v67, 0xbfb8aa3b, v88
	v_exp_f32_e32 v66, v66
	v_exp_f32_e32 v67, v67
	v_exp_f32_e32 v70, v68
	v_mul_f32_e32 v68, 0xbfb8aa3b, v92
	v_exp_f32_e32 v71, v68
	v_pk_add_f32 v[66:67], v[66:67], 1.0 op_sel_hi:[1,0]
	v_and_b32_e32 v93, 0xffff0000, v125
	v_mul_f32_e32 v66, v66, v67
	v_rcp_f32_e32 v68, v66
	v_pk_add_f32 v[66:67], v[70:71], 1.0 op_sel_hi:[1,0]
	s_nop 0
	v_mul_f32_e32 v66, v66, v67
	v_rcp_f32_e32 v66, v66
	v_mul_f32_e32 v67, v80, v88
	v_mul_f32_e32 v70, v67, v68
	v_mul_f32_e32 v67, v76, v92
	v_mul_f32_e32 v71, v67, v66
	v_mul_f32_e32 v66, 0xbfb8aa3b, v73
	v_mul_f32_e32 v67, 0xbfb8aa3b, v89
	v_exp_f32_e32 v66, v66
	v_exp_f32_e32 v67, v67
	v_mul_f32_e32 v68, 0xbfb8aa3b, v69
	v_mul_f32_e32 v69, 0xbfb8aa3b, v93
	v_exp_f32_e32 v68, v68
	v_exp_f32_e32 v69, v69
	v_pk_add_f32 v[66:67], v[66:67], 1.0 op_sel_hi:[1,0]
	s_nop 0
	v_mul_f32_e32 v66, v66, v67
	v_rcp_f32_e32 v72, v66
	v_pk_add_f32 v[66:67], v[68:69], 1.0 op_sel_hi:[1,0]
	v_mul_f32_e32 v68, v77, v93
	v_mul_f32_e32 v66, v66, v67
	v_rcp_f32_e32 v66, v66
	v_mul_f32_e32 v67, v81, v89
	v_mul_f32_e32 v67, v67, v72
	v_mul_f32_e32 v69, v68, v66
	v_cvt_pk_bf16_f32 v66, v78, v79
	v_cvt_pk_bf16_f32 v67, v70, v67
	v_add_u32_e32 v70, s22, v153
	v_cvt_pk_bf16_f32 v68, v74, v75
	v_cvt_pk_bf16_f32 v69, v71, v69
	v_ashrrev_i32_e32 v71, 31, v70
	v_lshlrev_b64 v[70:71], 11, v[70:71]
	v_lshl_add_u64 v[70:71], s[6:7], 0, v[70:71]
	v_lshl_add_u64 v[70:71], v[70:71], 0, v[144:145]
	global_store_dwordx4 v[70:71], v[66:69], off
	s_mov_b32 s22, s16
	s_nop 0
	v_add_u32_e32 v66, 0x80, v148
	v_ashrrev_i32_e32 v67, 31, v66
	v_lshlrev_b64 v[88:89], 11, v[66:67]
	v_lshl_add_u64 v[66:67], v[146:147], 0, v[88:89]
	global_load_dwordx4 v[80:83], v[66:67], off
	v_add_u32_e32 v66, 0x90, v148
	v_ashrrev_i32_e32 v67, 31, v66
	v_lshlrev_b64 v[78:79], 11, v[66:67]
	v_lshl_add_u64 v[66:67], v[146:147], 0, v[78:79]
	global_load_dwordx4 v[84:87], v[66:67], off
	v_add_u32_e32 v66, 0xa0, v148
	v_ashrrev_i32_e32 v67, 31, v66
	v_lshlrev_b64 v[76:77], 11, v[66:67]
	v_add_u32_e32 v66, 0xb0, v148
	v_ashrrev_i32_e32 v67, 31, v66
	v_lshl_add_u64 v[90:91], v[146:147], 0, v[76:77]
	v_lshlrev_b64 v[74:75], 11, v[66:67]
	v_lshl_add_u64 v[92:93], v[146:147], 0, v[74:75]
	global_load_dwordx4 v[70:73], v[90:91], off
	global_load_dwordx4 v[66:69], v[92:93], off
	s_waitcnt vmcnt(0)
; __device__ __forceinline__ u32x4 pack8(const float (&f)[8]) { u32x4 r; r[0] = cvt_pk_bf16(f[0], f[1]); r[1] = cvt_pk_bf16(f[2], f[3]); r[2] = cvt_pk_bf16(f[4], f[5]); r[3] = cvt_pk_bf16(f[6], f[7]); return r; }
;     __device__ __forceinline__ void operator()(EPI_ARGS) const {
;     ...
;         for (int ai = 0; ai < 2; ++ai) if (ai == 0 || !u.half) { u32x4 zz[4];
; #pragma unroll
;             for (int m = 0; m < 4; ++m) zz[m] = *(const u32x4*)(parts + E_PZB + (size_t)EPI_ROW * 1024 + col);
; #pragma unroll
;             for (int m = 0; m < 4; ++m) { float z[8]; unpack8(zz[m], z);
;                 const f32x4 a0 = acc[ai][0][m][0], a1 = acc[ai][0][m][1], b0 = acc[ai][1][m][0], b1 = acc[ai][1][m][1]; float o[8];
; #pragma unroll
;                 for (int j = 0; j < 4; ++j) { o[j] = a0[j] * z[j] * __builtin_amdgcn_rcpf((1.0f + __expf(-b0[j])) * (1.0f + __expf(-z[j]))); o[4 + j] = a1[j] * z[4 + j] * __builtin_amdgcn_rcpf((1.0f + __expf(-b1[j])) * (1.0f + __expf(-z[4 + j]))); }
;                 *(u32x4*)(O + (size_t)EPI_ROW * 1024 + col) = pack8(o); } }
	v_lshlrev_b32_e32 v90, 16, v80
	v_and_b32_e32 v91, 0xffff0000, v80
	v_lshlrev_b32_e32 v94, 16, v82
	v_exp_f32_e32 v80, v54
	v_mul_f32_e32 v54, 0xbfb8aa3b, v90
	v_lshlrev_b32_e32 v92, 16, v81
	v_and_b32_e32 v93, 0xffff0000, v81
	v_and_b32_e32 v95, 0xffff0000, v82
	v_exp_f32_e32 v81, v54
	v_exp_f32_e32 v82, v50
	v_mul_f32_e32 v50, 0xbfb8aa3b, v94
	v_lshlrev_b32_e32 v96, 16, v83
	v_and_b32_e32 v97, 0xffff0000, v83
	v_exp_f32_e32 v83, v50
	v_pk_add_f32 v[80:81], v[80:81], 1.0 op_sel_hi:[1,0]
	v_mul_f32_e32 v62, v62, v90
	v_mul_f32_e32 v50, v80, v81
	v_pk_add_f32 v[80:81], v[82:83], 1.0 op_sel_hi:[1,0]
	v_rcp_f32_e32 v50, v50
	v_mul_f32_e32 v54, v80, v81
	v_rcp_f32_e32 v54, v54
	v_mul_f32_e32 v62, v62, v50
	v_mul_f32_e32 v50, v58, v94
	v_mul_f32_e32 v58, v50, v54
	v_mul_f32_e32 v50, 0xbfb8aa3b, v55
	v_exp_f32_e32 v54, v50
	v_mul_f32_e32 v50, 0xbfb8aa3b, v91
	v_exp_f32_e32 v55, v50
	v_mul_f32_e32 v50, 0xbfb8aa3b, v51
	v_mul_f32_e32 v51, 0xbfb8aa3b, v95
	v_exp_f32_e32 v50, v50
	v_exp_f32_e32 v51, v51
	v_pk_add_f32 v[54:55], v[54:55], 1.0 op_sel_hi:[1,0]
	v_pk_add_f32 v[50:51], v[50:51], 1.0 op_sel_hi:[1,0]
	v_mul_f32_e32 v54, v54, v55
	v_rcp_f32_e32 v54, v54
	v_mul_f32_e32 v50, v50, v51
	v_rcp_f32_e32 v50, v50
	v_mul_f32_e32 v51, v63, v91
	v_mul_f32_e32 v63, v51, v54
	v_mul_f32_e32 v51, v59, v95
	v_mul_f32_e32 v59, v51, v50
	v_mul_f32_e32 v50, 0xbfb8aa3b, v56
	v_mul_f32_e32 v51, 0xbfb8aa3b, v92
	v_exp_f32_e32 v50, v50
	v_exp_f32_e32 v51, v51
	v_exp_f32_e32 v54, v52
	v_mul_f32_e32 v52, 0xbfb8aa3b, v96
	v_exp_f32_e32 v55, v52
	v_pk_add_f32 v[50:51], v[50:51], 1.0 op_sel_hi:[1,0]
	s_nop 0
	v_mul_f32_e32 v50, v50, v51
	v_rcp_f32_e32 v52, v50
	v_pk_add_f32 v[50:51], v[54:55], 1.0 op_sel_hi:[1,0]
	s_nop 0
	v_mul_f32_e32 v50, v50, v51
	v_rcp_f32_e32 v50, v50
	v_mul_f32_e32 v51, v64, v92
	v_mul_f32_e32 v54, v51, v52
	v_mul_f32_e32 v51, v60, v96
	v_mul_f32_e32 v55, v51, v50
	v_mul_f32_e32 v50, 0xbfb8aa3b, v57
	v_mul_f32_e32 v51, 0xbfb8aa3b, v93
	v_exp_f32_e32 v50, v50
	v_exp_f32_e32 v51, v51
	v_mul_f32_e32 v52, 0xbfb8aa3b, v53
	v_mul_f32_e32 v53, 0xbfb8aa3b, v97
	v_exp_f32_e32 v52, v52
	v_exp_f32_e32 v53, v53
	v_pk_add_f32 v[50:51], v[50:51], 1.0 op_sel_hi:[1,0]
	v_lshlrev_b32_e32 v60, 16, v87
	v_mul_f32_e32 v50, v50, v51
	v_rcp_f32_e32 v56, v50
	v_pk_add_f32 v[50:51], v[52:53], 1.0 op_sel_hi:[1,0]
	v_mul_f32_e32 v52, v61, v97
	v_mul_f32_e32 v50, v50, v51
	v_rcp_f32_e32 v50, v50
	v_mul_f32_e32 v51, v65, v93
	v_mul_f32_e32 v51, v51, v56
	v_lshlrev_b32_e32 v56, 16, v85
	v_mul_f32_e32 v53, v52, v50
	v_cvt_pk_bf16_f32 v50, v62, v63
	v_cvt_pk_bf16_f32 v51, v54, v51
	v_cvt_pk_bf16_f32 v52, v58, v59
	v_cvt_pk_bf16_f32 v53, v55, v53
	v_lshl_add_u64 v[54:55], s[6:7], 0, v[88:89]
	v_lshl_add_u64 v[54:55], v[54:55], 0, v[144:145]
	global_store_dwordx4 v[54:55], v[50:53], off
	v_lshlrev_b32_e32 v54, 16, v84
	v_lshlrev_b32_e32 v58, 16, v86
	v_exp_f32_e32 v50, v38
	v_mul_f32_e32 v38, 0xbfb8aa3b, v54
	v_exp_f32_e32 v51, v38
	v_exp_f32_e32 v52, v34
	v_mul_f32_e32 v34, 0xbfb8aa3b, v58
	v_exp_f32_e32 v53, v34
	v_pk_add_f32 v[50:51], v[50:51], 1.0 op_sel_hi:[1,0]
	v_mul_f32_e32 v46, v46, v54
	v_mul_f32_e32 v34, v50, v51
	v_pk_add_f32 v[50:51], v[52:53], 1.0 op_sel_hi:[1,0]
	v_rcp_f32_e32 v34, v34
	v_mul_f32_e32 v38, v50, v51
	v_rcp_f32_e32 v38, v38
	v_and_b32_e32 v55, 0xffff0000, v84
	v_mul_f32_e32 v46, v46, v34
	v_mul_f32_e32 v34, v42, v58
	v_mul_f32_e32 v42, v34, v38
	v_mul_f32_e32 v34, 0xbfb8aa3b, v39
	v_and_b32_e32 v59, 0xffff0000, v86
	v_exp_f32_e32 v38, v34
	v_mul_f32_e32 v34, 0xbfb8aa3b, v55
	v_exp_f32_e32 v39, v34
	v_mul_f32_e32 v34, 0xbfb8aa3b, v35
	v_mul_f32_e32 v35, 0xbfb8aa3b, v59
	v_exp_f32_e32 v34, v34
	v_exp_f32_e32 v35, v35
	v_pk_add_f32 v[38:39], v[38:39], 1.0 op_sel_hi:[1,0]
	v_and_b32_e32 v57, 0xffff0000, v85
	v_mul_f32_e32 v38, v38, v39
	v_pk_add_f32 v[34:35], v[34:35], 1.0 op_sel_hi:[1,0]
	v_rcp_f32_e32 v38, v38
	v_mul_f32_e32 v34, v34, v35
	v_rcp_f32_e32 v34, v34
	v_mul_f32_e32 v35, v47, v55
	v_mul_f32_e32 v47, v35, v38
	v_mul_f32_e32 v35, v43, v59
	v_mul_f32_e32 v43, v35, v34
	v_mul_f32_e32 v34, 0xbfb8aa3b, v40
	v_mul_f32_e32 v35, 0xbfb8aa3b, v56
	v_exp_f32_e32 v34, v34
	v_exp_f32_e32 v35, v35
	v_exp_f32_e32 v38, v36
	v_mul_f32_e32 v36, 0xbfb8aa3b, v60
	v_exp_f32_e32 v39, v36
	v_pk_add_f32 v[34:35], v[34:35], 1.0 op_sel_hi:[1,0]
	v_and_b32_e32 v61, 0xffff0000, v87
	v_mul_f32_e32 v34, v34, v35
	v_rcp_f32_e32 v36, v34
	v_pk_add_f32 v[34:35], v[38:39], 1.0 op_sel_hi:[1,0]
	s_nop 0
	v_mul_f32_e32 v34, v34, v35
	v_rcp_f32_e32 v34, v34
	v_mul_f32_e32 v35, v48, v56
	v_mul_f32_e32 v38, v35, v36
	v_mul_f32_e32 v35, v44, v60
	v_mul_f32_e32 v39, v35, v34
	v_mul_f32_e32 v34, 0xbfb8aa3b, v41
	v_mul_f32_e32 v35, 0xbfb8aa3b, v57
	v_exp_f32_e32 v34, v34
	v_exp_f32_e32 v35, v35
	v_mul_f32_e32 v36, 0xbfb8aa3b, v37
	v_mul_f32_e32 v37, 0xbfb8aa3b, v61
	v_exp_f32_e32 v36, v36
	v_exp_f32_e32 v37, v37
	v_pk_add_f32 v[34:35], v[34:35], 1.0 op_sel_hi:[1,0]
	v_lshlrev_b32_e32 v44, 16, v73
	v_mul_f32_e32 v34, v34, v35
	v_rcp_f32_e32 v40, v34
	v_pk_add_f32 v[34:35], v[36:37], 1.0 op_sel_hi:[1,0]
	v_mul_f32_e32 v36, v45, v61
	v_mul_f32_e32 v34, v34, v35
	v_rcp_f32_e32 v34, v34
	v_mul_f32_e32 v35, v49, v57
	v_mul_f32_e32 v35, v35, v40
	v_lshlrev_b32_e32 v40, 16, v71
	v_mul_f32_e32 v37, v36, v34
	v_cvt_pk_bf16_f32 v34, v46, v47
	v_cvt_pk_bf16_f32 v35, v38, v35
	v_cvt_pk_bf16_f32 v36, v42, v43
	v_cvt_pk_bf16_f32 v37, v39, v37
	v_lshl_add_u64 v[38:39], s[6:7], 0, v[78:79]
; __device__ __forceinline__ u32x4 pack8(const float (&f)[8]) { u32x4 r; r[0] = cvt_pk_bf16(f[0], f[1]); r[1] = cvt_pk_bf16(f[2], f[3]); r[2] = cvt_pk_bf16(f[4], f[5]); r[3] = cvt_pk_bf16(f[6], f[7]); return r; }
; #define PG8_WAIT_V(n) asm volatile("s_waitcnt vmcnt(" #n ")" ::: "memory")
; #define PG8_BAR __builtin_amdgcn_s_barrier()
; template <class Sched, class Epi>
; __device__ __forceinline__ void gemm_phase(LAS unsigned char* lds, const Sched& S, const Epi& E, const int K, const int lda, const int ldb) {
;     ...
;         if (!has_next) break;
; #pragma unroll
;         for (int a = 0; a < 2; ++a)
; #pragma unroll
;             for (int b = 0; b < 2; ++b)
; #pragma unroll
;                 for (int m = 0; m < 4; ++m)
; #pragma unroll
;                     for (int n = 0; n < 2; ++n) acc[a][b][m][n] = (f32x4){0.f, 0.f, 0.f, 0.f};
;         cur = nxt; cA = nA; cB = nB; ++ui;
;     }
;     PG8_WAIT_V(0);
;     if (wr == 0) PG8_BAR;
;     PG8_BAR;
;     __device__ __forceinline__ void operator()(EPI_ARGS) const {
;     ...
;             for (int m = 0; m < 4; ++m) { float z[8]; unpack8(zz[m], z);
;                 const f32x4 a0 = acc[ai][0][m][0], a1 = acc[ai][0][m][1], b0 = acc[ai][1][m][0], b1 = acc[ai][1][m][1]; float o[8];
; #pragma unroll
;                 for (int j = 0; j < 4; ++j) { o[j] = a0[j] * z[j] * __builtin_amdgcn_rcpf((1.0f + __expf(-b0[j])) * (1.0f + __expf(-z[j]))); o[4 + j] = a1[j] * z[4 + j] * __builtin_amdgcn_rcpf((1.0f + __expf(-b1[j])) * (1.0f + __expf(-z[4 + j]))); }
;                 *(u32x4*)(O + (size_t)EPI_ROW * 1024 + col) = pack8(o); } }
	v_lshl_add_u64 v[38:39], v[38:39], 0, v[144:145]
	global_store_dwordx4 v[38:39], v[34:37], off
	v_lshlrev_b32_e32 v38, 16, v70
	v_lshlrev_b32_e32 v42, 16, v72
	v_exp_f32_e32 v34, v22
	v_mul_f32_e32 v22, 0xbfb8aa3b, v38
	v_exp_f32_e32 v35, v22
	v_exp_f32_e32 v36, v18
	v_mul_f32_e32 v18, 0xbfb8aa3b, v42
	v_exp_f32_e32 v37, v18
	v_pk_add_f32 v[34:35], v[34:35], 1.0 op_sel_hi:[1,0]
	v_mul_f32_e32 v30, v30, v38
	v_mul_f32_e32 v18, v34, v35
	v_pk_add_f32 v[34:35], v[36:37], 1.0 op_sel_hi:[1,0]
	v_rcp_f32_e32 v18, v18
	v_mul_f32_e32 v22, v34, v35
	v_rcp_f32_e32 v22, v22
	v_and_b32_e32 v39, 0xffff0000, v70
	v_mul_f32_e32 v30, v30, v18
	v_mul_f32_e32 v18, v26, v42
	v_mul_f32_e32 v26, v18, v22
	v_mul_f32_e32 v18, 0xbfb8aa3b, v23
	v_and_b32_e32 v43, 0xffff0000, v72
	v_exp_f32_e32 v22, v18
	v_mul_f32_e32 v18, 0xbfb8aa3b, v39
	v_exp_f32_e32 v23, v18
	v_mul_f32_e32 v18, 0xbfb8aa3b, v19
	v_mul_f32_e32 v19, 0xbfb8aa3b, v43
	v_exp_f32_e32 v18, v18
	v_exp_f32_e32 v19, v19
	v_pk_add_f32 v[22:23], v[22:23], 1.0 op_sel_hi:[1,0]
	v_and_b32_e32 v41, 0xffff0000, v71
	v_mul_f32_e32 v22, v22, v23
	v_pk_add_f32 v[18:19], v[18:19], 1.0 op_sel_hi:[1,0]
	v_rcp_f32_e32 v22, v22
	v_mul_f32_e32 v18, v18, v19
	v_rcp_f32_e32 v18, v18
	v_mul_f32_e32 v19, v31, v39
	v_mul_f32_e32 v31, v19, v22
	v_mul_f32_e32 v19, v27, v43
	v_mul_f32_e32 v27, v19, v18
	v_mul_f32_e32 v18, 0xbfb8aa3b, v24
	v_mul_f32_e32 v19, 0xbfb8aa3b, v40
	v_exp_f32_e32 v18, v18
	v_exp_f32_e32 v19, v19
	v_exp_f32_e32 v22, v20
	v_mul_f32_e32 v20, 0xbfb8aa3b, v44
	v_exp_f32_e32 v23, v20
	v_pk_add_f32 v[18:19], v[18:19], 1.0 op_sel_hi:[1,0]
	v_and_b32_e32 v45, 0xffff0000, v73
	v_mul_f32_e32 v18, v18, v19
	v_rcp_f32_e32 v20, v18
	v_pk_add_f32 v[18:19], v[22:23], 1.0 op_sel_hi:[1,0]
	s_nop 0
	v_mul_f32_e32 v18, v18, v19
	v_rcp_f32_e32 v18, v18
	v_mul_f32_e32 v19, v32, v40
	v_mul_f32_e32 v22, v19, v20
	v_mul_f32_e32 v19, v28, v44
	v_mul_f32_e32 v23, v19, v18
	v_mul_f32_e32 v18, 0xbfb8aa3b, v25
	v_mul_f32_e32 v19, 0xbfb8aa3b, v41
	v_exp_f32_e32 v18, v18
	v_exp_f32_e32 v19, v19
	v_mul_f32_e32 v20, 0xbfb8aa3b, v21
	v_mul_f32_e32 v21, 0xbfb8aa3b, v45
	v_exp_f32_e32 v20, v20
	v_exp_f32_e32 v21, v21
	v_pk_add_f32 v[18:19], v[18:19], 1.0 op_sel_hi:[1,0]
	v_lshlrev_b32_e32 v28, 16, v69
	v_mul_f32_e32 v18, v18, v19
	v_rcp_f32_e32 v24, v18
	v_pk_add_f32 v[18:19], v[20:21], 1.0 op_sel_hi:[1,0]
	v_mul_f32_e32 v20, v29, v45
	v_mul_f32_e32 v18, v18, v19
	v_rcp_f32_e32 v18, v18
	v_mul_f32_e32 v19, v33, v41
	v_mul_f32_e32 v19, v19, v24
	v_lshlrev_b32_e32 v24, 16, v67
	v_mul_f32_e32 v21, v20, v18
	v_cvt_pk_bf16_f32 v18, v30, v31
	v_cvt_pk_bf16_f32 v19, v22, v19
	v_cvt_pk_bf16_f32 v20, v26, v27
	v_cvt_pk_bf16_f32 v21, v23, v21
	v_lshl_add_u64 v[22:23], s[6:7], 0, v[76:77]
	v_lshl_add_u64 v[22:23], v[22:23], 0, v[144:145]
	global_store_dwordx4 v[22:23], v[18:21], off
	v_lshlrev_b32_e32 v22, 16, v66
	v_lshlrev_b32_e32 v26, 16, v68
	v_exp_f32_e32 v18, v6
	v_mul_f32_e32 v6, 0xbfb8aa3b, v22
	v_exp_f32_e32 v19, v6
	v_exp_f32_e32 v20, v2
	v_mul_f32_e32 v2, 0xbfb8aa3b, v26
	v_exp_f32_e32 v21, v2
	v_pk_add_f32 v[18:19], v[18:19], 1.0 op_sel_hi:[1,0]
	v_mul_f32_e32 v14, v14, v22
	v_mul_f32_e32 v2, v18, v19
	v_pk_add_f32 v[18:19], v[20:21], 1.0 op_sel_hi:[1,0]
	v_rcp_f32_e32 v2, v2
	v_mul_f32_e32 v6, v18, v19
	v_rcp_f32_e32 v6, v6
	v_and_b32_e32 v23, 0xffff0000, v66
	v_mul_f32_e32 v14, v14, v2
	v_mul_f32_e32 v2, v10, v26
	v_mul_f32_e32 v10, v2, v6
	v_mul_f32_e32 v2, 0xbfb8aa3b, v7
	v_and_b32_e32 v27, 0xffff0000, v68
	v_exp_f32_e32 v6, v2
	v_mul_f32_e32 v2, 0xbfb8aa3b, v23
	v_exp_f32_e32 v7, v2
	v_mul_f32_e32 v2, 0xbfb8aa3b, v3
	v_mul_f32_e32 v3, 0xbfb8aa3b, v27
	v_exp_f32_e32 v2, v2
	v_exp_f32_e32 v3, v3
	v_pk_add_f32 v[6:7], v[6:7], 1.0 op_sel_hi:[1,0]
	v_and_b32_e32 v25, 0xffff0000, v67
	v_mul_f32_e32 v6, v6, v7
	v_pk_add_f32 v[2:3], v[2:3], 1.0 op_sel_hi:[1,0]
	v_rcp_f32_e32 v6, v6
	v_mul_f32_e32 v2, v2, v3
	v_rcp_f32_e32 v2, v2
	v_mul_f32_e32 v3, v15, v23
	v_mul_f32_e32 v15, v3, v6
	v_mul_f32_e32 v3, v11, v27
	v_mul_f32_e32 v11, v3, v2
	v_mul_f32_e32 v2, 0xbfb8aa3b, v8
	v_mul_f32_e32 v3, 0xbfb8aa3b, v24
	v_exp_f32_e32 v2, v2
	v_exp_f32_e32 v3, v3
	v_exp_f32_e32 v6, v4
	v_mul_f32_e32 v4, 0xbfb8aa3b, v28
	v_exp_f32_e32 v7, v4
	v_pk_add_f32 v[2:3], v[2:3], 1.0 op_sel_hi:[1,0]
	v_and_b32_e32 v29, 0xffff0000, v69
	v_mul_f32_e32 v2, v2, v3
	v_rcp_f32_e32 v4, v2
	v_pk_add_f32 v[2:3], v[6:7], 1.0 op_sel_hi:[1,0]
	s_nop 0
	v_mul_f32_e32 v2, v2, v3
	v_rcp_f32_e32 v2, v2
	v_mul_f32_e32 v3, v16, v24
	v_mul_f32_e32 v6, v3, v4
	v_mul_f32_e32 v3, v12, v28
	v_mul_f32_e32 v7, v3, v2
	v_mul_f32_e32 v2, 0xbfb8aa3b, v9
	v_mul_f32_e32 v3, 0xbfb8aa3b, v25
	v_exp_f32_e32 v2, v2
	v_exp_f32_e32 v3, v3
	v_mul_f32_e32 v4, 0xbfb8aa3b, v5
	v_mul_f32_e32 v5, 0xbfb8aa3b, v29
	v_exp_f32_e32 v4, v4
	v_exp_f32_e32 v5, v5
	v_pk_add_f32 v[2:3], v[2:3], 1.0 op_sel_hi:[1,0]
	s_nop 0
	v_mul_f32_e32 v2, v2, v3
	v_rcp_f32_e32 v8, v2
	v_pk_add_f32 v[2:3], v[4:5], 1.0 op_sel_hi:[1,0]
	v_mul_f32_e32 v4, v13, v29
	v_mul_f32_e32 v2, v2, v3
	v_rcp_f32_e32 v2, v2
	v_mul_f32_e32 v3, v17, v25
	v_mul_f32_e32 v3, v3, v8
	v_mul_f32_e32 v5, v4, v2
	v_cvt_pk_bf16_f32 v2, v14, v15
	v_cvt_pk_bf16_f32 v3, v6, v3
	v_cvt_pk_bf16_f32 v4, v10, v11
	v_cvt_pk_bf16_f32 v5, v7, v5
	v_lshl_add_u64 v[6:7], s[6:7], 0, v[74:75]
	v_lshl_add_u64 v[6:7], v[6:7], 0, v[144:145]
	global_store_dwordx4 v[6:7], v[2:5], off
	s_cbranch_vccz .LBB0_1408
	s_waitcnt vmcnt(0)
	s_cmpk_gt_u32 s2, 0xff
	s_cbranch_scc1 .LBB0_1419
	s_barrier

; #define PG8_STAGE(bufoff, gbase, voff) do { _Pragma("unroll") for (int _i = 0; _i < 2; ++_i) \
;         __builtin_amdgcn_global_load_lds((const unsigned*)((const char*)(gbase) + (voff)[_i]), (LAS unsigned*)(lds + (bufoff) + ldsw + _i * 8192), 16, 0, 0); } while (0)
; #define PG8_LDA(dst, b, h) do { _Pragma("unroll") for (int m = 0; m < 4; ++m) _Pragma("unroll") for (int k = 0; k < 2; ++k) dst[m][k] = *(const LAS bf16x8*)(lds + PG8_SA(b, h) + aoff + m * 2048 + k * 1024); } while (0)
; #define PG8_LDB(dst, b, h) do { _Pragma("unroll") for (int n = 0; n < 2; ++n) _Pragma("unroll") for (int k = 0; k < 2; ++k) dst[n][k] = *(const LAS bf16x8*)(lds + PG8_SB(b, h) + boff + n * 2048 + k * 1024); } while (0)
; #define PG8_MMA(ai, bj, At, Bt) do { __builtin_amdgcn_s_setprio(1); _Pragma("unroll") for (int m = 0; m < 4; ++m) _Pragma("unroll") for (int n = 0; n < 2; ++n) _Pragma("unroll") for (int k = 0; k < 2; ++k) \
;         acc[ai][bj][m][n] = __builtin_amdgcn_mfma_f32_16x16x32_bf16(Bt[n][k], At[m][k], acc[ai][bj][m][n], 0, 0, 0); __builtin_amdgcn_s_setprio(0); } while (0)
; #define PG8_WAIT_V(n) asm volatile("s_waitcnt vmcnt(" #n ")" ::: "memory")
; #define PG8_BAR __builtin_amdgcn_s_barrier()
; template <class Sched, class Epi>
; __device__ __forceinline__ void gemm_phase(LAS unsigned char* lds, const Sched& S, const Epi& E, const int K, const int lda, const int ldb) {
;     ...
;         for (int t = 0; t < nt; t += 2) {
;             const bool last = (t == nt - 2);
;             const char* a1 = cA + (size_t)(t + 1) * kstep;
;             const char* a2 = last ? nA : cA + (size_t)(t + 2) * kstep; const char* b2 = last ? nB : cB + (size_t)(t + 2) * kstep;
;             const char* a3 = a2 + kstep; const char* b3 = b2 + kstep;
;             PG8_LDB(B0, 0, 0); PG8_SCHED; PG8_LDA(At, 0, 0); PG8_STAGE(PG8_SA(1, 1), a1 + hstepA, voffA);
;             PG8_WAIT_L(8); PG8_BAR; PG8_WAIT_L(0); PG8_MMA(0, 0, At, B0); PG8_BAR; PG8_SCHED;
;             PG8_LDB(B1, 0, 1); PG8_STAGE(PG8_SB(0, 0), b2, voffB);
;             PG8_BAR; PG8_WAIT_L(0); PG8_MMA(0, 1, At, B1); PG8_BAR;
;             PG8_LDA(At, 0, 1); PG8_STAGE(PG8_SA(0, 0), a2, voffA);
;             PG8_BAR; PG8_WAIT_L(0); if (!chalf) PG8_MMA(1, 0, At, B0); PG8_BAR; PG8_SCHED;
;             PG8_STAGE(PG8_SB(0, 1), b2 + hstepB, voffB);
;             PG8_WAIT_V(6); PG8_BAR; if (!chalf) PG8_MMA(1, 1, At, B1); PG8_BAR;
.LBB0_1486:
	ds_read_b128 v[130:133], v233
	ds_read_b128 v[134:137], v233 offset:1024
	ds_read_b128 v[138:141], v233 offset:2048
	ds_read_b128 v[142:145], v233 offset:3072
	s_add_u32 s26, s6, 0xfffc0080
	s_addc_u32 s27, s7, -1
	s_cmp_eq_u32 s19, 12
	s_cselect_b32 s29, s21, s27
	s_cselect_b32 s28, s20, s26
	s_cselect_b32 s27, s23, s17
	s_cselect_b32 s26, s22, s15
	s_add_i32 m0, s31, 0xc000
	ds_read_b128 v[146:149], v234
	ds_read_b128 v[150:153], v234 offset:1024
	ds_read_b128 v[154:157], v234 offset:2048
	ds_read_b128 v[158:161], v234 offset:3072
	ds_read_b128 v[162:165], v234 offset:4096
	ds_read_b128 v[166:169], v234 offset:5120
	ds_read_b128 v[170:173], v234 offset:6144
	ds_read_b128 v[174:177], v234 offset:7168
	global_load_lds_dwordx4 v208, s[6:7]
	s_add_i32 m0, s31, 0xe000
	s_nop 0
	global_load_lds_dwordx4 v206, s[6:7]
	s_waitcnt lgkmcnt(8)
	s_barrier
	s_waitcnt lgkmcnt(0)
	s_setprio 1
	s_waitcnt lgkmcnt(0)
	v_mfma_f32_16x16x32_bf16 v[126:129], v[130:133], v[146:149], v[126:129]
	v_mfma_f32_16x16x32_bf16 v[122:125], v[138:141], v[146:149], v[122:125]
	v_mfma_f32_16x16x32_bf16 v[118:121], v[130:133], v[154:157], v[118:121]
	v_mfma_f32_16x16x32_bf16 v[114:117], v[138:141], v[154:157], v[114:117]
	v_mfma_f32_16x16x32_bf16 v[110:113], v[130:133], v[162:165], v[110:113]
	v_mfma_f32_16x16x32_bf16 v[106:109], v[138:141], v[162:165], v[106:109]
	v_mfma_f32_16x16x32_bf16 v[102:105], v[130:133], v[170:173], v[102:105]
	v_mfma_f32_16x16x32_bf16 v[98:101], v[138:141], v[170:173], v[98:101]
	v_mfma_f32_16x16x32_bf16 v[126:129], v[134:137], v[150:153], v[126:129]
	v_mfma_f32_16x16x32_bf16 v[122:125], v[142:145], v[150:153], v[122:125]
	v_mfma_f32_16x16x32_bf16 v[118:121], v[134:137], v[158:161], v[118:121]
	v_mfma_f32_16x16x32_bf16 v[114:117], v[142:145], v[158:161], v[114:117]
	v_mfma_f32_16x16x32_bf16 v[110:113], v[134:137], v[166:169], v[110:113]
	v_mfma_f32_16x16x32_bf16 v[106:109], v[142:145], v[166:169], v[106:109]
	v_mfma_f32_16x16x32_bf16 v[102:105], v[134:137], v[174:177], v[102:105]
	v_mfma_f32_16x16x32_bf16 v[98:101], v[142:145], v[174:177], v[98:101]
	s_setprio 0
	s_barrier
	s_add_i32 s49, s43, s25
	v_lshl_add_u64 v[194:195], s[26:27], 0, v[200:201]
	s_mov_b32 m0, s49
	ds_read_b128 v[178:181], v235
	ds_read_b128 v[182:185], v235 offset:1024
	ds_read_b128 v[186:189], v235 offset:2048
	ds_read_b128 v[190:193], v235 offset:3072
	global_load_lds_dwordx4 v[194:195], off
	v_lshl_add_u64 v[196:197], s[26:27], 0, v[204:205]
	s_add_i32 m0, s49, 0x2000
	s_nop 0
	global_load_lds_dwordx4 v[196:197], off
	s_barrier
	s_waitcnt lgkmcnt(0)
	s_setprio 1
	s_waitcnt lgkmcnt(0)
	v_mfma_f32_16x16x32_bf16 v[94:97], v[178:181], v[146:149], v[94:97]
	v_mfma_f32_16x16x32_bf16 v[90:93], v[186:189], v[146:149], v[90:93]
	v_mfma_f32_16x16x32_bf16 v[86:89], v[178:181], v[154:157], v[86:89]
	v_mfma_f32_16x16x32_bf16 v[82:85], v[186:189], v[154:157], v[82:85]
	v_mfma_f32_16x16x32_bf16 v[78:81], v[178:181], v[162:165], v[78:81]
	v_mfma_f32_16x16x32_bf16 v[74:77], v[186:189], v[162:165], v[74:77]
	v_mfma_f32_16x16x32_bf16 v[70:73], v[178:181], v[170:173], v[70:73]
	v_mfma_f32_16x16x32_bf16 v[66:69], v[186:189], v[170:173], v[66:69]
	v_mfma_f32_16x16x32_bf16 v[94:97], v[182:185], v[150:153], v[94:97]
	v_mfma_f32_16x16x32_bf16 v[90:93], v[190:193], v[150:153], v[90:93]
	v_mfma_f32_16x16x32_bf16 v[86:89], v[182:185], v[158:161], v[86:89]
	v_mfma_f32_16x16x32_bf16 v[82:85], v[190:193], v[158:161], v[82:85]
	v_mfma_f32_16x16x32_bf16 v[78:81], v[182:185], v[166:169], v[78:81]
	v_mfma_f32_16x16x32_bf16 v[74:77], v[190:193], v[166:169], v[74:77]
	v_mfma_f32_16x16x32_bf16 v[70:73], v[182:185], v[174:177], v[70:73]
	v_mfma_f32_16x16x32_bf16 v[66:69], v[190:193], v[174:177], v[66:69]
	s_setprio 0
	s_mov_b32 m0, s31
	v_lshl_add_u64 v[212:213], s[28:29], 0, v[198:199]
	s_barrier
	ds_read_b128 v[146:149], v234 offset:16384
	ds_read_b128 v[150:153], v234 offset:17408
	ds_read_b128 v[154:157], v234 offset:18432
	ds_read_b128 v[158:161], v234 offset:19456
	ds_read_b128 v[162:165], v234 offset:20480
	ds_read_b128 v[166:169], v234 offset:21504
	ds_read_b128 v[170:173], v234 offset:22528
	ds_read_b128 v[174:177], v234 offset:23552
	global_load_lds_dwordx4 v[212:213], off
	v_lshl_add_u64 v[214:215], s[28:29], 0, v[202:203]
	s_mov_b32 m0, s33
	s_nop 0
	global_load_lds_dwordx4 v[214:215], off
	s_barrier
	s_waitcnt lgkmcnt(0)
	s_setprio 1
	s_waitcnt lgkmcnt(0)
	v_mfma_f32_16x16x32_bf16 v[62:65], v[130:133], v[146:149], v[62:65]
	v_mfma_f32_16x16x32_bf16 v[58:61], v[138:141], v[146:149], v[58:61]
	v_mfma_f32_16x16x32_bf16 v[54:57], v[130:133], v[154:157], v[54:57]
	v_mfma_f32_16x16x32_bf16 v[50:53], v[138:141], v[154:157], v[50:53]
	v_mfma_f32_16x16x32_bf16 v[46:49], v[130:133], v[162:165], v[46:49]
	v_mfma_f32_16x16x32_bf16 v[42:45], v[138:141], v[162:165], v[42:45]
	v_mfma_f32_16x16x32_bf16 v[38:41], v[130:133], v[170:173], v[38:41]
	v_mfma_f32_16x16x32_bf16 v[34:37], v[138:141], v[170:173], v[34:37]
	v_mfma_f32_16x16x32_bf16 v[62:65], v[134:137], v[150:153], v[62:65]
	v_mfma_f32_16x16x32_bf16 v[58:61], v[142:145], v[150:153], v[58:61]
	v_mfma_f32_16x16x32_bf16 v[54:57], v[134:137], v[158:161], v[54:57]
	v_mfma_f32_16x16x32_bf16 v[50:53], v[142:145], v[158:161], v[50:53]
	v_mfma_f32_16x16x32_bf16 v[46:49], v[134:137], v[166:169], v[46:49]
	v_mfma_f32_16x16x32_bf16 v[42:45], v[142:145], v[166:169], v[42:45]
	v_mfma_f32_16x16x32_bf16 v[38:41], v[134:137], v[174:177], v[38:41]
	v_mfma_f32_16x16x32_bf16 v[34:37], v[142:145], v[174:177], v[34:37]
	s_setprio 0
	s_barrier
; #define PG8_STAGE(bufoff, gbase, voff) do { _Pragma("unroll") for (int _i = 0; _i < 2; ++_i) \
;         __builtin_amdgcn_global_load_lds((const unsigned*)((const char*)(gbase) + (voff)[_i]), (LAS unsigned*)(lds + (bufoff) + ldsw + _i * 8192), 16, 0, 0); } while (0)
; #define PG8_LDA(dst, b, h) do { _Pragma("unroll") for (int m = 0; m < 4; ++m) _Pragma("unroll") for (int k = 0; k < 2; ++k) dst[m][k] = *(const LAS bf16x8*)(lds + PG8_SA(b, h) + aoff + m * 2048 + k * 1024); } while (0)
; #define PG8_LDB(dst, b, h) do { _Pragma("unroll") for (int n = 0; n < 2; ++n) _Pragma("unroll") for (int k = 0; k < 2; ++k) dst[n][k] = *(const LAS bf16x8*)(lds + PG8_SB(b, h) + boff + n * 2048 + k * 1024); } while (0)
; #define PG8_MMA(ai, bj, At, Bt) do { __builtin_amdgcn_s_setprio(1); _Pragma("unroll") for (int m = 0; m < 4; ++m) _Pragma("unroll") for (int n = 0; n < 2; ++n) _Pragma("unroll") for (int k = 0; k < 2; ++k) \
;         acc[ai][bj][m][n] = __builtin_amdgcn_mfma_f32_16x16x32_bf16(Bt[n][k], At[m][k], acc[ai][bj][m][n], 0, 0, 0); __builtin_amdgcn_s_setprio(0); } while (0)
; #define PG8_WAIT_V(n) asm volatile("s_waitcnt vmcnt(" #n ")" ::: "memory")
; #define PG8_WAIT_L(n) asm volatile("s_waitcnt lgkmcnt(" #n ")" ::: "memory")
; #define PG8_BAR __builtin_amdgcn_s_barrier()
; #define PG8_SCHED __builtin_amdgcn_sched_barrier(0)
; template <class Sched, class Epi>
; __device__ __forceinline__ void gemm_phase(LAS unsigned char* lds, const Sched& S, const Epi& E, const int K, const int lda, const int ldb) {
;     ...
;             PG8_STAGE(PG8_SB(0, 1), b2 + hstepB, voffB);
;             PG8_WAIT_V(6); PG8_BAR; if (!chalf) PG8_MMA(1, 1, At, B1); PG8_BAR;
;             PG8_LDB(B0, 1, 0); PG8_SCHED; PG8_LDA(At, 1, 0); PG8_STAGE(PG8_SA(0, 1), a2 + hstepA, voffA);
;             PG8_WAIT_L(8); PG8_BAR; PG8_WAIT_L(0); PG8_MMA(0, 0, At, B0); PG8_BAR; PG8_SCHED;
;             PG8_LDB(B1, 1, 1); PG8_STAGE(PG8_SB(1, 0), b3, voffB);
;             PG8_BAR; PG8_WAIT_L(0); PG8_MMA(0, 1, At, B1); PG8_BAR;
;             PG8_LDA(At, 1, 1); PG8_STAGE(PG8_SA(1, 0), a3, voffA);
;             PG8_BAR; PG8_WAIT_L(0); if (!chalf) PG8_MMA(1, 0, At, B0); PG8_BAR; PG8_SCHED;
	s_add_u32 s50, s26, 0x40000
	s_addc_u32 s51, s27, 0
	s_add_i32 s49, s44, s25
	s_mov_b32 m0, s49
	s_nop 0
	global_load_lds_dwordx4 v200, s[50:51]
	s_add_i32 m0, s49, 0x2000
	s_nop 0
	global_load_lds_dwordx4 v204, s[50:51]
	s_waitcnt vmcnt(6)
	s_barrier
	s_setprio 1
	v_mfma_f32_16x16x32_bf16 v[30:33], v[178:181], v[146:149], v[30:33]
	v_mfma_f32_16x16x32_bf16 v[26:29], v[186:189], v[146:149], v[26:29]
	v_mfma_f32_16x16x32_bf16 v[22:25], v[178:181], v[154:157], v[22:25]
	v_mfma_f32_16x16x32_bf16 v[18:21], v[186:189], v[154:157], v[18:21]
	v_mfma_f32_16x16x32_bf16 v[14:17], v[178:181], v[162:165], v[14:17]
	v_mfma_f32_16x16x32_bf16 v[10:13], v[186:189], v[162:165], v[10:13]
	v_mfma_f32_16x16x32_bf16 v[6:9], v[178:181], v[170:173], v[6:9]
	v_mfma_f32_16x16x32_bf16 v[2:5], v[186:189], v[170:173], v[2:5]
	v_mfma_f32_16x16x32_bf16 v[30:33], v[182:185], v[150:153], v[30:33]
	v_mfma_f32_16x16x32_bf16 v[26:29], v[190:193], v[150:153], v[26:29]
	v_mfma_f32_16x16x32_bf16 v[22:25], v[182:185], v[158:161], v[22:25]
	v_mfma_f32_16x16x32_bf16 v[18:21], v[190:193], v[158:161], v[18:21]
	v_mfma_f32_16x16x32_bf16 v[14:17], v[182:185], v[166:169], v[14:17]
	v_mfma_f32_16x16x32_bf16 v[10:13], v[190:193], v[166:169], v[10:13]
	v_mfma_f32_16x16x32_bf16 v[6:9], v[182:185], v[174:177], v[6:9]
	v_mfma_f32_16x16x32_bf16 v[2:5], v[190:193], v[174:177], v[2:5]
	s_setprio 0
	s_add_i32 s49, 16, 0x18000
	v_add_u32_e32 v142, s49, v224
	s_barrier
	ds_read_b128 v[130:133], v142
	ds_read_b128 v[134:137], v142 offset:1024
	ds_read_b128 v[138:141], v142 offset:2048
	ds_read_b128 v[142:145], v142 offset:3072
	s_add_u32 s28, s28, 0x40000
	s_addc_u32 s29, s29, 0
	s_mov_b32 m0, s34
	ds_read_b128 v[146:149], v234 offset:32768
	ds_read_b128 v[150:153], v234 offset:33792
	ds_read_b128 v[154:157], v234 offset:34816
	ds_read_b128 v[158:161], v234 offset:35840
	ds_read_b128 v[162:165], v234 offset:36864
	ds_read_b128 v[166:169], v234 offset:37888
	ds_read_b128 v[170:173], v234 offset:38912
	ds_read_b128 v[174:177], v234 offset:39936
	global_load_lds_dwordx4 v198, s[28:29]
	s_mov_b32 m0, s35
	s_nop 0
	global_load_lds_dwordx4 v202, s[28:29]
	s_waitcnt lgkmcnt(8)
	s_barrier
	s_waitcnt lgkmcnt(0)
	s_setprio 1
	s_waitcnt lgkmcnt(0)
	v_mfma_f32_16x16x32_bf16 v[126:129], v[130:133], v[146:149], v[126:129]
	v_mfma_f32_16x16x32_bf16 v[122:125], v[138:141], v[146:149], v[122:125]
	v_mfma_f32_16x16x32_bf16 v[118:121], v[130:133], v[154:157], v[118:121]
	v_mfma_f32_16x16x32_bf16 v[114:117], v[138:141], v[154:157], v[114:117]
	v_mfma_f32_16x16x32_bf16 v[110:113], v[130:133], v[162:165], v[110:113]
	v_mfma_f32_16x16x32_bf16 v[106:109], v[138:141], v[162:165], v[106:109]
	v_mfma_f32_16x16x32_bf16 v[102:105], v[130:133], v[170:173], v[102:105]
	v_mfma_f32_16x16x32_bf16 v[98:101], v[138:141], v[170:173], v[98:101]
	v_mfma_f32_16x16x32_bf16 v[126:129], v[134:137], v[150:153], v[126:129]
	v_mfma_f32_16x16x32_bf16 v[122:125], v[142:145], v[150:153], v[122:125]
	v_mfma_f32_16x16x32_bf16 v[118:121], v[134:137], v[158:161], v[118:121]
	v_mfma_f32_16x16x32_bf16 v[114:117], v[142:145], v[158:161], v[114:117]
	v_mfma_f32_16x16x32_bf16 v[110:113], v[134:137], v[166:169], v[110:113]
	v_mfma_f32_16x16x32_bf16 v[106:109], v[142:145], v[166:169], v[106:109]
	v_mfma_f32_16x16x32_bf16 v[102:105], v[134:137], v[174:177], v[102:105]
	v_mfma_f32_16x16x32_bf16 v[98:101], v[142:145], v[174:177], v[98:101]
	s_setprio 0
	s_barrier
	s_add_i32 s28, 16, 0x1c000
	s_add_i32 s29, s49, s25
	v_add_u32_e32 v190, s28, v224
	v_lshl_add_u64 v[194:195], v[194:195], 0, s[12:13]
	s_mov_b32 m0, s29
	ds_read_b128 v[178:181], v190
	ds_read_b128 v[182:185], v190 offset:1024
	ds_read_b128 v[186:189], v190 offset:2048
	ds_read_b128 v[190:193], v190 offset:3072
	global_load_lds_dwordx4 v[194:195], off
	v_lshl_add_u64 v[194:195], v[196:197], 0, s[12:13]
	s_add_i32 m0, s29, 0x2000
	s_nop 0
	global_load_lds_dwordx4 v[194:195], off
	s_barrier
	s_waitcnt lgkmcnt(0)
	s_setprio 1
	s_waitcnt lgkmcnt(0)
	v_mfma_f32_16x16x32_bf16 v[94:97], v[178:181], v[146:149], v[94:97]
	v_mfma_f32_16x16x32_bf16 v[90:93], v[186:189], v[146:149], v[90:93]
	v_mfma_f32_16x16x32_bf16 v[86:89], v[178:181], v[154:157], v[86:89]
	v_mfma_f32_16x16x32_bf16 v[82:85], v[186:189], v[154:157], v[82:85]
	v_mfma_f32_16x16x32_bf16 v[78:81], v[178:181], v[162:165], v[78:81]
	v_mfma_f32_16x16x32_bf16 v[74:77], v[186:189], v[162:165], v[74:77]
	v_mfma_f32_16x16x32_bf16 v[70:73], v[178:181], v[170:173], v[70:73]
	v_mfma_f32_16x16x32_bf16 v[66:69], v[186:189], v[170:173], v[66:69]
	v_mfma_f32_16x16x32_bf16 v[94:97], v[182:185], v[150:153], v[94:97]
	v_mfma_f32_16x16x32_bf16 v[90:93], v[190:193], v[150:153], v[90:93]
	v_mfma_f32_16x16x32_bf16 v[86:89], v[182:185], v[158:161], v[86:89]
	v_mfma_f32_16x16x32_bf16 v[82:85], v[190:193], v[158:161], v[82:85]
	v_mfma_f32_16x16x32_bf16 v[78:81], v[182:185], v[166:169], v[78:81]
	v_mfma_f32_16x16x32_bf16 v[74:77], v[190:193], v[166:169], v[74:77]
	v_mfma_f32_16x16x32_bf16 v[70:73], v[182:185], v[174:177], v[70:73]
	v_mfma_f32_16x16x32_bf16 v[66:69], v[190:193], v[174:177], v[66:69]
	s_setprio 0
	s_mov_b32 m0, s39
	v_lshl_add_u64 v[194:195], v[212:213], 0, s[12:13]
	s_barrier
; #define PG8_STAGE(bufoff, gbase, voff) do { _Pragma("unroll") for (int _i = 0; _i < 2; ++_i) \
;         __builtin_amdgcn_global_load_lds((const unsigned*)((const char*)(gbase) + (voff)[_i]), (LAS unsigned*)(lds + (bufoff) + ldsw + _i * 8192), 16, 0, 0); } while (0)
; #define PG8_LDA(dst, b, h) do { _Pragma("unroll") for (int m = 0; m < 4; ++m) _Pragma("unroll") for (int k = 0; k < 2; ++k) dst[m][k] = *(const LAS bf16x8*)(lds + PG8_SA(b, h) + aoff + m * 2048 + k * 1024); } while (0)
; #define PG8_MMA(ai, bj, At, Bt) do { __builtin_amdgcn_s_setprio(1); _Pragma("unroll") for (int m = 0; m < 4; ++m) _Pragma("unroll") for (int n = 0; n < 2; ++n) _Pragma("unroll") for (int k = 0; k < 2; ++k) \
;         acc[ai][bj][m][n] = __builtin_amdgcn_mfma_f32_16x16x32_bf16(Bt[n][k], At[m][k], acc[ai][bj][m][n], 0, 0, 0); __builtin_amdgcn_s_setprio(0); } while (0)
; #define PG8_WAIT_V(n) asm volatile("s_waitcnt vmcnt(" #n ")" ::: "memory")
; #define PG8_WAIT_L(n) asm volatile("s_waitcnt lgkmcnt(" #n ")" ::: "memory")
; #define PG8_BAR __builtin_amdgcn_s_barrier()
; #define PG8_SCHED __builtin_amdgcn_sched_barrier(0)
; #define MRG_LOAD(slot, bidx_) { const int ai = (bidx_) >> 1, bj = (bidx_) & 1; _Pragma("unroll") for (int m = 0; m < 4; ++m) { \
;             gg[slot][m] = *(const u32x4*)(parts + E_PGL + (size_t)EPI_ROW * 6144 + br * DM + EPI_COL(bj)); \
;             pp[slot][m] = br > 0 ? *(const u32x4*)(MB + (size_t)EPI_ROW * DM + EPI_COL(bj)) : (u32x4){0u, 0u, 0u, 0u}; } }
; template <class Sched, class Epi>
; __device__ __forceinline__ void gemm_phase(LAS unsigned char* lds, const Sched& S, const Epi& E, const int K, const int lda, const int ldb) {
;     ...
;             PG8_LDA(At, 1, 1); PG8_STAGE(PG8_SA(1, 0), a3, voffA);
;             PG8_BAR; PG8_WAIT_L(0); if (!chalf) PG8_MMA(1, 0, At, B0); PG8_BAR; PG8_SCHED;
;             PG8_STAGE(PG8_SB(1, 1), b3 + hstepB, voffB);
;             PG8_WAIT_V(6); PG8_BAR; if (!chalf) PG8_MMA(1, 1, At, B1); PG8_BAR;
;         }
;     __device__ __forceinline__ void operator()(EPI_ARGS) const {
;         const int br = u.z; const int nb = u.half ? 2 : 4;
;         u32x4 gg[2][4], pp[2][4];
;     ...
;         MRG_LOAD(0, 0)
	ds_read_b128 v[146:149], v234 offset:49152
	ds_read_b128 v[150:153], v234 offset:50176
	ds_read_b128 v[154:157], v234 offset:51200
	ds_read_b128 v[158:161], v234 offset:52224
	ds_read_b128 v[162:165], v234 offset:53248
	ds_read_b128 v[166:169], v234 offset:54272
	ds_read_b128 v[170:173], v234 offset:55296
	ds_read_b128 v[174:177], v234 offset:56320
	global_load_lds_dwordx4 v[194:195], off
	v_lshl_add_u64 v[194:195], v[214:215], 0, s[12:13]
	s_mov_b32 m0, s40
	s_nop 0
	global_load_lds_dwordx4 v[194:195], off
	s_barrier
	s_waitcnt lgkmcnt(0)
	s_setprio 1
	s_waitcnt lgkmcnt(0)
	v_mfma_f32_16x16x32_bf16 v[62:65], v[130:133], v[146:149], v[62:65]
	v_mfma_f32_16x16x32_bf16 v[58:61], v[138:141], v[146:149], v[58:61]
	v_mfma_f32_16x16x32_bf16 v[54:57], v[130:133], v[154:157], v[54:57]
	v_mfma_f32_16x16x32_bf16 v[50:53], v[138:141], v[154:157], v[50:53]
	v_mfma_f32_16x16x32_bf16 v[46:49], v[130:133], v[162:165], v[46:49]
	v_mfma_f32_16x16x32_bf16 v[42:45], v[138:141], v[162:165], v[42:45]
	v_mfma_f32_16x16x32_bf16 v[38:41], v[130:133], v[170:173], v[38:41]
	v_mfma_f32_16x16x32_bf16 v[34:37], v[138:141], v[170:173], v[34:37]
	v_mfma_f32_16x16x32_bf16 v[62:65], v[134:137], v[150:153], v[62:65]
	v_mfma_f32_16x16x32_bf16 v[58:61], v[142:145], v[150:153], v[58:61]
	v_mfma_f32_16x16x32_bf16 v[54:57], v[134:137], v[158:161], v[54:57]
	v_mfma_f32_16x16x32_bf16 v[50:53], v[142:145], v[158:161], v[50:53]
	v_mfma_f32_16x16x32_bf16 v[46:49], v[134:137], v[166:169], v[46:49]
	v_mfma_f32_16x16x32_bf16 v[42:45], v[142:145], v[166:169], v[42:45]
	v_mfma_f32_16x16x32_bf16 v[38:41], v[134:137], v[174:177], v[38:41]
	v_mfma_f32_16x16x32_bf16 v[34:37], v[142:145], v[174:177], v[34:37]
	s_setprio 0
	s_barrier
	s_add_u32 s26, s26, 0x40080
	s_addc_u32 s27, s27, 0
	s_add_i32 s28, s28, s25
	s_mov_b32 m0, s28
	s_nop 0
	global_load_lds_dwordx4 v200, s[26:27]
	s_add_i32 m0, s28, 0x2000
	s_nop 0
	global_load_lds_dwordx4 v204, s[26:27]
	s_waitcnt vmcnt(6)
	s_barrier
	s_setprio 1
	v_mfma_f32_16x16x32_bf16 v[30:33], v[178:181], v[146:149], v[30:33]
	v_mfma_f32_16x16x32_bf16 v[26:29], v[186:189], v[146:149], v[26:29]
	v_mfma_f32_16x16x32_bf16 v[22:25], v[178:181], v[154:157], v[22:25]
	v_mfma_f32_16x16x32_bf16 v[18:21], v[186:189], v[154:157], v[18:21]
	v_mfma_f32_16x16x32_bf16 v[14:17], v[178:181], v[162:165], v[14:17]
	v_mfma_f32_16x16x32_bf16 v[10:13], v[186:189], v[162:165], v[10:13]
	v_mfma_f32_16x16x32_bf16 v[6:9], v[178:181], v[170:173], v[6:9]
	v_mfma_f32_16x16x32_bf16 v[2:5], v[186:189], v[170:173], v[2:5]
	v_mfma_f32_16x16x32_bf16 v[30:33], v[182:185], v[150:153], v[30:33]
	v_mfma_f32_16x16x32_bf16 v[26:29], v[190:193], v[150:153], v[26:29]
	v_mfma_f32_16x16x32_bf16 v[22:25], v[182:185], v[158:161], v[22:25]
	v_mfma_f32_16x16x32_bf16 v[18:21], v[190:193], v[158:161], v[18:21]
	v_mfma_f32_16x16x32_bf16 v[14:17], v[182:185], v[166:169], v[14:17]
	v_mfma_f32_16x16x32_bf16 v[10:13], v[190:193], v[166:169], v[10:13]
	v_mfma_f32_16x16x32_bf16 v[6:9], v[182:185], v[174:177], v[6:9]
	v_mfma_f32_16x16x32_bf16 v[2:5], v[190:193], v[174:177], v[2:5]
	s_setprio 0
	s_add_i32 s19, s19, 2
	s_add_u32 s15, s15, 0x100
	s_addc_u32 s17, s17, 0
	s_add_u32 s6, s6, 0x100
	s_addc_u32 s7, s7, 0
	s_cmp_gt_u32 s19, 13
	s_barrier
	s_cbranch_scc0 .LBB0_1486
	s_lshl_b32 s6, s48, 11
	s_ashr_i32 s7, s6, 31
	s_lshl_b64 s[26:27], s[6:7], 1
	v_lshl_or_b32 v134, s47, 8, v232
	s_add_u32 s6, s41, s26
	v_ashrrev_i32_e32 v135, 31, v134
	s_addc_u32 s7, s42, s27
	v_lshlrev_b64 v[212:213], 1, v[134:135]
	v_add_u32_e32 v130, s24, v1
	v_lshl_add_u64 v[216:217], s[6:7], 0, v[212:213]
	v_mad_i64_i32 v[132:133], s[6:7], v130, s45, v[216:217]
	global_load_dwordx4 v[194:197], v[132:133], off
	v_ashrrev_i32_e32 v131, 31, v130
	s_cmp_gt_i32 s48, 0
	v_lshl_add_u64 v[218:219], s[8:9], 0, v[212:213]
	v_lshlrev_b64 v[132:133], 12, v[130:131]
	s_cselect_b64 s[28:29], -1, 0
	s_cmp_lt_i32 s48, 1
	v_lshl_add_u64 v[136:137], v[218:219], 0, v[132:133]
	s_cbranch_scc1 .LBB0_1489
	global_load_dwordx4 v[190:193], v[136:137], off
	s_branch .LBB0_1490

; #define PG8_STAGE(bufoff, gbase, voff) do { _Pragma("unroll") for (int _i = 0; _i < 2; ++_i) \
;         __builtin_amdgcn_global_load_lds((const unsigned*)((const char*)(gbase) + (voff)[_i]), (LAS unsigned*)(lds + (bufoff) + ldsw + _i * 8192), 16, 0, 0); } while (0)
; #define PG8_LDA(dst, b, h) do { _Pragma("unroll") for (int m = 0; m < 4; ++m) _Pragma("unroll") for (int k = 0; k < 2; ++k) dst[m][k] = *(const LAS bf16x8*)(lds + PG8_SA(b, h) + aoff + m * 2048 + k * 1024); } while (0)
; #define PG8_LDB(dst, b, h) do { _Pragma("unroll") for (int n = 0; n < 2; ++n) _Pragma("unroll") for (int k = 0; k < 2; ++k) dst[n][k] = *(const LAS bf16x8*)(lds + PG8_SB(b, h) + boff + n * 2048 + k * 1024); } while (0)
; #define PG8_MMA(ai, bj, At, Bt) do { __builtin_amdgcn_s_setprio(1); _Pragma("unroll") for (int m = 0; m < 4; ++m) _Pragma("unroll") for (int n = 0; n < 2; ++n) _Pragma("unroll") for (int k = 0; k < 2; ++k) \
;         acc[ai][bj][m][n] = __builtin_amdgcn_mfma_f32_16x16x32_bf16(Bt[n][k], At[m][k], acc[ai][bj][m][n], 0, 0, 0); __builtin_amdgcn_s_setprio(0); } while (0)
; #define PG8_WAIT_V(n) asm volatile("s_waitcnt vmcnt(" #n ")" ::: "memory")
; #define PG8_BAR __builtin_amdgcn_s_barrier()
; template <class Sched, class Epi>
; __device__ __forceinline__ void gemm_phase(LAS unsigned char* lds, const Sched& S, const Epi& E, const int K, const int lda, const int ldb) {
;     ...
;         for (int t = 0; t < nt; t += 2) {
;             const bool last = (t == nt - 2);
;             const char* a1 = cA + (size_t)(t + 1) * kstep;
;             const char* a2 = last ? nA : cA + (size_t)(t + 2) * kstep; const char* b2 = last ? nB : cB + (size_t)(t + 2) * kstep;
;             const char* a3 = a2 + kstep; const char* b3 = b2 + kstep;
;             PG8_LDB(B0, 0, 0); PG8_SCHED; PG8_LDA(At, 0, 0); PG8_STAGE(PG8_SA(1, 1), a1 + hstepA, voffA);
;             PG8_WAIT_L(8); PG8_BAR; PG8_WAIT_L(0); PG8_MMA(0, 0, At, B0); PG8_BAR; PG8_SCHED;
;             PG8_LDB(B1, 0, 1); PG8_STAGE(PG8_SB(0, 0), b2, voffB);
;             PG8_BAR; PG8_WAIT_L(0); PG8_MMA(0, 1, At, B1); PG8_BAR;
;             PG8_LDA(At, 0, 1); PG8_STAGE(PG8_SA(0, 0), a2, voffA);
;             PG8_BAR; PG8_WAIT_L(0); if (!chalf) PG8_MMA(1, 0, At, B0); PG8_BAR; PG8_SCHED;
;             PG8_STAGE(PG8_SB(0, 1), b2 + hstepB, voffB);
;             PG8_WAIT_V(6); PG8_BAR; if (!chalf) PG8_MMA(1, 1, At, B1); PG8_BAR;
.LBB0_1593:
	ds_read_b128 v[156:159], v153
	ds_read_b128 v[160:163], v153 offset:1024
	ds_read_b128 v[164:167], v153 offset:2048
	ds_read_b128 v[168:171], v153 offset:3072
	s_add_u32 s28, s26, 0xfff80080
	s_addc_u32 s29, s27, -1
	s_cmp_eq_u32 s46, 28
	s_cselect_b32 s35, s23, s29
	s_cselect_b32 s34, s22, s28
	s_cselect_b32 s29, s25, s17
	s_cselect_b32 s28, s24, s15
	s_add_i32 m0, s5, 0xc000
	ds_read_b128 v[172:175], v154
	ds_read_b128 v[176:179], v154 offset:1024
	ds_read_b128 v[180:183], v154 offset:2048
	ds_read_b128 v[184:187], v154 offset:3072
	ds_read_b128 v[188:191], v154 offset:4096
	ds_read_b128 v[192:195], v154 offset:5120
	ds_read_b128 v[196:199], v154 offset:6144
	ds_read_b128 v[200:203], v154 offset:7168
	global_load_lds_dwordx4 v140, s[26:27]
	s_add_i32 m0, s5, 0xe000
	s_nop 0
	global_load_lds_dwordx4 v138, s[26:27]
	s_waitcnt lgkmcnt(8)
	s_barrier
	s_waitcnt lgkmcnt(0)
	s_setprio 1
	s_waitcnt lgkmcnt(0)
	v_mfma_f32_16x16x32_bf16 v[126:129], v[156:159], v[172:175], v[126:129]
	v_mfma_f32_16x16x32_bf16 v[122:125], v[164:167], v[172:175], v[122:125]
	v_mfma_f32_16x16x32_bf16 v[114:117], v[156:159], v[180:183], v[114:117]
	v_mfma_f32_16x16x32_bf16 v[106:109], v[164:167], v[180:183], v[106:109]
	v_mfma_f32_16x16x32_bf16 v[98:101], v[156:159], v[188:191], v[98:101]
	v_mfma_f32_16x16x32_bf16 v[90:93], v[164:167], v[188:191], v[90:93]
	v_mfma_f32_16x16x32_bf16 v[82:85], v[156:159], v[196:199], v[82:85]
	v_mfma_f32_16x16x32_bf16 v[74:77], v[164:167], v[196:199], v[74:77]
	v_mfma_f32_16x16x32_bf16 v[126:129], v[160:163], v[176:179], v[126:129]
	v_mfma_f32_16x16x32_bf16 v[122:125], v[168:171], v[176:179], v[122:125]
	v_mfma_f32_16x16x32_bf16 v[114:117], v[160:163], v[184:187], v[114:117]
	v_mfma_f32_16x16x32_bf16 v[106:109], v[168:171], v[184:187], v[106:109]
	v_mfma_f32_16x16x32_bf16 v[98:101], v[160:163], v[192:195], v[98:101]
	v_mfma_f32_16x16x32_bf16 v[90:93], v[168:171], v[192:195], v[90:93]
	v_mfma_f32_16x16x32_bf16 v[82:85], v[160:163], v[200:203], v[82:85]
	v_mfma_f32_16x16x32_bf16 v[74:77], v[168:171], v[200:203], v[74:77]
	s_setprio 0
	s_barrier
	s_add_i32 s47, s43, s31
	v_lshl_add_u64 v[220:221], s[28:29], 0, v[132:133]
	s_mov_b32 m0, s47
	ds_read_b128 v[204:207], v155
	ds_read_b128 v[208:211], v155 offset:1024
	ds_read_b128 v[212:215], v155 offset:2048
	ds_read_b128 v[216:219], v155 offset:3072
	global_load_lds_dwordx4 v[220:221], off
	v_lshl_add_u64 v[222:223], s[28:29], 0, v[136:137]
	s_add_i32 m0, s47, 0x2000
	s_nop 0
	global_load_lds_dwordx4 v[222:223], off
	s_barrier
	s_waitcnt lgkmcnt(0)
	s_setprio 1
	s_waitcnt lgkmcnt(0)
	v_mfma_f32_16x16x32_bf16 v[118:121], v[204:207], v[172:175], v[118:121]
	v_mfma_f32_16x16x32_bf16 v[110:113], v[212:215], v[172:175], v[110:113]
	v_mfma_f32_16x16x32_bf16 v[102:105], v[204:207], v[180:183], v[102:105]
	v_mfma_f32_16x16x32_bf16 v[94:97], v[212:215], v[180:183], v[94:97]
	v_mfma_f32_16x16x32_bf16 v[86:89], v[204:207], v[188:191], v[86:89]
	v_mfma_f32_16x16x32_bf16 v[78:81], v[212:215], v[188:191], v[78:81]
	v_mfma_f32_16x16x32_bf16 v[70:73], v[204:207], v[196:199], v[70:73]
	v_mfma_f32_16x16x32_bf16 v[66:69], v[212:215], v[196:199], v[66:69]
	v_mfma_f32_16x16x32_bf16 v[118:121], v[208:211], v[176:179], v[118:121]
	v_mfma_f32_16x16x32_bf16 v[110:113], v[216:219], v[176:179], v[110:113]
	v_mfma_f32_16x16x32_bf16 v[102:105], v[208:211], v[184:187], v[102:105]
	v_mfma_f32_16x16x32_bf16 v[94:97], v[216:219], v[184:187], v[94:97]
	v_mfma_f32_16x16x32_bf16 v[86:89], v[208:211], v[192:195], v[86:89]
	v_mfma_f32_16x16x32_bf16 v[78:81], v[216:219], v[192:195], v[78:81]
	v_mfma_f32_16x16x32_bf16 v[70:73], v[208:211], v[200:203], v[70:73]
	v_mfma_f32_16x16x32_bf16 v[66:69], v[216:219], v[200:203], v[66:69]
	s_setprio 0
	s_mov_b32 m0, s5
	v_lshl_add_u64 v[224:225], s[34:35], 0, v[130:131]
	s_barrier
	ds_read_b128 v[172:175], v154 offset:16384
	ds_read_b128 v[176:179], v154 offset:17408
	ds_read_b128 v[180:183], v154 offset:18432
	ds_read_b128 v[184:187], v154 offset:19456
	ds_read_b128 v[188:191], v154 offset:20480
	ds_read_b128 v[192:195], v154 offset:21504
	ds_read_b128 v[196:199], v154 offset:22528
	ds_read_b128 v[200:203], v154 offset:23552
	global_load_lds_dwordx4 v[224:225], off
	v_lshl_add_u64 v[226:227], s[34:35], 0, v[134:135]
	s_mov_b32 m0, s33
	s_nop 0
	global_load_lds_dwordx4 v[226:227], off
	s_barrier
	s_waitcnt lgkmcnt(0)
	s_setprio 1
	s_waitcnt lgkmcnt(0)
	v_mfma_f32_16x16x32_bf16 v[62:65], v[156:159], v[172:175], v[62:65]
	v_mfma_f32_16x16x32_bf16 v[58:61], v[164:167], v[172:175], v[58:61]
	v_mfma_f32_16x16x32_bf16 v[54:57], v[156:159], v[180:183], v[54:57]
	v_mfma_f32_16x16x32_bf16 v[46:49], v[164:167], v[180:183], v[46:49]
	v_mfma_f32_16x16x32_bf16 v[38:41], v[156:159], v[188:191], v[38:41]
	v_mfma_f32_16x16x32_bf16 v[30:33], v[164:167], v[188:191], v[30:33]
	v_mfma_f32_16x16x32_bf16 v[22:25], v[156:159], v[196:199], v[22:25]
	v_mfma_f32_16x16x32_bf16 v[14:17], v[164:167], v[196:199], v[14:17]
	v_mfma_f32_16x16x32_bf16 v[62:65], v[160:163], v[176:179], v[62:65]
	v_mfma_f32_16x16x32_bf16 v[58:61], v[168:171], v[176:179], v[58:61]
	v_mfma_f32_16x16x32_bf16 v[54:57], v[160:163], v[184:187], v[54:57]
	v_mfma_f32_16x16x32_bf16 v[46:49], v[168:171], v[184:187], v[46:49]
	v_mfma_f32_16x16x32_bf16 v[38:41], v[160:163], v[192:195], v[38:41]
	v_mfma_f32_16x16x32_bf16 v[30:33], v[168:171], v[192:195], v[30:33]
	v_mfma_f32_16x16x32_bf16 v[22:25], v[160:163], v[200:203], v[22:25]
	v_mfma_f32_16x16x32_bf16 v[14:17], v[168:171], v[200:203], v[14:17]
	s_setprio 0
	s_barrier
; #define PG8_STAGE(bufoff, gbase, voff) do { _Pragma("unroll") for (int _i = 0; _i < 2; ++_i) \
;         __builtin_amdgcn_global_load_lds((const unsigned*)((const char*)(gbase) + (voff)[_i]), (LAS unsigned*)(lds + (bufoff) + ldsw + _i * 8192), 16, 0, 0); } while (0)
; #define PG8_LDA(dst, b, h) do { _Pragma("unroll") for (int m = 0; m < 4; ++m) _Pragma("unroll") for (int k = 0; k < 2; ++k) dst[m][k] = *(const LAS bf16x8*)(lds + PG8_SA(b, h) + aoff + m * 2048 + k * 1024); } while (0)
; #define PG8_LDB(dst, b, h) do { _Pragma("unroll") for (int n = 0; n < 2; ++n) _Pragma("unroll") for (int k = 0; k < 2; ++k) dst[n][k] = *(const LAS bf16x8*)(lds + PG8_SB(b, h) + boff + n * 2048 + k * 1024); } while (0)
; #define PG8_MMA(ai, bj, At, Bt) do { __builtin_amdgcn_s_setprio(1); _Pragma("unroll") for (int m = 0; m < 4; ++m) _Pragma("unroll") for (int n = 0; n < 2; ++n) _Pragma("unroll") for (int k = 0; k < 2; ++k) \
;         acc[ai][bj][m][n] = __builtin_amdgcn_mfma_f32_16x16x32_bf16(Bt[n][k], At[m][k], acc[ai][bj][m][n], 0, 0, 0); __builtin_amdgcn_s_setprio(0); } while (0)
; #define PG8_WAIT_V(n) asm volatile("s_waitcnt vmcnt(" #n ")" ::: "memory")
; #define PG8_WAIT_L(n) asm volatile("s_waitcnt lgkmcnt(" #n ")" ::: "memory")
; #define PG8_BAR __builtin_amdgcn_s_barrier()
; #define PG8_SCHED __builtin_amdgcn_sched_barrier(0)
; template <class Sched, class Epi>
; __device__ __forceinline__ void gemm_phase(LAS unsigned char* lds, const Sched& S, const Epi& E, const int K, const int lda, const int ldb) {
;     ...
;             PG8_STAGE(PG8_SB(0, 1), b2 + hstepB, voffB);
;             PG8_WAIT_V(6); PG8_BAR; if (!chalf) PG8_MMA(1, 1, At, B1); PG8_BAR;
;             PG8_LDB(B0, 1, 0); PG8_SCHED; PG8_LDA(At, 1, 0); PG8_STAGE(PG8_SA(0, 1), a2 + hstepA, voffA);
;             PG8_WAIT_L(8); PG8_BAR; PG8_WAIT_L(0); PG8_MMA(0, 0, At, B0); PG8_BAR; PG8_SCHED;
;             PG8_LDB(B1, 1, 1); PG8_STAGE(PG8_SB(1, 0), b3, voffB);
;             PG8_BAR; PG8_WAIT_L(0); PG8_MMA(0, 1, At, B1); PG8_BAR;
;             PG8_LDA(At, 1, 1); PG8_STAGE(PG8_SA(1, 0), a3, voffA);
;             PG8_BAR; PG8_WAIT_L(0); if (!chalf) PG8_MMA(1, 0, At, B0); PG8_BAR; PG8_SCHED;
	s_add_u32 s48, s28, 0x80000
	s_addc_u32 s49, s29, 0
	s_add_i32 s47, s44, s31
	s_mov_b32 m0, s47
	s_nop 0
	global_load_lds_dwordx4 v132, s[48:49]
	s_add_i32 m0, s47, 0x2000
	s_nop 0
	global_load_lds_dwordx4 v136, s[48:49]
	s_waitcnt vmcnt(6)
	s_barrier
	s_setprio 1
	v_mfma_f32_16x16x32_bf16 v[50:53], v[204:207], v[172:175], v[50:53]
	v_mfma_f32_16x16x32_bf16 v[42:45], v[212:215], v[172:175], v[42:45]
	v_mfma_f32_16x16x32_bf16 v[34:37], v[204:207], v[180:183], v[34:37]
	v_mfma_f32_16x16x32_bf16 v[26:29], v[212:215], v[180:183], v[26:29]
	v_mfma_f32_16x16x32_bf16 v[18:21], v[204:207], v[188:191], v[18:21]
	v_mfma_f32_16x16x32_bf16 v[10:13], v[212:215], v[188:191], v[10:13]
	v_mfma_f32_16x16x32_bf16 v[6:9], v[204:207], v[196:199], v[6:9]
	v_mfma_f32_16x16x32_bf16 v[2:5], v[212:215], v[196:199], v[2:5]
	v_mfma_f32_16x16x32_bf16 v[50:53], v[208:211], v[176:179], v[50:53]
	v_mfma_f32_16x16x32_bf16 v[42:45], v[216:219], v[176:179], v[42:45]
	v_mfma_f32_16x16x32_bf16 v[34:37], v[208:211], v[184:187], v[34:37]
	v_mfma_f32_16x16x32_bf16 v[26:29], v[216:219], v[184:187], v[26:29]
	v_mfma_f32_16x16x32_bf16 v[18:21], v[208:211], v[192:195], v[18:21]
	v_mfma_f32_16x16x32_bf16 v[10:13], v[216:219], v[192:195], v[10:13]
	v_mfma_f32_16x16x32_bf16 v[6:9], v[208:211], v[200:203], v[6:9]
	v_mfma_f32_16x16x32_bf16 v[2:5], v[216:219], v[200:203], v[2:5]
	s_setprio 0
	s_add_i32 s47, 16, 0x18000
	v_add_u32_e32 v168, s47, v144
	s_barrier
	ds_read_b128 v[156:159], v168
	ds_read_b128 v[160:163], v168 offset:1024
	ds_read_b128 v[164:167], v168 offset:2048
	ds_read_b128 v[168:171], v168 offset:3072
	s_add_u32 s34, s34, 0x80000
	s_addc_u32 s35, s35, 0
	s_mov_b32 m0, s36
	ds_read_b128 v[172:175], v154 offset:32768
	ds_read_b128 v[176:179], v154 offset:33792
	ds_read_b128 v[180:183], v154 offset:34816
	ds_read_b128 v[184:187], v154 offset:35840
	ds_read_b128 v[188:191], v154 offset:36864
	ds_read_b128 v[192:195], v154 offset:37888
	ds_read_b128 v[196:199], v154 offset:38912
	ds_read_b128 v[200:203], v154 offset:39936
	global_load_lds_dwordx4 v130, s[34:35]
	s_mov_b32 m0, s37
	s_nop 0
	global_load_lds_dwordx4 v134, s[34:35]
	s_waitcnt lgkmcnt(8)
	s_barrier
	s_waitcnt lgkmcnt(0)
	s_setprio 1
	s_waitcnt lgkmcnt(0)
	v_mfma_f32_16x16x32_bf16 v[126:129], v[156:159], v[172:175], v[126:129]
	v_mfma_f32_16x16x32_bf16 v[122:125], v[164:167], v[172:175], v[122:125]
	v_mfma_f32_16x16x32_bf16 v[114:117], v[156:159], v[180:183], v[114:117]
	v_mfma_f32_16x16x32_bf16 v[106:109], v[164:167], v[180:183], v[106:109]
	v_mfma_f32_16x16x32_bf16 v[98:101], v[156:159], v[188:191], v[98:101]
	v_mfma_f32_16x16x32_bf16 v[90:93], v[164:167], v[188:191], v[90:93]
	v_mfma_f32_16x16x32_bf16 v[82:85], v[156:159], v[196:199], v[82:85]
	v_mfma_f32_16x16x32_bf16 v[74:77], v[164:167], v[196:199], v[74:77]
	v_mfma_f32_16x16x32_bf16 v[126:129], v[160:163], v[176:179], v[126:129]
	v_mfma_f32_16x16x32_bf16 v[122:125], v[168:171], v[176:179], v[122:125]
	v_mfma_f32_16x16x32_bf16 v[114:117], v[160:163], v[184:187], v[114:117]
	v_mfma_f32_16x16x32_bf16 v[106:109], v[168:171], v[184:187], v[106:109]
	v_mfma_f32_16x16x32_bf16 v[98:101], v[160:163], v[192:195], v[98:101]
	v_mfma_f32_16x16x32_bf16 v[90:93], v[168:171], v[192:195], v[90:93]
	v_mfma_f32_16x16x32_bf16 v[82:85], v[160:163], v[200:203], v[82:85]
	v_mfma_f32_16x16x32_bf16 v[74:77], v[168:171], v[200:203], v[74:77]
	s_setprio 0
	s_barrier
	s_add_i32 s34, 16, 0x1c000
	s_add_i32 s35, s47, s31
	v_add_u32_e32 v216, s34, v144
	v_lshl_add_u64 v[220:221], v[220:221], 0, s[8:9]
	s_mov_b32 m0, s35
	ds_read_b128 v[204:207], v216
	ds_read_b128 v[208:211], v216 offset:1024
	ds_read_b128 v[212:215], v216 offset:2048
	ds_read_b128 v[216:219], v216 offset:3072
	global_load_lds_dwordx4 v[220:221], off
	v_lshl_add_u64 v[220:221], v[222:223], 0, s[8:9]
	s_add_i32 m0, s35, 0x2000
	s_nop 0
	global_load_lds_dwordx4 v[220:221], off
	s_barrier
	s_waitcnt lgkmcnt(0)
	s_setprio 1
	s_waitcnt lgkmcnt(0)
	v_mfma_f32_16x16x32_bf16 v[118:121], v[204:207], v[172:175], v[118:121]
	v_mfma_f32_16x16x32_bf16 v[110:113], v[212:215], v[172:175], v[110:113]
	v_mfma_f32_16x16x32_bf16 v[102:105], v[204:207], v[180:183], v[102:105]
	v_mfma_f32_16x16x32_bf16 v[94:97], v[212:215], v[180:183], v[94:97]
	v_mfma_f32_16x16x32_bf16 v[86:89], v[204:207], v[188:191], v[86:89]
	v_mfma_f32_16x16x32_bf16 v[78:81], v[212:215], v[188:191], v[78:81]
	v_mfma_f32_16x16x32_bf16 v[70:73], v[204:207], v[196:199], v[70:73]
	v_mfma_f32_16x16x32_bf16 v[66:69], v[212:215], v[196:199], v[66:69]
	v_mfma_f32_16x16x32_bf16 v[118:121], v[208:211], v[176:179], v[118:121]
	v_mfma_f32_16x16x32_bf16 v[110:113], v[216:219], v[176:179], v[110:113]
	v_mfma_f32_16x16x32_bf16 v[102:105], v[208:211], v[184:187], v[102:105]
	v_mfma_f32_16x16x32_bf16 v[94:97], v[216:219], v[184:187], v[94:97]
	v_mfma_f32_16x16x32_bf16 v[86:89], v[208:211], v[192:195], v[86:89]
	v_mfma_f32_16x16x32_bf16 v[78:81], v[216:219], v[192:195], v[78:81]
	v_mfma_f32_16x16x32_bf16 v[70:73], v[208:211], v[200:203], v[70:73]
	v_mfma_f32_16x16x32_bf16 v[66:69], v[216:219], v[200:203], v[66:69]
	s_setprio 0
	s_mov_b32 m0, s39
	v_lshl_add_u64 v[220:221], v[224:225], 0, s[8:9]
	s_barrier
	ds_read_b128 v[172:175], v154 offset:49152
	ds_read_b128 v[176:179], v154 offset:50176
	ds_read_b128 v[180:183], v154 offset:51200
	ds_read_b128 v[184:187], v154 offset:52224
	ds_read_b128 v[188:191], v154 offset:53248
	ds_read_b128 v[192:195], v154 offset:54272
	ds_read_b128 v[196:199], v154 offset:55296
	ds_read_b128 v[200:203], v154 offset:56320
	global_load_lds_dwordx4 v[220:221], off
	v_lshl_add_u64 v[220:221], v[226:227], 0, s[8:9]
	s_mov_b32 m0, s40
	s_nop 0
	global_load_lds_dwordx4 v[220:221], off
	s_barrier
; #define PG8_STAGE(bufoff, gbase, voff) do { _Pragma("unroll") for (int _i = 0; _i < 2; ++_i) \
;         __builtin_amdgcn_global_load_lds((const unsigned*)((const char*)(gbase) + (voff)[_i]), (LAS unsigned*)(lds + (bufoff) + ldsw + _i * 8192), 16, 0, 0); } while (0)
; #define PG8_MMA(ai, bj, At, Bt) do { __builtin_amdgcn_s_setprio(1); _Pragma("unroll") for (int m = 0; m < 4; ++m) _Pragma("unroll") for (int n = 0; n < 2; ++n) _Pragma("unroll") for (int k = 0; k < 2; ++k) \
;         acc[ai][bj][m][n] = __builtin_amdgcn_mfma_f32_16x16x32_bf16(Bt[n][k], At[m][k], acc[ai][bj][m][n], 0, 0, 0); __builtin_amdgcn_s_setprio(0); } while (0)
; #define PG8_WAIT_V(n) asm volatile("s_waitcnt vmcnt(" #n ")" ::: "memory")
; #define PG8_WAIT_L(n) asm volatile("s_waitcnt lgkmcnt(" #n ")" ::: "memory")
; #define PG8_BAR __builtin_amdgcn_s_barrier()
; #define PG8_SCHED __builtin_amdgcn_sched_barrier(0)
; template <class Sched, class Epi>
; __device__ __forceinline__ void gemm_phase(LAS unsigned char* lds, const Sched& S, const Epi& E, const int K, const int lda, const int ldb) {
;     ...
;             PG8_BAR; PG8_WAIT_L(0); if (!chalf) PG8_MMA(1, 0, At, B0); PG8_BAR; PG8_SCHED;
;             PG8_STAGE(PG8_SB(1, 1), b3 + hstepB, voffB);
;             PG8_WAIT_V(6); PG8_BAR; if (!chalf) PG8_MMA(1, 1, At, B1); PG8_BAR;
;         }
	s_waitcnt lgkmcnt(0)
	s_setprio 1
	s_waitcnt lgkmcnt(0)
	v_mfma_f32_16x16x32_bf16 v[62:65], v[156:159], v[172:175], v[62:65]
	v_mfma_f32_16x16x32_bf16 v[58:61], v[164:167], v[172:175], v[58:61]
	v_mfma_f32_16x16x32_bf16 v[54:57], v[156:159], v[180:183], v[54:57]
	v_mfma_f32_16x16x32_bf16 v[46:49], v[164:167], v[180:183], v[46:49]
	v_mfma_f32_16x16x32_bf16 v[38:41], v[156:159], v[188:191], v[38:41]
	v_mfma_f32_16x16x32_bf16 v[30:33], v[164:167], v[188:191], v[30:33]
	v_mfma_f32_16x16x32_bf16 v[22:25], v[156:159], v[196:199], v[22:25]
	v_mfma_f32_16x16x32_bf16 v[14:17], v[164:167], v[196:199], v[14:17]
	v_mfma_f32_16x16x32_bf16 v[62:65], v[160:163], v[176:179], v[62:65]
	v_mfma_f32_16x16x32_bf16 v[58:61], v[168:171], v[176:179], v[58:61]
	v_mfma_f32_16x16x32_bf16 v[54:57], v[160:163], v[184:187], v[54:57]
	v_mfma_f32_16x16x32_bf16 v[46:49], v[168:171], v[184:187], v[46:49]
	v_mfma_f32_16x16x32_bf16 v[38:41], v[160:163], v[192:195], v[38:41]
	v_mfma_f32_16x16x32_bf16 v[30:33], v[168:171], v[192:195], v[30:33]
	v_mfma_f32_16x16x32_bf16 v[22:25], v[160:163], v[200:203], v[22:25]
	v_mfma_f32_16x16x32_bf16 v[14:17], v[168:171], v[200:203], v[14:17]
	s_setprio 0
	s_barrier
	s_add_u32 s28, s28, 0x80080
	s_addc_u32 s29, s29, 0
	s_add_i32 s34, s34, s31
	s_mov_b32 m0, s34
	s_nop 0
	global_load_lds_dwordx4 v132, s[28:29]
	s_add_i32 m0, s34, 0x2000
	s_nop 0
	global_load_lds_dwordx4 v136, s[28:29]
	s_waitcnt vmcnt(6)
	s_barrier
	s_setprio 1
	v_mfma_f32_16x16x32_bf16 v[50:53], v[204:207], v[172:175], v[50:53]
	v_mfma_f32_16x16x32_bf16 v[42:45], v[212:215], v[172:175], v[42:45]
	v_mfma_f32_16x16x32_bf16 v[34:37], v[204:207], v[180:183], v[34:37]
	v_mfma_f32_16x16x32_bf16 v[26:29], v[212:215], v[180:183], v[26:29]
	v_mfma_f32_16x16x32_bf16 v[18:21], v[204:207], v[188:191], v[18:21]
	v_mfma_f32_16x16x32_bf16 v[10:13], v[212:215], v[188:191], v[10:13]
	v_mfma_f32_16x16x32_bf16 v[6:9], v[204:207], v[196:199], v[6:9]
	v_mfma_f32_16x16x32_bf16 v[2:5], v[212:215], v[196:199], v[2:5]
	v_mfma_f32_16x16x32_bf16 v[50:53], v[208:211], v[176:179], v[50:53]
	v_mfma_f32_16x16x32_bf16 v[42:45], v[216:219], v[176:179], v[42:45]
	v_mfma_f32_16x16x32_bf16 v[34:37], v[208:211], v[184:187], v[34:37]
	v_mfma_f32_16x16x32_bf16 v[26:29], v[216:219], v[184:187], v[26:29]
	v_mfma_f32_16x16x32_bf16 v[18:21], v[208:211], v[192:195], v[18:21]
	v_mfma_f32_16x16x32_bf16 v[10:13], v[216:219], v[192:195], v[10:13]
	v_mfma_f32_16x16x32_bf16 v[6:9], v[208:211], v[200:203], v[6:9]
	v_mfma_f32_16x16x32_bf16 v[2:5], v[216:219], v[200:203], v[2:5]
	s_setprio 0
	s_add_i32 s46, s46, 2
	s_add_u32 s15, s15, 0x100
	s_addc_u32 s17, s17, 0
	s_add_u32 s26, s26, 0x100
	s_addc_u32 s27, s27, 0
	s_cmp_gt_u32 s46, 29
	s_barrier
	s_cbranch_scc0 .LBB0_1593
; __device__ __forceinline__ unsigned cvt_pk_bf16(float lo, float hi) { unsigned r; asm volatile("v_cvt_pk_bf16_f32 %0, %1, %2" : "=v"(r) : "v"(lo), "v"(hi)); return r; }
; #define PG8_WAIT_V(n) asm volatile("s_waitcnt vmcnt(" #n ")" ::: "memory")
; #define PG8_BAR __builtin_amdgcn_s_barrier()
; #define EPI_FOR_ROWS _Pragma("unroll") for (int ai = 0; ai < 2; ++ai) if (ai == 0 || !u.half) _Pragma("unroll") for (int m = 0; m < 4; ++m)
; template <class Sched, class Epi>
; __device__ __forceinline__ void gemm_phase(LAS unsigned char* lds, const Sched& S, const Epi& E, const int K, const int lda, const int ldb) {
;     ...
;         E(acc, cur, wr, wc, fr, fq);
;         if (!has_next) break;
; #pragma unroll
;         for (int a = 0; a < 2; ++a)
; #pragma unroll
;             for (int b = 0; b < 2; ++b)
; #pragma unroll
;                 for (int m = 0; m < 4; ++m)
; #pragma unroll
;                     for (int n = 0; n < 2; ++n) acc[a][b][m][n] = (f32x4){0.f, 0.f, 0.f, 0.f};
;         cur = nxt; cA = nA; cB = nB; ++ui;
;     }
;     PG8_WAIT_V(0);
;     if (wr == 0) PG8_BAR;
;     PG8_BAR;
;     __device__ __forceinline__ void operator()(EPI_ARGS) const {
;         EPI_FOR_ROWS { bf16_t* rp = O + (size_t)EPI_ROW * ldc;
; #pragma unroll
;             for (int bj = 0; bj < 2; ++bj) { const f32x4 v0 = acc[ai][bj][m][0], v1 = acc[ai][bj][m][1]; u32x4 o;
;                 o[0] = cvt_pk_bf16(v0[0], v0[1]); o[1] = cvt_pk_bf16(v0[2], v0[3]); o[2] = cvt_pk_bf16(v1[0], v1[1]); o[3] = cvt_pk_bf16(v1[2], v1[3]);
;                 *(u32x4*)(rp + EPI_COL(bj)) = o; } }
	v_add_u32_e32 v156, s4, v1
	v_ashrrev_i32_e32 v157, 31, v156
	v_cvt_pk_bf16_f32 v126, v126, v127
	v_cvt_pk_bf16_f32 v127, v128, v129
	v_cvt_pk_bf16_f32 v128, v122, v123
	v_lshl_or_b32 v122, s45, 8, v152
	v_lshlrev_b64 v[156:157], 12, v[156:157]
	v_ashrrev_i32_e32 v123, 31, v122
	v_lshl_add_u64 v[156:157], s[6:7], 0, v[156:157]
	v_lshlrev_b64 v[122:123], 1, v[122:123]
	v_cvt_pk_bf16_f32 v129, v124, v125
	v_lshl_add_u64 v[124:125], v[156:157], 0, v[122:123]
	global_store_dwordx4 v[124:125], v[126:129], off
	v_cvt_pk_bf16_f32 v118, v118, v119
	v_cvt_pk_bf16_f32 v119, v120, v121
	v_cvt_pk_bf16_f32 v120, v110, v111
	v_add_u32_e32 v110, s4, v145
	v_ashrrev_i32_e32 v111, 31, v110
	v_lshlrev_b64 v[110:111], 12, v[110:111]
	v_cvt_pk_bf16_f32 v121, v112, v113
	global_store_dwordx4 v[124:125], v[118:121], off offset:256
	s_and_b64 vcc, exec, s[12:13]
	s_mov_b32 s45, s14
	v_lshl_add_u64 v[118:119], s[6:7], 0, v[110:111]
	v_cvt_pk_bf16_f32 v110, v114, v115
	v_cvt_pk_bf16_f32 v111, v116, v117
	v_cvt_pk_bf16_f32 v112, v106, v107
	v_lshl_add_u64 v[106:107], v[118:119], 0, v[122:123]
	v_cvt_pk_bf16_f32 v113, v108, v109
	global_store_dwordx4 v[106:107], v[110:113], off
	v_cvt_pk_bf16_f32 v102, v102, v103
	v_cvt_pk_bf16_f32 v103, v104, v105
	v_cvt_pk_bf16_f32 v104, v94, v95
	v_add_u32_e32 v94, s4, v146
	v_ashrrev_i32_e32 v95, 31, v94
	v_lshlrev_b64 v[94:95], 12, v[94:95]
	v_cvt_pk_bf16_f32 v105, v96, v97
	global_store_dwordx4 v[106:107], v[102:105], off offset:256
	s_mov_b64 s[28:29], s[20:21]
	s_mov_b64 s[26:27], s[18:19]
	v_lshl_add_u64 v[102:103], s[6:7], 0, v[94:95]
	v_cvt_pk_bf16_f32 v94, v98, v99
	v_cvt_pk_bf16_f32 v95, v100, v101
	v_cvt_pk_bf16_f32 v96, v90, v91
	v_lshl_add_u64 v[90:91], v[102:103], 0, v[122:123]
	v_cvt_pk_bf16_f32 v97, v92, v93
	global_store_dwordx4 v[90:91], v[94:97], off
	v_cvt_pk_bf16_f32 v86, v86, v87
	v_cvt_pk_bf16_f32 v87, v88, v89
	v_cvt_pk_bf16_f32 v88, v78, v79
	v_add_u32_e32 v78, s4, v147
	v_ashrrev_i32_e32 v79, 31, v78
	v_lshlrev_b64 v[78:79], 12, v[78:79]
	v_cvt_pk_bf16_f32 v89, v80, v81
	global_store_dwordx4 v[90:91], v[86:89], off offset:256
	s_nop 1
	v_lshl_add_u64 v[86:87], s[6:7], 0, v[78:79]
	v_cvt_pk_bf16_f32 v78, v82, v83
	v_cvt_pk_bf16_f32 v79, v84, v85
	v_cvt_pk_bf16_f32 v80, v74, v75
	v_lshl_add_u64 v[74:75], v[86:87], 0, v[122:123]
	v_cvt_pk_bf16_f32 v81, v76, v77
	global_store_dwordx4 v[74:75], v[78:81], off
	v_cvt_pk_bf16_f32 v70, v70, v71
	v_cvt_pk_bf16_f32 v71, v72, v73
	v_cvt_pk_bf16_f32 v72, v66, v67
	v_add_u32_e32 v66, s4, v148
	v_ashrrev_i32_e32 v67, 31, v66
	v_lshlrev_b64 v[66:67], 12, v[66:67]
	v_lshl_add_u64 v[66:67], s[6:7], 0, v[66:67]
	v_cvt_pk_bf16_f32 v73, v68, v69
	global_store_dwordx4 v[74:75], v[70:73], off offset:256
	v_cvt_pk_bf16_f32 v62, v62, v63
	v_cvt_pk_bf16_f32 v63, v64, v65
	v_cvt_pk_bf16_f32 v64, v58, v59
	v_lshl_add_u64 v[58:59], v[66:67], 0, v[122:123]
	v_cvt_pk_bf16_f32 v65, v60, v61
	global_store_dwordx4 v[58:59], v[62:65], off
	v_cvt_pk_bf16_f32 v50, v50, v51
	v_cvt_pk_bf16_f32 v51, v52, v53
	v_cvt_pk_bf16_f32 v52, v42, v43
	v_add_u32_e32 v42, s4, v149
	v_ashrrev_i32_e32 v43, 31, v42
	v_lshlrev_b64 v[42:43], 12, v[42:43]
	v_cvt_pk_bf16_f32 v53, v44, v45
	global_store_dwordx4 v[58:59], v[50:53], off offset:256
	s_nop 1
	v_lshl_add_u64 v[50:51], s[6:7], 0, v[42:43]
	v_cvt_pk_bf16_f32 v42, v54, v55
	v_cvt_pk_bf16_f32 v43, v56, v57
	v_cvt_pk_bf16_f32 v44, v46, v47
	v_lshl_add_u64 v[46:47], v[50:51], 0, v[122:123]
	v_cvt_pk_bf16_f32 v45, v48, v49
	global_store_dwordx4 v[46:47], v[42:45], off
	v_cvt_pk_bf16_f32 v34, v34, v35
	v_cvt_pk_bf16_f32 v35, v36, v37
	v_cvt_pk_bf16_f32 v36, v26, v27
	v_add_u32_e32 v26, s4, v150
	v_ashrrev_i32_e32 v27, 31, v26
	v_lshlrev_b64 v[26:27], 12, v[26:27]
	v_cvt_pk_bf16_f32 v37, v28, v29
	global_store_dwordx4 v[46:47], v[34:37], off offset:256
	s_nop 1
	v_lshl_add_u64 v[34:35], s[6:7], 0, v[26:27]
	v_cvt_pk_bf16_f32 v26, v38, v39
	v_cvt_pk_bf16_f32 v27, v40, v41
	v_cvt_pk_bf16_f32 v28, v30, v31
	v_lshl_add_u64 v[30:31], v[34:35], 0, v[122:123]
	v_cvt_pk_bf16_f32 v29, v32, v33
	global_store_dwordx4 v[30:31], v[26:29], off
	v_cvt_pk_bf16_f32 v18, v18, v19
	v_cvt_pk_bf16_f32 v19, v20, v21
	v_cvt_pk_bf16_f32 v20, v10, v11
	v_add_u32_e32 v10, s4, v151
	v_ashrrev_i32_e32 v11, 31, v10
	v_lshlrev_b64 v[10:11], 12, v[10:11]
	v_cvt_pk_bf16_f32 v21, v12, v13
	global_store_dwordx4 v[30:31], v[18:21], off offset:256
	s_mov_b32 s4, s16
	s_nop 0
	v_lshl_add_u64 v[18:19], s[6:7], 0, v[10:11]
	v_cvt_pk_bf16_f32 v10, v22, v23
	v_cvt_pk_bf16_f32 v11, v24, v25
	v_cvt_pk_bf16_f32 v12, v14, v15
	v_lshl_add_u64 v[14:15], v[18:19], 0, v[122:123]
	v_cvt_pk_bf16_f32 v13, v16, v17
	global_store_dwordx4 v[14:15], v[10:13], off
	v_cvt_pk_bf16_f32 v6, v6, v7
	v_cvt_pk_bf16_f32 v7, v8, v9
	v_cvt_pk_bf16_f32 v8, v2, v3
	v_cvt_pk_bf16_f32 v9, v4, v5
	global_store_dwordx4 v[14:15], v[6:9], off offset:256
	s_cbranch_vccz .LBB0_1586
	s_waitcnt vmcnt(0)
	s_cmpk_gt_u32 s1, 0xff
	s_cbranch_scc1 .LBB0_1597
	s_barrier
